# K-loops: MFMA order keeps the first source fragment fixed for four consecutive MFMAs (n0: m0..m3, n1: m3..m0)
# baseline (speedup 1.0000x reference)
; #define PG8_STAGEA(bufoff, gbase) PG8_STAGE_(bufoff, gbase, voffA)
; #define PG8_STAGEB(bufoff, gbase) PG8_STAGE_(bufoff, gbase, voffB)
; #define PG8_LDA(dst, b, h) do { _Pragma("unroll") for (int m = 0; m < 4; ++m) _Pragma("unroll") for (int k = 0; k < 2; ++k) dst[m][k] = *(const LAS bf16x8*)(lds + PG8_SA(b, h) + aoff + m * 2048 + k * 1024); } while (0)
; #define PG8_LDB(dst, b, h) do { _Pragma("unroll") for (int n = 0; n < 2; ++n) _Pragma("unroll") for (int k = 0; k < 2; ++k) dst[n][k] = *(const LAS bf16x8*)(lds + PG8_SB(b, h) + boff + n * 2048 + k * 1024); } while (0)
; #define PG8_MMA(ai, bj, At, Bt_) do { __builtin_amdgcn_s_setprio(1); _Pragma("unroll") for (int m = 0; m < 4; ++m) _Pragma("unroll") for (int n = 0; n < 2; ++n) _Pragma("unroll") for (int k = 0; k < 2; ++k) \
;         acc[ai][bj][m][n] = __builtin_amdgcn_mfma_f32_16x16x32_bf16(Bt_[n][k], At[m][k], acc[ai][bj][m][n], 0, 0, 0); __builtin_amdgcn_s_setprio(0); } while (0)
; #define PG8_WAIT_V(n) asm volatile("s_waitcnt vmcnt(" #n ")" ::: "memory")
; #define PG8_WAIT_L(n) asm volatile("s_waitcnt lgkmcnt(" #n ")" ::: "memory")
; #define PG8_BAR __builtin_amdgcn_s_barrier()
; #define PG8_SCHED __builtin_amdgcn_sched_barrier(0)
; template <int EK, int SK = -1>
; __device__ __forceinline__ void gemm_phase(LAS unsigned char* lds, const bf16_t* A, const bf16_t* Bt, int nM, int N, int K, const EpiArgs& E) {
;     ...
;         const bool has_next = S.next(ui + 1, nxt);
;         const char* nA = has_next ? (const char*)A + (size_t)nxt.pm * tstep : cA; const char* nB = has_next ? (const char*)Bt + (size_t)nxt.pn * tstep : cB;
;         for (int t = 0; t < nt; t += 2) {
;             const bool last = (t == nt - 2);
;             const char* a1 = cA + (size_t)(t + 1) * kstep;
;             const char* a2 = last ? nA : cA + (size_t)(t + 2) * kstep; const char* b2 = last ? nB : cB + (size_t)(t + 2) * kstep;
;             const char* a3 = a2 + kstep; const char* b3 = b2 + kstep;
;             PG8_LDB(B0, 0, 0); PG8_LDB(B1, 0, 1); PG8_SCHED; PG8_LDA(At, 0, 0); PG8_STAGEA(PG8_SA(1, 1), a1 + hstep);
;             PG8_WAIT_V(8); PG8_WAIT_L(0); PG8_BAR; PG8_MMA(0, 0, At, B0); PG8_MMA(0, 1, At, B1); PG8_BAR; PG8_SCHED;
;             PG8_LDA(At, 0, 1); PG8_STAGEB(PG8_SB(0, 0), b2); PG8_STAGEB(PG8_SB(0, 1), b2 + hstep); PG8_STAGEA(PG8_SA(0, 0), a2);
.LBB0_197:
	s_add_u32 s58, s78, 0x100
	s_addc_u32 s59, s79, 0
	s_ashr_i32 s75, s74, 31
	s_lshl_b64 s[76:77], s[74:75], 19
	s_add_u32 s80, s62, s76
	s_addc_u32 s81, s63, s77
	s_and_b64 s[76:77], s[6:7], exec
	s_cselect_b32 s75, s81, s71
	s_cselect_b32 s90, s80, s70
	s_ashr_i32 s73, s72, 31
	s_lshl_b64 s[76:77], s[72:73], 19
	s_add_u32 s76, s30, s76
	s_addc_u32 s77, s31, s77
	s_and_b64 s[82:83], s[6:7], exec
	s_cselect_b32 s73, s77, s79
	s_cselect_b32 s91, s76, s78
	v_lshl_add_u64 v[146:147], s[70:71], 0, v[138:139]
	v_lshl_add_u64 v[148:149], s[70:71], 0, v[140:141]
	s_mov_b32 s92, -2
	s_mov_b64 s[78:79], 0
	v_add_u32_e32 v150, s54, v152
	ds_read_b128 v[156:159], v150
	ds_read_b128 v[160:163], v150 offset:1024
	ds_read_b128 v[164:167], v150 offset:2048
	ds_read_b128 v[168:171], v150 offset:3072
	v_add_u32_e32 v150, s55, v152
	s_add_u32 s82, s70, s78
	ds_read_b128 v[172:175], v150
	ds_read_b128 v[176:179], v150 offset:1024
	ds_read_b128 v[180:183], v150 offset:2048
	ds_read_b128 v[184:187], v150 offset:3072
	s_addc_u32 s83, s71, s79
	s_add_u32 s82, s82, 0x100
	s_addc_u32 s83, s83, 0
	s_add_u32 s93, s58, s78
	s_addc_u32 s94, s59, s79
	s_cmpk_eq_i32 s78, 0x700
	s_cselect_b32 s85, s75, s83
	s_cselect_b32 s84, s90, s82
	s_cselect_b32 s83, s73, s94
	s_cselect_b32 s82, s91, s93
	v_lshl_add_u64 v[150:151], v[146:147], 0, s[78:79]
	s_add_i32 m0, s67, 0xc000
	ds_read_b128 v[188:191], v155
	ds_read_b128 v[192:195], v155 offset:1024
	ds_read_b128 v[196:199], v155 offset:2048
	ds_read_b128 v[200:203], v155 offset:3072
	ds_read_b128 v[204:207], v155 offset:4096
	ds_read_b128 v[208:211], v155 offset:5120
	ds_read_b128 v[212:215], v155 offset:6144
	ds_read_b128 v[216:219], v155 offset:7168
	global_load_lds_dwordx4 v[150:151], off
	v_lshl_add_u64 v[150:151], v[148:149], 0, s[78:79]
	s_add_i32 m0, s67, 0xe000
	s_nop 0
	global_load_lds_dwordx4 v[150:151], off
	s_waitcnt vmcnt(8)
	s_waitcnt lgkmcnt(0)
	s_barrier
	s_waitcnt lgkmcnt(0)
	v_mfma_f32_16x16x32_bf16 v[110:113], v[156:159], v[188:191], 0
	v_mfma_f32_16x16x32_bf16 v[102:105], v[156:159], v[196:199], 0
	v_mfma_f32_16x16x32_bf16 v[94:97], v[156:159], v[204:207], 0
	v_mfma_f32_16x16x32_bf16 v[86:89], v[156:159], v[212:215], 0
	v_mfma_f32_16x16x32_bf16 v[82:85], v[164:167], v[212:215], 0
	v_mfma_f32_16x16x32_bf16 v[90:93], v[164:167], v[204:207], 0
	v_mfma_f32_16x16x32_bf16 v[98:101], v[164:167], v[196:199], 0
	v_mfma_f32_16x16x32_bf16 v[106:109], v[164:167], v[188:191], 0
	v_mfma_f32_16x16x32_bf16 v[110:113], v[160:163], v[192:195], v[110:113]
	v_mfma_f32_16x16x32_bf16 v[102:105], v[160:163], v[200:203], v[102:105]
	v_mfma_f32_16x16x32_bf16 v[94:97], v[160:163], v[208:211], v[94:97]
	v_mfma_f32_16x16x32_bf16 v[86:89], v[160:163], v[216:219], v[86:89]
	v_mfma_f32_16x16x32_bf16 v[82:85], v[168:171], v[216:219], v[82:85]
	v_mfma_f32_16x16x32_bf16 v[90:93], v[168:171], v[208:211], v[90:93]
	v_mfma_f32_16x16x32_bf16 v[98:101], v[168:171], v[200:203], v[98:101]
	v_mfma_f32_16x16x32_bf16 v[106:109], v[168:171], v[192:195], v[106:109]
	v_mfma_f32_16x16x32_bf16 v[78:81], v[172:175], v[188:191], 0
	v_mfma_f32_16x16x32_bf16 v[70:73], v[172:175], v[196:199], 0
	v_mfma_f32_16x16x32_bf16 v[62:65], v[172:175], v[204:207], 0
	v_mfma_f32_16x16x32_bf16 v[54:57], v[172:175], v[212:215], 0
	v_mfma_f32_16x16x32_bf16 v[50:53], v[180:183], v[212:215], 0
	v_mfma_f32_16x16x32_bf16 v[58:61], v[180:183], v[204:207], 0
	v_mfma_f32_16x16x32_bf16 v[66:69], v[180:183], v[196:199], 0
	v_mfma_f32_16x16x32_bf16 v[74:77], v[180:183], v[188:191], 0
	v_mfma_f32_16x16x32_bf16 v[78:81], v[176:179], v[192:195], v[78:81]
	v_mfma_f32_16x16x32_bf16 v[70:73], v[176:179], v[200:203], v[70:73]
	v_mfma_f32_16x16x32_bf16 v[62:65], v[176:179], v[208:211], v[62:65]
	v_mfma_f32_16x16x32_bf16 v[54:57], v[176:179], v[216:219], v[54:57]
	v_mfma_f32_16x16x32_bf16 v[50:53], v[184:187], v[216:219], v[50:53]
	v_mfma_f32_16x16x32_bf16 v[58:61], v[184:187], v[208:211], v[58:61]
	v_mfma_f32_16x16x32_bf16 v[66:69], v[184:187], v[200:203], v[66:69]
	v_mfma_f32_16x16x32_bf16 v[74:77], v[184:187], v[192:195], v[74:77]
	s_barrier
	s_add_i32 s93, s54, s87
	v_lshl_add_u64 v[150:151], s[82:83], 0, v[132:133]
	s_mov_b32 m0, s93
	ds_read_b128 v[188:191], v155 offset:16384
	ds_read_b128 v[192:195], v155 offset:17408
	ds_read_b128 v[196:199], v155 offset:18432
	ds_read_b128 v[200:203], v155 offset:19456
	ds_read_b128 v[204:207], v155 offset:20480
	ds_read_b128 v[208:211], v155 offset:21504
	ds_read_b128 v[212:215], v155 offset:22528
	ds_read_b128 v[216:219], v155 offset:23552
	global_load_lds_dwordx4 v[150:151], off
	s_add_i32 m0, s93, 0x2000
	s_add_u32 s94, s82, 0x40000
	v_lshl_add_u64 v[220:221], s[82:83], 0, v[136:137]
	s_addc_u32 s95, s83, 0
	s_add_i32 s93, s55, s87
	global_load_lds_dwordx4 v[220:221], off
	v_lshl_add_u64 v[222:223], s[94:95], 0, v[132:133]
	s_mov_b32 m0, s93
	v_lshl_add_u64 v[224:225], s[84:85], 0, v[134:135]
	global_load_lds_dwordx4 v[222:223], off
	v_lshl_add_u64 v[222:223], s[94:95], 0, v[136:137]
	s_add_i32 m0, s93, 0x2000
	s_nop 0
	global_load_lds_dwordx4 v[222:223], off
	v_lshl_add_u64 v[222:223], s[84:85], 0, v[130:131]
	s_mov_b32 m0, s67
	s_nop 0
	global_load_lds_dwordx4 v[222:223], off
	s_mov_b32 m0, s69
	s_nop 0
	global_load_lds_dwordx4 v[224:225], off
	s_waitcnt vmcnt(8)
	s_waitcnt lgkmcnt(0)
	s_barrier
; #define PG8_STAGEA(bufoff, gbase) PG8_STAGE_(bufoff, gbase, voffA)
; #define PG8_LDA(dst, b, h) do { _Pragma("unroll") for (int m = 0; m < 4; ++m) _Pragma("unroll") for (int k = 0; k < 2; ++k) dst[m][k] = *(const LAS bf16x8*)(lds + PG8_SA(b, h) + aoff + m * 2048 + k * 1024); } while (0)
; #define PG8_LDB(dst, b, h) do { _Pragma("unroll") for (int n = 0; n < 2; ++n) _Pragma("unroll") for (int k = 0; k < 2; ++k) dst[n][k] = *(const LAS bf16x8*)(lds + PG8_SB(b, h) + boff + n * 2048 + k * 1024); } while (0)
; #define PG8_MMA(ai, bj, At, Bt_) do { __builtin_amdgcn_s_setprio(1); _Pragma("unroll") for (int m = 0; m < 4; ++m) _Pragma("unroll") for (int n = 0; n < 2; ++n) _Pragma("unroll") for (int k = 0; k < 2; ++k) \
;         acc[ai][bj][m][n] = __builtin_amdgcn_mfma_f32_16x16x32_bf16(Bt_[n][k], At[m][k], acc[ai][bj][m][n], 0, 0, 0); __builtin_amdgcn_s_setprio(0); } while (0)
; #define PG8_WAIT_V(n) asm volatile("s_waitcnt vmcnt(" #n ")" ::: "memory")
; #define PG8_WAIT_L(n) asm volatile("s_waitcnt lgkmcnt(" #n ")" ::: "memory")
; #define PG8_BAR __builtin_amdgcn_s_barrier()
; #define PG8_SCHED __builtin_amdgcn_sched_barrier(0)
; template <int EK, int SK = -1>
; __device__ __forceinline__ void gemm_phase(LAS unsigned char* lds, const bf16_t* A, const bf16_t* Bt, int nM, int N, int K, const EpiArgs& E) {
;     ...
;             PG8_WAIT_V(8); PG8_WAIT_L(0); PG8_BAR; PG8_MMA(1, 0, At, B0); PG8_MMA(1, 1, At, B1); PG8_BAR; PG8_SCHED;
;             PG8_LDB(B0, 1, 0); PG8_LDB(B1, 1, 1); PG8_SCHED; PG8_LDA(At, 1, 0); PG8_STAGEA(PG8_SA(0, 1), a2 + hstep);
;             PG8_WAIT_V(8); PG8_WAIT_L(0); PG8_BAR; PG8_MMA(0, 0, At, B0); PG8_MMA(0, 1, At, B1); PG8_BAR; PG8_SCHED;
	s_waitcnt lgkmcnt(0)
	v_mfma_f32_16x16x32_bf16 v[46:49], v[156:159], v[188:191], 0
	v_mfma_f32_16x16x32_bf16 v[38:41], v[156:159], v[196:199], 0
	v_mfma_f32_16x16x32_bf16 v[30:33], v[156:159], v[204:207], 0
	v_mfma_f32_16x16x32_bf16 v[22:25], v[156:159], v[212:215], 0
	v_mfma_f32_16x16x32_bf16 v[18:21], v[164:167], v[212:215], 0
	v_mfma_f32_16x16x32_bf16 v[26:29], v[164:167], v[204:207], 0
	v_mfma_f32_16x16x32_bf16 v[34:37], v[164:167], v[196:199], 0
	v_mfma_f32_16x16x32_bf16 v[42:45], v[164:167], v[188:191], 0
	v_mfma_f32_16x16x32_bf16 v[46:49], v[160:163], v[192:195], v[46:49]
	v_mfma_f32_16x16x32_bf16 v[38:41], v[160:163], v[200:203], v[38:41]
	v_mfma_f32_16x16x32_bf16 v[30:33], v[160:163], v[208:211], v[30:33]
	v_mfma_f32_16x16x32_bf16 v[22:25], v[160:163], v[216:219], v[22:25]
	v_mfma_f32_16x16x32_bf16 v[18:21], v[168:171], v[216:219], v[18:21]
	v_mfma_f32_16x16x32_bf16 v[26:29], v[168:171], v[208:211], v[26:29]
	v_mfma_f32_16x16x32_bf16 v[34:37], v[168:171], v[200:203], v[34:37]
	v_mfma_f32_16x16x32_bf16 v[42:45], v[168:171], v[192:195], v[42:45]
	v_mfma_f32_16x16x32_bf16 v[14:17], v[172:175], v[188:191], 0
	v_mfma_f32_16x16x32_bf16 v[6:9], v[172:175], v[196:199], 0
	v_mfma_f32_16x16x32_bf16 v[114:117], v[172:175], v[204:207], 0
	v_mfma_f32_16x16x32_bf16 v[122:125], v[172:175], v[212:215], 0
	v_mfma_f32_16x16x32_bf16 v[126:129], v[180:183], v[212:215], 0
	v_mfma_f32_16x16x32_bf16 v[118:121], v[180:183], v[204:207], 0
	v_mfma_f32_16x16x32_bf16 v[2:5], v[180:183], v[196:199], 0
	v_mfma_f32_16x16x32_bf16 v[10:13], v[180:183], v[188:191], 0
	v_mfma_f32_16x16x32_bf16 v[14:17], v[176:179], v[192:195], v[14:17]
	v_mfma_f32_16x16x32_bf16 v[6:9], v[176:179], v[200:203], v[6:9]
	v_mfma_f32_16x16x32_bf16 v[114:117], v[176:179], v[208:211], v[114:117]
	v_mfma_f32_16x16x32_bf16 v[122:125], v[176:179], v[216:219], v[122:125]
	v_mfma_f32_16x16x32_bf16 v[126:129], v[184:187], v[216:219], v[126:129]
	v_mfma_f32_16x16x32_bf16 v[118:121], v[184:187], v[208:211], v[118:121]
	v_mfma_f32_16x16x32_bf16 v[2:5], v[184:187], v[200:203], v[2:5]
	v_mfma_f32_16x16x32_bf16 v[10:13], v[184:187], v[192:195], v[10:13]
	s_barrier
	s_add_i32 s93, 0, 0x18000
	s_add_i32 s94, 0, 0x1c000
	v_add_u32_e32 v168, s93, v152
	v_add_u32_e32 v184, s94, v152
	ds_read_b128 v[156:159], v168
	ds_read_b128 v[160:163], v168 offset:1024
	ds_read_b128 v[164:167], v168 offset:2048
	ds_read_b128 v[168:171], v168 offset:3072
	ds_read_b128 v[172:175], v184
	ds_read_b128 v[176:179], v184 offset:1024
	ds_read_b128 v[180:183], v184 offset:2048
	ds_read_b128 v[184:187], v184 offset:3072
	s_add_u32 s84, s84, 0x40000
	s_addc_u32 s85, s85, 0
	s_mov_b32 m0, s88
	v_lshl_add_u64 v[226:227], s[84:85], 0, v[130:131]
	ds_read_b128 v[188:191], v155 offset:32768
	ds_read_b128 v[192:195], v155 offset:33792
	ds_read_b128 v[196:199], v155 offset:34816
	ds_read_b128 v[200:203], v155 offset:35840
	ds_read_b128 v[204:207], v155 offset:36864
	ds_read_b128 v[208:211], v155 offset:37888
	ds_read_b128 v[212:215], v155 offset:38912
	ds_read_b128 v[216:219], v155 offset:39936
	global_load_lds_dwordx4 v[226:227], off
	v_lshl_add_u64 v[226:227], s[84:85], 0, v[134:135]
	s_mov_b32 m0, s89
	s_nop 0
	global_load_lds_dwordx4 v[226:227], off
	s_waitcnt vmcnt(8)
	s_waitcnt lgkmcnt(0)
	s_barrier
	s_waitcnt lgkmcnt(0)
	v_mfma_f32_16x16x32_bf16 v[110:113], v[156:159], v[188:191], v[110:113]
	v_mfma_f32_16x16x32_bf16 v[102:105], v[156:159], v[196:199], v[102:105]
	v_mfma_f32_16x16x32_bf16 v[94:97], v[156:159], v[204:207], v[94:97]
	v_mfma_f32_16x16x32_bf16 v[86:89], v[156:159], v[212:215], v[86:89]
	v_mfma_f32_16x16x32_bf16 v[82:85], v[164:167], v[212:215], v[82:85]
	v_mfma_f32_16x16x32_bf16 v[90:93], v[164:167], v[204:207], v[90:93]
	v_mfma_f32_16x16x32_bf16 v[98:101], v[164:167], v[196:199], v[98:101]
	v_mfma_f32_16x16x32_bf16 v[106:109], v[164:167], v[188:191], v[106:109]
	v_mfma_f32_16x16x32_bf16 v[110:113], v[160:163], v[192:195], v[110:113]
	v_mfma_f32_16x16x32_bf16 v[102:105], v[160:163], v[200:203], v[102:105]
	v_mfma_f32_16x16x32_bf16 v[94:97], v[160:163], v[208:211], v[94:97]
	v_mfma_f32_16x16x32_bf16 v[86:89], v[160:163], v[216:219], v[86:89]
	v_mfma_f32_16x16x32_bf16 v[82:85], v[168:171], v[216:219], v[82:85]
	v_mfma_f32_16x16x32_bf16 v[90:93], v[168:171], v[208:211], v[90:93]
	v_mfma_f32_16x16x32_bf16 v[98:101], v[168:171], v[200:203], v[98:101]
	v_mfma_f32_16x16x32_bf16 v[106:109], v[168:171], v[192:195], v[106:109]
	v_mfma_f32_16x16x32_bf16 v[78:81], v[172:175], v[188:191], v[78:81]
	v_mfma_f32_16x16x32_bf16 v[70:73], v[172:175], v[196:199], v[70:73]
	v_mfma_f32_16x16x32_bf16 v[62:65], v[172:175], v[204:207], v[62:65]
	v_mfma_f32_16x16x32_bf16 v[54:57], v[172:175], v[212:215], v[54:57]
	v_mfma_f32_16x16x32_bf16 v[50:53], v[180:183], v[212:215], v[50:53]
	v_mfma_f32_16x16x32_bf16 v[58:61], v[180:183], v[204:207], v[58:61]
	v_mfma_f32_16x16x32_bf16 v[66:69], v[180:183], v[196:199], v[66:69]
	v_mfma_f32_16x16x32_bf16 v[74:77], v[180:183], v[188:191], v[74:77]
	v_mfma_f32_16x16x32_bf16 v[78:81], v[176:179], v[192:195], v[78:81]
	v_mfma_f32_16x16x32_bf16 v[70:73], v[176:179], v[200:203], v[70:73]
	v_mfma_f32_16x16x32_bf16 v[62:65], v[176:179], v[208:211], v[62:65]
	v_mfma_f32_16x16x32_bf16 v[54:57], v[176:179], v[216:219], v[54:57]
	v_mfma_f32_16x16x32_bf16 v[50:53], v[184:187], v[216:219], v[50:53]
	v_mfma_f32_16x16x32_bf16 v[58:61], v[184:187], v[208:211], v[58:61]
	v_mfma_f32_16x16x32_bf16 v[66:69], v[184:187], v[200:203], v[66:69]
	v_mfma_f32_16x16x32_bf16 v[74:77], v[184:187], v[192:195], v[74:77]
	s_barrier
; #define PG8_STAGEA(bufoff, gbase) PG8_STAGE_(bufoff, gbase, voffA)
; #define PG8_STAGEB(bufoff, gbase) PG8_STAGE_(bufoff, gbase, voffB)
; #define PG8_LDA(dst, b, h) do { _Pragma("unroll") for (int m = 0; m < 4; ++m) _Pragma("unroll") for (int k = 0; k < 2; ++k) dst[m][k] = *(const LAS bf16x8*)(lds + PG8_SA(b, h) + aoff + m * 2048 + k * 1024); } while (0)
; #define PG8_LDB(dst, b, h) do { _Pragma("unroll") for (int n = 0; n < 2; ++n) _Pragma("unroll") for (int k = 0; k < 2; ++k) dst[n][k] = *(const LAS bf16x8*)(lds + PG8_SB(b, h) + boff + n * 2048 + k * 1024); } while (0)
; #define PG8_WAIT_V(n) asm volatile("s_waitcnt vmcnt(" #n ")" ::: "memory")
; #define PG8_WAIT_L(n) asm volatile("s_waitcnt lgkmcnt(" #n ")" ::: "memory")
; #define PG8_BAR __builtin_amdgcn_s_barrier()
; #define PG8_SCHED __builtin_amdgcn_sched_barrier(0)
; template <int EK, int SK = -1>
; __device__ __forceinline__ void gemm_phase(LAS unsigned char* lds, const bf16_t* A, const bf16_t* Bt, int nM, int N, int K, const EpiArgs& E) {
;     ...
;         for (int t = 0; t < nt; t += 2) {
;             const bool last = (t == nt - 2);
;             const char* a1 = cA + (size_t)(t + 1) * kstep;
;             const char* a2 = last ? nA : cA + (size_t)(t + 2) * kstep; const char* b2 = last ? nB : cB + (size_t)(t + 2) * kstep;
;             const char* a3 = a2 + kstep; const char* b3 = b2 + kstep;
;             PG8_LDB(B0, 0, 0); PG8_LDB(B1, 0, 1); PG8_SCHED; PG8_LDA(At, 0, 0); PG8_STAGEA(PG8_SA(1, 1), a1 + hstep);
;             PG8_WAIT_V(8); PG8_WAIT_L(0); PG8_BAR; PG8_MMA(0, 0, At, B0); PG8_MMA(0, 1, At, B1); PG8_BAR; PG8_SCHED;
;             PG8_LDA(At, 0, 1); PG8_STAGEB(PG8_SB(0, 0), b2); PG8_STAGEB(PG8_SB(0, 1), b2 + hstep); PG8_STAGEA(PG8_SA(0, 0), a2);
;             PG8_WAIT_V(8); PG8_WAIT_L(0); PG8_BAR; PG8_MMA(1, 0, At, B0); PG8_MMA(1, 1, At, B1); PG8_BAR; PG8_SCHED;
;             PG8_LDB(B0, 1, 0); PG8_LDB(B1, 1, 1); PG8_SCHED; PG8_LDA(At, 1, 0); PG8_STAGEA(PG8_SA(0, 1), a2 + hstep);
;             PG8_WAIT_V(8); PG8_WAIT_L(0); PG8_BAR; PG8_MMA(0, 0, At, B0); PG8_MMA(0, 1, At, B1); PG8_BAR; PG8_SCHED;
;             PG8_LDA(At, 1, 1); PG8_STAGEB(PG8_SB(1, 0), b3); PG8_STAGEB(PG8_SB(1, 1), b3 + hstep); PG8_STAGEA(PG8_SA(1, 0), a3);
;             PG8_WAIT_V(8); PG8_WAIT_L(0); PG8_BAR; PG8_MMA(1, 0, At, B0); PG8_MMA(1, 1, At, B1); PG8_BAR; PG8_SCHED;
	s_add_i32 s84, s93, s87
	v_lshl_add_u64 v[150:151], v[150:151], 0, s[10:11]
	s_mov_b32 m0, s84
	ds_read_b128 v[188:191], v155 offset:49152
	ds_read_b128 v[192:195], v155 offset:50176
	ds_read_b128 v[196:199], v155 offset:51200
	ds_read_b128 v[200:203], v155 offset:52224
	ds_read_b128 v[204:207], v155 offset:53248
	ds_read_b128 v[208:211], v155 offset:54272
	ds_read_b128 v[212:215], v155 offset:55296
	ds_read_b128 v[216:219], v155 offset:56320
	global_load_lds_dwordx4 v[150:151], off
	s_add_i32 m0, s84, 0x2000
	s_add_u32 s82, s82, 0x40080
	v_lshl_add_u64 v[150:151], v[220:221], 0, s[10:11]
	s_addc_u32 s83, s83, 0
	s_add_i32 s84, s94, s87
	global_load_lds_dwordx4 v[150:151], off
	v_lshl_add_u64 v[150:151], s[82:83], 0, v[132:133]
	s_mov_b32 m0, s84
	s_nop 0
	global_load_lds_dwordx4 v[150:151], off
	v_lshl_add_u64 v[150:151], s[82:83], 0, v[136:137]
	s_add_i32 m0, s84, 0x2000
	s_nop 0
	global_load_lds_dwordx4 v[150:151], off
	v_lshl_add_u64 v[150:151], v[222:223], 0, s[10:11]
	s_mov_b32 m0, s52
	s_nop 0
	global_load_lds_dwordx4 v[150:151], off
	v_lshl_add_u64 v[150:151], v[224:225], 0, s[10:11]
	s_mov_b32 m0, s53
	s_nop 0
	global_load_lds_dwordx4 v[150:151], off
	s_waitcnt vmcnt(8)
	s_waitcnt lgkmcnt(0)
	s_barrier
	s_waitcnt lgkmcnt(0)
	v_mfma_f32_16x16x32_bf16 v[46:49], v[156:159], v[188:191], v[46:49]
	v_mfma_f32_16x16x32_bf16 v[38:41], v[156:159], v[196:199], v[38:41]
	v_mfma_f32_16x16x32_bf16 v[30:33], v[156:159], v[204:207], v[30:33]
	v_mfma_f32_16x16x32_bf16 v[22:25], v[156:159], v[212:215], v[22:25]
	v_mfma_f32_16x16x32_bf16 v[18:21], v[164:167], v[212:215], v[18:21]
	v_mfma_f32_16x16x32_bf16 v[26:29], v[164:167], v[204:207], v[26:29]
	v_mfma_f32_16x16x32_bf16 v[34:37], v[164:167], v[196:199], v[34:37]
	v_mfma_f32_16x16x32_bf16 v[42:45], v[164:167], v[188:191], v[42:45]
	v_mfma_f32_16x16x32_bf16 v[46:49], v[160:163], v[192:195], v[46:49]
	v_mfma_f32_16x16x32_bf16 v[38:41], v[160:163], v[200:203], v[38:41]
	v_mfma_f32_16x16x32_bf16 v[30:33], v[160:163], v[208:211], v[30:33]
	v_mfma_f32_16x16x32_bf16 v[22:25], v[160:163], v[216:219], v[22:25]
	v_mfma_f32_16x16x32_bf16 v[18:21], v[168:171], v[216:219], v[18:21]
	v_mfma_f32_16x16x32_bf16 v[26:29], v[168:171], v[208:211], v[26:29]
	v_mfma_f32_16x16x32_bf16 v[34:37], v[168:171], v[200:203], v[34:37]
	v_mfma_f32_16x16x32_bf16 v[42:45], v[168:171], v[192:195], v[42:45]
	v_mfma_f32_16x16x32_bf16 v[14:17], v[172:175], v[188:191], v[14:17]
	v_mfma_f32_16x16x32_bf16 v[6:9], v[172:175], v[196:199], v[6:9]
	v_mfma_f32_16x16x32_bf16 v[114:117], v[172:175], v[204:207], v[114:117]
	v_mfma_f32_16x16x32_bf16 v[122:125], v[172:175], v[212:215], v[122:125]
	v_mfma_f32_16x16x32_bf16 v[126:129], v[180:183], v[212:215], v[126:129]
	v_mfma_f32_16x16x32_bf16 v[118:121], v[180:183], v[204:207], v[118:121]
	v_mfma_f32_16x16x32_bf16 v[2:5], v[180:183], v[196:199], v[2:5]
	v_mfma_f32_16x16x32_bf16 v[10:13], v[180:183], v[188:191], v[10:13]
	v_mfma_f32_16x16x32_bf16 v[14:17], v[176:179], v[192:195], v[14:17]
	v_mfma_f32_16x16x32_bf16 v[6:9], v[176:179], v[200:203], v[6:9]
	v_mfma_f32_16x16x32_bf16 v[114:117], v[176:179], v[208:211], v[114:117]
	v_mfma_f32_16x16x32_bf16 v[122:125], v[176:179], v[216:219], v[122:125]
	v_mfma_f32_16x16x32_bf16 v[126:129], v[184:187], v[216:219], v[126:129]
	v_mfma_f32_16x16x32_bf16 v[118:121], v[184:187], v[208:211], v[118:121]
	v_mfma_f32_16x16x32_bf16 v[2:5], v[184:187], v[200:203], v[2:5]
	v_mfma_f32_16x16x32_bf16 v[10:13], v[184:187], v[192:195], v[10:13]
	s_barrier
	s_add_i32 s92, s92, 2
	s_add_u32 s78, s78, 0x100
	s_addc_u32 s79, s79, 0
	s_cmp_gt_u32 s92, 13
	s_cbranch_scc0 .LBB0_198
	s_branch .Lmy_kexit_0
.LBB0_198:
	v_add_u32_e32 v150, s54, v152
	ds_read_b128 v[156:159], v150
	ds_read_b128 v[160:163], v150 offset:1024
	ds_read_b128 v[164:167], v150 offset:2048
	ds_read_b128 v[168:171], v150 offset:3072
	v_add_u32_e32 v150, s55, v152
	s_add_u32 s82, s70, s78
	ds_read_b128 v[172:175], v150
	ds_read_b128 v[176:179], v150 offset:1024
	ds_read_b128 v[180:183], v150 offset:2048
	ds_read_b128 v[184:187], v150 offset:3072
	s_addc_u32 s83, s71, s79
	s_add_u32 s82, s82, 0x100
	s_addc_u32 s83, s83, 0
	s_add_u32 s93, s58, s78
	s_addc_u32 s94, s59, s79
	s_cmpk_eq_i32 s78, 0x700
	s_cselect_b32 s85, s75, s83
	s_cselect_b32 s84, s90, s82
	s_cselect_b32 s83, s73, s94
	s_cselect_b32 s82, s91, s93
	v_lshl_add_u64 v[150:151], v[146:147], 0, s[78:79]
	s_add_i32 m0, s67, 0xc000
	ds_read_b128 v[188:191], v155
	ds_read_b128 v[192:195], v155 offset:1024
	ds_read_b128 v[196:199], v155 offset:2048
	ds_read_b128 v[200:203], v155 offset:3072
	ds_read_b128 v[204:207], v155 offset:4096
	ds_read_b128 v[208:211], v155 offset:5120
	ds_read_b128 v[212:215], v155 offset:6144
	ds_read_b128 v[216:219], v155 offset:7168
	global_load_lds_dwordx4 v[150:151], off
	v_lshl_add_u64 v[150:151], v[148:149], 0, s[78:79]
	s_add_i32 m0, s67, 0xe000
	s_nop 0
	global_load_lds_dwordx4 v[150:151], off
	s_waitcnt vmcnt(8)
	s_waitcnt lgkmcnt(0)
	s_barrier
; #define PG8_STAGEA(bufoff, gbase) PG8_STAGE_(bufoff, gbase, voffA)
; #define PG8_STAGEB(bufoff, gbase) PG8_STAGE_(bufoff, gbase, voffB)
; #define PG8_LDA(dst, b, h) do { _Pragma("unroll") for (int m = 0; m < 4; ++m) _Pragma("unroll") for (int k = 0; k < 2; ++k) dst[m][k] = *(const LAS bf16x8*)(lds + PG8_SA(b, h) + aoff + m * 2048 + k * 1024); } while (0)
; #define PG8_MMA(ai, bj, At, Bt_) do { __builtin_amdgcn_s_setprio(1); _Pragma("unroll") for (int m = 0; m < 4; ++m) _Pragma("unroll") for (int n = 0; n < 2; ++n) _Pragma("unroll") for (int k = 0; k < 2; ++k) \
;         acc[ai][bj][m][n] = __builtin_amdgcn_mfma_f32_16x16x32_bf16(Bt_[n][k], At[m][k], acc[ai][bj][m][n], 0, 0, 0); __builtin_amdgcn_s_setprio(0); } while (0)
; #define PG8_WAIT_V(n) asm volatile("s_waitcnt vmcnt(" #n ")" ::: "memory")
; #define PG8_WAIT_L(n) asm volatile("s_waitcnt lgkmcnt(" #n ")" ::: "memory")
; #define PG8_BAR __builtin_amdgcn_s_barrier()
; #define PG8_SCHED __builtin_amdgcn_sched_barrier(0)
; template <int EK, int SK = -1>
; __device__ __forceinline__ void gemm_phase(LAS unsigned char* lds, const bf16_t* A, const bf16_t* Bt, int nM, int N, int K, const EpiArgs& E) {
;     ...
;             PG8_WAIT_V(8); PG8_WAIT_L(0); PG8_BAR; PG8_MMA(0, 0, At, B0); PG8_MMA(0, 1, At, B1); PG8_BAR; PG8_SCHED;
;             PG8_LDA(At, 0, 1); PG8_STAGEB(PG8_SB(0, 0), b2); PG8_STAGEB(PG8_SB(0, 1), b2 + hstep); PG8_STAGEA(PG8_SA(0, 0), a2);
;             PG8_WAIT_V(8); PG8_WAIT_L(0); PG8_BAR; PG8_MMA(1, 0, At, B0); PG8_MMA(1, 1, At, B1); PG8_BAR; PG8_SCHED;
	s_waitcnt lgkmcnt(0)
	v_mfma_f32_16x16x32_bf16 v[110:113], v[156:159], v[188:191], v[110:113]
	v_mfma_f32_16x16x32_bf16 v[102:105], v[156:159], v[196:199], v[102:105]
	v_mfma_f32_16x16x32_bf16 v[94:97], v[156:159], v[204:207], v[94:97]
	v_mfma_f32_16x16x32_bf16 v[86:89], v[156:159], v[212:215], v[86:89]
	v_mfma_f32_16x16x32_bf16 v[82:85], v[164:167], v[212:215], v[82:85]
	v_mfma_f32_16x16x32_bf16 v[90:93], v[164:167], v[204:207], v[90:93]
	v_mfma_f32_16x16x32_bf16 v[98:101], v[164:167], v[196:199], v[98:101]
	v_mfma_f32_16x16x32_bf16 v[106:109], v[164:167], v[188:191], v[106:109]
	v_mfma_f32_16x16x32_bf16 v[110:113], v[160:163], v[192:195], v[110:113]
	v_mfma_f32_16x16x32_bf16 v[102:105], v[160:163], v[200:203], v[102:105]
	v_mfma_f32_16x16x32_bf16 v[94:97], v[160:163], v[208:211], v[94:97]
	v_mfma_f32_16x16x32_bf16 v[86:89], v[160:163], v[216:219], v[86:89]
	v_mfma_f32_16x16x32_bf16 v[82:85], v[168:171], v[216:219], v[82:85]
	v_mfma_f32_16x16x32_bf16 v[90:93], v[168:171], v[208:211], v[90:93]
	v_mfma_f32_16x16x32_bf16 v[98:101], v[168:171], v[200:203], v[98:101]
	v_mfma_f32_16x16x32_bf16 v[106:109], v[168:171], v[192:195], v[106:109]
	v_mfma_f32_16x16x32_bf16 v[78:81], v[172:175], v[188:191], v[78:81]
	v_mfma_f32_16x16x32_bf16 v[70:73], v[172:175], v[196:199], v[70:73]
	v_mfma_f32_16x16x32_bf16 v[62:65], v[172:175], v[204:207], v[62:65]
	v_mfma_f32_16x16x32_bf16 v[54:57], v[172:175], v[212:215], v[54:57]
	v_mfma_f32_16x16x32_bf16 v[50:53], v[180:183], v[212:215], v[50:53]
	v_mfma_f32_16x16x32_bf16 v[58:61], v[180:183], v[204:207], v[58:61]
	v_mfma_f32_16x16x32_bf16 v[66:69], v[180:183], v[196:199], v[66:69]
	v_mfma_f32_16x16x32_bf16 v[74:77], v[180:183], v[188:191], v[74:77]
	v_mfma_f32_16x16x32_bf16 v[78:81], v[176:179], v[192:195], v[78:81]
	v_mfma_f32_16x16x32_bf16 v[70:73], v[176:179], v[200:203], v[70:73]
	v_mfma_f32_16x16x32_bf16 v[62:65], v[176:179], v[208:211], v[62:65]
	v_mfma_f32_16x16x32_bf16 v[54:57], v[176:179], v[216:219], v[54:57]
	v_mfma_f32_16x16x32_bf16 v[50:53], v[184:187], v[216:219], v[50:53]
	v_mfma_f32_16x16x32_bf16 v[58:61], v[184:187], v[208:211], v[58:61]
	v_mfma_f32_16x16x32_bf16 v[66:69], v[184:187], v[200:203], v[66:69]
	v_mfma_f32_16x16x32_bf16 v[74:77], v[184:187], v[192:195], v[74:77]
	s_barrier
	s_add_i32 s93, s54, s87
	v_lshl_add_u64 v[150:151], s[82:83], 0, v[132:133]
	s_mov_b32 m0, s93
	ds_read_b128 v[188:191], v155 offset:16384
	ds_read_b128 v[192:195], v155 offset:17408
	ds_read_b128 v[196:199], v155 offset:18432
	ds_read_b128 v[200:203], v155 offset:19456
	ds_read_b128 v[204:207], v155 offset:20480
	ds_read_b128 v[208:211], v155 offset:21504
	ds_read_b128 v[212:215], v155 offset:22528
	ds_read_b128 v[216:219], v155 offset:23552
	global_load_lds_dwordx4 v[150:151], off
	s_add_i32 m0, s93, 0x2000
	s_add_u32 s94, s82, 0x40000
	v_lshl_add_u64 v[220:221], s[82:83], 0, v[136:137]
	s_addc_u32 s95, s83, 0
	s_add_i32 s93, s55, s87
	global_load_lds_dwordx4 v[220:221], off
	v_lshl_add_u64 v[222:223], s[94:95], 0, v[132:133]
	s_mov_b32 m0, s93
	v_lshl_add_u64 v[224:225], s[84:85], 0, v[134:135]
	global_load_lds_dwordx4 v[222:223], off
	v_lshl_add_u64 v[222:223], s[94:95], 0, v[136:137]
	s_add_i32 m0, s93, 0x2000
	s_nop 0
	global_load_lds_dwordx4 v[222:223], off
	v_lshl_add_u64 v[222:223], s[84:85], 0, v[130:131]
	s_mov_b32 m0, s67
	s_nop 0
	global_load_lds_dwordx4 v[222:223], off
	s_mov_b32 m0, s69
	s_nop 0
	global_load_lds_dwordx4 v[224:225], off
	s_waitcnt vmcnt(8)
	s_waitcnt lgkmcnt(0)
	s_barrier
	s_waitcnt lgkmcnt(0)
	v_mfma_f32_16x16x32_bf16 v[46:49], v[156:159], v[188:191], v[46:49]
	v_mfma_f32_16x16x32_bf16 v[38:41], v[156:159], v[196:199], v[38:41]
	v_mfma_f32_16x16x32_bf16 v[30:33], v[156:159], v[204:207], v[30:33]
	v_mfma_f32_16x16x32_bf16 v[22:25], v[156:159], v[212:215], v[22:25]
	v_mfma_f32_16x16x32_bf16 v[18:21], v[164:167], v[212:215], v[18:21]
	v_mfma_f32_16x16x32_bf16 v[26:29], v[164:167], v[204:207], v[26:29]
	v_mfma_f32_16x16x32_bf16 v[34:37], v[164:167], v[196:199], v[34:37]
	v_mfma_f32_16x16x32_bf16 v[42:45], v[164:167], v[188:191], v[42:45]
	v_mfma_f32_16x16x32_bf16 v[46:49], v[160:163], v[192:195], v[46:49]
	v_mfma_f32_16x16x32_bf16 v[38:41], v[160:163], v[200:203], v[38:41]
	v_mfma_f32_16x16x32_bf16 v[30:33], v[160:163], v[208:211], v[30:33]
	v_mfma_f32_16x16x32_bf16 v[22:25], v[160:163], v[216:219], v[22:25]
	v_mfma_f32_16x16x32_bf16 v[18:21], v[168:171], v[216:219], v[18:21]
	v_mfma_f32_16x16x32_bf16 v[26:29], v[168:171], v[208:211], v[26:29]
	v_mfma_f32_16x16x32_bf16 v[34:37], v[168:171], v[200:203], v[34:37]
	v_mfma_f32_16x16x32_bf16 v[42:45], v[168:171], v[192:195], v[42:45]
	v_mfma_f32_16x16x32_bf16 v[14:17], v[172:175], v[188:191], v[14:17]
	v_mfma_f32_16x16x32_bf16 v[6:9], v[172:175], v[196:199], v[6:9]
	v_mfma_f32_16x16x32_bf16 v[114:117], v[172:175], v[204:207], v[114:117]
	v_mfma_f32_16x16x32_bf16 v[122:125], v[172:175], v[212:215], v[122:125]
	v_mfma_f32_16x16x32_bf16 v[126:129], v[180:183], v[212:215], v[126:129]
	v_mfma_f32_16x16x32_bf16 v[118:121], v[180:183], v[204:207], v[118:121]
	v_mfma_f32_16x16x32_bf16 v[2:5], v[180:183], v[196:199], v[2:5]
	v_mfma_f32_16x16x32_bf16 v[10:13], v[180:183], v[188:191], v[10:13]
	v_mfma_f32_16x16x32_bf16 v[14:17], v[176:179], v[192:195], v[14:17]
	v_mfma_f32_16x16x32_bf16 v[6:9], v[176:179], v[200:203], v[6:9]
	v_mfma_f32_16x16x32_bf16 v[114:117], v[176:179], v[208:211], v[114:117]
	v_mfma_f32_16x16x32_bf16 v[122:125], v[176:179], v[216:219], v[122:125]
	v_mfma_f32_16x16x32_bf16 v[126:129], v[184:187], v[216:219], v[126:129]
	v_mfma_f32_16x16x32_bf16 v[118:121], v[184:187], v[208:211], v[118:121]
	v_mfma_f32_16x16x32_bf16 v[2:5], v[184:187], v[200:203], v[2:5]
	v_mfma_f32_16x16x32_bf16 v[10:13], v[184:187], v[192:195], v[10:13]
	s_barrier
; #define PG8_STAGEA(bufoff, gbase) PG8_STAGE_(bufoff, gbase, voffA)
; #define PG8_STAGEB(bufoff, gbase) PG8_STAGE_(bufoff, gbase, voffB)
; #define PG8_LDA(dst, b, h) do { _Pragma("unroll") for (int m = 0; m < 4; ++m) _Pragma("unroll") for (int k = 0; k < 2; ++k) dst[m][k] = *(const LAS bf16x8*)(lds + PG8_SA(b, h) + aoff + m * 2048 + k * 1024); } while (0)
; #define PG8_LDB(dst, b, h) do { _Pragma("unroll") for (int n = 0; n < 2; ++n) _Pragma("unroll") for (int k = 0; k < 2; ++k) dst[n][k] = *(const LAS bf16x8*)(lds + PG8_SB(b, h) + boff + n * 2048 + k * 1024); } while (0)
; #define PG8_MMA(ai, bj, At, Bt_) do { __builtin_amdgcn_s_setprio(1); _Pragma("unroll") for (int m = 0; m < 4; ++m) _Pragma("unroll") for (int n = 0; n < 2; ++n) _Pragma("unroll") for (int k = 0; k < 2; ++k) \
;         acc[ai][bj][m][n] = __builtin_amdgcn_mfma_f32_16x16x32_bf16(Bt_[n][k], At[m][k], acc[ai][bj][m][n], 0, 0, 0); __builtin_amdgcn_s_setprio(0); } while (0)
; #define PG8_WAIT_V(n) asm volatile("s_waitcnt vmcnt(" #n ")" ::: "memory")
; #define PG8_WAIT_L(n) asm volatile("s_waitcnt lgkmcnt(" #n ")" ::: "memory")
; #define PG8_BAR __builtin_amdgcn_s_barrier()
; #define PG8_SCHED __builtin_amdgcn_sched_barrier(0)
; template <int EK, int SK = -1>
; __device__ __forceinline__ void gemm_phase(LAS unsigned char* lds, const bf16_t* A, const bf16_t* Bt, int nM, int N, int K, const EpiArgs& E) {
;     ...
;             PG8_LDB(B0, 1, 0); PG8_LDB(B1, 1, 1); PG8_SCHED; PG8_LDA(At, 1, 0); PG8_STAGEA(PG8_SA(0, 1), a2 + hstep);
;             PG8_WAIT_V(8); PG8_WAIT_L(0); PG8_BAR; PG8_MMA(0, 0, At, B0); PG8_MMA(0, 1, At, B1); PG8_BAR; PG8_SCHED;
;             PG8_LDA(At, 1, 1); PG8_STAGEB(PG8_SB(1, 0), b3); PG8_STAGEB(PG8_SB(1, 1), b3 + hstep); PG8_STAGEA(PG8_SA(1, 0), a3);
;             PG8_WAIT_V(8); PG8_WAIT_L(0); PG8_BAR; PG8_MMA(1, 0, At, B0); PG8_MMA(1, 1, At, B1); PG8_BAR; PG8_SCHED;
;         }
	s_add_i32 s93, 0, 0x18000
	s_add_i32 s94, 0, 0x1c000
	v_add_u32_e32 v168, s93, v152
	v_add_u32_e32 v184, s94, v152
	ds_read_b128 v[156:159], v168
	ds_read_b128 v[160:163], v168 offset:1024
	ds_read_b128 v[164:167], v168 offset:2048
	ds_read_b128 v[168:171], v168 offset:3072
	ds_read_b128 v[172:175], v184
	ds_read_b128 v[176:179], v184 offset:1024
	ds_read_b128 v[180:183], v184 offset:2048
	ds_read_b128 v[184:187], v184 offset:3072
	s_add_u32 s84, s84, 0x40000
	s_addc_u32 s85, s85, 0
	s_mov_b32 m0, s88
	v_lshl_add_u64 v[226:227], s[84:85], 0, v[130:131]
	ds_read_b128 v[188:191], v155 offset:32768
	ds_read_b128 v[192:195], v155 offset:33792
	ds_read_b128 v[196:199], v155 offset:34816
	ds_read_b128 v[200:203], v155 offset:35840
	ds_read_b128 v[204:207], v155 offset:36864
	ds_read_b128 v[208:211], v155 offset:37888
	ds_read_b128 v[212:215], v155 offset:38912
	ds_read_b128 v[216:219], v155 offset:39936
	global_load_lds_dwordx4 v[226:227], off
	v_lshl_add_u64 v[226:227], s[84:85], 0, v[134:135]
	s_mov_b32 m0, s89
	s_nop 0
	global_load_lds_dwordx4 v[226:227], off
	s_waitcnt vmcnt(8)
	s_waitcnt lgkmcnt(0)
	s_barrier
	s_waitcnt lgkmcnt(0)
	v_mfma_f32_16x16x32_bf16 v[110:113], v[156:159], v[188:191], v[110:113]
	v_mfma_f32_16x16x32_bf16 v[102:105], v[156:159], v[196:199], v[102:105]
	v_mfma_f32_16x16x32_bf16 v[94:97], v[156:159], v[204:207], v[94:97]
	v_mfma_f32_16x16x32_bf16 v[86:89], v[156:159], v[212:215], v[86:89]
	v_mfma_f32_16x16x32_bf16 v[82:85], v[164:167], v[212:215], v[82:85]
	v_mfma_f32_16x16x32_bf16 v[90:93], v[164:167], v[204:207], v[90:93]
	v_mfma_f32_16x16x32_bf16 v[98:101], v[164:167], v[196:199], v[98:101]
	v_mfma_f32_16x16x32_bf16 v[106:109], v[164:167], v[188:191], v[106:109]
	v_mfma_f32_16x16x32_bf16 v[110:113], v[160:163], v[192:195], v[110:113]
	v_mfma_f32_16x16x32_bf16 v[102:105], v[160:163], v[200:203], v[102:105]
	v_mfma_f32_16x16x32_bf16 v[94:97], v[160:163], v[208:211], v[94:97]
	v_mfma_f32_16x16x32_bf16 v[86:89], v[160:163], v[216:219], v[86:89]
	v_mfma_f32_16x16x32_bf16 v[82:85], v[168:171], v[216:219], v[82:85]
	v_mfma_f32_16x16x32_bf16 v[90:93], v[168:171], v[208:211], v[90:93]
	v_mfma_f32_16x16x32_bf16 v[98:101], v[168:171], v[200:203], v[98:101]
	v_mfma_f32_16x16x32_bf16 v[106:109], v[168:171], v[192:195], v[106:109]
	v_mfma_f32_16x16x32_bf16 v[78:81], v[172:175], v[188:191], v[78:81]
	v_mfma_f32_16x16x32_bf16 v[70:73], v[172:175], v[196:199], v[70:73]
	v_mfma_f32_16x16x32_bf16 v[62:65], v[172:175], v[204:207], v[62:65]
	v_mfma_f32_16x16x32_bf16 v[54:57], v[172:175], v[212:215], v[54:57]
	v_mfma_f32_16x16x32_bf16 v[50:53], v[180:183], v[212:215], v[50:53]
	v_mfma_f32_16x16x32_bf16 v[58:61], v[180:183], v[204:207], v[58:61]
	v_mfma_f32_16x16x32_bf16 v[66:69], v[180:183], v[196:199], v[66:69]
	v_mfma_f32_16x16x32_bf16 v[74:77], v[180:183], v[188:191], v[74:77]
	v_mfma_f32_16x16x32_bf16 v[78:81], v[176:179], v[192:195], v[78:81]
	v_mfma_f32_16x16x32_bf16 v[70:73], v[176:179], v[200:203], v[70:73]
	v_mfma_f32_16x16x32_bf16 v[62:65], v[176:179], v[208:211], v[62:65]
	v_mfma_f32_16x16x32_bf16 v[54:57], v[176:179], v[216:219], v[54:57]
	v_mfma_f32_16x16x32_bf16 v[50:53], v[184:187], v[216:219], v[50:53]
	v_mfma_f32_16x16x32_bf16 v[58:61], v[184:187], v[208:211], v[58:61]
	v_mfma_f32_16x16x32_bf16 v[66:69], v[184:187], v[200:203], v[66:69]
	v_mfma_f32_16x16x32_bf16 v[74:77], v[184:187], v[192:195], v[74:77]
	s_barrier
	s_add_i32 s84, s93, s87
	v_lshl_add_u64 v[150:151], v[150:151], 0, s[10:11]
	s_mov_b32 m0, s84
	ds_read_b128 v[188:191], v155 offset:49152
	ds_read_b128 v[192:195], v155 offset:50176
	ds_read_b128 v[196:199], v155 offset:51200
	ds_read_b128 v[200:203], v155 offset:52224
	ds_read_b128 v[204:207], v155 offset:53248
	ds_read_b128 v[208:211], v155 offset:54272
	ds_read_b128 v[212:215], v155 offset:55296
	ds_read_b128 v[216:219], v155 offset:56320
	global_load_lds_dwordx4 v[150:151], off
	s_add_i32 m0, s84, 0x2000
	s_add_u32 s82, s82, 0x40080
	v_lshl_add_u64 v[150:151], v[220:221], 0, s[10:11]
	s_addc_u32 s83, s83, 0
	s_add_i32 s84, s94, s87
	global_load_lds_dwordx4 v[150:151], off
	v_lshl_add_u64 v[150:151], s[82:83], 0, v[132:133]
	s_mov_b32 m0, s84
	s_nop 0
	global_load_lds_dwordx4 v[150:151], off
	v_lshl_add_u64 v[150:151], s[82:83], 0, v[136:137]
	s_add_i32 m0, s84, 0x2000
	s_nop 0
	global_load_lds_dwordx4 v[150:151], off
	v_lshl_add_u64 v[150:151], v[222:223], 0, s[10:11]
	s_mov_b32 m0, s52
	s_nop 0
	global_load_lds_dwordx4 v[150:151], off
	v_lshl_add_u64 v[150:151], v[224:225], 0, s[10:11]
	s_mov_b32 m0, s53
	s_nop 0
	global_load_lds_dwordx4 v[150:151], off
	s_waitcnt vmcnt(8)
	s_waitcnt lgkmcnt(0)
	s_barrier
	s_waitcnt lgkmcnt(0)
	v_mfma_f32_16x16x32_bf16 v[46:49], v[156:159], v[188:191], v[46:49]
	v_mfma_f32_16x16x32_bf16 v[38:41], v[156:159], v[196:199], v[38:41]
	v_mfma_f32_16x16x32_bf16 v[30:33], v[156:159], v[204:207], v[30:33]
	v_mfma_f32_16x16x32_bf16 v[22:25], v[156:159], v[212:215], v[22:25]
	v_mfma_f32_16x16x32_bf16 v[18:21], v[164:167], v[212:215], v[18:21]
	v_mfma_f32_16x16x32_bf16 v[26:29], v[164:167], v[204:207], v[26:29]
	v_mfma_f32_16x16x32_bf16 v[34:37], v[164:167], v[196:199], v[34:37]
	v_mfma_f32_16x16x32_bf16 v[42:45], v[164:167], v[188:191], v[42:45]
	v_mfma_f32_16x16x32_bf16 v[46:49], v[160:163], v[192:195], v[46:49]
	v_mfma_f32_16x16x32_bf16 v[38:41], v[160:163], v[200:203], v[38:41]
	v_mfma_f32_16x16x32_bf16 v[30:33], v[160:163], v[208:211], v[30:33]
	v_mfma_f32_16x16x32_bf16 v[22:25], v[160:163], v[216:219], v[22:25]
	v_mfma_f32_16x16x32_bf16 v[18:21], v[168:171], v[216:219], v[18:21]
	v_mfma_f32_16x16x32_bf16 v[26:29], v[168:171], v[208:211], v[26:29]
	v_mfma_f32_16x16x32_bf16 v[34:37], v[168:171], v[200:203], v[34:37]
	v_mfma_f32_16x16x32_bf16 v[42:45], v[168:171], v[192:195], v[42:45]
	v_mfma_f32_16x16x32_bf16 v[14:17], v[172:175], v[188:191], v[14:17]
	v_mfma_f32_16x16x32_bf16 v[6:9], v[172:175], v[196:199], v[6:9]
	v_mfma_f32_16x16x32_bf16 v[114:117], v[172:175], v[204:207], v[114:117]
	v_mfma_f32_16x16x32_bf16 v[122:125], v[172:175], v[212:215], v[122:125]
	v_mfma_f32_16x16x32_bf16 v[126:129], v[180:183], v[212:215], v[126:129]
	v_mfma_f32_16x16x32_bf16 v[118:121], v[180:183], v[204:207], v[118:121]
	v_mfma_f32_16x16x32_bf16 v[2:5], v[180:183], v[196:199], v[2:5]
	v_mfma_f32_16x16x32_bf16 v[10:13], v[180:183], v[188:191], v[10:13]
	v_mfma_f32_16x16x32_bf16 v[14:17], v[176:179], v[192:195], v[14:17]
	v_mfma_f32_16x16x32_bf16 v[6:9], v[176:179], v[200:203], v[6:9]
	v_mfma_f32_16x16x32_bf16 v[114:117], v[176:179], v[208:211], v[114:117]
	v_mfma_f32_16x16x32_bf16 v[122:125], v[176:179], v[216:219], v[122:125]
	v_mfma_f32_16x16x32_bf16 v[126:129], v[184:187], v[216:219], v[126:129]
	v_mfma_f32_16x16x32_bf16 v[118:121], v[184:187], v[208:211], v[118:121]
	v_mfma_f32_16x16x32_bf16 v[2:5], v[184:187], v[200:203], v[2:5]
	v_mfma_f32_16x16x32_bf16 v[10:13], v[184:187], v[192:195], v[10:13]
	s_barrier
	s_add_i32 s92, s92, 2
	s_add_u32 s78, s78, 0x100
	s_addc_u32 s79, s79, 0
	s_cmp_gt_u32 s92, 13
	s_cbranch_scc0 .LBB0_198

; #define PG8_STAGEA(bufoff, gbase) PG8_STAGE_(bufoff, gbase, voffA)
; #define PG8_STAGEB(bufoff, gbase) PG8_STAGE_(bufoff, gbase, voffB)
; #define PG8_LDA(dst, b, h) do { _Pragma("unroll") for (int m = 0; m < 4; ++m) _Pragma("unroll") for (int k = 0; k < 2; ++k) dst[m][k] = *(const LAS bf16x8*)(lds + PG8_SA(b, h) + aoff + m * 2048 + k * 1024); } while (0)
; #define PG8_LDB(dst, b, h) do { _Pragma("unroll") for (int n = 0; n < 2; ++n) _Pragma("unroll") for (int k = 0; k < 2; ++k) dst[n][k] = *(const LAS bf16x8*)(lds + PG8_SB(b, h) + boff + n * 2048 + k * 1024); } while (0)
; #define PG8_MMA(ai, bj, At, Bt_) do { __builtin_amdgcn_s_setprio(1); _Pragma("unroll") for (int m = 0; m < 4; ++m) _Pragma("unroll") for (int n = 0; n < 2; ++n) _Pragma("unroll") for (int k = 0; k < 2; ++k) \
;         acc[ai][bj][m][n] = __builtin_amdgcn_mfma_f32_16x16x32_bf16(Bt_[n][k], At[m][k], acc[ai][bj][m][n], 0, 0, 0); __builtin_amdgcn_s_setprio(0); } while (0)
; #define PG8_WAIT_V(n) asm volatile("s_waitcnt vmcnt(" #n ")" ::: "memory")
; #define PG8_WAIT_L(n) asm volatile("s_waitcnt lgkmcnt(" #n ")" ::: "memory")
; #define PG8_BAR __builtin_amdgcn_s_barrier()
; #define PG8_SCHED __builtin_amdgcn_sched_barrier(0)
; template <int EK, int SK = -1>
; __device__ __forceinline__ void gemm_phase(LAS unsigned char* lds, const bf16_t* A, const bf16_t* Bt, int nM, int N, int K, const EpiArgs& E) {
;     ...
;         const bool has_next = S.next(ui + 1, nxt);
;         const char* nA = has_next ? (const char*)A + (size_t)nxt.pm * tstep : cA; const char* nB = has_next ? (const char*)Bt + (size_t)nxt.pn * tstep : cB;
;         for (int t = 0; t < nt; t += 2) {
;             const bool last = (t == nt - 2);
;             const char* a1 = cA + (size_t)(t + 1) * kstep;
;             const char* a2 = last ? nA : cA + (size_t)(t + 2) * kstep; const char* b2 = last ? nB : cB + (size_t)(t + 2) * kstep;
;             const char* a3 = a2 + kstep; const char* b3 = b2 + kstep;
;             PG8_LDB(B0, 0, 0); PG8_LDB(B1, 0, 1); PG8_SCHED; PG8_LDA(At, 0, 0); PG8_STAGEA(PG8_SA(1, 1), a1 + hstep);
;             PG8_WAIT_V(8); PG8_WAIT_L(0); PG8_BAR; PG8_MMA(0, 0, At, B0); PG8_MMA(0, 1, At, B1); PG8_BAR; PG8_SCHED;
;             PG8_LDA(At, 0, 1); PG8_STAGEB(PG8_SB(0, 0), b2); PG8_STAGEB(PG8_SB(0, 1), b2 + hstep); PG8_STAGEA(PG8_SA(0, 0), a2);
.LBB0_412:
	s_add_u32 s53, s80, 0x100
	s_addc_u32 s54, s81, 0
	s_ashr_i32 s75, s74, 31
	s_lshl_b64 s[56:57], s[74:75], 19
	s_add_u32 s78, s66, s56
	s_addc_u32 s79, s67, s57
	s_and_b64 s[56:57], s[8:9], exec
	s_cselect_b32 s40, s79, s19
	s_cselect_b32 s55, s78, s18
	s_ashr_i32 s73, s72, 31
	s_lshl_b64 s[56:57], s[72:73], 19
	s_add_u32 s76, s86, s56
	s_addc_u32 s77, s87, s57
	s_and_b64 s[56:57], s[8:9], exec
	s_cselect_b32 s56, s77, s81
	s_cselect_b32 s57, s76, s80
	v_lshl_add_u64 v[146:147], s[18:19], 0, v[138:139]
	v_lshl_add_u64 v[148:149], s[18:19], 0, v[140:141]
	s_mov_b32 s58, -2
	s_mov_b64 s[80:81], 0
	v_add_u32_e32 v150, s95, v152
	ds_read_b128 v[156:159], v150
	ds_read_b128 v[160:163], v150 offset:1024
	ds_read_b128 v[164:167], v150 offset:2048
	ds_read_b128 v[168:171], v150 offset:3072
	v_add_u32_e32 v150, s96, v152
	s_add_u32 s59, s18, s80
	ds_read_b128 v[172:175], v150
	ds_read_b128 v[176:179], v150 offset:1024
	ds_read_b128 v[180:183], v150 offset:2048
	ds_read_b128 v[184:187], v150 offset:3072
	s_addc_u32 s73, s19, s81
	s_add_u32 s59, s59, 0x100
	s_addc_u32 s73, s73, 0
	s_add_u32 s75, s53, s80
	s_addc_u32 s82, s54, s81
	s_cmpk_eq_i32 s80, 0x700
	s_cselect_b32 s85, s40, s73
	s_cselect_b32 s84, s55, s59
	s_cselect_b32 s83, s56, s82
	s_cselect_b32 s82, s57, s75
	v_lshl_add_u64 v[150:151], v[146:147], 0, s[80:81]
	s_add_i32 m0, s15, 0xc000
	ds_read_b128 v[188:191], v154
	ds_read_b128 v[192:195], v154 offset:1024
	ds_read_b128 v[196:199], v154 offset:2048
	ds_read_b128 v[200:203], v154 offset:3072
	ds_read_b128 v[204:207], v154 offset:4096
	ds_read_b128 v[208:211], v154 offset:5120
	ds_read_b128 v[212:215], v154 offset:6144
	ds_read_b128 v[216:219], v154 offset:7168
	global_load_lds_dwordx4 v[150:151], off
	v_lshl_add_u64 v[150:151], v[148:149], 0, s[80:81]
	s_add_i32 m0, s15, 0xe000
	s_nop 0
	global_load_lds_dwordx4 v[150:151], off
	s_waitcnt vmcnt(8)
	s_waitcnt lgkmcnt(0)
	s_barrier
	s_waitcnt lgkmcnt(0)
	v_mfma_f32_16x16x32_bf16 v[126:129], v[156:159], v[188:191], 0
	v_mfma_f32_16x16x32_bf16 v[118:121], v[156:159], v[196:199], 0
	v_mfma_f32_16x16x32_bf16 v[110:113], v[156:159], v[204:207], 0
	v_mfma_f32_16x16x32_bf16 v[102:105], v[156:159], v[212:215], 0
	v_mfma_f32_16x16x32_bf16 v[98:101], v[164:167], v[212:215], 0
	v_mfma_f32_16x16x32_bf16 v[106:109], v[164:167], v[204:207], 0
	v_mfma_f32_16x16x32_bf16 v[114:117], v[164:167], v[196:199], 0
	v_mfma_f32_16x16x32_bf16 v[122:125], v[164:167], v[188:191], 0
	v_mfma_f32_16x16x32_bf16 v[126:129], v[160:163], v[192:195], v[126:129]
	v_mfma_f32_16x16x32_bf16 v[118:121], v[160:163], v[200:203], v[118:121]
	v_mfma_f32_16x16x32_bf16 v[110:113], v[160:163], v[208:211], v[110:113]
	v_mfma_f32_16x16x32_bf16 v[102:105], v[160:163], v[216:219], v[102:105]
	v_mfma_f32_16x16x32_bf16 v[98:101], v[168:171], v[216:219], v[98:101]
	v_mfma_f32_16x16x32_bf16 v[106:109], v[168:171], v[208:211], v[106:109]
	v_mfma_f32_16x16x32_bf16 v[114:117], v[168:171], v[200:203], v[114:117]
	v_mfma_f32_16x16x32_bf16 v[122:125], v[168:171], v[192:195], v[122:125]
	v_mfma_f32_16x16x32_bf16 v[94:97], v[172:175], v[188:191], 0
	v_mfma_f32_16x16x32_bf16 v[86:89], v[172:175], v[196:199], 0
	v_mfma_f32_16x16x32_bf16 v[78:81], v[172:175], v[204:207], 0
	v_mfma_f32_16x16x32_bf16 v[70:73], v[172:175], v[212:215], 0
	v_mfma_f32_16x16x32_bf16 v[66:69], v[180:183], v[212:215], 0
	v_mfma_f32_16x16x32_bf16 v[74:77], v[180:183], v[204:207], 0
	v_mfma_f32_16x16x32_bf16 v[82:85], v[180:183], v[196:199], 0
	v_mfma_f32_16x16x32_bf16 v[90:93], v[180:183], v[188:191], 0
	v_mfma_f32_16x16x32_bf16 v[94:97], v[176:179], v[192:195], v[94:97]
	v_mfma_f32_16x16x32_bf16 v[86:89], v[176:179], v[200:203], v[86:89]
	v_mfma_f32_16x16x32_bf16 v[78:81], v[176:179], v[208:211], v[78:81]
	v_mfma_f32_16x16x32_bf16 v[70:73], v[176:179], v[216:219], v[70:73]
	v_mfma_f32_16x16x32_bf16 v[66:69], v[184:187], v[216:219], v[66:69]
	v_mfma_f32_16x16x32_bf16 v[74:77], v[184:187], v[208:211], v[74:77]
	v_mfma_f32_16x16x32_bf16 v[82:85], v[184:187], v[200:203], v[82:85]
	v_mfma_f32_16x16x32_bf16 v[90:93], v[184:187], v[192:195], v[90:93]
	s_barrier
	s_add_i32 s59, s95, s88
	v_lshl_add_u64 v[150:151], s[82:83], 0, v[132:133]
	s_mov_b32 m0, s59
	ds_read_b128 v[188:191], v154 offset:16384
	ds_read_b128 v[192:195], v154 offset:17408
	ds_read_b128 v[196:199], v154 offset:18432
	ds_read_b128 v[200:203], v154 offset:19456
	ds_read_b128 v[204:207], v154 offset:20480
	ds_read_b128 v[208:211], v154 offset:21504
	ds_read_b128 v[212:215], v154 offset:22528
	ds_read_b128 v[216:219], v154 offset:23552
	global_load_lds_dwordx4 v[150:151], off
	s_add_i32 m0, s59, 0x2000
	s_add_u32 vcc_lo, s82, 0x40000
	v_lshl_add_u64 v[220:221], s[82:83], 0, v[136:137]
	s_addc_u32 vcc_hi, s83, 0
	s_add_i32 s59, s96, s88
	global_load_lds_dwordx4 v[220:221], off
	v_lshl_add_u64 v[222:223], vcc, 0, v[132:133]
	s_mov_b32 m0, s59
	v_lshl_add_u64 v[224:225], s[84:85], 0, v[134:135]
	global_load_lds_dwordx4 v[222:223], off
	v_lshl_add_u64 v[222:223], vcc, 0, v[136:137]
	s_add_i32 m0, s59, 0x2000
	s_nop 0
	global_load_lds_dwordx4 v[222:223], off
	v_lshl_add_u64 v[222:223], s[84:85], 0, v[130:131]
	s_mov_b32 m0, s15
	s_nop 0
	global_load_lds_dwordx4 v[222:223], off
	s_mov_b32 m0, s17
	s_nop 0
	global_load_lds_dwordx4 v[224:225], off
	s_waitcnt vmcnt(8)
	s_waitcnt lgkmcnt(0)
	s_barrier
; #define PG8_STAGEA(bufoff, gbase) PG8_STAGE_(bufoff, gbase, voffA)
; #define PG8_STAGEB(bufoff, gbase) PG8_STAGE_(bufoff, gbase, voffB)
; #define PG8_LDA(dst, b, h) do { _Pragma("unroll") for (int m = 0; m < 4; ++m) _Pragma("unroll") for (int k = 0; k < 2; ++k) dst[m][k] = *(const LAS bf16x8*)(lds + PG8_SA(b, h) + aoff + m * 2048 + k * 1024); } while (0)
; #define PG8_LDB(dst, b, h) do { _Pragma("unroll") for (int n = 0; n < 2; ++n) _Pragma("unroll") for (int k = 0; k < 2; ++k) dst[n][k] = *(const LAS bf16x8*)(lds + PG8_SB(b, h) + boff + n * 2048 + k * 1024); } while (0)
; #define PG8_MMA(ai, bj, At, Bt_) do { __builtin_amdgcn_s_setprio(1); _Pragma("unroll") for (int m = 0; m < 4; ++m) _Pragma("unroll") for (int n = 0; n < 2; ++n) _Pragma("unroll") for (int k = 0; k < 2; ++k) \
;         acc[ai][bj][m][n] = __builtin_amdgcn_mfma_f32_16x16x32_bf16(Bt_[n][k], At[m][k], acc[ai][bj][m][n], 0, 0, 0); __builtin_amdgcn_s_setprio(0); } while (0)
; #define PG8_WAIT_V(n) asm volatile("s_waitcnt vmcnt(" #n ")" ::: "memory")
; #define PG8_WAIT_L(n) asm volatile("s_waitcnt lgkmcnt(" #n ")" ::: "memory")
; #define PG8_BAR __builtin_amdgcn_s_barrier()
; #define PG8_SCHED __builtin_amdgcn_sched_barrier(0)
; template <int EK, int SK = -1>
; __device__ __forceinline__ void gemm_phase(LAS unsigned char* lds, const bf16_t* A, const bf16_t* Bt, int nM, int N, int K, const EpiArgs& E) {
;     ...
;             PG8_WAIT_V(8); PG8_WAIT_L(0); PG8_BAR; PG8_MMA(0, 0, At, B0); PG8_MMA(0, 1, At, B1); PG8_BAR; PG8_SCHED;
;             PG8_LDA(At, 0, 1); PG8_STAGEB(PG8_SB(0, 0), b2); PG8_STAGEB(PG8_SB(0, 1), b2 + hstep); PG8_STAGEA(PG8_SA(0, 0), a2);
;             PG8_WAIT_V(8); PG8_WAIT_L(0); PG8_BAR; PG8_MMA(1, 0, At, B0); PG8_MMA(1, 1, At, B1); PG8_BAR; PG8_SCHED;
;             PG8_LDB(B0, 1, 0); PG8_LDB(B1, 1, 1); PG8_SCHED; PG8_LDA(At, 1, 0); PG8_STAGEA(PG8_SA(0, 1), a2 + hstep);
;             PG8_WAIT_V(8); PG8_WAIT_L(0); PG8_BAR; PG8_MMA(0, 0, At, B0); PG8_MMA(0, 1, At, B1); PG8_BAR; PG8_SCHED;
;             PG8_LDA(At, 1, 1); PG8_STAGEB(PG8_SB(1, 0), b3); PG8_STAGEB(PG8_SB(1, 1), b3 + hstep); PG8_STAGEA(PG8_SA(1, 0), a3);
;             PG8_WAIT_V(8); PG8_WAIT_L(0); PG8_BAR; PG8_MMA(1, 0, At, B0); PG8_MMA(1, 1, At, B1); PG8_BAR; PG8_SCHED;
	s_waitcnt lgkmcnt(0)
	v_mfma_f32_16x16x32_bf16 v[62:65], v[156:159], v[188:191], 0
	v_mfma_f32_16x16x32_bf16 v[54:57], v[156:159], v[196:199], 0
	v_mfma_f32_16x16x32_bf16 v[46:49], v[156:159], v[204:207], 0
	v_mfma_f32_16x16x32_bf16 v[38:41], v[156:159], v[212:215], 0
	v_mfma_f32_16x16x32_bf16 v[34:37], v[164:167], v[212:215], 0
	v_mfma_f32_16x16x32_bf16 v[42:45], v[164:167], v[204:207], 0
	v_mfma_f32_16x16x32_bf16 v[50:53], v[164:167], v[196:199], 0
	v_mfma_f32_16x16x32_bf16 v[58:61], v[164:167], v[188:191], 0
	v_mfma_f32_16x16x32_bf16 v[62:65], v[160:163], v[192:195], v[62:65]
	v_mfma_f32_16x16x32_bf16 v[54:57], v[160:163], v[200:203], v[54:57]
	v_mfma_f32_16x16x32_bf16 v[46:49], v[160:163], v[208:211], v[46:49]
	v_mfma_f32_16x16x32_bf16 v[38:41], v[160:163], v[216:219], v[38:41]
	v_mfma_f32_16x16x32_bf16 v[34:37], v[168:171], v[216:219], v[34:37]
	v_mfma_f32_16x16x32_bf16 v[42:45], v[168:171], v[208:211], v[42:45]
	v_mfma_f32_16x16x32_bf16 v[50:53], v[168:171], v[200:203], v[50:53]
	v_mfma_f32_16x16x32_bf16 v[58:61], v[168:171], v[192:195], v[58:61]
	v_mfma_f32_16x16x32_bf16 v[30:33], v[172:175], v[188:191], 0
	v_mfma_f32_16x16x32_bf16 v[22:25], v[172:175], v[196:199], 0
	v_mfma_f32_16x16x32_bf16 v[14:17], v[172:175], v[204:207], 0
	v_mfma_f32_16x16x32_bf16 v[6:9], v[172:175], v[212:215], 0
	v_mfma_f32_16x16x32_bf16 v[2:5], v[180:183], v[212:215], 0
	v_mfma_f32_16x16x32_bf16 v[10:13], v[180:183], v[204:207], 0
	v_mfma_f32_16x16x32_bf16 v[18:21], v[180:183], v[196:199], 0
	v_mfma_f32_16x16x32_bf16 v[26:29], v[180:183], v[188:191], 0
	v_mfma_f32_16x16x32_bf16 v[30:33], v[176:179], v[192:195], v[30:33]
	v_mfma_f32_16x16x32_bf16 v[22:25], v[176:179], v[200:203], v[22:25]
	v_mfma_f32_16x16x32_bf16 v[14:17], v[176:179], v[208:211], v[14:17]
	v_mfma_f32_16x16x32_bf16 v[6:9], v[176:179], v[216:219], v[6:9]
	v_mfma_f32_16x16x32_bf16 v[2:5], v[184:187], v[216:219], v[2:5]
	v_mfma_f32_16x16x32_bf16 v[10:13], v[184:187], v[208:211], v[10:13]
	v_mfma_f32_16x16x32_bf16 v[18:21], v[184:187], v[200:203], v[18:21]
	v_mfma_f32_16x16x32_bf16 v[26:29], v[184:187], v[192:195], v[26:29]
	s_barrier
	s_add_i32 s59, 0, 0x18000
	s_add_i32 s73, 0, 0x1c000
	v_add_u32_e32 v168, s59, v152
	v_add_u32_e32 v184, s73, v152
	ds_read_b128 v[156:159], v168
	ds_read_b128 v[160:163], v168 offset:1024
	ds_read_b128 v[164:167], v168 offset:2048
	ds_read_b128 v[168:171], v168 offset:3072
	ds_read_b128 v[172:175], v184
	ds_read_b128 v[176:179], v184 offset:1024
	ds_read_b128 v[180:183], v184 offset:2048
	ds_read_b128 v[184:187], v184 offset:3072
	s_add_u32 s84, s84, 0x40000
	s_addc_u32 s85, s85, 0
	s_mov_b32 m0, s89
	v_lshl_add_u64 v[226:227], s[84:85], 0, v[130:131]
	ds_read_b128 v[188:191], v154 offset:32768
	ds_read_b128 v[192:195], v154 offset:33792
	ds_read_b128 v[196:199], v154 offset:34816
	ds_read_b128 v[200:203], v154 offset:35840
	ds_read_b128 v[204:207], v154 offset:36864
	ds_read_b128 v[208:211], v154 offset:37888
	ds_read_b128 v[212:215], v154 offset:38912
	ds_read_b128 v[216:219], v154 offset:39936
	global_load_lds_dwordx4 v[226:227], off
	v_lshl_add_u64 v[226:227], s[84:85], 0, v[134:135]
	s_mov_b32 m0, s90
	s_nop 0
	global_load_lds_dwordx4 v[226:227], off
	s_waitcnt vmcnt(8)
	s_waitcnt lgkmcnt(0)
	s_barrier
	s_waitcnt lgkmcnt(0)
	v_mfma_f32_16x16x32_bf16 v[126:129], v[156:159], v[188:191], v[126:129]
	v_mfma_f32_16x16x32_bf16 v[118:121], v[156:159], v[196:199], v[118:121]
	v_mfma_f32_16x16x32_bf16 v[110:113], v[156:159], v[204:207], v[110:113]
	v_mfma_f32_16x16x32_bf16 v[102:105], v[156:159], v[212:215], v[102:105]
	v_mfma_f32_16x16x32_bf16 v[98:101], v[164:167], v[212:215], v[98:101]
	v_mfma_f32_16x16x32_bf16 v[106:109], v[164:167], v[204:207], v[106:109]
	v_mfma_f32_16x16x32_bf16 v[114:117], v[164:167], v[196:199], v[114:117]
	v_mfma_f32_16x16x32_bf16 v[122:125], v[164:167], v[188:191], v[122:125]
	v_mfma_f32_16x16x32_bf16 v[126:129], v[160:163], v[192:195], v[126:129]
	v_mfma_f32_16x16x32_bf16 v[118:121], v[160:163], v[200:203], v[118:121]
	v_mfma_f32_16x16x32_bf16 v[110:113], v[160:163], v[208:211], v[110:113]
	v_mfma_f32_16x16x32_bf16 v[102:105], v[160:163], v[216:219], v[102:105]
	v_mfma_f32_16x16x32_bf16 v[98:101], v[168:171], v[216:219], v[98:101]
	v_mfma_f32_16x16x32_bf16 v[106:109], v[168:171], v[208:211], v[106:109]
	v_mfma_f32_16x16x32_bf16 v[114:117], v[168:171], v[200:203], v[114:117]
	v_mfma_f32_16x16x32_bf16 v[122:125], v[168:171], v[192:195], v[122:125]
	v_mfma_f32_16x16x32_bf16 v[94:97], v[172:175], v[188:191], v[94:97]
	v_mfma_f32_16x16x32_bf16 v[86:89], v[172:175], v[196:199], v[86:89]
	v_mfma_f32_16x16x32_bf16 v[78:81], v[172:175], v[204:207], v[78:81]
	v_mfma_f32_16x16x32_bf16 v[70:73], v[172:175], v[212:215], v[70:73]
	v_mfma_f32_16x16x32_bf16 v[66:69], v[180:183], v[212:215], v[66:69]
	v_mfma_f32_16x16x32_bf16 v[74:77], v[180:183], v[204:207], v[74:77]
	v_mfma_f32_16x16x32_bf16 v[82:85], v[180:183], v[196:199], v[82:85]
	v_mfma_f32_16x16x32_bf16 v[90:93], v[180:183], v[188:191], v[90:93]
	v_mfma_f32_16x16x32_bf16 v[94:97], v[176:179], v[192:195], v[94:97]
	v_mfma_f32_16x16x32_bf16 v[86:89], v[176:179], v[200:203], v[86:89]
	v_mfma_f32_16x16x32_bf16 v[78:81], v[176:179], v[208:211], v[78:81]
	v_mfma_f32_16x16x32_bf16 v[70:73], v[176:179], v[216:219], v[70:73]
	v_mfma_f32_16x16x32_bf16 v[66:69], v[184:187], v[216:219], v[66:69]
	v_mfma_f32_16x16x32_bf16 v[74:77], v[184:187], v[208:211], v[74:77]
	v_mfma_f32_16x16x32_bf16 v[82:85], v[184:187], v[200:203], v[82:85]
	v_mfma_f32_16x16x32_bf16 v[90:93], v[184:187], v[192:195], v[90:93]
	s_barrier
; #define PG8_STAGEA(bufoff, gbase) PG8_STAGE_(bufoff, gbase, voffA)
; #define PG8_STAGEB(bufoff, gbase) PG8_STAGE_(bufoff, gbase, voffB)
; #define PG8_LDA(dst, b, h) do { _Pragma("unroll") for (int m = 0; m < 4; ++m) _Pragma("unroll") for (int k = 0; k < 2; ++k) dst[m][k] = *(const LAS bf16x8*)(lds + PG8_SA(b, h) + aoff + m * 2048 + k * 1024); } while (0)
; #define PG8_LDB(dst, b, h) do { _Pragma("unroll") for (int n = 0; n < 2; ++n) _Pragma("unroll") for (int k = 0; k < 2; ++k) dst[n][k] = *(const LAS bf16x8*)(lds + PG8_SB(b, h) + boff + n * 2048 + k * 1024); } while (0)
; #define PG8_MMA(ai, bj, At, Bt_) do { __builtin_amdgcn_s_setprio(1); _Pragma("unroll") for (int m = 0; m < 4; ++m) _Pragma("unroll") for (int n = 0; n < 2; ++n) _Pragma("unroll") for (int k = 0; k < 2; ++k) \
;         acc[ai][bj][m][n] = __builtin_amdgcn_mfma_f32_16x16x32_bf16(Bt_[n][k], At[m][k], acc[ai][bj][m][n], 0, 0, 0); __builtin_amdgcn_s_setprio(0); } while (0)
; #define PG8_WAIT_V(n) asm volatile("s_waitcnt vmcnt(" #n ")" ::: "memory")
; #define PG8_WAIT_L(n) asm volatile("s_waitcnt lgkmcnt(" #n ")" ::: "memory")
; template <int EK, int SK = -1>
; __device__ __forceinline__ void gemm_phase(LAS unsigned char* lds, const bf16_t* A, const bf16_t* Bt, int nM, int N, int K, const EpiArgs& E) {
;     ...
;         for (int t = 0; t < nt; t += 2) {
;             const bool last = (t == nt - 2);
;             const char* a1 = cA + (size_t)(t + 1) * kstep;
;             const char* a2 = last ? nA : cA + (size_t)(t + 2) * kstep; const char* b2 = last ? nB : cB + (size_t)(t + 2) * kstep;
;             const char* a3 = a2 + kstep; const char* b3 = b2 + kstep;
;             PG8_LDB(B0, 0, 0); PG8_LDB(B1, 0, 1); PG8_SCHED; PG8_LDA(At, 0, 0); PG8_STAGEA(PG8_SA(1, 1), a1 + hstep);
;     ...
;             PG8_WAIT_V(8); PG8_WAIT_L(0); PG8_BAR; PG8_MMA(1, 0, At, B0); PG8_MMA(1, 1, At, B1); PG8_BAR; PG8_SCHED;
;             PG8_LDB(B0, 1, 0); PG8_LDB(B1, 1, 1); PG8_SCHED; PG8_LDA(At, 1, 0); PG8_STAGEA(PG8_SA(0, 1), a2 + hstep);
;             PG8_WAIT_V(8); PG8_WAIT_L(0); PG8_BAR; PG8_MMA(0, 0, At, B0); PG8_MMA(0, 1, At, B1); PG8_BAR; PG8_SCHED;
;             PG8_LDA(At, 1, 1); PG8_STAGEB(PG8_SB(1, 0), b3); PG8_STAGEB(PG8_SB(1, 1), b3 + hstep); PG8_STAGEA(PG8_SA(1, 0), a3);
;             PG8_WAIT_V(8); PG8_WAIT_L(0); PG8_BAR; PG8_MMA(1, 0, At, B0); PG8_MMA(1, 1, At, B1); PG8_BAR; PG8_SCHED;
	s_add_i32 s59, s59, s88
	v_lshl_add_u64 v[150:151], v[150:151], 0, s[68:69]
	s_mov_b32 m0, s59
	ds_read_b128 v[188:191], v154 offset:49152
	ds_read_b128 v[192:195], v154 offset:50176
	ds_read_b128 v[196:199], v154 offset:51200
	ds_read_b128 v[200:203], v154 offset:52224
	ds_read_b128 v[204:207], v154 offset:53248
	ds_read_b128 v[208:211], v154 offset:54272
	ds_read_b128 v[212:215], v154 offset:55296
	ds_read_b128 v[216:219], v154 offset:56320
	global_load_lds_dwordx4 v[150:151], off
	s_add_i32 m0, s59, 0x2000
	s_add_u32 s82, s82, 0x40080
	v_lshl_add_u64 v[150:151], v[220:221], 0, s[68:69]
	s_addc_u32 s83, s83, 0
	s_add_i32 s59, s73, s88
	global_load_lds_dwordx4 v[150:151], off
	v_lshl_add_u64 v[150:151], s[82:83], 0, v[132:133]
	s_mov_b32 m0, s59
	s_nop 0
	global_load_lds_dwordx4 v[150:151], off
	v_lshl_add_u64 v[150:151], s[82:83], 0, v[136:137]
	s_add_i32 m0, s59, 0x2000
	s_nop 0
	global_load_lds_dwordx4 v[150:151], off
	v_lshl_add_u64 v[150:151], v[222:223], 0, s[68:69]
	s_mov_b32 m0, s93
	s_nop 0
	global_load_lds_dwordx4 v[150:151], off
	v_lshl_add_u64 v[150:151], v[224:225], 0, s[68:69]
	s_mov_b32 m0, s94
	s_nop 0
	global_load_lds_dwordx4 v[150:151], off
	s_waitcnt vmcnt(8)
	s_waitcnt lgkmcnt(0)
	s_barrier
	s_waitcnt lgkmcnt(0)
	v_mfma_f32_16x16x32_bf16 v[62:65], v[156:159], v[188:191], v[62:65]
	v_mfma_f32_16x16x32_bf16 v[54:57], v[156:159], v[196:199], v[54:57]
	v_mfma_f32_16x16x32_bf16 v[46:49], v[156:159], v[204:207], v[46:49]
	v_mfma_f32_16x16x32_bf16 v[38:41], v[156:159], v[212:215], v[38:41]
	v_mfma_f32_16x16x32_bf16 v[34:37], v[164:167], v[212:215], v[34:37]
	v_mfma_f32_16x16x32_bf16 v[42:45], v[164:167], v[204:207], v[42:45]
	v_mfma_f32_16x16x32_bf16 v[50:53], v[164:167], v[196:199], v[50:53]
	v_mfma_f32_16x16x32_bf16 v[58:61], v[164:167], v[188:191], v[58:61]
	v_mfma_f32_16x16x32_bf16 v[62:65], v[160:163], v[192:195], v[62:65]
	v_mfma_f32_16x16x32_bf16 v[54:57], v[160:163], v[200:203], v[54:57]
	v_mfma_f32_16x16x32_bf16 v[46:49], v[160:163], v[208:211], v[46:49]
	v_mfma_f32_16x16x32_bf16 v[38:41], v[160:163], v[216:219], v[38:41]
	v_mfma_f32_16x16x32_bf16 v[34:37], v[168:171], v[216:219], v[34:37]
	v_mfma_f32_16x16x32_bf16 v[42:45], v[168:171], v[208:211], v[42:45]
	v_mfma_f32_16x16x32_bf16 v[50:53], v[168:171], v[200:203], v[50:53]
	v_mfma_f32_16x16x32_bf16 v[58:61], v[168:171], v[192:195], v[58:61]
	v_mfma_f32_16x16x32_bf16 v[30:33], v[172:175], v[188:191], v[30:33]
	v_mfma_f32_16x16x32_bf16 v[22:25], v[172:175], v[196:199], v[22:25]
	v_mfma_f32_16x16x32_bf16 v[14:17], v[172:175], v[204:207], v[14:17]
	v_mfma_f32_16x16x32_bf16 v[6:9], v[172:175], v[212:215], v[6:9]
	v_mfma_f32_16x16x32_bf16 v[2:5], v[180:183], v[212:215], v[2:5]
	v_mfma_f32_16x16x32_bf16 v[10:13], v[180:183], v[204:207], v[10:13]
	v_mfma_f32_16x16x32_bf16 v[18:21], v[180:183], v[196:199], v[18:21]
	v_mfma_f32_16x16x32_bf16 v[26:29], v[180:183], v[188:191], v[26:29]
	v_mfma_f32_16x16x32_bf16 v[30:33], v[176:179], v[192:195], v[30:33]
	v_mfma_f32_16x16x32_bf16 v[22:25], v[176:179], v[200:203], v[22:25]
	v_mfma_f32_16x16x32_bf16 v[14:17], v[176:179], v[208:211], v[14:17]
	v_mfma_f32_16x16x32_bf16 v[6:9], v[176:179], v[216:219], v[6:9]
	v_mfma_f32_16x16x32_bf16 v[2:5], v[184:187], v[216:219], v[2:5]
	v_mfma_f32_16x16x32_bf16 v[10:13], v[184:187], v[208:211], v[10:13]
	v_mfma_f32_16x16x32_bf16 v[18:21], v[184:187], v[200:203], v[18:21]
	v_mfma_f32_16x16x32_bf16 v[26:29], v[184:187], v[192:195], v[26:29]
	s_barrier
	s_add_i32 s58, s58, 2
	s_add_u32 s80, s80, 0x100
	s_addc_u32 s81, s81, 0
	s_cmp_gt_u32 s58, 13
	s_cbranch_scc0 .LBB0_413
	s_branch .Lmy_kexit_1
.LBB0_413:
	v_add_u32_e32 v150, s95, v152
	ds_read_b128 v[156:159], v150
	ds_read_b128 v[160:163], v150 offset:1024
	ds_read_b128 v[164:167], v150 offset:2048
	ds_read_b128 v[168:171], v150 offset:3072
	v_add_u32_e32 v150, s96, v152
	s_add_u32 s59, s18, s80
	ds_read_b128 v[172:175], v150
	ds_read_b128 v[176:179], v150 offset:1024
	ds_read_b128 v[180:183], v150 offset:2048
	ds_read_b128 v[184:187], v150 offset:3072
	s_addc_u32 s73, s19, s81
	s_add_u32 s59, s59, 0x100
	s_addc_u32 s73, s73, 0
	s_add_u32 s75, s53, s80
	s_addc_u32 s82, s54, s81
	s_cmpk_eq_i32 s80, 0x700
	s_cselect_b32 s85, s40, s73
	s_cselect_b32 s84, s55, s59
	s_cselect_b32 s83, s56, s82
	s_cselect_b32 s82, s57, s75
	v_lshl_add_u64 v[150:151], v[146:147], 0, s[80:81]
	s_add_i32 m0, s15, 0xc000
	ds_read_b128 v[188:191], v154
	ds_read_b128 v[192:195], v154 offset:1024
	ds_read_b128 v[196:199], v154 offset:2048
	ds_read_b128 v[200:203], v154 offset:3072
	ds_read_b128 v[204:207], v154 offset:4096
	ds_read_b128 v[208:211], v154 offset:5120
	ds_read_b128 v[212:215], v154 offset:6144
	ds_read_b128 v[216:219], v154 offset:7168
	global_load_lds_dwordx4 v[150:151], off
	v_lshl_add_u64 v[150:151], v[148:149], 0, s[80:81]
	s_add_i32 m0, s15, 0xe000
	s_nop 0
	global_load_lds_dwordx4 v[150:151], off
	s_waitcnt vmcnt(8)
	s_waitcnt lgkmcnt(0)
	s_barrier
; #define PG8_STAGEA(bufoff, gbase) PG8_STAGE_(bufoff, gbase, voffA)
; #define PG8_STAGEB(bufoff, gbase) PG8_STAGE_(bufoff, gbase, voffB)
; #define PG8_LDA(dst, b, h) do { _Pragma("unroll") for (int m = 0; m < 4; ++m) _Pragma("unroll") for (int k = 0; k < 2; ++k) dst[m][k] = *(const LAS bf16x8*)(lds + PG8_SA(b, h) + aoff + m * 2048 + k * 1024); } while (0)
; #define PG8_LDB(dst, b, h) do { _Pragma("unroll") for (int n = 0; n < 2; ++n) _Pragma("unroll") for (int k = 0; k < 2; ++k) dst[n][k] = *(const LAS bf16x8*)(lds + PG8_SB(b, h) + boff + n * 2048 + k * 1024); } while (0)
; #define PG8_MMA(ai, bj, At, Bt_) do { __builtin_amdgcn_s_setprio(1); _Pragma("unroll") for (int m = 0; m < 4; ++m) _Pragma("unroll") for (int n = 0; n < 2; ++n) _Pragma("unroll") for (int k = 0; k < 2; ++k) \
;         acc[ai][bj][m][n] = __builtin_amdgcn_mfma_f32_16x16x32_bf16(Bt_[n][k], At[m][k], acc[ai][bj][m][n], 0, 0, 0); __builtin_amdgcn_s_setprio(0); } while (0)
; #define PG8_WAIT_V(n) asm volatile("s_waitcnt vmcnt(" #n ")" ::: "memory")
; #define PG8_WAIT_L(n) asm volatile("s_waitcnt lgkmcnt(" #n ")" ::: "memory")
; #define PG8_BAR __builtin_amdgcn_s_barrier()
; #define PG8_SCHED __builtin_amdgcn_sched_barrier(0)
; template <int EK, int SK = -1>
; __device__ __forceinline__ void gemm_phase(LAS unsigned char* lds, const bf16_t* A, const bf16_t* Bt, int nM, int N, int K, const EpiArgs& E) {
;     ...
;             PG8_LDB(B0, 0, 0); PG8_LDB(B1, 0, 1); PG8_SCHED; PG8_LDA(At, 0, 0); PG8_STAGEA(PG8_SA(1, 1), a1 + hstep);
;             PG8_WAIT_V(8); PG8_WAIT_L(0); PG8_BAR; PG8_MMA(0, 0, At, B0); PG8_MMA(0, 1, At, B1); PG8_BAR; PG8_SCHED;
;             PG8_LDA(At, 0, 1); PG8_STAGEB(PG8_SB(0, 0), b2); PG8_STAGEB(PG8_SB(0, 1), b2 + hstep); PG8_STAGEA(PG8_SA(0, 0), a2);
;             PG8_WAIT_V(8); PG8_WAIT_L(0); PG8_BAR; PG8_MMA(1, 0, At, B0); PG8_MMA(1, 1, At, B1); PG8_BAR; PG8_SCHED;
	s_waitcnt lgkmcnt(0)
	v_mfma_f32_16x16x32_bf16 v[126:129], v[156:159], v[188:191], v[126:129]
	v_mfma_f32_16x16x32_bf16 v[118:121], v[156:159], v[196:199], v[118:121]
	v_mfma_f32_16x16x32_bf16 v[110:113], v[156:159], v[204:207], v[110:113]
	v_mfma_f32_16x16x32_bf16 v[102:105], v[156:159], v[212:215], v[102:105]
	v_mfma_f32_16x16x32_bf16 v[98:101], v[164:167], v[212:215], v[98:101]
	v_mfma_f32_16x16x32_bf16 v[106:109], v[164:167], v[204:207], v[106:109]
	v_mfma_f32_16x16x32_bf16 v[114:117], v[164:167], v[196:199], v[114:117]
	v_mfma_f32_16x16x32_bf16 v[122:125], v[164:167], v[188:191], v[122:125]
	v_mfma_f32_16x16x32_bf16 v[126:129], v[160:163], v[192:195], v[126:129]
	v_mfma_f32_16x16x32_bf16 v[118:121], v[160:163], v[200:203], v[118:121]
	v_mfma_f32_16x16x32_bf16 v[110:113], v[160:163], v[208:211], v[110:113]
	v_mfma_f32_16x16x32_bf16 v[102:105], v[160:163], v[216:219], v[102:105]
	v_mfma_f32_16x16x32_bf16 v[98:101], v[168:171], v[216:219], v[98:101]
	v_mfma_f32_16x16x32_bf16 v[106:109], v[168:171], v[208:211], v[106:109]
	v_mfma_f32_16x16x32_bf16 v[114:117], v[168:171], v[200:203], v[114:117]
	v_mfma_f32_16x16x32_bf16 v[122:125], v[168:171], v[192:195], v[122:125]
	v_mfma_f32_16x16x32_bf16 v[94:97], v[172:175], v[188:191], v[94:97]
	v_mfma_f32_16x16x32_bf16 v[86:89], v[172:175], v[196:199], v[86:89]
	v_mfma_f32_16x16x32_bf16 v[78:81], v[172:175], v[204:207], v[78:81]
	v_mfma_f32_16x16x32_bf16 v[70:73], v[172:175], v[212:215], v[70:73]
	v_mfma_f32_16x16x32_bf16 v[66:69], v[180:183], v[212:215], v[66:69]
	v_mfma_f32_16x16x32_bf16 v[74:77], v[180:183], v[204:207], v[74:77]
	v_mfma_f32_16x16x32_bf16 v[82:85], v[180:183], v[196:199], v[82:85]
	v_mfma_f32_16x16x32_bf16 v[90:93], v[180:183], v[188:191], v[90:93]
	v_mfma_f32_16x16x32_bf16 v[94:97], v[176:179], v[192:195], v[94:97]
	v_mfma_f32_16x16x32_bf16 v[86:89], v[176:179], v[200:203], v[86:89]
	v_mfma_f32_16x16x32_bf16 v[78:81], v[176:179], v[208:211], v[78:81]
	v_mfma_f32_16x16x32_bf16 v[70:73], v[176:179], v[216:219], v[70:73]
	v_mfma_f32_16x16x32_bf16 v[66:69], v[184:187], v[216:219], v[66:69]
	v_mfma_f32_16x16x32_bf16 v[74:77], v[184:187], v[208:211], v[74:77]
	v_mfma_f32_16x16x32_bf16 v[82:85], v[184:187], v[200:203], v[82:85]
	v_mfma_f32_16x16x32_bf16 v[90:93], v[184:187], v[192:195], v[90:93]
	s_barrier
	s_add_i32 s59, s95, s88
	v_lshl_add_u64 v[150:151], s[82:83], 0, v[132:133]
	s_mov_b32 m0, s59
	ds_read_b128 v[188:191], v154 offset:16384
	ds_read_b128 v[192:195], v154 offset:17408
	ds_read_b128 v[196:199], v154 offset:18432
	ds_read_b128 v[200:203], v154 offset:19456
	ds_read_b128 v[204:207], v154 offset:20480
	ds_read_b128 v[208:211], v154 offset:21504
	ds_read_b128 v[212:215], v154 offset:22528
	ds_read_b128 v[216:219], v154 offset:23552
	global_load_lds_dwordx4 v[150:151], off
	s_add_i32 m0, s59, 0x2000
	s_add_u32 vcc_lo, s82, 0x40000
	v_lshl_add_u64 v[220:221], s[82:83], 0, v[136:137]
	s_addc_u32 vcc_hi, s83, 0
	s_add_i32 s59, s96, s88
	global_load_lds_dwordx4 v[220:221], off
	v_lshl_add_u64 v[222:223], vcc, 0, v[132:133]
	s_mov_b32 m0, s59
	v_lshl_add_u64 v[224:225], s[84:85], 0, v[134:135]
	global_load_lds_dwordx4 v[222:223], off
	v_lshl_add_u64 v[222:223], vcc, 0, v[136:137]
	s_add_i32 m0, s59, 0x2000
	s_nop 0
	global_load_lds_dwordx4 v[222:223], off
	v_lshl_add_u64 v[222:223], s[84:85], 0, v[130:131]
	s_mov_b32 m0, s15
	s_nop 0
	global_load_lds_dwordx4 v[222:223], off
	s_mov_b32 m0, s17
	s_nop 0
	global_load_lds_dwordx4 v[224:225], off
	s_waitcnt vmcnt(8)
	s_waitcnt lgkmcnt(0)
	s_barrier
	s_waitcnt lgkmcnt(0)
	v_mfma_f32_16x16x32_bf16 v[62:65], v[156:159], v[188:191], v[62:65]
	v_mfma_f32_16x16x32_bf16 v[54:57], v[156:159], v[196:199], v[54:57]
	v_mfma_f32_16x16x32_bf16 v[46:49], v[156:159], v[204:207], v[46:49]
	v_mfma_f32_16x16x32_bf16 v[38:41], v[156:159], v[212:215], v[38:41]
	v_mfma_f32_16x16x32_bf16 v[34:37], v[164:167], v[212:215], v[34:37]
	v_mfma_f32_16x16x32_bf16 v[42:45], v[164:167], v[204:207], v[42:45]
	v_mfma_f32_16x16x32_bf16 v[50:53], v[164:167], v[196:199], v[50:53]
	v_mfma_f32_16x16x32_bf16 v[58:61], v[164:167], v[188:191], v[58:61]
	v_mfma_f32_16x16x32_bf16 v[62:65], v[160:163], v[192:195], v[62:65]
	v_mfma_f32_16x16x32_bf16 v[54:57], v[160:163], v[200:203], v[54:57]
	v_mfma_f32_16x16x32_bf16 v[46:49], v[160:163], v[208:211], v[46:49]
	v_mfma_f32_16x16x32_bf16 v[38:41], v[160:163], v[216:219], v[38:41]
	v_mfma_f32_16x16x32_bf16 v[34:37], v[168:171], v[216:219], v[34:37]
	v_mfma_f32_16x16x32_bf16 v[42:45], v[168:171], v[208:211], v[42:45]
	v_mfma_f32_16x16x32_bf16 v[50:53], v[168:171], v[200:203], v[50:53]
	v_mfma_f32_16x16x32_bf16 v[58:61], v[168:171], v[192:195], v[58:61]
	v_mfma_f32_16x16x32_bf16 v[30:33], v[172:175], v[188:191], v[30:33]
	v_mfma_f32_16x16x32_bf16 v[22:25], v[172:175], v[196:199], v[22:25]
	v_mfma_f32_16x16x32_bf16 v[14:17], v[172:175], v[204:207], v[14:17]
	v_mfma_f32_16x16x32_bf16 v[6:9], v[172:175], v[212:215], v[6:9]
	v_mfma_f32_16x16x32_bf16 v[2:5], v[180:183], v[212:215], v[2:5]
	v_mfma_f32_16x16x32_bf16 v[10:13], v[180:183], v[204:207], v[10:13]
	v_mfma_f32_16x16x32_bf16 v[18:21], v[180:183], v[196:199], v[18:21]
	v_mfma_f32_16x16x32_bf16 v[26:29], v[180:183], v[188:191], v[26:29]
	v_mfma_f32_16x16x32_bf16 v[30:33], v[176:179], v[192:195], v[30:33]
	v_mfma_f32_16x16x32_bf16 v[22:25], v[176:179], v[200:203], v[22:25]
	v_mfma_f32_16x16x32_bf16 v[14:17], v[176:179], v[208:211], v[14:17]
	v_mfma_f32_16x16x32_bf16 v[6:9], v[176:179], v[216:219], v[6:9]
	v_mfma_f32_16x16x32_bf16 v[2:5], v[184:187], v[216:219], v[2:5]
	v_mfma_f32_16x16x32_bf16 v[10:13], v[184:187], v[208:211], v[10:13]
	v_mfma_f32_16x16x32_bf16 v[18:21], v[184:187], v[200:203], v[18:21]
	v_mfma_f32_16x16x32_bf16 v[26:29], v[184:187], v[192:195], v[26:29]
	s_barrier
; #define PG8_STAGEA(bufoff, gbase) PG8_STAGE_(bufoff, gbase, voffA)
; #define PG8_STAGEB(bufoff, gbase) PG8_STAGE_(bufoff, gbase, voffB)
; #define PG8_LDA(dst, b, h) do { _Pragma("unroll") for (int m = 0; m < 4; ++m) _Pragma("unroll") for (int k = 0; k < 2; ++k) dst[m][k] = *(const LAS bf16x8*)(lds + PG8_SA(b, h) + aoff + m * 2048 + k * 1024); } while (0)
; #define PG8_LDB(dst, b, h) do { _Pragma("unroll") for (int n = 0; n < 2; ++n) _Pragma("unroll") for (int k = 0; k < 2; ++k) dst[n][k] = *(const LAS bf16x8*)(lds + PG8_SB(b, h) + boff + n * 2048 + k * 1024); } while (0)
; #define PG8_MMA(ai, bj, At, Bt_) do { __builtin_amdgcn_s_setprio(1); _Pragma("unroll") for (int m = 0; m < 4; ++m) _Pragma("unroll") for (int n = 0; n < 2; ++n) _Pragma("unroll") for (int k = 0; k < 2; ++k) \
;         acc[ai][bj][m][n] = __builtin_amdgcn_mfma_f32_16x16x32_bf16(Bt_[n][k], At[m][k], acc[ai][bj][m][n], 0, 0, 0); __builtin_amdgcn_s_setprio(0); } while (0)
; #define PG8_WAIT_V(n) asm volatile("s_waitcnt vmcnt(" #n ")" ::: "memory")
; #define PG8_WAIT_L(n) asm volatile("s_waitcnt lgkmcnt(" #n ")" ::: "memory")
; #define PG8_BAR __builtin_amdgcn_s_barrier()
; #define PG8_SCHED __builtin_amdgcn_sched_barrier(0)
; template <int EK, int SK = -1>
; __device__ __forceinline__ void gemm_phase(LAS unsigned char* lds, const bf16_t* A, const bf16_t* Bt, int nM, int N, int K, const EpiArgs& E) {
;     ...
;         for (int t = 0; t < nt; t += 2) {
;     ...
;             PG8_LDB(B0, 1, 0); PG8_LDB(B1, 1, 1); PG8_SCHED; PG8_LDA(At, 1, 0); PG8_STAGEA(PG8_SA(0, 1), a2 + hstep);
;             PG8_WAIT_V(8); PG8_WAIT_L(0); PG8_BAR; PG8_MMA(0, 0, At, B0); PG8_MMA(0, 1, At, B1); PG8_BAR; PG8_SCHED;
;             PG8_LDA(At, 1, 1); PG8_STAGEB(PG8_SB(1, 0), b3); PG8_STAGEB(PG8_SB(1, 1), b3 + hstep); PG8_STAGEA(PG8_SA(1, 0), a3);
;             PG8_WAIT_V(8); PG8_WAIT_L(0); PG8_BAR; PG8_MMA(1, 0, At, B0); PG8_MMA(1, 1, At, B1); PG8_BAR; PG8_SCHED;
	s_add_i32 s59, 0, 0x18000
	s_add_i32 s73, 0, 0x1c000
	v_add_u32_e32 v168, s59, v152
	v_add_u32_e32 v184, s73, v152
	ds_read_b128 v[156:159], v168
	ds_read_b128 v[160:163], v168 offset:1024
	ds_read_b128 v[164:167], v168 offset:2048
	ds_read_b128 v[168:171], v168 offset:3072
	ds_read_b128 v[172:175], v184
	ds_read_b128 v[176:179], v184 offset:1024
	ds_read_b128 v[180:183], v184 offset:2048
	ds_read_b128 v[184:187], v184 offset:3072
	s_add_u32 s84, s84, 0x40000
	s_addc_u32 s85, s85, 0
	s_mov_b32 m0, s89
	v_lshl_add_u64 v[226:227], s[84:85], 0, v[130:131]
	ds_read_b128 v[188:191], v154 offset:32768
	ds_read_b128 v[192:195], v154 offset:33792
	ds_read_b128 v[196:199], v154 offset:34816
	ds_read_b128 v[200:203], v154 offset:35840
	ds_read_b128 v[204:207], v154 offset:36864
	ds_read_b128 v[208:211], v154 offset:37888
	ds_read_b128 v[212:215], v154 offset:38912
	ds_read_b128 v[216:219], v154 offset:39936
	global_load_lds_dwordx4 v[226:227], off
	v_lshl_add_u64 v[226:227], s[84:85], 0, v[134:135]
	s_mov_b32 m0, s90
	s_nop 0
	global_load_lds_dwordx4 v[226:227], off
	s_waitcnt vmcnt(8)
	s_waitcnt lgkmcnt(0)
	s_barrier
	s_waitcnt lgkmcnt(0)
	v_mfma_f32_16x16x32_bf16 v[126:129], v[156:159], v[188:191], v[126:129]
	v_mfma_f32_16x16x32_bf16 v[118:121], v[156:159], v[196:199], v[118:121]
	v_mfma_f32_16x16x32_bf16 v[110:113], v[156:159], v[204:207], v[110:113]
	v_mfma_f32_16x16x32_bf16 v[102:105], v[156:159], v[212:215], v[102:105]
	v_mfma_f32_16x16x32_bf16 v[98:101], v[164:167], v[212:215], v[98:101]
	v_mfma_f32_16x16x32_bf16 v[106:109], v[164:167], v[204:207], v[106:109]
	v_mfma_f32_16x16x32_bf16 v[114:117], v[164:167], v[196:199], v[114:117]
	v_mfma_f32_16x16x32_bf16 v[122:125], v[164:167], v[188:191], v[122:125]
	v_mfma_f32_16x16x32_bf16 v[126:129], v[160:163], v[192:195], v[126:129]
	v_mfma_f32_16x16x32_bf16 v[118:121], v[160:163], v[200:203], v[118:121]
	v_mfma_f32_16x16x32_bf16 v[110:113], v[160:163], v[208:211], v[110:113]
	v_mfma_f32_16x16x32_bf16 v[102:105], v[160:163], v[216:219], v[102:105]
	v_mfma_f32_16x16x32_bf16 v[98:101], v[168:171], v[216:219], v[98:101]
	v_mfma_f32_16x16x32_bf16 v[106:109], v[168:171], v[208:211], v[106:109]
	v_mfma_f32_16x16x32_bf16 v[114:117], v[168:171], v[200:203], v[114:117]
	v_mfma_f32_16x16x32_bf16 v[122:125], v[168:171], v[192:195], v[122:125]
	v_mfma_f32_16x16x32_bf16 v[94:97], v[172:175], v[188:191], v[94:97]
	v_mfma_f32_16x16x32_bf16 v[86:89], v[172:175], v[196:199], v[86:89]
	v_mfma_f32_16x16x32_bf16 v[78:81], v[172:175], v[204:207], v[78:81]
	v_mfma_f32_16x16x32_bf16 v[70:73], v[172:175], v[212:215], v[70:73]
	v_mfma_f32_16x16x32_bf16 v[66:69], v[180:183], v[212:215], v[66:69]
	v_mfma_f32_16x16x32_bf16 v[74:77], v[180:183], v[204:207], v[74:77]
	v_mfma_f32_16x16x32_bf16 v[82:85], v[180:183], v[196:199], v[82:85]
	v_mfma_f32_16x16x32_bf16 v[90:93], v[180:183], v[188:191], v[90:93]
	v_mfma_f32_16x16x32_bf16 v[94:97], v[176:179], v[192:195], v[94:97]
	v_mfma_f32_16x16x32_bf16 v[86:89], v[176:179], v[200:203], v[86:89]
	v_mfma_f32_16x16x32_bf16 v[78:81], v[176:179], v[208:211], v[78:81]
	v_mfma_f32_16x16x32_bf16 v[70:73], v[176:179], v[216:219], v[70:73]
	v_mfma_f32_16x16x32_bf16 v[66:69], v[184:187], v[216:219], v[66:69]
	v_mfma_f32_16x16x32_bf16 v[74:77], v[184:187], v[208:211], v[74:77]
	v_mfma_f32_16x16x32_bf16 v[82:85], v[184:187], v[200:203], v[82:85]
	v_mfma_f32_16x16x32_bf16 v[90:93], v[184:187], v[192:195], v[90:93]
	s_barrier
	s_add_i32 s59, s59, s88
	v_lshl_add_u64 v[150:151], v[150:151], 0, s[68:69]
	s_mov_b32 m0, s59
	ds_read_b128 v[188:191], v154 offset:49152
	ds_read_b128 v[192:195], v154 offset:50176
	ds_read_b128 v[196:199], v154 offset:51200
	ds_read_b128 v[200:203], v154 offset:52224
	ds_read_b128 v[204:207], v154 offset:53248
	ds_read_b128 v[208:211], v154 offset:54272
	ds_read_b128 v[212:215], v154 offset:55296
	ds_read_b128 v[216:219], v154 offset:56320
	global_load_lds_dwordx4 v[150:151], off
	s_add_i32 m0, s59, 0x2000
	s_add_u32 s82, s82, 0x40080
	v_lshl_add_u64 v[150:151], v[220:221], 0, s[68:69]
	s_addc_u32 s83, s83, 0
	s_add_i32 s59, s73, s88
	global_load_lds_dwordx4 v[150:151], off
	v_lshl_add_u64 v[150:151], s[82:83], 0, v[132:133]
	s_mov_b32 m0, s59
	s_nop 0
	global_load_lds_dwordx4 v[150:151], off
	v_lshl_add_u64 v[150:151], s[82:83], 0, v[136:137]
	s_add_i32 m0, s59, 0x2000
	s_nop 0
	global_load_lds_dwordx4 v[150:151], off
	v_lshl_add_u64 v[150:151], v[222:223], 0, s[68:69]
	s_mov_b32 m0, s93
	s_nop 0
	global_load_lds_dwordx4 v[150:151], off
	v_lshl_add_u64 v[150:151], v[224:225], 0, s[68:69]
	s_mov_b32 m0, s94
	s_nop 0
	global_load_lds_dwordx4 v[150:151], off
	s_waitcnt vmcnt(8)
	s_waitcnt lgkmcnt(0)
	s_barrier
	s_waitcnt lgkmcnt(0)
	v_mfma_f32_16x16x32_bf16 v[62:65], v[156:159], v[188:191], v[62:65]
	v_mfma_f32_16x16x32_bf16 v[54:57], v[156:159], v[196:199], v[54:57]
	v_mfma_f32_16x16x32_bf16 v[46:49], v[156:159], v[204:207], v[46:49]
	v_mfma_f32_16x16x32_bf16 v[38:41], v[156:159], v[212:215], v[38:41]
	v_mfma_f32_16x16x32_bf16 v[34:37], v[164:167], v[212:215], v[34:37]
	v_mfma_f32_16x16x32_bf16 v[42:45], v[164:167], v[204:207], v[42:45]
	v_mfma_f32_16x16x32_bf16 v[50:53], v[164:167], v[196:199], v[50:53]
	v_mfma_f32_16x16x32_bf16 v[58:61], v[164:167], v[188:191], v[58:61]
	v_mfma_f32_16x16x32_bf16 v[62:65], v[160:163], v[192:195], v[62:65]
	v_mfma_f32_16x16x32_bf16 v[54:57], v[160:163], v[200:203], v[54:57]
	v_mfma_f32_16x16x32_bf16 v[46:49], v[160:163], v[208:211], v[46:49]
	v_mfma_f32_16x16x32_bf16 v[38:41], v[160:163], v[216:219], v[38:41]
	v_mfma_f32_16x16x32_bf16 v[34:37], v[168:171], v[216:219], v[34:37]
	v_mfma_f32_16x16x32_bf16 v[42:45], v[168:171], v[208:211], v[42:45]
	v_mfma_f32_16x16x32_bf16 v[50:53], v[168:171], v[200:203], v[50:53]
	v_mfma_f32_16x16x32_bf16 v[58:61], v[168:171], v[192:195], v[58:61]
	v_mfma_f32_16x16x32_bf16 v[30:33], v[172:175], v[188:191], v[30:33]
	v_mfma_f32_16x16x32_bf16 v[22:25], v[172:175], v[196:199], v[22:25]
	v_mfma_f32_16x16x32_bf16 v[14:17], v[172:175], v[204:207], v[14:17]
	v_mfma_f32_16x16x32_bf16 v[6:9], v[172:175], v[212:215], v[6:9]
	v_mfma_f32_16x16x32_bf16 v[2:5], v[180:183], v[212:215], v[2:5]
	v_mfma_f32_16x16x32_bf16 v[10:13], v[180:183], v[204:207], v[10:13]
	v_mfma_f32_16x16x32_bf16 v[18:21], v[180:183], v[196:199], v[18:21]
	v_mfma_f32_16x16x32_bf16 v[26:29], v[180:183], v[188:191], v[26:29]
	v_mfma_f32_16x16x32_bf16 v[30:33], v[176:179], v[192:195], v[30:33]
	v_mfma_f32_16x16x32_bf16 v[22:25], v[176:179], v[200:203], v[22:25]
	v_mfma_f32_16x16x32_bf16 v[14:17], v[176:179], v[208:211], v[14:17]
	v_mfma_f32_16x16x32_bf16 v[6:9], v[176:179], v[216:219], v[6:9]
	v_mfma_f32_16x16x32_bf16 v[2:5], v[184:187], v[216:219], v[2:5]
	v_mfma_f32_16x16x32_bf16 v[10:13], v[184:187], v[208:211], v[10:13]
	v_mfma_f32_16x16x32_bf16 v[18:21], v[184:187], v[200:203], v[18:21]
	v_mfma_f32_16x16x32_bf16 v[26:29], v[184:187], v[192:195], v[26:29]
	s_barrier
	s_add_i32 s58, s58, 2
	s_add_u32 s80, s80, 0x100
	s_addc_u32 s81, s81, 0
	s_cmp_gt_u32 s58, 13
	s_cbranch_scc0 .LBB0_413

; #define PG8_STAGEA(bufoff, gbase) PG8_STAGE_(bufoff, gbase, voffA)
; #define PG8_STAGEB(bufoff, gbase) PG8_STAGE_(bufoff, gbase, voffB)
; #define PG8_LDA(dst, b, h) do { _Pragma("unroll") for (int m = 0; m < 4; ++m) _Pragma("unroll") for (int k = 0; k < 2; ++k) dst[m][k] = *(const LAS bf16x8*)(lds + PG8_SA(b, h) + aoff + m * 2048 + k * 1024); } while (0)
; #define PG8_LDB(dst, b, h) do { _Pragma("unroll") for (int n = 0; n < 2; ++n) _Pragma("unroll") for (int k = 0; k < 2; ++k) dst[n][k] = *(const LAS bf16x8*)(lds + PG8_SB(b, h) + boff + n * 2048 + k * 1024); } while (0)
; #define PG8_MMA(ai, bj, At, Bt_) do { __builtin_amdgcn_s_setprio(1); _Pragma("unroll") for (int m = 0; m < 4; ++m) _Pragma("unroll") for (int n = 0; n < 2; ++n) _Pragma("unroll") for (int k = 0; k < 2; ++k) \
;         acc[ai][bj][m][n] = __builtin_amdgcn_mfma_f32_16x16x32_bf16(Bt_[n][k], At[m][k], acc[ai][bj][m][n], 0, 0, 0); __builtin_amdgcn_s_setprio(0); } while (0)
; #define PG8_WAIT_V(n) asm volatile("s_waitcnt vmcnt(" #n ")" ::: "memory")
; #define PG8_WAIT_L(n) asm volatile("s_waitcnt lgkmcnt(" #n ")" ::: "memory")
; #define PG8_BAR __builtin_amdgcn_s_barrier()
; template <int EK, int SK = -1>
; __device__ __forceinline__ void gemm_phase(LAS unsigned char* lds, const bf16_t* A, const bf16_t* Bt, int nM, int N, int K, const EpiArgs& E) {
;     ...
;         const bool has_next = S.next(ui + 1, nxt);
;         const char* nA = has_next ? (const char*)A + (size_t)nxt.pm * tstep : cA; const char* nB = has_next ? (const char*)Bt + (size_t)nxt.pn * tstep : cB;
;         for (int t = 0; t < nt; t += 2) {
;             const bool last = (t == nt - 2);
;             const char* a1 = cA + (size_t)(t + 1) * kstep;
;             const char* a2 = last ? nA : cA + (size_t)(t + 2) * kstep; const char* b2 = last ? nB : cB + (size_t)(t + 2) * kstep;
;             const char* a3 = a2 + kstep; const char* b3 = b2 + kstep;
;             PG8_LDB(B0, 0, 0); PG8_LDB(B1, 0, 1); PG8_SCHED; PG8_LDA(At, 0, 0); PG8_STAGEA(PG8_SA(1, 1), a1 + hstep);
;             PG8_WAIT_V(8); PG8_WAIT_L(0); PG8_BAR; PG8_MMA(0, 0, At, B0); PG8_MMA(0, 1, At, B1); PG8_BAR; PG8_SCHED;
;             PG8_LDA(At, 0, 1); PG8_STAGEB(PG8_SB(0, 0), b2); PG8_STAGEB(PG8_SB(0, 1), b2 + hstep); PG8_STAGEA(PG8_SA(0, 0), a2);
;             PG8_WAIT_V(8); PG8_WAIT_L(0); PG8_BAR; PG8_MMA(1, 0, At, B0); PG8_MMA(1, 1, At, B1); PG8_BAR; PG8_SCHED;
.LBB0_537:
	s_add_u32 s54, s74, 0x100
	s_addc_u32 s55, s75, 0
	s_ashr_i32 s69, s68, 31
	s_lshl_b64 s[56:57], s[68:69], 19
	s_add_u32 s72, s62, s56
	s_addc_u32 s73, s63, s57
	s_and_b64 s[56:57], s[6:7], exec
	s_cselect_b32 s56, s73, s39
	s_cselect_b32 s57, s72, s38
	s_ashr_i32 s41, s40, 31
	s_lshl_b64 s[58:59], s[40:41], 19
	s_add_u32 s70, s81, s58
	s_addc_u32 s71, s82, s59
	s_and_b64 s[58:59], s[6:7], exec
	s_cselect_b32 s41, s71, s75
	s_cselect_b32 s58, s70, s74
	v_lshl_add_u64 v[146:147], s[38:39], 0, v[138:139]
	v_lshl_add_u64 v[148:149], s[38:39], 0, v[140:141]
	s_mov_b32 s59, -2
	s_mov_b64 s[74:75], 0
	v_add_u32_e32 v154, s88, v159
	ds_read_b128 v[150:153], v154
	ds_read_b128 v[164:167], v154 offset:1024
	ds_read_b128 v[168:171], v154 offset:2048
	ds_read_b128 v[172:175], v154 offset:3072
	v_add_u32_e32 v154, s89, v159
	s_add_u32 s69, s38, s74
	ds_read_b128 v[176:179], v154
	ds_read_b128 v[180:183], v154 offset:1024
	ds_read_b128 v[184:187], v154 offset:2048
	ds_read_b128 v[188:191], v154 offset:3072
	s_addc_u32 s76, s39, s75
	s_add_u32 s69, s69, 0x100
	s_addc_u32 s76, s76, 0
	s_add_u32 s91, s54, s74
	s_addc_u32 s77, s55, s75
	s_cmpk_eq_i32 s74, 0x700
	s_cselect_b32 s79, s56, s76
	s_cselect_b32 s78, s57, s69
	s_cselect_b32 s77, s41, s77
	s_cselect_b32 s76, s58, s91
	v_lshl_add_u64 v[154:155], v[146:147], 0, s[74:75]
	s_add_i32 m0, s15, 0xc000
	ds_read_b128 v[192:195], v162
	ds_read_b128 v[196:199], v162 offset:1024
	ds_read_b128 v[200:203], v162 offset:2048
	ds_read_b128 v[204:207], v162 offset:3072
	ds_read_b128 v[208:211], v162 offset:4096
	ds_read_b128 v[212:215], v162 offset:5120
	ds_read_b128 v[216:219], v162 offset:6144
	ds_read_b128 v[220:223], v162 offset:7168
	global_load_lds_dwordx4 v[154:155], off
	v_lshl_add_u64 v[154:155], v[148:149], 0, s[74:75]
	s_add_i32 m0, s15, 0xe000
	s_nop 0
	global_load_lds_dwordx4 v[154:155], off
	s_waitcnt vmcnt(8)
	s_waitcnt lgkmcnt(0)
	s_barrier
	s_waitcnt lgkmcnt(0)
	v_mfma_f32_16x16x32_bf16 v[110:113], v[150:153], v[192:195], 0
	v_mfma_f32_16x16x32_bf16 v[102:105], v[150:153], v[200:203], 0
	v_mfma_f32_16x16x32_bf16 v[94:97], v[150:153], v[208:211], 0
	v_mfma_f32_16x16x32_bf16 v[86:89], v[150:153], v[216:219], 0
	v_mfma_f32_16x16x32_bf16 v[82:85], v[168:171], v[216:219], 0
	v_mfma_f32_16x16x32_bf16 v[90:93], v[168:171], v[208:211], 0
	v_mfma_f32_16x16x32_bf16 v[98:101], v[168:171], v[200:203], 0
	v_mfma_f32_16x16x32_bf16 v[106:109], v[168:171], v[192:195], 0
	v_mfma_f32_16x16x32_bf16 v[110:113], v[164:167], v[196:199], v[110:113]
	v_mfma_f32_16x16x32_bf16 v[102:105], v[164:167], v[204:207], v[102:105]
	v_mfma_f32_16x16x32_bf16 v[94:97], v[164:167], v[212:215], v[94:97]
	v_mfma_f32_16x16x32_bf16 v[86:89], v[164:167], v[220:223], v[86:89]
	v_mfma_f32_16x16x32_bf16 v[82:85], v[172:175], v[220:223], v[82:85]
	v_mfma_f32_16x16x32_bf16 v[90:93], v[172:175], v[212:215], v[90:93]
	v_mfma_f32_16x16x32_bf16 v[98:101], v[172:175], v[204:207], v[98:101]
	v_mfma_f32_16x16x32_bf16 v[106:109], v[172:175], v[196:199], v[106:109]
	v_mfma_f32_16x16x32_bf16 v[78:81], v[176:179], v[192:195], 0
	v_mfma_f32_16x16x32_bf16 v[70:73], v[176:179], v[200:203], 0
	v_mfma_f32_16x16x32_bf16 v[62:65], v[176:179], v[208:211], 0
	v_mfma_f32_16x16x32_bf16 v[54:57], v[176:179], v[216:219], 0
	v_mfma_f32_16x16x32_bf16 v[50:53], v[184:187], v[216:219], 0
	v_mfma_f32_16x16x32_bf16 v[58:61], v[184:187], v[208:211], 0
	v_mfma_f32_16x16x32_bf16 v[66:69], v[184:187], v[200:203], 0
	v_mfma_f32_16x16x32_bf16 v[74:77], v[184:187], v[192:195], 0
	v_mfma_f32_16x16x32_bf16 v[78:81], v[180:183], v[196:199], v[78:81]
	v_mfma_f32_16x16x32_bf16 v[70:73], v[180:183], v[204:207], v[70:73]
	v_mfma_f32_16x16x32_bf16 v[62:65], v[180:183], v[212:215], v[62:65]
	v_mfma_f32_16x16x32_bf16 v[54:57], v[180:183], v[220:223], v[54:57]
	v_mfma_f32_16x16x32_bf16 v[50:53], v[188:191], v[220:223], v[50:53]
	v_mfma_f32_16x16x32_bf16 v[58:61], v[188:191], v[212:215], v[58:61]
	v_mfma_f32_16x16x32_bf16 v[66:69], v[188:191], v[204:207], v[66:69]
	v_mfma_f32_16x16x32_bf16 v[74:77], v[188:191], v[196:199], v[74:77]
	s_barrier
	s_add_i32 s69, s88, s83
	v_lshl_add_u64 v[154:155], s[76:77], 0, v[132:133]
	s_mov_b32 m0, s69
	ds_read_b128 v[192:195], v162 offset:16384
	ds_read_b128 v[196:199], v162 offset:17408
	ds_read_b128 v[200:203], v162 offset:18432
	ds_read_b128 v[204:207], v162 offset:19456
	ds_read_b128 v[208:211], v162 offset:20480
	ds_read_b128 v[212:215], v162 offset:21504
	ds_read_b128 v[216:219], v162 offset:22528
	ds_read_b128 v[220:223], v162 offset:23552
	global_load_lds_dwordx4 v[154:155], off
	s_add_i32 m0, s69, 0x2000
	s_add_u32 s92, s76, 0x40000
	v_lshl_add_u64 v[224:225], s[76:77], 0, v[136:137]
	s_addc_u32 s93, s77, 0
	s_add_i32 s69, s89, s83
	global_load_lds_dwordx4 v[224:225], off
	v_lshl_add_u64 v[226:227], s[92:93], 0, v[132:133]
	s_mov_b32 m0, s69
	v_lshl_add_u64 v[228:229], s[78:79], 0, v[134:135]
	global_load_lds_dwordx4 v[226:227], off
	v_lshl_add_u64 v[226:227], s[92:93], 0, v[136:137]
	s_add_i32 m0, s69, 0x2000
	s_nop 0
	global_load_lds_dwordx4 v[226:227], off
	v_lshl_add_u64 v[226:227], s[78:79], 0, v[130:131]
	s_mov_b32 m0, s15
	s_nop 0
	global_load_lds_dwordx4 v[226:227], off
	s_mov_b32 m0, s17
	s_nop 0
	global_load_lds_dwordx4 v[228:229], off
	s_waitcnt vmcnt(8)
	s_waitcnt lgkmcnt(0)
	s_barrier
; #define PG8_STAGEA(bufoff, gbase) PG8_STAGE_(bufoff, gbase, voffA)
; #define PG8_LDA(dst, b, h) do { _Pragma("unroll") for (int m = 0; m < 4; ++m) _Pragma("unroll") for (int k = 0; k < 2; ++k) dst[m][k] = *(const LAS bf16x8*)(lds + PG8_SA(b, h) + aoff + m * 2048 + k * 1024); } while (0)
; #define PG8_LDB(dst, b, h) do { _Pragma("unroll") for (int n = 0; n < 2; ++n) _Pragma("unroll") for (int k = 0; k < 2; ++k) dst[n][k] = *(const LAS bf16x8*)(lds + PG8_SB(b, h) + boff + n * 2048 + k * 1024); } while (0)
; #define PG8_MMA(ai, bj, At, Bt_) do { __builtin_amdgcn_s_setprio(1); _Pragma("unroll") for (int m = 0; m < 4; ++m) _Pragma("unroll") for (int n = 0; n < 2; ++n) _Pragma("unroll") for (int k = 0; k < 2; ++k) \
;         acc[ai][bj][m][n] = __builtin_amdgcn_mfma_f32_16x16x32_bf16(Bt_[n][k], At[m][k], acc[ai][bj][m][n], 0, 0, 0); __builtin_amdgcn_s_setprio(0); } while (0)
; #define PG8_WAIT_V(n) asm volatile("s_waitcnt vmcnt(" #n ")" ::: "memory")
; #define PG8_WAIT_L(n) asm volatile("s_waitcnt lgkmcnt(" #n ")" ::: "memory")
; #define PG8_BAR __builtin_amdgcn_s_barrier()
; #define PG8_SCHED __builtin_amdgcn_sched_barrier(0)
; template <int EK, int SK = -1>
; __device__ __forceinline__ void gemm_phase(LAS unsigned char* lds, const bf16_t* A, const bf16_t* Bt, int nM, int N, int K, const EpiArgs& E) {
;     ...
;             PG8_WAIT_V(8); PG8_WAIT_L(0); PG8_BAR; PG8_MMA(1, 0, At, B0); PG8_MMA(1, 1, At, B1); PG8_BAR; PG8_SCHED;
;             PG8_LDB(B0, 1, 0); PG8_LDB(B1, 1, 1); PG8_SCHED; PG8_LDA(At, 1, 0); PG8_STAGEA(PG8_SA(0, 1), a2 + hstep);
;             PG8_WAIT_V(8); PG8_WAIT_L(0); PG8_BAR; PG8_MMA(0, 0, At, B0); PG8_MMA(0, 1, At, B1); PG8_BAR; PG8_SCHED;
	s_waitcnt lgkmcnt(0)
	v_mfma_f32_16x16x32_bf16 v[46:49], v[150:153], v[192:195], 0
	v_mfma_f32_16x16x32_bf16 v[38:41], v[150:153], v[200:203], 0
	v_mfma_f32_16x16x32_bf16 v[30:33], v[150:153], v[208:211], 0
	v_mfma_f32_16x16x32_bf16 v[22:25], v[150:153], v[216:219], 0
	v_mfma_f32_16x16x32_bf16 v[18:21], v[168:171], v[216:219], 0
	v_mfma_f32_16x16x32_bf16 v[26:29], v[168:171], v[208:211], 0
	v_mfma_f32_16x16x32_bf16 v[34:37], v[168:171], v[200:203], 0
	v_mfma_f32_16x16x32_bf16 v[42:45], v[168:171], v[192:195], 0
	v_mfma_f32_16x16x32_bf16 v[46:49], v[164:167], v[196:199], v[46:49]
	v_mfma_f32_16x16x32_bf16 v[38:41], v[164:167], v[204:207], v[38:41]
	v_mfma_f32_16x16x32_bf16 v[30:33], v[164:167], v[212:215], v[30:33]
	v_mfma_f32_16x16x32_bf16 v[22:25], v[164:167], v[220:223], v[22:25]
	v_mfma_f32_16x16x32_bf16 v[18:21], v[172:175], v[220:223], v[18:21]
	v_mfma_f32_16x16x32_bf16 v[26:29], v[172:175], v[212:215], v[26:29]
	v_mfma_f32_16x16x32_bf16 v[34:37], v[172:175], v[204:207], v[34:37]
	v_mfma_f32_16x16x32_bf16 v[42:45], v[172:175], v[196:199], v[42:45]
	v_mfma_f32_16x16x32_bf16 v[14:17], v[176:179], v[192:195], 0
	v_mfma_f32_16x16x32_bf16 v[6:9], v[176:179], v[200:203], 0
	v_mfma_f32_16x16x32_bf16 v[114:117], v[176:179], v[208:211], 0
	v_mfma_f32_16x16x32_bf16 v[122:125], v[176:179], v[216:219], 0
	v_mfma_f32_16x16x32_bf16 v[126:129], v[184:187], v[216:219], 0
	v_mfma_f32_16x16x32_bf16 v[118:121], v[184:187], v[208:211], 0
	v_mfma_f32_16x16x32_bf16 v[2:5], v[184:187], v[200:203], 0
	v_mfma_f32_16x16x32_bf16 v[10:13], v[184:187], v[192:195], 0
	v_mfma_f32_16x16x32_bf16 v[14:17], v[180:183], v[196:199], v[14:17]
	v_mfma_f32_16x16x32_bf16 v[6:9], v[180:183], v[204:207], v[6:9]
	v_mfma_f32_16x16x32_bf16 v[114:117], v[180:183], v[212:215], v[114:117]
	v_mfma_f32_16x16x32_bf16 v[122:125], v[180:183], v[220:223], v[122:125]
	v_mfma_f32_16x16x32_bf16 v[126:129], v[188:191], v[220:223], v[126:129]
	v_mfma_f32_16x16x32_bf16 v[118:121], v[188:191], v[212:215], v[118:121]
	v_mfma_f32_16x16x32_bf16 v[2:5], v[188:191], v[204:207], v[2:5]
	v_mfma_f32_16x16x32_bf16 v[10:13], v[188:191], v[196:199], v[10:13]
	s_barrier
	s_add_i32 s69, 0, 0x18000
	v_add_u32_e32 v163, s69, v159
	s_add_i32 s91, 0, 0x1c000
	ds_read_b128 v[150:153], v163
	ds_read_b128 v[164:167], v163 offset:1024
	ds_read_b128 v[168:171], v163 offset:2048
	ds_read_b128 v[172:175], v163 offset:3072
	v_add_u32_e32 v163, s91, v159
	ds_read_b128 v[176:179], v163
	ds_read_b128 v[180:183], v163 offset:1024
	ds_read_b128 v[184:187], v163 offset:2048
	ds_read_b128 v[188:191], v163 offset:3072
	s_add_u32 s78, s78, 0x40000
	s_addc_u32 s79, s79, 0
	s_mov_b32 m0, s84
	v_lshl_add_u64 v[230:231], s[78:79], 0, v[130:131]
	ds_read_b128 v[192:195], v162 offset:32768
	ds_read_b128 v[196:199], v162 offset:33792
	ds_read_b128 v[200:203], v162 offset:34816
	ds_read_b128 v[204:207], v162 offset:35840
	ds_read_b128 v[208:211], v162 offset:36864
	ds_read_b128 v[212:215], v162 offset:37888
	ds_read_b128 v[216:219], v162 offset:38912
	ds_read_b128 v[220:223], v162 offset:39936
	global_load_lds_dwordx4 v[230:231], off
	v_lshl_add_u64 v[230:231], s[78:79], 0, v[134:135]
	s_mov_b32 m0, s85
	s_nop 0
	global_load_lds_dwordx4 v[230:231], off
	s_waitcnt vmcnt(8)
	s_waitcnt lgkmcnt(0)
	s_barrier
	s_waitcnt lgkmcnt(0)
	v_mfma_f32_16x16x32_bf16 v[110:113], v[150:153], v[192:195], v[110:113]
	v_mfma_f32_16x16x32_bf16 v[102:105], v[150:153], v[200:203], v[102:105]
	v_mfma_f32_16x16x32_bf16 v[94:97], v[150:153], v[208:211], v[94:97]
	v_mfma_f32_16x16x32_bf16 v[86:89], v[150:153], v[216:219], v[86:89]
	v_mfma_f32_16x16x32_bf16 v[82:85], v[168:171], v[216:219], v[82:85]
	v_mfma_f32_16x16x32_bf16 v[90:93], v[168:171], v[208:211], v[90:93]
	v_mfma_f32_16x16x32_bf16 v[98:101], v[168:171], v[200:203], v[98:101]
	v_mfma_f32_16x16x32_bf16 v[106:109], v[168:171], v[192:195], v[106:109]
	v_mfma_f32_16x16x32_bf16 v[110:113], v[164:167], v[196:199], v[110:113]
	v_mfma_f32_16x16x32_bf16 v[102:105], v[164:167], v[204:207], v[102:105]
	v_mfma_f32_16x16x32_bf16 v[94:97], v[164:167], v[212:215], v[94:97]
	v_mfma_f32_16x16x32_bf16 v[86:89], v[164:167], v[220:223], v[86:89]
	v_mfma_f32_16x16x32_bf16 v[82:85], v[172:175], v[220:223], v[82:85]
	v_mfma_f32_16x16x32_bf16 v[90:93], v[172:175], v[212:215], v[90:93]
	v_mfma_f32_16x16x32_bf16 v[98:101], v[172:175], v[204:207], v[98:101]
	v_mfma_f32_16x16x32_bf16 v[106:109], v[172:175], v[196:199], v[106:109]
	v_mfma_f32_16x16x32_bf16 v[78:81], v[176:179], v[192:195], v[78:81]
	v_mfma_f32_16x16x32_bf16 v[70:73], v[176:179], v[200:203], v[70:73]
	v_mfma_f32_16x16x32_bf16 v[62:65], v[176:179], v[208:211], v[62:65]
	v_mfma_f32_16x16x32_bf16 v[54:57], v[176:179], v[216:219], v[54:57]
	v_mfma_f32_16x16x32_bf16 v[50:53], v[184:187], v[216:219], v[50:53]
	v_mfma_f32_16x16x32_bf16 v[58:61], v[184:187], v[208:211], v[58:61]
	v_mfma_f32_16x16x32_bf16 v[66:69], v[184:187], v[200:203], v[66:69]
	v_mfma_f32_16x16x32_bf16 v[74:77], v[184:187], v[192:195], v[74:77]
	v_mfma_f32_16x16x32_bf16 v[78:81], v[180:183], v[196:199], v[78:81]
	v_mfma_f32_16x16x32_bf16 v[70:73], v[180:183], v[204:207], v[70:73]
	v_mfma_f32_16x16x32_bf16 v[62:65], v[180:183], v[212:215], v[62:65]
	v_mfma_f32_16x16x32_bf16 v[54:57], v[180:183], v[220:223], v[54:57]
	v_mfma_f32_16x16x32_bf16 v[50:53], v[188:191], v[220:223], v[50:53]
	v_mfma_f32_16x16x32_bf16 v[58:61], v[188:191], v[212:215], v[58:61]
	v_mfma_f32_16x16x32_bf16 v[66:69], v[188:191], v[204:207], v[66:69]
	v_mfma_f32_16x16x32_bf16 v[74:77], v[188:191], v[196:199], v[74:77]
	s_barrier
; #define PG8_STAGEA(bufoff, gbase) PG8_STAGE_(bufoff, gbase, voffA)
; #define PG8_STAGEB(bufoff, gbase) PG8_STAGE_(bufoff, gbase, voffB)
; #define PG8_LDA(dst, b, h) do { _Pragma("unroll") for (int m = 0; m < 4; ++m) _Pragma("unroll") for (int k = 0; k < 2; ++k) dst[m][k] = *(const LAS bf16x8*)(lds + PG8_SA(b, h) + aoff + m * 2048 + k * 1024); } while (0)
; #define PG8_LDB(dst, b, h) do { _Pragma("unroll") for (int n = 0; n < 2; ++n) _Pragma("unroll") for (int k = 0; k < 2; ++k) dst[n][k] = *(const LAS bf16x8*)(lds + PG8_SB(b, h) + boff + n * 2048 + k * 1024); } while (0)
; #define PG8_MMA(ai, bj, At, Bt_) do { __builtin_amdgcn_s_setprio(1); _Pragma("unroll") for (int m = 0; m < 4; ++m) _Pragma("unroll") for (int n = 0; n < 2; ++n) _Pragma("unroll") for (int k = 0; k < 2; ++k) \
;         acc[ai][bj][m][n] = __builtin_amdgcn_mfma_f32_16x16x32_bf16(Bt_[n][k], At[m][k], acc[ai][bj][m][n], 0, 0, 0); __builtin_amdgcn_s_setprio(0); } while (0)
; #define PG8_WAIT_V(n) asm volatile("s_waitcnt vmcnt(" #n ")" ::: "memory")
; #define PG8_WAIT_L(n) asm volatile("s_waitcnt lgkmcnt(" #n ")" ::: "memory")
; #define PG8_BAR __builtin_amdgcn_s_barrier()
; #define PG8_SCHED __builtin_amdgcn_sched_barrier(0)
; template <int EK, int SK = -1>
; __device__ __forceinline__ void gemm_phase(LAS unsigned char* lds, const bf16_t* A, const bf16_t* Bt, int nM, int N, int K, const EpiArgs& E) {
;     ...
;         for (int t = 0; t < nt; t += 2) {
;             const bool last = (t == nt - 2);
;             const char* a1 = cA + (size_t)(t + 1) * kstep;
;             const char* a2 = last ? nA : cA + (size_t)(t + 2) * kstep; const char* b2 = last ? nB : cB + (size_t)(t + 2) * kstep;
;             const char* a3 = a2 + kstep; const char* b3 = b2 + kstep;
;             PG8_LDB(B0, 0, 0); PG8_LDB(B1, 0, 1); PG8_SCHED; PG8_LDA(At, 0, 0); PG8_STAGEA(PG8_SA(1, 1), a1 + hstep);
;     ...
;             PG8_LDA(At, 1, 1); PG8_STAGEB(PG8_SB(1, 0), b3); PG8_STAGEB(PG8_SB(1, 1), b3 + hstep); PG8_STAGEA(PG8_SA(1, 0), a3);
;             PG8_WAIT_V(8); PG8_WAIT_L(0); PG8_BAR; PG8_MMA(1, 0, At, B0); PG8_MMA(1, 1, At, B1); PG8_BAR; PG8_SCHED;
	s_add_i32 s69, s69, s83
	v_lshl_add_u64 v[154:155], v[154:155], 0, s[10:11]
	s_mov_b32 m0, s69
	ds_read_b128 v[192:195], v162 offset:49152
	ds_read_b128 v[196:199], v162 offset:50176
	ds_read_b128 v[200:203], v162 offset:51200
	ds_read_b128 v[204:207], v162 offset:52224
	ds_read_b128 v[208:211], v162 offset:53248
	ds_read_b128 v[212:215], v162 offset:54272
	ds_read_b128 v[216:219], v162 offset:55296
	ds_read_b128 v[220:223], v162 offset:56320
	global_load_lds_dwordx4 v[154:155], off
	s_add_i32 m0, s69, 0x2000
	s_add_u32 s76, s76, 0x40080
	v_lshl_add_u64 v[154:155], v[224:225], 0, s[10:11]
	s_addc_u32 s77, s77, 0
	s_add_i32 s69, s91, s83
	global_load_lds_dwordx4 v[154:155], off
	v_lshl_add_u64 v[154:155], s[76:77], 0, v[132:133]
	s_mov_b32 m0, s69
	s_nop 0
	global_load_lds_dwordx4 v[154:155], off
	v_lshl_add_u64 v[154:155], s[76:77], 0, v[136:137]
	s_add_i32 m0, s69, 0x2000
	s_nop 0
	global_load_lds_dwordx4 v[154:155], off
	v_lshl_add_u64 v[154:155], v[226:227], 0, s[10:11]
	s_mov_b32 m0, s86
	s_nop 0
	global_load_lds_dwordx4 v[154:155], off
	v_lshl_add_u64 v[154:155], v[228:229], 0, s[10:11]
	s_mov_b32 m0, s87
	s_nop 0
	global_load_lds_dwordx4 v[154:155], off
	s_waitcnt vmcnt(8)
	s_waitcnt lgkmcnt(0)
	s_barrier
	s_waitcnt lgkmcnt(0)
	v_mfma_f32_16x16x32_bf16 v[46:49], v[150:153], v[192:195], v[46:49]
	v_mfma_f32_16x16x32_bf16 v[38:41], v[150:153], v[200:203], v[38:41]
	v_mfma_f32_16x16x32_bf16 v[30:33], v[150:153], v[208:211], v[30:33]
	v_mfma_f32_16x16x32_bf16 v[22:25], v[150:153], v[216:219], v[22:25]
	v_mfma_f32_16x16x32_bf16 v[18:21], v[168:171], v[216:219], v[18:21]
	v_mfma_f32_16x16x32_bf16 v[26:29], v[168:171], v[208:211], v[26:29]
	v_mfma_f32_16x16x32_bf16 v[34:37], v[168:171], v[200:203], v[34:37]
	v_mfma_f32_16x16x32_bf16 v[42:45], v[168:171], v[192:195], v[42:45]
	v_mfma_f32_16x16x32_bf16 v[46:49], v[164:167], v[196:199], v[46:49]
	v_mfma_f32_16x16x32_bf16 v[38:41], v[164:167], v[204:207], v[38:41]
	v_mfma_f32_16x16x32_bf16 v[30:33], v[164:167], v[212:215], v[30:33]
	v_mfma_f32_16x16x32_bf16 v[22:25], v[164:167], v[220:223], v[22:25]
	v_mfma_f32_16x16x32_bf16 v[18:21], v[172:175], v[220:223], v[18:21]
	v_mfma_f32_16x16x32_bf16 v[26:29], v[172:175], v[212:215], v[26:29]
	v_mfma_f32_16x16x32_bf16 v[34:37], v[172:175], v[204:207], v[34:37]
	v_mfma_f32_16x16x32_bf16 v[42:45], v[172:175], v[196:199], v[42:45]
	v_mfma_f32_16x16x32_bf16 v[14:17], v[176:179], v[192:195], v[14:17]
	v_mfma_f32_16x16x32_bf16 v[6:9], v[176:179], v[200:203], v[6:9]
	v_mfma_f32_16x16x32_bf16 v[114:117], v[176:179], v[208:211], v[114:117]
	v_mfma_f32_16x16x32_bf16 v[122:125], v[176:179], v[216:219], v[122:125]
	v_mfma_f32_16x16x32_bf16 v[126:129], v[184:187], v[216:219], v[126:129]
	v_mfma_f32_16x16x32_bf16 v[118:121], v[184:187], v[208:211], v[118:121]
	v_mfma_f32_16x16x32_bf16 v[2:5], v[184:187], v[200:203], v[2:5]
	v_mfma_f32_16x16x32_bf16 v[10:13], v[184:187], v[192:195], v[10:13]
	v_mfma_f32_16x16x32_bf16 v[14:17], v[180:183], v[196:199], v[14:17]
	v_mfma_f32_16x16x32_bf16 v[6:9], v[180:183], v[204:207], v[6:9]
	v_mfma_f32_16x16x32_bf16 v[114:117], v[180:183], v[212:215], v[114:117]
	v_mfma_f32_16x16x32_bf16 v[122:125], v[180:183], v[220:223], v[122:125]
	v_mfma_f32_16x16x32_bf16 v[126:129], v[188:191], v[220:223], v[126:129]
	v_mfma_f32_16x16x32_bf16 v[118:121], v[188:191], v[212:215], v[118:121]
	v_mfma_f32_16x16x32_bf16 v[2:5], v[188:191], v[204:207], v[2:5]
	v_mfma_f32_16x16x32_bf16 v[10:13], v[188:191], v[196:199], v[10:13]
	s_barrier
	s_add_i32 s59, s59, 2
	s_add_u32 s74, s74, 0x100
	s_addc_u32 s75, s75, 0
	s_cmp_gt_u32 s59, 13
	s_cbranch_scc0 .LBB0_538
	s_branch .Lmy_kexit_2
.LBB0_538:
	v_add_u32_e32 v154, s88, v159
	ds_read_b128 v[150:153], v154
	ds_read_b128 v[164:167], v154 offset:1024
	ds_read_b128 v[168:171], v154 offset:2048
	ds_read_b128 v[172:175], v154 offset:3072
	v_add_u32_e32 v154, s89, v159
	s_add_u32 s69, s38, s74
	ds_read_b128 v[176:179], v154
	ds_read_b128 v[180:183], v154 offset:1024
	ds_read_b128 v[184:187], v154 offset:2048
	ds_read_b128 v[188:191], v154 offset:3072
	s_addc_u32 s76, s39, s75
	s_add_u32 s69, s69, 0x100
	s_addc_u32 s76, s76, 0
	s_add_u32 s91, s54, s74
	s_addc_u32 s77, s55, s75
	s_cmpk_eq_i32 s74, 0x700
	s_cselect_b32 s79, s56, s76
	s_cselect_b32 s78, s57, s69
	s_cselect_b32 s77, s41, s77
	s_cselect_b32 s76, s58, s91
	v_lshl_add_u64 v[154:155], v[146:147], 0, s[74:75]
	s_add_i32 m0, s15, 0xc000
	ds_read_b128 v[192:195], v162
	ds_read_b128 v[196:199], v162 offset:1024
	ds_read_b128 v[200:203], v162 offset:2048
	ds_read_b128 v[204:207], v162 offset:3072
	ds_read_b128 v[208:211], v162 offset:4096
	ds_read_b128 v[212:215], v162 offset:5120
	ds_read_b128 v[216:219], v162 offset:6144
	ds_read_b128 v[220:223], v162 offset:7168
	global_load_lds_dwordx4 v[154:155], off
	v_lshl_add_u64 v[154:155], v[148:149], 0, s[74:75]
	s_add_i32 m0, s15, 0xe000
	s_nop 0
	global_load_lds_dwordx4 v[154:155], off
	s_waitcnt vmcnt(8)
	s_waitcnt lgkmcnt(0)
	s_barrier
; #define PG8_STAGEA(bufoff, gbase) PG8_STAGE_(bufoff, gbase, voffA)
; #define PG8_STAGEB(bufoff, gbase) PG8_STAGE_(bufoff, gbase, voffB)
; #define PG8_LDA(dst, b, h) do { _Pragma("unroll") for (int m = 0; m < 4; ++m) _Pragma("unroll") for (int k = 0; k < 2; ++k) dst[m][k] = *(const LAS bf16x8*)(lds + PG8_SA(b, h) + aoff + m * 2048 + k * 1024); } while (0)
; #define PG8_LDB(dst, b, h) do { _Pragma("unroll") for (int n = 0; n < 2; ++n) _Pragma("unroll") for (int k = 0; k < 2; ++k) dst[n][k] = *(const LAS bf16x8*)(lds + PG8_SB(b, h) + boff + n * 2048 + k * 1024); } while (0)
; #define PG8_MMA(ai, bj, At, Bt_) do { __builtin_amdgcn_s_setprio(1); _Pragma("unroll") for (int m = 0; m < 4; ++m) _Pragma("unroll") for (int n = 0; n < 2; ++n) _Pragma("unroll") for (int k = 0; k < 2; ++k) \
;         acc[ai][bj][m][n] = __builtin_amdgcn_mfma_f32_16x16x32_bf16(Bt_[n][k], At[m][k], acc[ai][bj][m][n], 0, 0, 0); __builtin_amdgcn_s_setprio(0); } while (0)
; #define PG8_WAIT_V(n) asm volatile("s_waitcnt vmcnt(" #n ")" ::: "memory")
; #define PG8_WAIT_L(n) asm volatile("s_waitcnt lgkmcnt(" #n ")" ::: "memory")
; #define PG8_BAR __builtin_amdgcn_s_barrier()
; #define PG8_SCHED __builtin_amdgcn_sched_barrier(0)
; template <int EK, int SK = -1>
; __device__ __forceinline__ void gemm_phase(LAS unsigned char* lds, const bf16_t* A, const bf16_t* Bt, int nM, int N, int K, const EpiArgs& E) {
;     ...
;             PG8_LDB(B0, 0, 0); PG8_LDB(B1, 0, 1); PG8_SCHED; PG8_LDA(At, 0, 0); PG8_STAGEA(PG8_SA(1, 1), a1 + hstep);
;             PG8_WAIT_V(8); PG8_WAIT_L(0); PG8_BAR; PG8_MMA(0, 0, At, B0); PG8_MMA(0, 1, At, B1); PG8_BAR; PG8_SCHED;
;             PG8_LDA(At, 0, 1); PG8_STAGEB(PG8_SB(0, 0), b2); PG8_STAGEB(PG8_SB(0, 1), b2 + hstep); PG8_STAGEA(PG8_SA(0, 0), a2);
;             PG8_WAIT_V(8); PG8_WAIT_L(0); PG8_BAR; PG8_MMA(1, 0, At, B0); PG8_MMA(1, 1, At, B1); PG8_BAR; PG8_SCHED;
	s_waitcnt lgkmcnt(0)
	v_mfma_f32_16x16x32_bf16 v[110:113], v[150:153], v[192:195], v[110:113]
	v_mfma_f32_16x16x32_bf16 v[102:105], v[150:153], v[200:203], v[102:105]
	v_mfma_f32_16x16x32_bf16 v[94:97], v[150:153], v[208:211], v[94:97]
	v_mfma_f32_16x16x32_bf16 v[86:89], v[150:153], v[216:219], v[86:89]
	v_mfma_f32_16x16x32_bf16 v[82:85], v[168:171], v[216:219], v[82:85]
	v_mfma_f32_16x16x32_bf16 v[90:93], v[168:171], v[208:211], v[90:93]
	v_mfma_f32_16x16x32_bf16 v[98:101], v[168:171], v[200:203], v[98:101]
	v_mfma_f32_16x16x32_bf16 v[106:109], v[168:171], v[192:195], v[106:109]
	v_mfma_f32_16x16x32_bf16 v[110:113], v[164:167], v[196:199], v[110:113]
	v_mfma_f32_16x16x32_bf16 v[102:105], v[164:167], v[204:207], v[102:105]
	v_mfma_f32_16x16x32_bf16 v[94:97], v[164:167], v[212:215], v[94:97]
	v_mfma_f32_16x16x32_bf16 v[86:89], v[164:167], v[220:223], v[86:89]
	v_mfma_f32_16x16x32_bf16 v[82:85], v[172:175], v[220:223], v[82:85]
	v_mfma_f32_16x16x32_bf16 v[90:93], v[172:175], v[212:215], v[90:93]
	v_mfma_f32_16x16x32_bf16 v[98:101], v[172:175], v[204:207], v[98:101]
	v_mfma_f32_16x16x32_bf16 v[106:109], v[172:175], v[196:199], v[106:109]
	v_mfma_f32_16x16x32_bf16 v[78:81], v[176:179], v[192:195], v[78:81]
	v_mfma_f32_16x16x32_bf16 v[70:73], v[176:179], v[200:203], v[70:73]
	v_mfma_f32_16x16x32_bf16 v[62:65], v[176:179], v[208:211], v[62:65]
	v_mfma_f32_16x16x32_bf16 v[54:57], v[176:179], v[216:219], v[54:57]
	v_mfma_f32_16x16x32_bf16 v[50:53], v[184:187], v[216:219], v[50:53]
	v_mfma_f32_16x16x32_bf16 v[58:61], v[184:187], v[208:211], v[58:61]
	v_mfma_f32_16x16x32_bf16 v[66:69], v[184:187], v[200:203], v[66:69]
	v_mfma_f32_16x16x32_bf16 v[74:77], v[184:187], v[192:195], v[74:77]
	v_mfma_f32_16x16x32_bf16 v[78:81], v[180:183], v[196:199], v[78:81]
	v_mfma_f32_16x16x32_bf16 v[70:73], v[180:183], v[204:207], v[70:73]
	v_mfma_f32_16x16x32_bf16 v[62:65], v[180:183], v[212:215], v[62:65]
	v_mfma_f32_16x16x32_bf16 v[54:57], v[180:183], v[220:223], v[54:57]
	v_mfma_f32_16x16x32_bf16 v[50:53], v[188:191], v[220:223], v[50:53]
	v_mfma_f32_16x16x32_bf16 v[58:61], v[188:191], v[212:215], v[58:61]
	v_mfma_f32_16x16x32_bf16 v[66:69], v[188:191], v[204:207], v[66:69]
	v_mfma_f32_16x16x32_bf16 v[74:77], v[188:191], v[196:199], v[74:77]
	s_barrier
	s_add_i32 s69, s88, s83
	v_lshl_add_u64 v[154:155], s[76:77], 0, v[132:133]
	s_mov_b32 m0, s69
	ds_read_b128 v[192:195], v162 offset:16384
	ds_read_b128 v[196:199], v162 offset:17408
	ds_read_b128 v[200:203], v162 offset:18432
	ds_read_b128 v[204:207], v162 offset:19456
	ds_read_b128 v[208:211], v162 offset:20480
	ds_read_b128 v[212:215], v162 offset:21504
	ds_read_b128 v[216:219], v162 offset:22528
	ds_read_b128 v[220:223], v162 offset:23552
	global_load_lds_dwordx4 v[154:155], off
	s_add_i32 m0, s69, 0x2000
	s_add_u32 s92, s76, 0x40000
	v_lshl_add_u64 v[224:225], s[76:77], 0, v[136:137]
	s_addc_u32 s93, s77, 0
	s_add_i32 s69, s89, s83
	global_load_lds_dwordx4 v[224:225], off
	v_lshl_add_u64 v[226:227], s[92:93], 0, v[132:133]
	s_mov_b32 m0, s69
	v_lshl_add_u64 v[228:229], s[78:79], 0, v[134:135]
	global_load_lds_dwordx4 v[226:227], off
	v_lshl_add_u64 v[226:227], s[92:93], 0, v[136:137]
	s_add_i32 m0, s69, 0x2000
	s_nop 0
	global_load_lds_dwordx4 v[226:227], off
	v_lshl_add_u64 v[226:227], s[78:79], 0, v[130:131]
	s_mov_b32 m0, s15
	s_nop 0
	global_load_lds_dwordx4 v[226:227], off
	s_mov_b32 m0, s17
	s_nop 0
	global_load_lds_dwordx4 v[228:229], off
	s_waitcnt vmcnt(8)
	s_waitcnt lgkmcnt(0)
	s_barrier
	s_waitcnt lgkmcnt(0)
	v_mfma_f32_16x16x32_bf16 v[46:49], v[150:153], v[192:195], v[46:49]
	v_mfma_f32_16x16x32_bf16 v[38:41], v[150:153], v[200:203], v[38:41]
	v_mfma_f32_16x16x32_bf16 v[30:33], v[150:153], v[208:211], v[30:33]
	v_mfma_f32_16x16x32_bf16 v[22:25], v[150:153], v[216:219], v[22:25]
	v_mfma_f32_16x16x32_bf16 v[18:21], v[168:171], v[216:219], v[18:21]
	v_mfma_f32_16x16x32_bf16 v[26:29], v[168:171], v[208:211], v[26:29]
	v_mfma_f32_16x16x32_bf16 v[34:37], v[168:171], v[200:203], v[34:37]
	v_mfma_f32_16x16x32_bf16 v[42:45], v[168:171], v[192:195], v[42:45]
	v_mfma_f32_16x16x32_bf16 v[46:49], v[164:167], v[196:199], v[46:49]
	v_mfma_f32_16x16x32_bf16 v[38:41], v[164:167], v[204:207], v[38:41]
	v_mfma_f32_16x16x32_bf16 v[30:33], v[164:167], v[212:215], v[30:33]
	v_mfma_f32_16x16x32_bf16 v[22:25], v[164:167], v[220:223], v[22:25]
	v_mfma_f32_16x16x32_bf16 v[18:21], v[172:175], v[220:223], v[18:21]
	v_mfma_f32_16x16x32_bf16 v[26:29], v[172:175], v[212:215], v[26:29]
	v_mfma_f32_16x16x32_bf16 v[34:37], v[172:175], v[204:207], v[34:37]
	v_mfma_f32_16x16x32_bf16 v[42:45], v[172:175], v[196:199], v[42:45]
	v_mfma_f32_16x16x32_bf16 v[14:17], v[176:179], v[192:195], v[14:17]
	v_mfma_f32_16x16x32_bf16 v[6:9], v[176:179], v[200:203], v[6:9]
	v_mfma_f32_16x16x32_bf16 v[114:117], v[176:179], v[208:211], v[114:117]
	v_mfma_f32_16x16x32_bf16 v[122:125], v[176:179], v[216:219], v[122:125]
	v_mfma_f32_16x16x32_bf16 v[126:129], v[184:187], v[216:219], v[126:129]
	v_mfma_f32_16x16x32_bf16 v[118:121], v[184:187], v[208:211], v[118:121]
	v_mfma_f32_16x16x32_bf16 v[2:5], v[184:187], v[200:203], v[2:5]
	v_mfma_f32_16x16x32_bf16 v[10:13], v[184:187], v[192:195], v[10:13]
	v_mfma_f32_16x16x32_bf16 v[14:17], v[180:183], v[196:199], v[14:17]
	v_mfma_f32_16x16x32_bf16 v[6:9], v[180:183], v[204:207], v[6:9]
	v_mfma_f32_16x16x32_bf16 v[114:117], v[180:183], v[212:215], v[114:117]
	v_mfma_f32_16x16x32_bf16 v[122:125], v[180:183], v[220:223], v[122:125]
	v_mfma_f32_16x16x32_bf16 v[126:129], v[188:191], v[220:223], v[126:129]
	v_mfma_f32_16x16x32_bf16 v[118:121], v[188:191], v[212:215], v[118:121]
	v_mfma_f32_16x16x32_bf16 v[2:5], v[188:191], v[204:207], v[2:5]
	v_mfma_f32_16x16x32_bf16 v[10:13], v[188:191], v[196:199], v[10:13]
	s_barrier
; #define PG8_STAGEA(bufoff, gbase) PG8_STAGE_(bufoff, gbase, voffA)
; #define PG8_STAGEB(bufoff, gbase) PG8_STAGE_(bufoff, gbase, voffB)
; #define PG8_LDA(dst, b, h) do { _Pragma("unroll") for (int m = 0; m < 4; ++m) _Pragma("unroll") for (int k = 0; k < 2; ++k) dst[m][k] = *(const LAS bf16x8*)(lds + PG8_SA(b, h) + aoff + m * 2048 + k * 1024); } while (0)
; #define PG8_LDB(dst, b, h) do { _Pragma("unroll") for (int n = 0; n < 2; ++n) _Pragma("unroll") for (int k = 0; k < 2; ++k) dst[n][k] = *(const LAS bf16x8*)(lds + PG8_SB(b, h) + boff + n * 2048 + k * 1024); } while (0)
; #define PG8_MMA(ai, bj, At, Bt_) do { __builtin_amdgcn_s_setprio(1); _Pragma("unroll") for (int m = 0; m < 4; ++m) _Pragma("unroll") for (int n = 0; n < 2; ++n) _Pragma("unroll") for (int k = 0; k < 2; ++k) \
;         acc[ai][bj][m][n] = __builtin_amdgcn_mfma_f32_16x16x32_bf16(Bt_[n][k], At[m][k], acc[ai][bj][m][n], 0, 0, 0); __builtin_amdgcn_s_setprio(0); } while (0)
; #define PG8_WAIT_V(n) asm volatile("s_waitcnt vmcnt(" #n ")" ::: "memory")
; #define PG8_WAIT_L(n) asm volatile("s_waitcnt lgkmcnt(" #n ")" ::: "memory")
; #define PG8_BAR __builtin_amdgcn_s_barrier()
; #define PG8_SCHED __builtin_amdgcn_sched_barrier(0)
; template <int EK, int SK = -1>
; __device__ __forceinline__ void gemm_phase(LAS unsigned char* lds, const bf16_t* A, const bf16_t* Bt, int nM, int N, int K, const EpiArgs& E) {
;     ...
;         for (int t = 0; t < nt; t += 2) {
;     ...
;             PG8_LDB(B0, 1, 0); PG8_LDB(B1, 1, 1); PG8_SCHED; PG8_LDA(At, 1, 0); PG8_STAGEA(PG8_SA(0, 1), a2 + hstep);
;             PG8_WAIT_V(8); PG8_WAIT_L(0); PG8_BAR; PG8_MMA(0, 0, At, B0); PG8_MMA(0, 1, At, B1); PG8_BAR; PG8_SCHED;
;             PG8_LDA(At, 1, 1); PG8_STAGEB(PG8_SB(1, 0), b3); PG8_STAGEB(PG8_SB(1, 1), b3 + hstep); PG8_STAGEA(PG8_SA(1, 0), a3);
;             PG8_WAIT_V(8); PG8_WAIT_L(0); PG8_BAR; PG8_MMA(1, 0, At, B0); PG8_MMA(1, 1, At, B1); PG8_BAR; PG8_SCHED;
	s_add_i32 s69, 0, 0x18000
	v_add_u32_e32 v163, s69, v159
	s_add_i32 s91, 0, 0x1c000
	ds_read_b128 v[150:153], v163
	ds_read_b128 v[164:167], v163 offset:1024
	ds_read_b128 v[168:171], v163 offset:2048
	ds_read_b128 v[172:175], v163 offset:3072
	v_add_u32_e32 v163, s91, v159
	ds_read_b128 v[176:179], v163
	ds_read_b128 v[180:183], v163 offset:1024
	ds_read_b128 v[184:187], v163 offset:2048
	ds_read_b128 v[188:191], v163 offset:3072
	s_add_u32 s78, s78, 0x40000
	s_addc_u32 s79, s79, 0
	s_mov_b32 m0, s84
	v_lshl_add_u64 v[230:231], s[78:79], 0, v[130:131]
	ds_read_b128 v[192:195], v162 offset:32768
	ds_read_b128 v[196:199], v162 offset:33792
	ds_read_b128 v[200:203], v162 offset:34816
	ds_read_b128 v[204:207], v162 offset:35840
	ds_read_b128 v[208:211], v162 offset:36864
	ds_read_b128 v[212:215], v162 offset:37888
	ds_read_b128 v[216:219], v162 offset:38912
	ds_read_b128 v[220:223], v162 offset:39936
	global_load_lds_dwordx4 v[230:231], off
	v_lshl_add_u64 v[230:231], s[78:79], 0, v[134:135]
	s_mov_b32 m0, s85
	s_nop 0
	global_load_lds_dwordx4 v[230:231], off
	s_waitcnt vmcnt(8)
	s_waitcnt lgkmcnt(0)
	s_barrier
	s_waitcnt lgkmcnt(0)
	v_mfma_f32_16x16x32_bf16 v[110:113], v[150:153], v[192:195], v[110:113]
	v_mfma_f32_16x16x32_bf16 v[102:105], v[150:153], v[200:203], v[102:105]
	v_mfma_f32_16x16x32_bf16 v[94:97], v[150:153], v[208:211], v[94:97]
	v_mfma_f32_16x16x32_bf16 v[86:89], v[150:153], v[216:219], v[86:89]
	v_mfma_f32_16x16x32_bf16 v[82:85], v[168:171], v[216:219], v[82:85]
	v_mfma_f32_16x16x32_bf16 v[90:93], v[168:171], v[208:211], v[90:93]
	v_mfma_f32_16x16x32_bf16 v[98:101], v[168:171], v[200:203], v[98:101]
	v_mfma_f32_16x16x32_bf16 v[106:109], v[168:171], v[192:195], v[106:109]
	v_mfma_f32_16x16x32_bf16 v[110:113], v[164:167], v[196:199], v[110:113]
	v_mfma_f32_16x16x32_bf16 v[102:105], v[164:167], v[204:207], v[102:105]
	v_mfma_f32_16x16x32_bf16 v[94:97], v[164:167], v[212:215], v[94:97]
	v_mfma_f32_16x16x32_bf16 v[86:89], v[164:167], v[220:223], v[86:89]
	v_mfma_f32_16x16x32_bf16 v[82:85], v[172:175], v[220:223], v[82:85]
	v_mfma_f32_16x16x32_bf16 v[90:93], v[172:175], v[212:215], v[90:93]
	v_mfma_f32_16x16x32_bf16 v[98:101], v[172:175], v[204:207], v[98:101]
	v_mfma_f32_16x16x32_bf16 v[106:109], v[172:175], v[196:199], v[106:109]
	v_mfma_f32_16x16x32_bf16 v[78:81], v[176:179], v[192:195], v[78:81]
	v_mfma_f32_16x16x32_bf16 v[70:73], v[176:179], v[200:203], v[70:73]
	v_mfma_f32_16x16x32_bf16 v[62:65], v[176:179], v[208:211], v[62:65]
	v_mfma_f32_16x16x32_bf16 v[54:57], v[176:179], v[216:219], v[54:57]
	v_mfma_f32_16x16x32_bf16 v[50:53], v[184:187], v[216:219], v[50:53]
	v_mfma_f32_16x16x32_bf16 v[58:61], v[184:187], v[208:211], v[58:61]
	v_mfma_f32_16x16x32_bf16 v[66:69], v[184:187], v[200:203], v[66:69]
	v_mfma_f32_16x16x32_bf16 v[74:77], v[184:187], v[192:195], v[74:77]
	v_mfma_f32_16x16x32_bf16 v[78:81], v[180:183], v[196:199], v[78:81]
	v_mfma_f32_16x16x32_bf16 v[70:73], v[180:183], v[204:207], v[70:73]
	v_mfma_f32_16x16x32_bf16 v[62:65], v[180:183], v[212:215], v[62:65]
	v_mfma_f32_16x16x32_bf16 v[54:57], v[180:183], v[220:223], v[54:57]
	v_mfma_f32_16x16x32_bf16 v[50:53], v[188:191], v[220:223], v[50:53]
	v_mfma_f32_16x16x32_bf16 v[58:61], v[188:191], v[212:215], v[58:61]
	v_mfma_f32_16x16x32_bf16 v[66:69], v[188:191], v[204:207], v[66:69]
	v_mfma_f32_16x16x32_bf16 v[74:77], v[188:191], v[196:199], v[74:77]
	s_barrier
	s_add_i32 s69, s69, s83
	v_lshl_add_u64 v[154:155], v[154:155], 0, s[10:11]
	s_mov_b32 m0, s69
	ds_read_b128 v[192:195], v162 offset:49152
	ds_read_b128 v[196:199], v162 offset:50176
	ds_read_b128 v[200:203], v162 offset:51200
	ds_read_b128 v[204:207], v162 offset:52224
	ds_read_b128 v[208:211], v162 offset:53248
	ds_read_b128 v[212:215], v162 offset:54272
	ds_read_b128 v[216:219], v162 offset:55296
	ds_read_b128 v[220:223], v162 offset:56320
	global_load_lds_dwordx4 v[154:155], off
	s_add_i32 m0, s69, 0x2000
	s_add_u32 s76, s76, 0x40080
	v_lshl_add_u64 v[154:155], v[224:225], 0, s[10:11]
	s_addc_u32 s77, s77, 0
	s_add_i32 s69, s91, s83
	global_load_lds_dwordx4 v[154:155], off
	v_lshl_add_u64 v[154:155], s[76:77], 0, v[132:133]
	s_mov_b32 m0, s69
	s_nop 0
	global_load_lds_dwordx4 v[154:155], off
	v_lshl_add_u64 v[154:155], s[76:77], 0, v[136:137]
	s_add_i32 m0, s69, 0x2000
	s_nop 0
	global_load_lds_dwordx4 v[154:155], off
	v_lshl_add_u64 v[154:155], v[226:227], 0, s[10:11]
	s_mov_b32 m0, s86
	s_nop 0
	global_load_lds_dwordx4 v[154:155], off
	v_lshl_add_u64 v[154:155], v[228:229], 0, s[10:11]
	s_mov_b32 m0, s87
	s_nop 0
	global_load_lds_dwordx4 v[154:155], off
	s_waitcnt vmcnt(8)
	s_waitcnt lgkmcnt(0)
	s_barrier
	s_waitcnt lgkmcnt(0)
	v_mfma_f32_16x16x32_bf16 v[46:49], v[150:153], v[192:195], v[46:49]
	v_mfma_f32_16x16x32_bf16 v[38:41], v[150:153], v[200:203], v[38:41]
	v_mfma_f32_16x16x32_bf16 v[30:33], v[150:153], v[208:211], v[30:33]
	v_mfma_f32_16x16x32_bf16 v[22:25], v[150:153], v[216:219], v[22:25]
	v_mfma_f32_16x16x32_bf16 v[18:21], v[168:171], v[216:219], v[18:21]
	v_mfma_f32_16x16x32_bf16 v[26:29], v[168:171], v[208:211], v[26:29]
	v_mfma_f32_16x16x32_bf16 v[34:37], v[168:171], v[200:203], v[34:37]
	v_mfma_f32_16x16x32_bf16 v[42:45], v[168:171], v[192:195], v[42:45]
	v_mfma_f32_16x16x32_bf16 v[46:49], v[164:167], v[196:199], v[46:49]
	v_mfma_f32_16x16x32_bf16 v[38:41], v[164:167], v[204:207], v[38:41]
	v_mfma_f32_16x16x32_bf16 v[30:33], v[164:167], v[212:215], v[30:33]
	v_mfma_f32_16x16x32_bf16 v[22:25], v[164:167], v[220:223], v[22:25]
	v_mfma_f32_16x16x32_bf16 v[18:21], v[172:175], v[220:223], v[18:21]
	v_mfma_f32_16x16x32_bf16 v[26:29], v[172:175], v[212:215], v[26:29]
	v_mfma_f32_16x16x32_bf16 v[34:37], v[172:175], v[204:207], v[34:37]
	v_mfma_f32_16x16x32_bf16 v[42:45], v[172:175], v[196:199], v[42:45]
	v_mfma_f32_16x16x32_bf16 v[14:17], v[176:179], v[192:195], v[14:17]
	v_mfma_f32_16x16x32_bf16 v[6:9], v[176:179], v[200:203], v[6:9]
	v_mfma_f32_16x16x32_bf16 v[114:117], v[176:179], v[208:211], v[114:117]
	v_mfma_f32_16x16x32_bf16 v[122:125], v[176:179], v[216:219], v[122:125]
	v_mfma_f32_16x16x32_bf16 v[126:129], v[184:187], v[216:219], v[126:129]
	v_mfma_f32_16x16x32_bf16 v[118:121], v[184:187], v[208:211], v[118:121]
	v_mfma_f32_16x16x32_bf16 v[2:5], v[184:187], v[200:203], v[2:5]
	v_mfma_f32_16x16x32_bf16 v[10:13], v[184:187], v[192:195], v[10:13]
	v_mfma_f32_16x16x32_bf16 v[14:17], v[180:183], v[196:199], v[14:17]
	v_mfma_f32_16x16x32_bf16 v[6:9], v[180:183], v[204:207], v[6:9]
	v_mfma_f32_16x16x32_bf16 v[114:117], v[180:183], v[212:215], v[114:117]
	v_mfma_f32_16x16x32_bf16 v[122:125], v[180:183], v[220:223], v[122:125]
	v_mfma_f32_16x16x32_bf16 v[126:129], v[188:191], v[220:223], v[126:129]
	v_mfma_f32_16x16x32_bf16 v[118:121], v[188:191], v[212:215], v[118:121]
	v_mfma_f32_16x16x32_bf16 v[2:5], v[188:191], v[204:207], v[2:5]
	v_mfma_f32_16x16x32_bf16 v[10:13], v[188:191], v[196:199], v[10:13]
	s_barrier
	s_add_i32 s59, s59, 2
	s_add_u32 s74, s74, 0x100
	s_addc_u32 s75, s75, 0
	s_cmp_gt_u32 s59, 13
	s_cbranch_scc0 .LBB0_538

; #define PG8_STAGEA(bufoff, gbase) PG8_STAGE_(bufoff, gbase, voffA)
; #define PG8_STAGEB(bufoff, gbase) PG8_STAGE_(bufoff, gbase, voffB)
; #define PG8_LDA(dst, b, h) do { _Pragma("unroll") for (int m = 0; m < 4; ++m) _Pragma("unroll") for (int k = 0; k < 2; ++k) dst[m][k] = *(const LAS bf16x8*)(lds + PG8_SA(b, h) + aoff + m * 2048 + k * 1024); } while (0)
; #define PG8_LDB(dst, b, h) do { _Pragma("unroll") for (int n = 0; n < 2; ++n) _Pragma("unroll") for (int k = 0; k < 2; ++k) dst[n][k] = *(const LAS bf16x8*)(lds + PG8_SB(b, h) + boff + n * 2048 + k * 1024); } while (0)
; #define PG8_MMA(ai, bj, At, Bt_) do { __builtin_amdgcn_s_setprio(1); _Pragma("unroll") for (int m = 0; m < 4; ++m) _Pragma("unroll") for (int n = 0; n < 2; ++n) _Pragma("unroll") for (int k = 0; k < 2; ++k) \
;         acc[ai][bj][m][n] = __builtin_amdgcn_mfma_f32_16x16x32_bf16(Bt_[n][k], At[m][k], acc[ai][bj][m][n], 0, 0, 0); __builtin_amdgcn_s_setprio(0); } while (0)
; #define PG8_WAIT_V(n) asm volatile("s_waitcnt vmcnt(" #n ")" ::: "memory")
; #define PG8_WAIT_L(n) asm volatile("s_waitcnt lgkmcnt(" #n ")" ::: "memory")
; #define PG8_BAR __builtin_amdgcn_s_barrier()
; template <int EK, int SK = -1>
; __device__ __forceinline__ void gemm_phase(LAS unsigned char* lds, const bf16_t* A, const bf16_t* Bt, int nM, int N, int K, const EpiArgs& E) {
;     ...
;         const bool has_next = S.next(ui + 1, nxt);
;         const char* nA = has_next ? (const char*)A + (size_t)nxt.pm * tstep : cA; const char* nB = has_next ? (const char*)Bt + (size_t)nxt.pn * tstep : cB;
;         for (int t = 0; t < nt; t += 2) {
;             const bool last = (t == nt - 2);
;             const char* a1 = cA + (size_t)(t + 1) * kstep;
;             const char* a2 = last ? nA : cA + (size_t)(t + 2) * kstep; const char* b2 = last ? nB : cB + (size_t)(t + 2) * kstep;
;             const char* a3 = a2 + kstep; const char* b3 = b2 + kstep;
;             PG8_LDB(B0, 0, 0); PG8_LDB(B1, 0, 1); PG8_SCHED; PG8_LDA(At, 0, 0); PG8_STAGEA(PG8_SA(1, 1), a1 + hstep);
;             PG8_WAIT_V(8); PG8_WAIT_L(0); PG8_BAR; PG8_MMA(0, 0, At, B0); PG8_MMA(0, 1, At, B1); PG8_BAR; PG8_SCHED;
;             PG8_LDA(At, 0, 1); PG8_STAGEB(PG8_SB(0, 0), b2); PG8_STAGEB(PG8_SB(0, 1), b2 + hstep); PG8_STAGEA(PG8_SA(0, 0), a2);
;             PG8_WAIT_V(8); PG8_WAIT_L(0); PG8_BAR; PG8_MMA(1, 0, At, B0); PG8_MMA(1, 1, At, B1); PG8_BAR; PG8_SCHED;
.LBB0_792:
	s_add_u32 s77, s38, 0x100
	s_addc_u32 s78, s39, 0
	v_lshl_add_u64 v[146:147], s[14:15], 0, v[138:139]
	v_lshl_add_u64 v[148:149], s[14:15], 0, v[140:141]
	s_mov_b32 s20, -2
	s_mov_b64 s[38:39], 0
	v_add_u32_e32 v150, s71, v152
	ds_read_b128 v[156:159], v150
	ds_read_b128 v[160:163], v150 offset:1024
	ds_read_b128 v[164:167], v150 offset:2048
	ds_read_b128 v[168:171], v150 offset:3072
	v_add_u32_e32 v150, s72, v152
	s_add_u32 s40, s14, s38
	ds_read_b128 v[172:175], v150
	ds_read_b128 v[176:179], v150 offset:1024
	ds_read_b128 v[180:183], v150 offset:2048
	ds_read_b128 v[184:187], v150 offset:3072
	s_addc_u32 s41, s15, s39
	s_add_u32 s40, s40, 0x100
	s_addc_u32 s41, s41, 0
	s_add_u32 s79, s77, s38
	s_addc_u32 s80, s78, s39
	s_cmpk_eq_i32 s38, 0x1500
	s_cselect_b32 s43, s37, s41
	s_cselect_b32 s42, s36, s40
	s_cselect_b32 s41, s11, s80
	s_cselect_b32 s40, s10, s79
	v_lshl_add_u64 v[150:151], v[146:147], 0, s[38:39]
	s_add_i32 m0, s55, 0xc000
	ds_read_b128 v[188:191], v154
	ds_read_b128 v[192:195], v154 offset:1024
	ds_read_b128 v[196:199], v154 offset:2048
	ds_read_b128 v[200:203], v154 offset:3072
	ds_read_b128 v[204:207], v154 offset:4096
	ds_read_b128 v[208:211], v154 offset:5120
	ds_read_b128 v[212:215], v154 offset:6144
	ds_read_b128 v[216:219], v154 offset:7168
	global_load_lds_dwordx4 v[150:151], off
	v_lshl_add_u64 v[150:151], v[148:149], 0, s[38:39]
	s_add_i32 m0, s55, 0xe000
	s_nop 0
	global_load_lds_dwordx4 v[150:151], off
	s_waitcnt vmcnt(8)
	s_waitcnt lgkmcnt(0)
	s_barrier
	s_waitcnt lgkmcnt(0)
	v_mfma_f32_16x16x32_bf16 v[126:129], v[156:159], v[188:191], 0
	v_mfma_f32_16x16x32_bf16 v[118:121], v[156:159], v[196:199], 0
	v_mfma_f32_16x16x32_bf16 v[110:113], v[156:159], v[204:207], 0
	v_mfma_f32_16x16x32_bf16 v[102:105], v[156:159], v[212:215], 0
	v_mfma_f32_16x16x32_bf16 v[98:101], v[164:167], v[212:215], 0
	v_mfma_f32_16x16x32_bf16 v[106:109], v[164:167], v[204:207], 0
	v_mfma_f32_16x16x32_bf16 v[114:117], v[164:167], v[196:199], 0
	v_mfma_f32_16x16x32_bf16 v[122:125], v[164:167], v[188:191], 0
	v_mfma_f32_16x16x32_bf16 v[126:129], v[160:163], v[192:195], v[126:129]
	v_mfma_f32_16x16x32_bf16 v[118:121], v[160:163], v[200:203], v[118:121]
	v_mfma_f32_16x16x32_bf16 v[110:113], v[160:163], v[208:211], v[110:113]
	v_mfma_f32_16x16x32_bf16 v[102:105], v[160:163], v[216:219], v[102:105]
	v_mfma_f32_16x16x32_bf16 v[98:101], v[168:171], v[216:219], v[98:101]
	v_mfma_f32_16x16x32_bf16 v[106:109], v[168:171], v[208:211], v[106:109]
	v_mfma_f32_16x16x32_bf16 v[114:117], v[168:171], v[200:203], v[114:117]
	v_mfma_f32_16x16x32_bf16 v[122:125], v[168:171], v[192:195], v[122:125]
	v_mfma_f32_16x16x32_bf16 v[94:97], v[172:175], v[188:191], 0
	v_mfma_f32_16x16x32_bf16 v[86:89], v[172:175], v[196:199], 0
	v_mfma_f32_16x16x32_bf16 v[78:81], v[172:175], v[204:207], 0
	v_mfma_f32_16x16x32_bf16 v[70:73], v[172:175], v[212:215], 0
	v_mfma_f32_16x16x32_bf16 v[66:69], v[180:183], v[212:215], 0
	v_mfma_f32_16x16x32_bf16 v[74:77], v[180:183], v[204:207], 0
	v_mfma_f32_16x16x32_bf16 v[82:85], v[180:183], v[196:199], 0
	v_mfma_f32_16x16x32_bf16 v[90:93], v[180:183], v[188:191], 0
	v_mfma_f32_16x16x32_bf16 v[94:97], v[176:179], v[192:195], v[94:97]
	v_mfma_f32_16x16x32_bf16 v[86:89], v[176:179], v[200:203], v[86:89]
	v_mfma_f32_16x16x32_bf16 v[78:81], v[176:179], v[208:211], v[78:81]
	v_mfma_f32_16x16x32_bf16 v[70:73], v[176:179], v[216:219], v[70:73]
	v_mfma_f32_16x16x32_bf16 v[66:69], v[184:187], v[216:219], v[66:69]
	v_mfma_f32_16x16x32_bf16 v[74:77], v[184:187], v[208:211], v[74:77]
	v_mfma_f32_16x16x32_bf16 v[82:85], v[184:187], v[200:203], v[82:85]
	v_mfma_f32_16x16x32_bf16 v[90:93], v[184:187], v[192:195], v[90:93]
	s_barrier
	s_add_i32 s79, s71, s54
	v_lshl_add_u64 v[150:151], s[40:41], 0, v[132:133]
	s_mov_b32 m0, s79
	ds_read_b128 v[188:191], v154 offset:16384
	ds_read_b128 v[192:195], v154 offset:17408
	ds_read_b128 v[196:199], v154 offset:18432
	ds_read_b128 v[200:203], v154 offset:19456
	ds_read_b128 v[204:207], v154 offset:20480
	ds_read_b128 v[208:211], v154 offset:21504
	ds_read_b128 v[212:215], v154 offset:22528
	ds_read_b128 v[216:219], v154 offset:23552
	global_load_lds_dwordx4 v[150:151], off
	s_add_i32 m0, s79, 0x2000
	s_add_u32 s80, s40, 0xb0000
	v_lshl_add_u64 v[220:221], s[40:41], 0, v[136:137]
	s_addc_u32 s81, s41, 0
	s_add_i32 s79, s72, s54
	global_load_lds_dwordx4 v[220:221], off
	v_lshl_add_u64 v[222:223], s[80:81], 0, v[132:133]
	s_mov_b32 m0, s79
	v_lshl_add_u64 v[224:225], s[42:43], 0, v[134:135]
	global_load_lds_dwordx4 v[222:223], off
	v_lshl_add_u64 v[222:223], s[80:81], 0, v[136:137]
	s_add_i32 m0, s79, 0x2000
	s_nop 0
	global_load_lds_dwordx4 v[222:223], off
	v_lshl_add_u64 v[222:223], s[42:43], 0, v[130:131]
	s_mov_b32 m0, s55
	s_nop 0
	global_load_lds_dwordx4 v[222:223], off
	s_mov_b32 m0, s56
	s_nop 0
	global_load_lds_dwordx4 v[224:225], off
	s_waitcnt vmcnt(8)
	s_waitcnt lgkmcnt(0)
	s_barrier
; #define PG8_STAGEA(bufoff, gbase) PG8_STAGE_(bufoff, gbase, voffA)
; #define PG8_LDA(dst, b, h) do { _Pragma("unroll") for (int m = 0; m < 4; ++m) _Pragma("unroll") for (int k = 0; k < 2; ++k) dst[m][k] = *(const LAS bf16x8*)(lds + PG8_SA(b, h) + aoff + m * 2048 + k * 1024); } while (0)
; #define PG8_LDB(dst, b, h) do { _Pragma("unroll") for (int n = 0; n < 2; ++n) _Pragma("unroll") for (int k = 0; k < 2; ++k) dst[n][k] = *(const LAS bf16x8*)(lds + PG8_SB(b, h) + boff + n * 2048 + k * 1024); } while (0)
; #define PG8_MMA(ai, bj, At, Bt_) do { __builtin_amdgcn_s_setprio(1); _Pragma("unroll") for (int m = 0; m < 4; ++m) _Pragma("unroll") for (int n = 0; n < 2; ++n) _Pragma("unroll") for (int k = 0; k < 2; ++k) \
;         acc[ai][bj][m][n] = __builtin_amdgcn_mfma_f32_16x16x32_bf16(Bt_[n][k], At[m][k], acc[ai][bj][m][n], 0, 0, 0); __builtin_amdgcn_s_setprio(0); } while (0)
; #define PG8_WAIT_V(n) asm volatile("s_waitcnt vmcnt(" #n ")" ::: "memory")
; #define PG8_WAIT_L(n) asm volatile("s_waitcnt lgkmcnt(" #n ")" ::: "memory")
; #define PG8_BAR __builtin_amdgcn_s_barrier()
; #define PG8_SCHED __builtin_amdgcn_sched_barrier(0)
; template <int EK, int SK = -1>
; __device__ __forceinline__ void gemm_phase(LAS unsigned char* lds, const bf16_t* A, const bf16_t* Bt, int nM, int N, int K, const EpiArgs& E) {
;     ...
;             PG8_WAIT_V(8); PG8_WAIT_L(0); PG8_BAR; PG8_MMA(1, 0, At, B0); PG8_MMA(1, 1, At, B1); PG8_BAR; PG8_SCHED;
;             PG8_LDB(B0, 1, 0); PG8_LDB(B1, 1, 1); PG8_SCHED; PG8_LDA(At, 1, 0); PG8_STAGEA(PG8_SA(0, 1), a2 + hstep);
;             PG8_WAIT_V(8); PG8_WAIT_L(0); PG8_BAR; PG8_MMA(0, 0, At, B0); PG8_MMA(0, 1, At, B1); PG8_BAR; PG8_SCHED;
	s_waitcnt lgkmcnt(0)
	v_mfma_f32_16x16x32_bf16 v[62:65], v[156:159], v[188:191], 0
	v_mfma_f32_16x16x32_bf16 v[54:57], v[156:159], v[196:199], 0
	v_mfma_f32_16x16x32_bf16 v[46:49], v[156:159], v[204:207], 0
	v_mfma_f32_16x16x32_bf16 v[38:41], v[156:159], v[212:215], 0
	v_mfma_f32_16x16x32_bf16 v[34:37], v[164:167], v[212:215], 0
	v_mfma_f32_16x16x32_bf16 v[42:45], v[164:167], v[204:207], 0
	v_mfma_f32_16x16x32_bf16 v[50:53], v[164:167], v[196:199], 0
	v_mfma_f32_16x16x32_bf16 v[58:61], v[164:167], v[188:191], 0
	v_mfma_f32_16x16x32_bf16 v[62:65], v[160:163], v[192:195], v[62:65]
	v_mfma_f32_16x16x32_bf16 v[54:57], v[160:163], v[200:203], v[54:57]
	v_mfma_f32_16x16x32_bf16 v[46:49], v[160:163], v[208:211], v[46:49]
	v_mfma_f32_16x16x32_bf16 v[38:41], v[160:163], v[216:219], v[38:41]
	v_mfma_f32_16x16x32_bf16 v[34:37], v[168:171], v[216:219], v[34:37]
	v_mfma_f32_16x16x32_bf16 v[42:45], v[168:171], v[208:211], v[42:45]
	v_mfma_f32_16x16x32_bf16 v[50:53], v[168:171], v[200:203], v[50:53]
	v_mfma_f32_16x16x32_bf16 v[58:61], v[168:171], v[192:195], v[58:61]
	v_mfma_f32_16x16x32_bf16 v[30:33], v[172:175], v[188:191], 0
	v_mfma_f32_16x16x32_bf16 v[22:25], v[172:175], v[196:199], 0
	v_mfma_f32_16x16x32_bf16 v[14:17], v[172:175], v[204:207], 0
	v_mfma_f32_16x16x32_bf16 v[6:9], v[172:175], v[212:215], 0
	v_mfma_f32_16x16x32_bf16 v[2:5], v[180:183], v[212:215], 0
	v_mfma_f32_16x16x32_bf16 v[10:13], v[180:183], v[204:207], 0
	v_mfma_f32_16x16x32_bf16 v[18:21], v[180:183], v[196:199], 0
	v_mfma_f32_16x16x32_bf16 v[26:29], v[180:183], v[188:191], 0
	v_mfma_f32_16x16x32_bf16 v[30:33], v[176:179], v[192:195], v[30:33]
	v_mfma_f32_16x16x32_bf16 v[22:25], v[176:179], v[200:203], v[22:25]
	v_mfma_f32_16x16x32_bf16 v[14:17], v[176:179], v[208:211], v[14:17]
	v_mfma_f32_16x16x32_bf16 v[6:9], v[176:179], v[216:219], v[6:9]
	v_mfma_f32_16x16x32_bf16 v[2:5], v[184:187], v[216:219], v[2:5]
	v_mfma_f32_16x16x32_bf16 v[10:13], v[184:187], v[208:211], v[10:13]
	v_mfma_f32_16x16x32_bf16 v[18:21], v[184:187], v[200:203], v[18:21]
	v_mfma_f32_16x16x32_bf16 v[26:29], v[184:187], v[192:195], v[26:29]
	s_barrier
	s_add_i32 s79, 0, 0x18000
	s_add_i32 s80, 0, 0x1c000
	v_add_u32_e32 v168, s79, v152
	v_add_u32_e32 v184, s80, v152
	ds_read_b128 v[156:159], v168
	ds_read_b128 v[160:163], v168 offset:1024
	ds_read_b128 v[164:167], v168 offset:2048
	ds_read_b128 v[168:171], v168 offset:3072
	ds_read_b128 v[172:175], v184
	ds_read_b128 v[176:179], v184 offset:1024
	ds_read_b128 v[180:183], v184 offset:2048
	ds_read_b128 v[184:187], v184 offset:3072
	s_add_u32 s42, s42, 0xb0000
	s_addc_u32 s43, s43, 0
	s_mov_b32 m0, s57
	v_lshl_add_u64 v[226:227], s[42:43], 0, v[130:131]
	ds_read_b128 v[188:191], v154 offset:32768
	ds_read_b128 v[192:195], v154 offset:33792
	ds_read_b128 v[196:199], v154 offset:34816
	ds_read_b128 v[200:203], v154 offset:35840
	ds_read_b128 v[204:207], v154 offset:36864
	ds_read_b128 v[208:211], v154 offset:37888
	ds_read_b128 v[212:215], v154 offset:38912
	ds_read_b128 v[216:219], v154 offset:39936
	global_load_lds_dwordx4 v[226:227], off
	v_lshl_add_u64 v[226:227], s[42:43], 0, v[134:135]
	s_mov_b32 m0, s58
	s_nop 0
	global_load_lds_dwordx4 v[226:227], off
	s_waitcnt vmcnt(8)
	s_waitcnt lgkmcnt(0)
	s_barrier
	s_waitcnt lgkmcnt(0)
	v_mfma_f32_16x16x32_bf16 v[126:129], v[156:159], v[188:191], v[126:129]
	v_mfma_f32_16x16x32_bf16 v[118:121], v[156:159], v[196:199], v[118:121]
	v_mfma_f32_16x16x32_bf16 v[110:113], v[156:159], v[204:207], v[110:113]
	v_mfma_f32_16x16x32_bf16 v[102:105], v[156:159], v[212:215], v[102:105]
	v_mfma_f32_16x16x32_bf16 v[98:101], v[164:167], v[212:215], v[98:101]
	v_mfma_f32_16x16x32_bf16 v[106:109], v[164:167], v[204:207], v[106:109]
	v_mfma_f32_16x16x32_bf16 v[114:117], v[164:167], v[196:199], v[114:117]
	v_mfma_f32_16x16x32_bf16 v[122:125], v[164:167], v[188:191], v[122:125]
	v_mfma_f32_16x16x32_bf16 v[126:129], v[160:163], v[192:195], v[126:129]
	v_mfma_f32_16x16x32_bf16 v[118:121], v[160:163], v[200:203], v[118:121]
	v_mfma_f32_16x16x32_bf16 v[110:113], v[160:163], v[208:211], v[110:113]
	v_mfma_f32_16x16x32_bf16 v[102:105], v[160:163], v[216:219], v[102:105]
	v_mfma_f32_16x16x32_bf16 v[98:101], v[168:171], v[216:219], v[98:101]
	v_mfma_f32_16x16x32_bf16 v[106:109], v[168:171], v[208:211], v[106:109]
	v_mfma_f32_16x16x32_bf16 v[114:117], v[168:171], v[200:203], v[114:117]
	v_mfma_f32_16x16x32_bf16 v[122:125], v[168:171], v[192:195], v[122:125]
	v_mfma_f32_16x16x32_bf16 v[94:97], v[172:175], v[188:191], v[94:97]
	v_mfma_f32_16x16x32_bf16 v[86:89], v[172:175], v[196:199], v[86:89]
	v_mfma_f32_16x16x32_bf16 v[78:81], v[172:175], v[204:207], v[78:81]
	v_mfma_f32_16x16x32_bf16 v[70:73], v[172:175], v[212:215], v[70:73]
	v_mfma_f32_16x16x32_bf16 v[66:69], v[180:183], v[212:215], v[66:69]
	v_mfma_f32_16x16x32_bf16 v[74:77], v[180:183], v[204:207], v[74:77]
	v_mfma_f32_16x16x32_bf16 v[82:85], v[180:183], v[196:199], v[82:85]
	v_mfma_f32_16x16x32_bf16 v[90:93], v[180:183], v[188:191], v[90:93]
	v_mfma_f32_16x16x32_bf16 v[94:97], v[176:179], v[192:195], v[94:97]
	v_mfma_f32_16x16x32_bf16 v[86:89], v[176:179], v[200:203], v[86:89]
	v_mfma_f32_16x16x32_bf16 v[78:81], v[176:179], v[208:211], v[78:81]
	v_mfma_f32_16x16x32_bf16 v[70:73], v[176:179], v[216:219], v[70:73]
	v_mfma_f32_16x16x32_bf16 v[66:69], v[184:187], v[216:219], v[66:69]
	v_mfma_f32_16x16x32_bf16 v[74:77], v[184:187], v[208:211], v[74:77]
	v_mfma_f32_16x16x32_bf16 v[82:85], v[184:187], v[200:203], v[82:85]
	v_mfma_f32_16x16x32_bf16 v[90:93], v[184:187], v[192:195], v[90:93]
	s_barrier
; #define PG8_STAGEA(bufoff, gbase) PG8_STAGE_(bufoff, gbase, voffA)
; #define PG8_STAGEB(bufoff, gbase) PG8_STAGE_(bufoff, gbase, voffB)
; #define PG8_LDA(dst, b, h) do { _Pragma("unroll") for (int m = 0; m < 4; ++m) _Pragma("unroll") for (int k = 0; k < 2; ++k) dst[m][k] = *(const LAS bf16x8*)(lds + PG8_SA(b, h) + aoff + m * 2048 + k * 1024); } while (0)
; #define PG8_LDB(dst, b, h) do { _Pragma("unroll") for (int n = 0; n < 2; ++n) _Pragma("unroll") for (int k = 0; k < 2; ++k) dst[n][k] = *(const LAS bf16x8*)(lds + PG8_SB(b, h) + boff + n * 2048 + k * 1024); } while (0)
; #define PG8_MMA(ai, bj, At, Bt_) do { __builtin_amdgcn_s_setprio(1); _Pragma("unroll") for (int m = 0; m < 4; ++m) _Pragma("unroll") for (int n = 0; n < 2; ++n) _Pragma("unroll") for (int k = 0; k < 2; ++k) \
;         acc[ai][bj][m][n] = __builtin_amdgcn_mfma_f32_16x16x32_bf16(Bt_[n][k], At[m][k], acc[ai][bj][m][n], 0, 0, 0); __builtin_amdgcn_s_setprio(0); } while (0)
; #define PG8_WAIT_V(n) asm volatile("s_waitcnt vmcnt(" #n ")" ::: "memory")
; #define PG8_WAIT_L(n) asm volatile("s_waitcnt lgkmcnt(" #n ")" ::: "memory")
; #define PG8_BAR __builtin_amdgcn_s_barrier()
; #define PG8_SCHED __builtin_amdgcn_sched_barrier(0)
; template <int EK, int SK = -1>
; __device__ __forceinline__ void gemm_phase(LAS unsigned char* lds, const bf16_t* A, const bf16_t* Bt, int nM, int N, int K, const EpiArgs& E) {
;     ...
;         for (int t = 0; t < nt; t += 2) {
;             const bool last = (t == nt - 2);
;             const char* a1 = cA + (size_t)(t + 1) * kstep;
;             const char* a2 = last ? nA : cA + (size_t)(t + 2) * kstep; const char* b2 = last ? nB : cB + (size_t)(t + 2) * kstep;
;             const char* a3 = a2 + kstep; const char* b3 = b2 + kstep;
;             PG8_LDB(B0, 0, 0); PG8_LDB(B1, 0, 1); PG8_SCHED; PG8_LDA(At, 0, 0); PG8_STAGEA(PG8_SA(1, 1), a1 + hstep);
;     ...
;             PG8_LDA(At, 1, 1); PG8_STAGEB(PG8_SB(1, 0), b3); PG8_STAGEB(PG8_SB(1, 1), b3 + hstep); PG8_STAGEA(PG8_SA(1, 0), a3);
;             PG8_WAIT_V(8); PG8_WAIT_L(0); PG8_BAR; PG8_MMA(1, 0, At, B0); PG8_MMA(1, 1, At, B1); PG8_BAR; PG8_SCHED;
	s_add_i32 s42, s79, s54
	v_lshl_add_u64 v[150:151], v[150:151], 0, s[22:23]
	s_mov_b32 m0, s42
	ds_read_b128 v[188:191], v154 offset:49152
	ds_read_b128 v[192:195], v154 offset:50176
	ds_read_b128 v[196:199], v154 offset:51200
	ds_read_b128 v[200:203], v154 offset:52224
	ds_read_b128 v[204:207], v154 offset:53248
	ds_read_b128 v[208:211], v154 offset:54272
	ds_read_b128 v[212:215], v154 offset:55296
	ds_read_b128 v[216:219], v154 offset:56320
	global_load_lds_dwordx4 v[150:151], off
	s_add_i32 m0, s42, 0x2000
	s_add_u32 s40, s40, 0xb0080
	v_lshl_add_u64 v[150:151], v[220:221], 0, s[22:23]
	s_addc_u32 s41, s41, 0
	s_add_i32 s42, s80, s54
	global_load_lds_dwordx4 v[150:151], off
	v_lshl_add_u64 v[150:151], s[40:41], 0, v[132:133]
	s_mov_b32 m0, s42
	s_nop 0
	global_load_lds_dwordx4 v[150:151], off
	v_lshl_add_u64 v[150:151], s[40:41], 0, v[136:137]
	s_add_i32 m0, s42, 0x2000
	s_nop 0
	global_load_lds_dwordx4 v[150:151], off
	v_lshl_add_u64 v[150:151], v[222:223], 0, s[22:23]
	s_mov_b32 m0, s69
	s_nop 0
	global_load_lds_dwordx4 v[150:151], off
	v_lshl_add_u64 v[150:151], v[224:225], 0, s[22:23]
	s_mov_b32 m0, s70
	s_nop 0
	global_load_lds_dwordx4 v[150:151], off
	s_waitcnt vmcnt(8)
	s_waitcnt lgkmcnt(0)
	s_barrier
	s_waitcnt lgkmcnt(0)
	v_mfma_f32_16x16x32_bf16 v[62:65], v[156:159], v[188:191], v[62:65]
	v_mfma_f32_16x16x32_bf16 v[54:57], v[156:159], v[196:199], v[54:57]
	v_mfma_f32_16x16x32_bf16 v[46:49], v[156:159], v[204:207], v[46:49]
	v_mfma_f32_16x16x32_bf16 v[38:41], v[156:159], v[212:215], v[38:41]
	v_mfma_f32_16x16x32_bf16 v[34:37], v[164:167], v[212:215], v[34:37]
	v_mfma_f32_16x16x32_bf16 v[42:45], v[164:167], v[204:207], v[42:45]
	v_mfma_f32_16x16x32_bf16 v[50:53], v[164:167], v[196:199], v[50:53]
	v_mfma_f32_16x16x32_bf16 v[58:61], v[164:167], v[188:191], v[58:61]
	v_mfma_f32_16x16x32_bf16 v[62:65], v[160:163], v[192:195], v[62:65]
	v_mfma_f32_16x16x32_bf16 v[54:57], v[160:163], v[200:203], v[54:57]
	v_mfma_f32_16x16x32_bf16 v[46:49], v[160:163], v[208:211], v[46:49]
	v_mfma_f32_16x16x32_bf16 v[38:41], v[160:163], v[216:219], v[38:41]
	v_mfma_f32_16x16x32_bf16 v[34:37], v[168:171], v[216:219], v[34:37]
	v_mfma_f32_16x16x32_bf16 v[42:45], v[168:171], v[208:211], v[42:45]
	v_mfma_f32_16x16x32_bf16 v[50:53], v[168:171], v[200:203], v[50:53]
	v_mfma_f32_16x16x32_bf16 v[58:61], v[168:171], v[192:195], v[58:61]
	v_mfma_f32_16x16x32_bf16 v[30:33], v[172:175], v[188:191], v[30:33]
	v_mfma_f32_16x16x32_bf16 v[22:25], v[172:175], v[196:199], v[22:25]
	v_mfma_f32_16x16x32_bf16 v[14:17], v[172:175], v[204:207], v[14:17]
	v_mfma_f32_16x16x32_bf16 v[6:9], v[172:175], v[212:215], v[6:9]
	v_mfma_f32_16x16x32_bf16 v[2:5], v[180:183], v[212:215], v[2:5]
	v_mfma_f32_16x16x32_bf16 v[10:13], v[180:183], v[204:207], v[10:13]
	v_mfma_f32_16x16x32_bf16 v[18:21], v[180:183], v[196:199], v[18:21]
	v_mfma_f32_16x16x32_bf16 v[26:29], v[180:183], v[188:191], v[26:29]
	v_mfma_f32_16x16x32_bf16 v[30:33], v[176:179], v[192:195], v[30:33]
	v_mfma_f32_16x16x32_bf16 v[22:25], v[176:179], v[200:203], v[22:25]
	v_mfma_f32_16x16x32_bf16 v[14:17], v[176:179], v[208:211], v[14:17]
	v_mfma_f32_16x16x32_bf16 v[6:9], v[176:179], v[216:219], v[6:9]
	v_mfma_f32_16x16x32_bf16 v[2:5], v[184:187], v[216:219], v[2:5]
	v_mfma_f32_16x16x32_bf16 v[10:13], v[184:187], v[208:211], v[10:13]
	v_mfma_f32_16x16x32_bf16 v[18:21], v[184:187], v[200:203], v[18:21]
	v_mfma_f32_16x16x32_bf16 v[26:29], v[184:187], v[192:195], v[26:29]
	s_barrier
	s_add_i32 s20, s20, 2
	s_add_u32 s38, s38, 0x100
	s_addc_u32 s39, s39, 0
	s_cmp_gt_u32 s20, 41
	s_cbranch_scc0 .LBB0_793
	s_branch .Lmy_kexit_3
.LBB0_793:
	v_add_u32_e32 v150, s71, v152
	ds_read_b128 v[156:159], v150
	ds_read_b128 v[160:163], v150 offset:1024
	ds_read_b128 v[164:167], v150 offset:2048
	ds_read_b128 v[168:171], v150 offset:3072
	v_add_u32_e32 v150, s72, v152
	s_add_u32 s40, s14, s38
	ds_read_b128 v[172:175], v150
	ds_read_b128 v[176:179], v150 offset:1024
	ds_read_b128 v[180:183], v150 offset:2048
	ds_read_b128 v[184:187], v150 offset:3072
	s_addc_u32 s41, s15, s39
	s_add_u32 s40, s40, 0x100
	s_addc_u32 s41, s41, 0
	s_add_u32 s79, s77, s38
	s_addc_u32 s80, s78, s39
	s_cmpk_eq_i32 s38, 0x1500
	s_cselect_b32 s43, s37, s41
	s_cselect_b32 s42, s36, s40
	s_cselect_b32 s41, s11, s80
	s_cselect_b32 s40, s10, s79
	v_lshl_add_u64 v[150:151], v[146:147], 0, s[38:39]
	s_add_i32 m0, s55, 0xc000
	ds_read_b128 v[188:191], v154
	ds_read_b128 v[192:195], v154 offset:1024
	ds_read_b128 v[196:199], v154 offset:2048
	ds_read_b128 v[200:203], v154 offset:3072
	ds_read_b128 v[204:207], v154 offset:4096
	ds_read_b128 v[208:211], v154 offset:5120
	ds_read_b128 v[212:215], v154 offset:6144
	ds_read_b128 v[216:219], v154 offset:7168
	global_load_lds_dwordx4 v[150:151], off
	v_lshl_add_u64 v[150:151], v[148:149], 0, s[38:39]
	s_add_i32 m0, s55, 0xe000
	s_nop 0
	global_load_lds_dwordx4 v[150:151], off
	s_waitcnt vmcnt(8)
	s_waitcnt lgkmcnt(0)
	s_barrier
; #define PG8_STAGEA(bufoff, gbase) PG8_STAGE_(bufoff, gbase, voffA)
; #define PG8_STAGEB(bufoff, gbase) PG8_STAGE_(bufoff, gbase, voffB)
; #define PG8_LDA(dst, b, h) do { _Pragma("unroll") for (int m = 0; m < 4; ++m) _Pragma("unroll") for (int k = 0; k < 2; ++k) dst[m][k] = *(const LAS bf16x8*)(lds + PG8_SA(b, h) + aoff + m * 2048 + k * 1024); } while (0)
; #define PG8_LDB(dst, b, h) do { _Pragma("unroll") for (int n = 0; n < 2; ++n) _Pragma("unroll") for (int k = 0; k < 2; ++k) dst[n][k] = *(const LAS bf16x8*)(lds + PG8_SB(b, h) + boff + n * 2048 + k * 1024); } while (0)
; #define PG8_MMA(ai, bj, At, Bt_) do { __builtin_amdgcn_s_setprio(1); _Pragma("unroll") for (int m = 0; m < 4; ++m) _Pragma("unroll") for (int n = 0; n < 2; ++n) _Pragma("unroll") for (int k = 0; k < 2; ++k) \
;         acc[ai][bj][m][n] = __builtin_amdgcn_mfma_f32_16x16x32_bf16(Bt_[n][k], At[m][k], acc[ai][bj][m][n], 0, 0, 0); __builtin_amdgcn_s_setprio(0); } while (0)
; #define PG8_WAIT_V(n) asm volatile("s_waitcnt vmcnt(" #n ")" ::: "memory")
; #define PG8_WAIT_L(n) asm volatile("s_waitcnt lgkmcnt(" #n ")" ::: "memory")
; #define PG8_BAR __builtin_amdgcn_s_barrier()
; #define PG8_SCHED __builtin_amdgcn_sched_barrier(0)
; template <int EK, int SK = -1>
; __device__ __forceinline__ void gemm_phase(LAS unsigned char* lds, const bf16_t* A, const bf16_t* Bt, int nM, int N, int K, const EpiArgs& E) {
;     ...
;             PG8_LDB(B0, 0, 0); PG8_LDB(B1, 0, 1); PG8_SCHED; PG8_LDA(At, 0, 0); PG8_STAGEA(PG8_SA(1, 1), a1 + hstep);
;             PG8_WAIT_V(8); PG8_WAIT_L(0); PG8_BAR; PG8_MMA(0, 0, At, B0); PG8_MMA(0, 1, At, B1); PG8_BAR; PG8_SCHED;
;             PG8_LDA(At, 0, 1); PG8_STAGEB(PG8_SB(0, 0), b2); PG8_STAGEB(PG8_SB(0, 1), b2 + hstep); PG8_STAGEA(PG8_SA(0, 0), a2);
;             PG8_WAIT_V(8); PG8_WAIT_L(0); PG8_BAR; PG8_MMA(1, 0, At, B0); PG8_MMA(1, 1, At, B1); PG8_BAR; PG8_SCHED;
	s_waitcnt lgkmcnt(0)
	v_mfma_f32_16x16x32_bf16 v[126:129], v[156:159], v[188:191], v[126:129]
	v_mfma_f32_16x16x32_bf16 v[118:121], v[156:159], v[196:199], v[118:121]
	v_mfma_f32_16x16x32_bf16 v[110:113], v[156:159], v[204:207], v[110:113]
	v_mfma_f32_16x16x32_bf16 v[102:105], v[156:159], v[212:215], v[102:105]
	v_mfma_f32_16x16x32_bf16 v[98:101], v[164:167], v[212:215], v[98:101]
	v_mfma_f32_16x16x32_bf16 v[106:109], v[164:167], v[204:207], v[106:109]
	v_mfma_f32_16x16x32_bf16 v[114:117], v[164:167], v[196:199], v[114:117]
	v_mfma_f32_16x16x32_bf16 v[122:125], v[164:167], v[188:191], v[122:125]
	v_mfma_f32_16x16x32_bf16 v[126:129], v[160:163], v[192:195], v[126:129]
	v_mfma_f32_16x16x32_bf16 v[118:121], v[160:163], v[200:203], v[118:121]
	v_mfma_f32_16x16x32_bf16 v[110:113], v[160:163], v[208:211], v[110:113]
	v_mfma_f32_16x16x32_bf16 v[102:105], v[160:163], v[216:219], v[102:105]
	v_mfma_f32_16x16x32_bf16 v[98:101], v[168:171], v[216:219], v[98:101]
	v_mfma_f32_16x16x32_bf16 v[106:109], v[168:171], v[208:211], v[106:109]
	v_mfma_f32_16x16x32_bf16 v[114:117], v[168:171], v[200:203], v[114:117]
	v_mfma_f32_16x16x32_bf16 v[122:125], v[168:171], v[192:195], v[122:125]
	v_mfma_f32_16x16x32_bf16 v[94:97], v[172:175], v[188:191], v[94:97]
	v_mfma_f32_16x16x32_bf16 v[86:89], v[172:175], v[196:199], v[86:89]
	v_mfma_f32_16x16x32_bf16 v[78:81], v[172:175], v[204:207], v[78:81]
	v_mfma_f32_16x16x32_bf16 v[70:73], v[172:175], v[212:215], v[70:73]
	v_mfma_f32_16x16x32_bf16 v[66:69], v[180:183], v[212:215], v[66:69]
	v_mfma_f32_16x16x32_bf16 v[74:77], v[180:183], v[204:207], v[74:77]
	v_mfma_f32_16x16x32_bf16 v[82:85], v[180:183], v[196:199], v[82:85]
	v_mfma_f32_16x16x32_bf16 v[90:93], v[180:183], v[188:191], v[90:93]
	v_mfma_f32_16x16x32_bf16 v[94:97], v[176:179], v[192:195], v[94:97]
	v_mfma_f32_16x16x32_bf16 v[86:89], v[176:179], v[200:203], v[86:89]
	v_mfma_f32_16x16x32_bf16 v[78:81], v[176:179], v[208:211], v[78:81]
	v_mfma_f32_16x16x32_bf16 v[70:73], v[176:179], v[216:219], v[70:73]
	v_mfma_f32_16x16x32_bf16 v[66:69], v[184:187], v[216:219], v[66:69]
	v_mfma_f32_16x16x32_bf16 v[74:77], v[184:187], v[208:211], v[74:77]
	v_mfma_f32_16x16x32_bf16 v[82:85], v[184:187], v[200:203], v[82:85]
	v_mfma_f32_16x16x32_bf16 v[90:93], v[184:187], v[192:195], v[90:93]
	s_barrier
	s_add_i32 s79, s71, s54
	v_lshl_add_u64 v[150:151], s[40:41], 0, v[132:133]
	s_mov_b32 m0, s79
	ds_read_b128 v[188:191], v154 offset:16384
	ds_read_b128 v[192:195], v154 offset:17408
	ds_read_b128 v[196:199], v154 offset:18432
	ds_read_b128 v[200:203], v154 offset:19456
	ds_read_b128 v[204:207], v154 offset:20480
	ds_read_b128 v[208:211], v154 offset:21504
	ds_read_b128 v[212:215], v154 offset:22528
	ds_read_b128 v[216:219], v154 offset:23552
	global_load_lds_dwordx4 v[150:151], off
	s_add_i32 m0, s79, 0x2000
	s_add_u32 s80, s40, 0xb0000
	v_lshl_add_u64 v[220:221], s[40:41], 0, v[136:137]
	s_addc_u32 s81, s41, 0
	s_add_i32 s79, s72, s54
	global_load_lds_dwordx4 v[220:221], off
	v_lshl_add_u64 v[222:223], s[80:81], 0, v[132:133]
	s_mov_b32 m0, s79
	v_lshl_add_u64 v[224:225], s[42:43], 0, v[134:135]
	global_load_lds_dwordx4 v[222:223], off
	v_lshl_add_u64 v[222:223], s[80:81], 0, v[136:137]
	s_add_i32 m0, s79, 0x2000
	s_nop 0
	global_load_lds_dwordx4 v[222:223], off
	v_lshl_add_u64 v[222:223], s[42:43], 0, v[130:131]
	s_mov_b32 m0, s55
	s_nop 0
	global_load_lds_dwordx4 v[222:223], off
	s_mov_b32 m0, s56
	s_nop 0
	global_load_lds_dwordx4 v[224:225], off
	s_waitcnt vmcnt(8)
	s_waitcnt lgkmcnt(0)
	s_barrier
	s_waitcnt lgkmcnt(0)
	v_mfma_f32_16x16x32_bf16 v[62:65], v[156:159], v[188:191], v[62:65]
	v_mfma_f32_16x16x32_bf16 v[54:57], v[156:159], v[196:199], v[54:57]
	v_mfma_f32_16x16x32_bf16 v[46:49], v[156:159], v[204:207], v[46:49]
	v_mfma_f32_16x16x32_bf16 v[38:41], v[156:159], v[212:215], v[38:41]
	v_mfma_f32_16x16x32_bf16 v[34:37], v[164:167], v[212:215], v[34:37]
	v_mfma_f32_16x16x32_bf16 v[42:45], v[164:167], v[204:207], v[42:45]
	v_mfma_f32_16x16x32_bf16 v[50:53], v[164:167], v[196:199], v[50:53]
	v_mfma_f32_16x16x32_bf16 v[58:61], v[164:167], v[188:191], v[58:61]
	v_mfma_f32_16x16x32_bf16 v[62:65], v[160:163], v[192:195], v[62:65]
	v_mfma_f32_16x16x32_bf16 v[54:57], v[160:163], v[200:203], v[54:57]
	v_mfma_f32_16x16x32_bf16 v[46:49], v[160:163], v[208:211], v[46:49]
	v_mfma_f32_16x16x32_bf16 v[38:41], v[160:163], v[216:219], v[38:41]
	v_mfma_f32_16x16x32_bf16 v[34:37], v[168:171], v[216:219], v[34:37]
	v_mfma_f32_16x16x32_bf16 v[42:45], v[168:171], v[208:211], v[42:45]
	v_mfma_f32_16x16x32_bf16 v[50:53], v[168:171], v[200:203], v[50:53]
	v_mfma_f32_16x16x32_bf16 v[58:61], v[168:171], v[192:195], v[58:61]
	v_mfma_f32_16x16x32_bf16 v[30:33], v[172:175], v[188:191], v[30:33]
	v_mfma_f32_16x16x32_bf16 v[22:25], v[172:175], v[196:199], v[22:25]
	v_mfma_f32_16x16x32_bf16 v[14:17], v[172:175], v[204:207], v[14:17]
	v_mfma_f32_16x16x32_bf16 v[6:9], v[172:175], v[212:215], v[6:9]
	v_mfma_f32_16x16x32_bf16 v[2:5], v[180:183], v[212:215], v[2:5]
	v_mfma_f32_16x16x32_bf16 v[10:13], v[180:183], v[204:207], v[10:13]
	v_mfma_f32_16x16x32_bf16 v[18:21], v[180:183], v[196:199], v[18:21]
	v_mfma_f32_16x16x32_bf16 v[26:29], v[180:183], v[188:191], v[26:29]
	v_mfma_f32_16x16x32_bf16 v[30:33], v[176:179], v[192:195], v[30:33]
	v_mfma_f32_16x16x32_bf16 v[22:25], v[176:179], v[200:203], v[22:25]
	v_mfma_f32_16x16x32_bf16 v[14:17], v[176:179], v[208:211], v[14:17]
	v_mfma_f32_16x16x32_bf16 v[6:9], v[176:179], v[216:219], v[6:9]
	v_mfma_f32_16x16x32_bf16 v[2:5], v[184:187], v[216:219], v[2:5]
	v_mfma_f32_16x16x32_bf16 v[10:13], v[184:187], v[208:211], v[10:13]
	v_mfma_f32_16x16x32_bf16 v[18:21], v[184:187], v[200:203], v[18:21]
	v_mfma_f32_16x16x32_bf16 v[26:29], v[184:187], v[192:195], v[26:29]
	s_barrier
; #define PG8_STAGEA(bufoff, gbase) PG8_STAGE_(bufoff, gbase, voffA)
; #define PG8_STAGEB(bufoff, gbase) PG8_STAGE_(bufoff, gbase, voffB)
; #define PG8_LDA(dst, b, h) do { _Pragma("unroll") for (int m = 0; m < 4; ++m) _Pragma("unroll") for (int k = 0; k < 2; ++k) dst[m][k] = *(const LAS bf16x8*)(lds + PG8_SA(b, h) + aoff + m * 2048 + k * 1024); } while (0)
; #define PG8_LDB(dst, b, h) do { _Pragma("unroll") for (int n = 0; n < 2; ++n) _Pragma("unroll") for (int k = 0; k < 2; ++k) dst[n][k] = *(const LAS bf16x8*)(lds + PG8_SB(b, h) + boff + n * 2048 + k * 1024); } while (0)
; #define PG8_MMA(ai, bj, At, Bt_) do { __builtin_amdgcn_s_setprio(1); _Pragma("unroll") for (int m = 0; m < 4; ++m) _Pragma("unroll") for (int n = 0; n < 2; ++n) _Pragma("unroll") for (int k = 0; k < 2; ++k) \
;         acc[ai][bj][m][n] = __builtin_amdgcn_mfma_f32_16x16x32_bf16(Bt_[n][k], At[m][k], acc[ai][bj][m][n], 0, 0, 0); __builtin_amdgcn_s_setprio(0); } while (0)
; #define PG8_WAIT_V(n) asm volatile("s_waitcnt vmcnt(" #n ")" ::: "memory")
; #define PG8_WAIT_L(n) asm volatile("s_waitcnt lgkmcnt(" #n ")" ::: "memory")
; #define PG8_BAR __builtin_amdgcn_s_barrier()
; #define PG8_SCHED __builtin_amdgcn_sched_barrier(0)
; template <int EK, int SK = -1>
; __device__ __forceinline__ void gemm_phase(LAS unsigned char* lds, const bf16_t* A, const bf16_t* Bt, int nM, int N, int K, const EpiArgs& E) {
;     ...
;         for (int t = 0; t < nt; t += 2) {
;     ...
;             PG8_LDB(B0, 1, 0); PG8_LDB(B1, 1, 1); PG8_SCHED; PG8_LDA(At, 1, 0); PG8_STAGEA(PG8_SA(0, 1), a2 + hstep);
;             PG8_WAIT_V(8); PG8_WAIT_L(0); PG8_BAR; PG8_MMA(0, 0, At, B0); PG8_MMA(0, 1, At, B1); PG8_BAR; PG8_SCHED;
;             PG8_LDA(At, 1, 1); PG8_STAGEB(PG8_SB(1, 0), b3); PG8_STAGEB(PG8_SB(1, 1), b3 + hstep); PG8_STAGEA(PG8_SA(1, 0), a3);
;             PG8_WAIT_V(8); PG8_WAIT_L(0); PG8_BAR; PG8_MMA(1, 0, At, B0); PG8_MMA(1, 1, At, B1); PG8_BAR; PG8_SCHED;
	s_add_i32 s79, 0, 0x18000
	s_add_i32 s80, 0, 0x1c000
	v_add_u32_e32 v168, s79, v152
	v_add_u32_e32 v184, s80, v152
	ds_read_b128 v[156:159], v168
	ds_read_b128 v[160:163], v168 offset:1024
	ds_read_b128 v[164:167], v168 offset:2048
	ds_read_b128 v[168:171], v168 offset:3072
	ds_read_b128 v[172:175], v184
	ds_read_b128 v[176:179], v184 offset:1024
	ds_read_b128 v[180:183], v184 offset:2048
	ds_read_b128 v[184:187], v184 offset:3072
	s_add_u32 s42, s42, 0xb0000
	s_addc_u32 s43, s43, 0
	s_mov_b32 m0, s57
	v_lshl_add_u64 v[226:227], s[42:43], 0, v[130:131]
	ds_read_b128 v[188:191], v154 offset:32768
	ds_read_b128 v[192:195], v154 offset:33792
	ds_read_b128 v[196:199], v154 offset:34816
	ds_read_b128 v[200:203], v154 offset:35840
	ds_read_b128 v[204:207], v154 offset:36864
	ds_read_b128 v[208:211], v154 offset:37888
	ds_read_b128 v[212:215], v154 offset:38912
	ds_read_b128 v[216:219], v154 offset:39936
	global_load_lds_dwordx4 v[226:227], off
	v_lshl_add_u64 v[226:227], s[42:43], 0, v[134:135]
	s_mov_b32 m0, s58
	s_nop 0
	global_load_lds_dwordx4 v[226:227], off
	s_waitcnt vmcnt(8)
	s_waitcnt lgkmcnt(0)
	s_barrier
	s_waitcnt lgkmcnt(0)
	v_mfma_f32_16x16x32_bf16 v[126:129], v[156:159], v[188:191], v[126:129]
	v_mfma_f32_16x16x32_bf16 v[118:121], v[156:159], v[196:199], v[118:121]
	v_mfma_f32_16x16x32_bf16 v[110:113], v[156:159], v[204:207], v[110:113]
	v_mfma_f32_16x16x32_bf16 v[102:105], v[156:159], v[212:215], v[102:105]
	v_mfma_f32_16x16x32_bf16 v[98:101], v[164:167], v[212:215], v[98:101]
	v_mfma_f32_16x16x32_bf16 v[106:109], v[164:167], v[204:207], v[106:109]
	v_mfma_f32_16x16x32_bf16 v[114:117], v[164:167], v[196:199], v[114:117]
	v_mfma_f32_16x16x32_bf16 v[122:125], v[164:167], v[188:191], v[122:125]
	v_mfma_f32_16x16x32_bf16 v[126:129], v[160:163], v[192:195], v[126:129]
	v_mfma_f32_16x16x32_bf16 v[118:121], v[160:163], v[200:203], v[118:121]
	v_mfma_f32_16x16x32_bf16 v[110:113], v[160:163], v[208:211], v[110:113]
	v_mfma_f32_16x16x32_bf16 v[102:105], v[160:163], v[216:219], v[102:105]
	v_mfma_f32_16x16x32_bf16 v[98:101], v[168:171], v[216:219], v[98:101]
	v_mfma_f32_16x16x32_bf16 v[106:109], v[168:171], v[208:211], v[106:109]
	v_mfma_f32_16x16x32_bf16 v[114:117], v[168:171], v[200:203], v[114:117]
	v_mfma_f32_16x16x32_bf16 v[122:125], v[168:171], v[192:195], v[122:125]
	v_mfma_f32_16x16x32_bf16 v[94:97], v[172:175], v[188:191], v[94:97]
	v_mfma_f32_16x16x32_bf16 v[86:89], v[172:175], v[196:199], v[86:89]
	v_mfma_f32_16x16x32_bf16 v[78:81], v[172:175], v[204:207], v[78:81]
	v_mfma_f32_16x16x32_bf16 v[70:73], v[172:175], v[212:215], v[70:73]
	v_mfma_f32_16x16x32_bf16 v[66:69], v[180:183], v[212:215], v[66:69]
	v_mfma_f32_16x16x32_bf16 v[74:77], v[180:183], v[204:207], v[74:77]
	v_mfma_f32_16x16x32_bf16 v[82:85], v[180:183], v[196:199], v[82:85]
	v_mfma_f32_16x16x32_bf16 v[90:93], v[180:183], v[188:191], v[90:93]
	v_mfma_f32_16x16x32_bf16 v[94:97], v[176:179], v[192:195], v[94:97]
	v_mfma_f32_16x16x32_bf16 v[86:89], v[176:179], v[200:203], v[86:89]
	v_mfma_f32_16x16x32_bf16 v[78:81], v[176:179], v[208:211], v[78:81]
	v_mfma_f32_16x16x32_bf16 v[70:73], v[176:179], v[216:219], v[70:73]
	v_mfma_f32_16x16x32_bf16 v[66:69], v[184:187], v[216:219], v[66:69]
	v_mfma_f32_16x16x32_bf16 v[74:77], v[184:187], v[208:211], v[74:77]
	v_mfma_f32_16x16x32_bf16 v[82:85], v[184:187], v[200:203], v[82:85]
	v_mfma_f32_16x16x32_bf16 v[90:93], v[184:187], v[192:195], v[90:93]
	s_barrier
	s_add_i32 s42, s79, s54
	v_lshl_add_u64 v[150:151], v[150:151], 0, s[22:23]
	s_mov_b32 m0, s42
	ds_read_b128 v[188:191], v154 offset:49152
	ds_read_b128 v[192:195], v154 offset:50176
	ds_read_b128 v[196:199], v154 offset:51200
	ds_read_b128 v[200:203], v154 offset:52224
	ds_read_b128 v[204:207], v154 offset:53248
	ds_read_b128 v[208:211], v154 offset:54272
	ds_read_b128 v[212:215], v154 offset:55296
	ds_read_b128 v[216:219], v154 offset:56320
	global_load_lds_dwordx4 v[150:151], off
	s_add_i32 m0, s42, 0x2000
	s_add_u32 s40, s40, 0xb0080
	v_lshl_add_u64 v[150:151], v[220:221], 0, s[22:23]
	s_addc_u32 s41, s41, 0
	s_add_i32 s42, s80, s54
	global_load_lds_dwordx4 v[150:151], off
	v_lshl_add_u64 v[150:151], s[40:41], 0, v[132:133]
	s_mov_b32 m0, s42
	s_nop 0
	global_load_lds_dwordx4 v[150:151], off
	v_lshl_add_u64 v[150:151], s[40:41], 0, v[136:137]
	s_add_i32 m0, s42, 0x2000
	s_nop 0
	global_load_lds_dwordx4 v[150:151], off
	v_lshl_add_u64 v[150:151], v[222:223], 0, s[22:23]
	s_mov_b32 m0, s69
	s_nop 0
	global_load_lds_dwordx4 v[150:151], off
	v_lshl_add_u64 v[150:151], v[224:225], 0, s[22:23]
	s_mov_b32 m0, s70
	s_nop 0
	global_load_lds_dwordx4 v[150:151], off
	s_waitcnt vmcnt(8)
	s_waitcnt lgkmcnt(0)
	s_barrier
	s_waitcnt lgkmcnt(0)
	v_mfma_f32_16x16x32_bf16 v[62:65], v[156:159], v[188:191], v[62:65]
	v_mfma_f32_16x16x32_bf16 v[54:57], v[156:159], v[196:199], v[54:57]
	v_mfma_f32_16x16x32_bf16 v[46:49], v[156:159], v[204:207], v[46:49]
	v_mfma_f32_16x16x32_bf16 v[38:41], v[156:159], v[212:215], v[38:41]
	v_mfma_f32_16x16x32_bf16 v[34:37], v[164:167], v[212:215], v[34:37]
	v_mfma_f32_16x16x32_bf16 v[42:45], v[164:167], v[204:207], v[42:45]
	v_mfma_f32_16x16x32_bf16 v[50:53], v[164:167], v[196:199], v[50:53]
	v_mfma_f32_16x16x32_bf16 v[58:61], v[164:167], v[188:191], v[58:61]
	v_mfma_f32_16x16x32_bf16 v[62:65], v[160:163], v[192:195], v[62:65]
	v_mfma_f32_16x16x32_bf16 v[54:57], v[160:163], v[200:203], v[54:57]
	v_mfma_f32_16x16x32_bf16 v[46:49], v[160:163], v[208:211], v[46:49]
	v_mfma_f32_16x16x32_bf16 v[38:41], v[160:163], v[216:219], v[38:41]
	v_mfma_f32_16x16x32_bf16 v[34:37], v[168:171], v[216:219], v[34:37]
	v_mfma_f32_16x16x32_bf16 v[42:45], v[168:171], v[208:211], v[42:45]
	v_mfma_f32_16x16x32_bf16 v[50:53], v[168:171], v[200:203], v[50:53]
	v_mfma_f32_16x16x32_bf16 v[58:61], v[168:171], v[192:195], v[58:61]
	v_mfma_f32_16x16x32_bf16 v[30:33], v[172:175], v[188:191], v[30:33]
	v_mfma_f32_16x16x32_bf16 v[22:25], v[172:175], v[196:199], v[22:25]
	v_mfma_f32_16x16x32_bf16 v[14:17], v[172:175], v[204:207], v[14:17]
	v_mfma_f32_16x16x32_bf16 v[6:9], v[172:175], v[212:215], v[6:9]
	v_mfma_f32_16x16x32_bf16 v[2:5], v[180:183], v[212:215], v[2:5]
	v_mfma_f32_16x16x32_bf16 v[10:13], v[180:183], v[204:207], v[10:13]
	v_mfma_f32_16x16x32_bf16 v[18:21], v[180:183], v[196:199], v[18:21]
	v_mfma_f32_16x16x32_bf16 v[26:29], v[180:183], v[188:191], v[26:29]
	v_mfma_f32_16x16x32_bf16 v[30:33], v[176:179], v[192:195], v[30:33]
	v_mfma_f32_16x16x32_bf16 v[22:25], v[176:179], v[200:203], v[22:25]
	v_mfma_f32_16x16x32_bf16 v[14:17], v[176:179], v[208:211], v[14:17]
	v_mfma_f32_16x16x32_bf16 v[6:9], v[176:179], v[216:219], v[6:9]
	v_mfma_f32_16x16x32_bf16 v[2:5], v[184:187], v[216:219], v[2:5]
	v_mfma_f32_16x16x32_bf16 v[10:13], v[184:187], v[208:211], v[10:13]
	v_mfma_f32_16x16x32_bf16 v[18:21], v[184:187], v[200:203], v[18:21]
	v_mfma_f32_16x16x32_bf16 v[26:29], v[184:187], v[192:195], v[26:29]
	s_barrier
	s_add_i32 s20, s20, 2
	s_add_u32 s38, s38, 0x100
	s_addc_u32 s39, s39, 0
	s_cmp_gt_u32 s20, 41
	s_cbranch_scc0 .LBB0_793

; #define PG8_STAGEA(bufoff, gbase) PG8_STAGE_(bufoff, gbase, voffA)
; #define PG8_STAGEB(bufoff, gbase) PG8_STAGE_(bufoff, gbase, voffB)
; #define PG8_LDA(dst, b, h) do { _Pragma("unroll") for (int m = 0; m < 4; ++m) _Pragma("unroll") for (int k = 0; k < 2; ++k) dst[m][k] = *(const LAS bf16x8*)(lds + PG8_SA(b, h) + aoff + m * 2048 + k * 1024); } while (0)
; #define PG8_LDB(dst, b, h) do { _Pragma("unroll") for (int n = 0; n < 2; ++n) _Pragma("unroll") for (int k = 0; k < 2; ++k) dst[n][k] = *(const LAS bf16x8*)(lds + PG8_SB(b, h) + boff + n * 2048 + k * 1024); } while (0)
; #define PG8_MMA(ai, bj, At, Bt_) do { __builtin_amdgcn_s_setprio(1); _Pragma("unroll") for (int m = 0; m < 4; ++m) _Pragma("unroll") for (int n = 0; n < 2; ++n) _Pragma("unroll") for (int k = 0; k < 2; ++k) \
;         acc[ai][bj][m][n] = __builtin_amdgcn_mfma_f32_16x16x32_bf16(Bt_[n][k], At[m][k], acc[ai][bj][m][n], 0, 0, 0); __builtin_amdgcn_s_setprio(0); } while (0)
; #define PG8_WAIT_V(n) asm volatile("s_waitcnt vmcnt(" #n ")" ::: "memory")
; #define PG8_WAIT_L(n) asm volatile("s_waitcnt lgkmcnt(" #n ")" ::: "memory")
; #define PG8_BAR __builtin_amdgcn_s_barrier()
; template <int EK, int SK = -1>
; __device__ __forceinline__ void gemm_phase(LAS unsigned char* lds, const bf16_t* A, const bf16_t* Bt, int nM, int N, int K, const EpiArgs& E) {
;     ...
;         const bool has_next = S.next(ui + 1, nxt);
;         const char* nA = has_next ? (const char*)A + (size_t)nxt.pm * tstep : cA; const char* nB = has_next ? (const char*)Bt + (size_t)nxt.pn * tstep : cB;
;         for (int t = 0; t < nt; t += 2) {
;             const bool last = (t == nt - 2);
;             const char* a1 = cA + (size_t)(t + 1) * kstep;
;             const char* a2 = last ? nA : cA + (size_t)(t + 2) * kstep; const char* b2 = last ? nB : cB + (size_t)(t + 2) * kstep;
;             const char* a3 = a2 + kstep; const char* b3 = b2 + kstep;
;             PG8_LDB(B0, 0, 0); PG8_LDB(B1, 0, 1); PG8_SCHED; PG8_LDA(At, 0, 0); PG8_STAGEA(PG8_SA(1, 1), a1 + hstep);
;             PG8_WAIT_V(8); PG8_WAIT_L(0); PG8_BAR; PG8_MMA(0, 0, At, B0); PG8_MMA(0, 1, At, B1); PG8_BAR; PG8_SCHED;
;             PG8_LDA(At, 0, 1); PG8_STAGEB(PG8_SB(0, 0), b2); PG8_STAGEB(PG8_SB(0, 1), b2 + hstep); PG8_STAGEA(PG8_SA(0, 0), a2);
;             PG8_WAIT_V(8); PG8_WAIT_L(0); PG8_BAR; PG8_MMA(1, 0, At, B0); PG8_MMA(1, 1, At, B1); PG8_BAR; PG8_SCHED;
.LBB0_928:
	s_add_u32 s86, s76, 0x100
	s_addc_u32 s87, s77, 0
	s_ashr_i32 s71, s70, 31
	s_lshl_b64 s[10:11], s[70:71], 19
	s_add_u32 s74, s62, s10
	s_addc_u32 s75, s63, s11
	s_and_b64 s[10:11], s[8:9], exec
	s_cselect_b32 s14, s75, s37
	s_cselect_b32 s71, s74, s36
	s_ashr_i32 s69, s68, 31
	s_lshl_b64 s[10:11], s[68:69], 19
	s_add_u32 s72, s43, s10
	s_addc_u32 s73, s45, s11
	s_and_b64 s[10:11], s[8:9], exec
	s_cselect_b32 s69, s73, s77
	s_cselect_b32 s88, s72, s76
	s_waitcnt lgkmcnt(0)
	v_lshl_add_u64 v[146:147], s[36:37], 0, v[138:139]
	v_lshl_add_u64 v[148:149], s[36:37], 0, v[140:141]
	s_mov_b32 s89, -2
	s_mov_b64 s[10:11], 0
	v_add_u32_e32 v158, s82, v160
	ds_read_b128 v[150:153], v158
	ds_read_b128 v[154:157], v158 offset:1024
	ds_read_b128 v[166:169], v158 offset:2048
	ds_read_b128 v[170:173], v158 offset:3072
	v_add_u32_e32 v158, s83, v160
	s_add_u32 s76, s36, s10
	ds_read_b128 v[174:177], v158
	ds_read_b128 v[178:181], v158 offset:1024
	ds_read_b128 v[182:185], v158 offset:2048
	ds_read_b128 v[186:189], v158 offset:3072
	s_addc_u32 s77, s37, s11
	s_add_u32 s76, s76, 0x100
	s_addc_u32 s77, s77, 0
	s_add_u32 s90, s86, s10
	s_addc_u32 s91, s87, s11
	s_cmpk_eq_i32 s10, 0x700
	s_cselect_b32 s79, s14, s77
	s_cselect_b32 s78, s71, s76
	s_cselect_b32 s77, s69, s91
	s_cselect_b32 s76, s88, s90
	v_lshl_add_u64 v[158:159], v[146:147], 0, s[10:11]
	s_add_i32 m0, s23, 0xc000
	ds_read_b128 v[190:193], v163
	ds_read_b128 v[194:197], v163 offset:1024
	ds_read_b128 v[198:201], v163 offset:2048
	ds_read_b128 v[202:205], v163 offset:3072
	ds_read_b128 v[206:209], v163 offset:4096
	ds_read_b128 v[210:213], v163 offset:5120
	ds_read_b128 v[214:217], v163 offset:6144
	ds_read_b128 v[218:221], v163 offset:7168
	global_load_lds_dwordx4 v[158:159], off
	v_lshl_add_u64 v[158:159], v[148:149], 0, s[10:11]
	s_add_i32 m0, s23, 0xe000
	s_nop 0
	global_load_lds_dwordx4 v[158:159], off
	s_waitcnt vmcnt(8)
	s_waitcnt lgkmcnt(0)
	s_barrier
	s_waitcnt lgkmcnt(0)
	v_mfma_f32_16x16x32_bf16 v[110:113], v[150:153], v[190:193], 0
	v_mfma_f32_16x16x32_bf16 v[102:105], v[150:153], v[198:201], 0
	v_mfma_f32_16x16x32_bf16 v[94:97], v[150:153], v[206:209], 0
	v_mfma_f32_16x16x32_bf16 v[86:89], v[150:153], v[214:217], 0
	v_mfma_f32_16x16x32_bf16 v[82:85], v[166:169], v[214:217], 0
	v_mfma_f32_16x16x32_bf16 v[90:93], v[166:169], v[206:209], 0
	v_mfma_f32_16x16x32_bf16 v[98:101], v[166:169], v[198:201], 0
	v_mfma_f32_16x16x32_bf16 v[106:109], v[166:169], v[190:193], 0
	v_mfma_f32_16x16x32_bf16 v[110:113], v[154:157], v[194:197], v[110:113]
	v_mfma_f32_16x16x32_bf16 v[102:105], v[154:157], v[202:205], v[102:105]
	v_mfma_f32_16x16x32_bf16 v[94:97], v[154:157], v[210:213], v[94:97]
	v_mfma_f32_16x16x32_bf16 v[86:89], v[154:157], v[218:221], v[86:89]
	v_mfma_f32_16x16x32_bf16 v[82:85], v[170:173], v[218:221], v[82:85]
	v_mfma_f32_16x16x32_bf16 v[90:93], v[170:173], v[210:213], v[90:93]
	v_mfma_f32_16x16x32_bf16 v[98:101], v[170:173], v[202:205], v[98:101]
	v_mfma_f32_16x16x32_bf16 v[106:109], v[170:173], v[194:197], v[106:109]
	v_mfma_f32_16x16x32_bf16 v[78:81], v[174:177], v[190:193], 0
	v_mfma_f32_16x16x32_bf16 v[70:73], v[174:177], v[198:201], 0
	v_mfma_f32_16x16x32_bf16 v[62:65], v[174:177], v[206:209], 0
	v_mfma_f32_16x16x32_bf16 v[54:57], v[174:177], v[214:217], 0
	v_mfma_f32_16x16x32_bf16 v[50:53], v[182:185], v[214:217], 0
	v_mfma_f32_16x16x32_bf16 v[58:61], v[182:185], v[206:209], 0
	v_mfma_f32_16x16x32_bf16 v[66:69], v[182:185], v[198:201], 0
	v_mfma_f32_16x16x32_bf16 v[74:77], v[182:185], v[190:193], 0
	v_mfma_f32_16x16x32_bf16 v[78:81], v[178:181], v[194:197], v[78:81]
	v_mfma_f32_16x16x32_bf16 v[70:73], v[178:181], v[202:205], v[70:73]
	v_mfma_f32_16x16x32_bf16 v[62:65], v[178:181], v[210:213], v[62:65]
	v_mfma_f32_16x16x32_bf16 v[54:57], v[178:181], v[218:221], v[54:57]
	v_mfma_f32_16x16x32_bf16 v[50:53], v[186:189], v[218:221], v[50:53]
	v_mfma_f32_16x16x32_bf16 v[58:61], v[186:189], v[210:213], v[58:61]
	v_mfma_f32_16x16x32_bf16 v[66:69], v[186:189], v[202:205], v[66:69]
	v_mfma_f32_16x16x32_bf16 v[74:77], v[186:189], v[194:197], v[74:77]
	s_barrier
	s_add_i32 s90, s82, s53
	v_lshl_add_u64 v[158:159], s[76:77], 0, v[132:133]
	s_mov_b32 m0, s90
	ds_read_b128 v[190:193], v163 offset:16384
	ds_read_b128 v[194:197], v163 offset:17408
	ds_read_b128 v[198:201], v163 offset:18432
	ds_read_b128 v[202:205], v163 offset:19456
	ds_read_b128 v[206:209], v163 offset:20480
	ds_read_b128 v[210:213], v163 offset:21504
	ds_read_b128 v[214:217], v163 offset:22528
	ds_read_b128 v[218:221], v163 offset:23552
	global_load_lds_dwordx4 v[158:159], off
	s_add_i32 m0, s90, 0x2000
	s_add_u32 s90, s76, 0x40000
	v_lshl_add_u64 v[222:223], s[76:77], 0, v[136:137]
	s_addc_u32 s91, s77, 0
	s_add_i32 s92, s83, s53
	global_load_lds_dwordx4 v[222:223], off
	v_lshl_add_u64 v[224:225], s[90:91], 0, v[132:133]
	s_mov_b32 m0, s92
	v_lshl_add_u64 v[226:227], s[78:79], 0, v[134:135]
	global_load_lds_dwordx4 v[224:225], off
	v_lshl_add_u64 v[224:225], s[90:91], 0, v[136:137]
	s_add_i32 m0, s92, 0x2000
	s_nop 0
	global_load_lds_dwordx4 v[224:225], off
	v_lshl_add_u64 v[224:225], s[78:79], 0, v[130:131]
	s_mov_b32 m0, s23
	s_nop 0
	global_load_lds_dwordx4 v[224:225], off
	s_mov_b32 m0, s27
	s_nop 0
	global_load_lds_dwordx4 v[226:227], off
	s_waitcnt vmcnt(8)
	s_waitcnt lgkmcnt(0)
	s_barrier
; #define PG8_STAGEA(bufoff, gbase) PG8_STAGE_(bufoff, gbase, voffA)
; #define PG8_LDA(dst, b, h) do { _Pragma("unroll") for (int m = 0; m < 4; ++m) _Pragma("unroll") for (int k = 0; k < 2; ++k) dst[m][k] = *(const LAS bf16x8*)(lds + PG8_SA(b, h) + aoff + m * 2048 + k * 1024); } while (0)
; #define PG8_LDB(dst, b, h) do { _Pragma("unroll") for (int n = 0; n < 2; ++n) _Pragma("unroll") for (int k = 0; k < 2; ++k) dst[n][k] = *(const LAS bf16x8*)(lds + PG8_SB(b, h) + boff + n * 2048 + k * 1024); } while (0)
; #define PG8_MMA(ai, bj, At, Bt_) do { __builtin_amdgcn_s_setprio(1); _Pragma("unroll") for (int m = 0; m < 4; ++m) _Pragma("unroll") for (int n = 0; n < 2; ++n) _Pragma("unroll") for (int k = 0; k < 2; ++k) \
;         acc[ai][bj][m][n] = __builtin_amdgcn_mfma_f32_16x16x32_bf16(Bt_[n][k], At[m][k], acc[ai][bj][m][n], 0, 0, 0); __builtin_amdgcn_s_setprio(0); } while (0)
; #define PG8_WAIT_V(n) asm volatile("s_waitcnt vmcnt(" #n ")" ::: "memory")
; #define PG8_WAIT_L(n) asm volatile("s_waitcnt lgkmcnt(" #n ")" ::: "memory")
; #define PG8_BAR __builtin_amdgcn_s_barrier()
; #define PG8_SCHED __builtin_amdgcn_sched_barrier(0)
; template <int EK, int SK = -1>
; __device__ __forceinline__ void gemm_phase(LAS unsigned char* lds, const bf16_t* A, const bf16_t* Bt, int nM, int N, int K, const EpiArgs& E) {
;     ...
;             PG8_WAIT_V(8); PG8_WAIT_L(0); PG8_BAR; PG8_MMA(1, 0, At, B0); PG8_MMA(1, 1, At, B1); PG8_BAR; PG8_SCHED;
;             PG8_LDB(B0, 1, 0); PG8_LDB(B1, 1, 1); PG8_SCHED; PG8_LDA(At, 1, 0); PG8_STAGEA(PG8_SA(0, 1), a2 + hstep);
;             PG8_WAIT_V(8); PG8_WAIT_L(0); PG8_BAR; PG8_MMA(0, 0, At, B0); PG8_MMA(0, 1, At, B1); PG8_BAR; PG8_SCHED;
	s_waitcnt lgkmcnt(0)
	v_mfma_f32_16x16x32_bf16 v[46:49], v[150:153], v[190:193], 0
	v_mfma_f32_16x16x32_bf16 v[38:41], v[150:153], v[198:201], 0
	v_mfma_f32_16x16x32_bf16 v[30:33], v[150:153], v[206:209], 0
	v_mfma_f32_16x16x32_bf16 v[22:25], v[150:153], v[214:217], 0
	v_mfma_f32_16x16x32_bf16 v[18:21], v[166:169], v[214:217], 0
	v_mfma_f32_16x16x32_bf16 v[26:29], v[166:169], v[206:209], 0
	v_mfma_f32_16x16x32_bf16 v[34:37], v[166:169], v[198:201], 0
	v_mfma_f32_16x16x32_bf16 v[42:45], v[166:169], v[190:193], 0
	v_mfma_f32_16x16x32_bf16 v[46:49], v[154:157], v[194:197], v[46:49]
	v_mfma_f32_16x16x32_bf16 v[38:41], v[154:157], v[202:205], v[38:41]
	v_mfma_f32_16x16x32_bf16 v[30:33], v[154:157], v[210:213], v[30:33]
	v_mfma_f32_16x16x32_bf16 v[22:25], v[154:157], v[218:221], v[22:25]
	v_mfma_f32_16x16x32_bf16 v[18:21], v[170:173], v[218:221], v[18:21]
	v_mfma_f32_16x16x32_bf16 v[26:29], v[170:173], v[210:213], v[26:29]
	v_mfma_f32_16x16x32_bf16 v[34:37], v[170:173], v[202:205], v[34:37]
	v_mfma_f32_16x16x32_bf16 v[42:45], v[170:173], v[194:197], v[42:45]
	v_mfma_f32_16x16x32_bf16 v[14:17], v[174:177], v[190:193], 0
	v_mfma_f32_16x16x32_bf16 v[6:9], v[174:177], v[198:201], 0
	v_mfma_f32_16x16x32_bf16 v[114:117], v[174:177], v[206:209], 0
	v_mfma_f32_16x16x32_bf16 v[122:125], v[174:177], v[214:217], 0
	v_mfma_f32_16x16x32_bf16 v[126:129], v[182:185], v[214:217], 0
	v_mfma_f32_16x16x32_bf16 v[118:121], v[182:185], v[206:209], 0
	v_mfma_f32_16x16x32_bf16 v[2:5], v[182:185], v[198:201], 0
	v_mfma_f32_16x16x32_bf16 v[10:13], v[182:185], v[190:193], 0
	v_mfma_f32_16x16x32_bf16 v[14:17], v[178:181], v[194:197], v[14:17]
	v_mfma_f32_16x16x32_bf16 v[6:9], v[178:181], v[202:205], v[6:9]
	v_mfma_f32_16x16x32_bf16 v[114:117], v[178:181], v[210:213], v[114:117]
	v_mfma_f32_16x16x32_bf16 v[122:125], v[178:181], v[218:221], v[122:125]
	v_mfma_f32_16x16x32_bf16 v[126:129], v[186:189], v[218:221], v[126:129]
	v_mfma_f32_16x16x32_bf16 v[118:121], v[186:189], v[210:213], v[118:121]
	v_mfma_f32_16x16x32_bf16 v[2:5], v[186:189], v[202:205], v[2:5]
	v_mfma_f32_16x16x32_bf16 v[10:13], v[186:189], v[194:197], v[10:13]
	s_barrier
	s_add_i32 s90, 0, 0x18000
	v_add_u32_e32 v165, s90, v160
	s_add_i32 s91, 0, 0x1c000
	ds_read_b128 v[150:153], v165
	ds_read_b128 v[154:157], v165 offset:1024
	ds_read_b128 v[166:169], v165 offset:2048
	ds_read_b128 v[170:173], v165 offset:3072
	v_add_u32_e32 v165, s91, v160
	ds_read_b128 v[174:177], v165
	ds_read_b128 v[178:181], v165 offset:1024
	ds_read_b128 v[182:185], v165 offset:2048
	ds_read_b128 v[186:189], v165 offset:3072
	s_add_u32 s78, s78, 0x40000
	s_addc_u32 s79, s79, 0
	s_mov_b32 m0, s55
	v_lshl_add_u64 v[228:229], s[78:79], 0, v[130:131]
	ds_read_b128 v[190:193], v163 offset:32768
	ds_read_b128 v[194:197], v163 offset:33792
	ds_read_b128 v[198:201], v163 offset:34816
	ds_read_b128 v[202:205], v163 offset:35840
	ds_read_b128 v[206:209], v163 offset:36864
	ds_read_b128 v[210:213], v163 offset:37888
	ds_read_b128 v[214:217], v163 offset:38912
	ds_read_b128 v[218:221], v163 offset:39936
	global_load_lds_dwordx4 v[228:229], off
	v_lshl_add_u64 v[228:229], s[78:79], 0, v[134:135]
	s_mov_b32 m0, s57
	s_nop 0
	global_load_lds_dwordx4 v[228:229], off
	s_waitcnt vmcnt(8)
	s_waitcnt lgkmcnt(0)
	s_barrier
	s_waitcnt lgkmcnt(0)
	v_mfma_f32_16x16x32_bf16 v[110:113], v[150:153], v[190:193], v[110:113]
	v_mfma_f32_16x16x32_bf16 v[102:105], v[150:153], v[198:201], v[102:105]
	v_mfma_f32_16x16x32_bf16 v[94:97], v[150:153], v[206:209], v[94:97]
	v_mfma_f32_16x16x32_bf16 v[86:89], v[150:153], v[214:217], v[86:89]
	v_mfma_f32_16x16x32_bf16 v[82:85], v[166:169], v[214:217], v[82:85]
	v_mfma_f32_16x16x32_bf16 v[90:93], v[166:169], v[206:209], v[90:93]
	v_mfma_f32_16x16x32_bf16 v[98:101], v[166:169], v[198:201], v[98:101]
	v_mfma_f32_16x16x32_bf16 v[106:109], v[166:169], v[190:193], v[106:109]
	v_mfma_f32_16x16x32_bf16 v[110:113], v[154:157], v[194:197], v[110:113]
	v_mfma_f32_16x16x32_bf16 v[102:105], v[154:157], v[202:205], v[102:105]
	v_mfma_f32_16x16x32_bf16 v[94:97], v[154:157], v[210:213], v[94:97]
	v_mfma_f32_16x16x32_bf16 v[86:89], v[154:157], v[218:221], v[86:89]
	v_mfma_f32_16x16x32_bf16 v[82:85], v[170:173], v[218:221], v[82:85]
	v_mfma_f32_16x16x32_bf16 v[90:93], v[170:173], v[210:213], v[90:93]
	v_mfma_f32_16x16x32_bf16 v[98:101], v[170:173], v[202:205], v[98:101]
	v_mfma_f32_16x16x32_bf16 v[106:109], v[170:173], v[194:197], v[106:109]
	v_mfma_f32_16x16x32_bf16 v[78:81], v[174:177], v[190:193], v[78:81]
	v_mfma_f32_16x16x32_bf16 v[70:73], v[174:177], v[198:201], v[70:73]
	v_mfma_f32_16x16x32_bf16 v[62:65], v[174:177], v[206:209], v[62:65]
	v_mfma_f32_16x16x32_bf16 v[54:57], v[174:177], v[214:217], v[54:57]
	v_mfma_f32_16x16x32_bf16 v[50:53], v[182:185], v[214:217], v[50:53]
	v_mfma_f32_16x16x32_bf16 v[58:61], v[182:185], v[206:209], v[58:61]
	v_mfma_f32_16x16x32_bf16 v[66:69], v[182:185], v[198:201], v[66:69]
	v_mfma_f32_16x16x32_bf16 v[74:77], v[182:185], v[190:193], v[74:77]
	v_mfma_f32_16x16x32_bf16 v[78:81], v[178:181], v[194:197], v[78:81]
	v_mfma_f32_16x16x32_bf16 v[70:73], v[178:181], v[202:205], v[70:73]
	v_mfma_f32_16x16x32_bf16 v[62:65], v[178:181], v[210:213], v[62:65]
	v_mfma_f32_16x16x32_bf16 v[54:57], v[178:181], v[218:221], v[54:57]
	v_mfma_f32_16x16x32_bf16 v[50:53], v[186:189], v[218:221], v[50:53]
	v_mfma_f32_16x16x32_bf16 v[58:61], v[186:189], v[210:213], v[58:61]
	v_mfma_f32_16x16x32_bf16 v[66:69], v[186:189], v[202:205], v[66:69]
	v_mfma_f32_16x16x32_bf16 v[74:77], v[186:189], v[194:197], v[74:77]
	s_barrier
; #define PG8_STAGEA(bufoff, gbase) PG8_STAGE_(bufoff, gbase, voffA)
; #define PG8_STAGEB(bufoff, gbase) PG8_STAGE_(bufoff, gbase, voffB)
; #define PG8_LDA(dst, b, h) do { _Pragma("unroll") for (int m = 0; m < 4; ++m) _Pragma("unroll") for (int k = 0; k < 2; ++k) dst[m][k] = *(const LAS bf16x8*)(lds + PG8_SA(b, h) + aoff + m * 2048 + k * 1024); } while (0)
; #define PG8_LDB(dst, b, h) do { _Pragma("unroll") for (int n = 0; n < 2; ++n) _Pragma("unroll") for (int k = 0; k < 2; ++k) dst[n][k] = *(const LAS bf16x8*)(lds + PG8_SB(b, h) + boff + n * 2048 + k * 1024); } while (0)
; #define PG8_MMA(ai, bj, At, Bt_) do { __builtin_amdgcn_s_setprio(1); _Pragma("unroll") for (int m = 0; m < 4; ++m) _Pragma("unroll") for (int n = 0; n < 2; ++n) _Pragma("unroll") for (int k = 0; k < 2; ++k) \
;         acc[ai][bj][m][n] = __builtin_amdgcn_mfma_f32_16x16x32_bf16(Bt_[n][k], At[m][k], acc[ai][bj][m][n], 0, 0, 0); __builtin_amdgcn_s_setprio(0); } while (0)
; #define PG8_WAIT_V(n) asm volatile("s_waitcnt vmcnt(" #n ")" ::: "memory")
; #define PG8_WAIT_L(n) asm volatile("s_waitcnt lgkmcnt(" #n ")" ::: "memory")
; #define PG8_BAR __builtin_amdgcn_s_barrier()
; #define PG8_SCHED __builtin_amdgcn_sched_barrier(0)
; template <int EK, int SK = -1>
; __device__ __forceinline__ void gemm_phase(LAS unsigned char* lds, const bf16_t* A, const bf16_t* Bt, int nM, int N, int K, const EpiArgs& E) {
;     ...
;             PG8_LDB(B0, 0, 0); PG8_LDB(B1, 0, 1); PG8_SCHED; PG8_LDA(At, 0, 0); PG8_STAGEA(PG8_SA(1, 1), a1 + hstep);
;             PG8_WAIT_V(8); PG8_WAIT_L(0); PG8_BAR; PG8_MMA(0, 0, At, B0); PG8_MMA(0, 1, At, B1); PG8_BAR; PG8_SCHED;
;             PG8_LDA(At, 0, 1); PG8_STAGEB(PG8_SB(0, 0), b2); PG8_STAGEB(PG8_SB(0, 1), b2 + hstep); PG8_STAGEA(PG8_SA(0, 0), a2);
;             PG8_WAIT_V(8); PG8_WAIT_L(0); PG8_BAR; PG8_MMA(1, 0, At, B0); PG8_MMA(1, 1, At, B1); PG8_BAR; PG8_SCHED;
;             PG8_LDB(B0, 1, 0); PG8_LDB(B1, 1, 1); PG8_SCHED; PG8_LDA(At, 1, 0); PG8_STAGEA(PG8_SA(0, 1), a2 + hstep);
;             PG8_WAIT_V(8); PG8_WAIT_L(0); PG8_BAR; PG8_MMA(0, 0, At, B0); PG8_MMA(0, 1, At, B1); PG8_BAR; PG8_SCHED;
;             PG8_LDA(At, 1, 1); PG8_STAGEB(PG8_SB(1, 0), b3); PG8_STAGEB(PG8_SB(1, 1), b3 + hstep); PG8_STAGEA(PG8_SA(1, 0), a3);
;             PG8_WAIT_V(8); PG8_WAIT_L(0); PG8_BAR; PG8_MMA(1, 0, At, B0); PG8_MMA(1, 1, At, B1); PG8_BAR; PG8_SCHED;
;         }
	s_add_i32 s78, s90, s53
	v_lshl_add_u64 v[158:159], v[158:159], 0, s[16:17]
	s_mov_b32 m0, s78
	ds_read_b128 v[190:193], v163 offset:49152
	ds_read_b128 v[194:197], v163 offset:50176
	ds_read_b128 v[198:201], v163 offset:51200
	ds_read_b128 v[202:205], v163 offset:52224
	ds_read_b128 v[206:209], v163 offset:53248
	ds_read_b128 v[210:213], v163 offset:54272
	ds_read_b128 v[214:217], v163 offset:55296
	ds_read_b128 v[218:221], v163 offset:56320
	global_load_lds_dwordx4 v[158:159], off
	s_add_i32 m0, s78, 0x2000
	s_add_u32 s76, s76, 0x40080
	v_lshl_add_u64 v[158:159], v[222:223], 0, s[16:17]
	s_addc_u32 s77, s77, 0
	s_add_i32 s78, s91, s53
	global_load_lds_dwordx4 v[158:159], off
	v_lshl_add_u64 v[158:159], s[76:77], 0, v[132:133]
	s_mov_b32 m0, s78
	s_nop 0
	global_load_lds_dwordx4 v[158:159], off
	v_lshl_add_u64 v[158:159], s[76:77], 0, v[136:137]
	s_add_i32 m0, s78, 0x2000
	s_nop 0
	global_load_lds_dwordx4 v[158:159], off
	v_lshl_add_u64 v[158:159], v[224:225], 0, s[16:17]
	s_mov_b32 m0, s80
	s_nop 0
	global_load_lds_dwordx4 v[158:159], off
	v_lshl_add_u64 v[158:159], v[226:227], 0, s[16:17]
	s_mov_b32 m0, s81
	s_nop 0
	global_load_lds_dwordx4 v[158:159], off
	s_waitcnt vmcnt(8)
	s_waitcnt lgkmcnt(0)
	s_barrier
	s_waitcnt lgkmcnt(0)
	v_mfma_f32_16x16x32_bf16 v[46:49], v[150:153], v[190:193], v[46:49]
	v_mfma_f32_16x16x32_bf16 v[38:41], v[150:153], v[198:201], v[38:41]
	v_mfma_f32_16x16x32_bf16 v[30:33], v[150:153], v[206:209], v[30:33]
	v_mfma_f32_16x16x32_bf16 v[22:25], v[150:153], v[214:217], v[22:25]
	v_mfma_f32_16x16x32_bf16 v[18:21], v[166:169], v[214:217], v[18:21]
	v_mfma_f32_16x16x32_bf16 v[26:29], v[166:169], v[206:209], v[26:29]
	v_mfma_f32_16x16x32_bf16 v[34:37], v[166:169], v[198:201], v[34:37]
	v_mfma_f32_16x16x32_bf16 v[42:45], v[166:169], v[190:193], v[42:45]
	v_mfma_f32_16x16x32_bf16 v[46:49], v[154:157], v[194:197], v[46:49]
	v_mfma_f32_16x16x32_bf16 v[38:41], v[154:157], v[202:205], v[38:41]
	v_mfma_f32_16x16x32_bf16 v[30:33], v[154:157], v[210:213], v[30:33]
	v_mfma_f32_16x16x32_bf16 v[22:25], v[154:157], v[218:221], v[22:25]
	v_mfma_f32_16x16x32_bf16 v[18:21], v[170:173], v[218:221], v[18:21]
	v_mfma_f32_16x16x32_bf16 v[26:29], v[170:173], v[210:213], v[26:29]
	v_mfma_f32_16x16x32_bf16 v[34:37], v[170:173], v[202:205], v[34:37]
	v_mfma_f32_16x16x32_bf16 v[42:45], v[170:173], v[194:197], v[42:45]
	v_mfma_f32_16x16x32_bf16 v[14:17], v[174:177], v[190:193], v[14:17]
	v_mfma_f32_16x16x32_bf16 v[6:9], v[174:177], v[198:201], v[6:9]
	v_mfma_f32_16x16x32_bf16 v[114:117], v[174:177], v[206:209], v[114:117]
	v_mfma_f32_16x16x32_bf16 v[122:125], v[174:177], v[214:217], v[122:125]
	v_mfma_f32_16x16x32_bf16 v[126:129], v[182:185], v[214:217], v[126:129]
	v_mfma_f32_16x16x32_bf16 v[118:121], v[182:185], v[206:209], v[118:121]
	v_mfma_f32_16x16x32_bf16 v[2:5], v[182:185], v[198:201], v[2:5]
	v_mfma_f32_16x16x32_bf16 v[10:13], v[182:185], v[190:193], v[10:13]
	v_mfma_f32_16x16x32_bf16 v[14:17], v[178:181], v[194:197], v[14:17]
	v_mfma_f32_16x16x32_bf16 v[6:9], v[178:181], v[202:205], v[6:9]
	v_mfma_f32_16x16x32_bf16 v[114:117], v[178:181], v[210:213], v[114:117]
	v_mfma_f32_16x16x32_bf16 v[122:125], v[178:181], v[218:221], v[122:125]
	v_mfma_f32_16x16x32_bf16 v[126:129], v[186:189], v[218:221], v[126:129]
	v_mfma_f32_16x16x32_bf16 v[118:121], v[186:189], v[210:213], v[118:121]
	v_mfma_f32_16x16x32_bf16 v[2:5], v[186:189], v[202:205], v[2:5]
	v_mfma_f32_16x16x32_bf16 v[10:13], v[186:189], v[194:197], v[10:13]
	s_barrier
	s_add_i32 s89, s89, 2
	s_add_u32 s10, s10, 0x100
	s_addc_u32 s11, s11, 0
	s_cmp_gt_u32 s89, 13
	s_cbranch_scc0 .LBB0_929
	s_branch .Lmy_kexit_4
.LBB0_929:
	v_add_u32_e32 v158, s82, v160
	ds_read_b128 v[150:153], v158
	ds_read_b128 v[154:157], v158 offset:1024
	ds_read_b128 v[166:169], v158 offset:2048
	ds_read_b128 v[170:173], v158 offset:3072
	v_add_u32_e32 v158, s83, v160
	s_add_u32 s76, s36, s10
	ds_read_b128 v[174:177], v158
	ds_read_b128 v[178:181], v158 offset:1024
	ds_read_b128 v[182:185], v158 offset:2048
	ds_read_b128 v[186:189], v158 offset:3072
	s_addc_u32 s77, s37, s11
	s_add_u32 s76, s76, 0x100
	s_addc_u32 s77, s77, 0
	s_add_u32 s90, s86, s10
	s_addc_u32 s91, s87, s11
	s_cmpk_eq_i32 s10, 0x700
	s_cselect_b32 s79, s14, s77
	s_cselect_b32 s78, s71, s76
	s_cselect_b32 s77, s69, s91
	s_cselect_b32 s76, s88, s90
	v_lshl_add_u64 v[158:159], v[146:147], 0, s[10:11]
	s_add_i32 m0, s23, 0xc000
	ds_read_b128 v[190:193], v163
	ds_read_b128 v[194:197], v163 offset:1024
	ds_read_b128 v[198:201], v163 offset:2048
	ds_read_b128 v[202:205], v163 offset:3072
	ds_read_b128 v[206:209], v163 offset:4096
	ds_read_b128 v[210:213], v163 offset:5120
	ds_read_b128 v[214:217], v163 offset:6144
	ds_read_b128 v[218:221], v163 offset:7168
	global_load_lds_dwordx4 v[158:159], off
	v_lshl_add_u64 v[158:159], v[148:149], 0, s[10:11]
	s_add_i32 m0, s23, 0xe000
	s_nop 0
	global_load_lds_dwordx4 v[158:159], off
	s_waitcnt vmcnt(8)
	s_waitcnt lgkmcnt(0)
	s_barrier
; #define PG8_STAGEA(bufoff, gbase) PG8_STAGE_(bufoff, gbase, voffA)
; #define PG8_STAGEB(bufoff, gbase) PG8_STAGE_(bufoff, gbase, voffB)
; #define PG8_LDA(dst, b, h) do { _Pragma("unroll") for (int m = 0; m < 4; ++m) _Pragma("unroll") for (int k = 0; k < 2; ++k) dst[m][k] = *(const LAS bf16x8*)(lds + PG8_SA(b, h) + aoff + m * 2048 + k * 1024); } while (0)
; #define PG8_MMA(ai, bj, At, Bt_) do { __builtin_amdgcn_s_setprio(1); _Pragma("unroll") for (int m = 0; m < 4; ++m) _Pragma("unroll") for (int n = 0; n < 2; ++n) _Pragma("unroll") for (int k = 0; k < 2; ++k) \
;         acc[ai][bj][m][n] = __builtin_amdgcn_mfma_f32_16x16x32_bf16(Bt_[n][k], At[m][k], acc[ai][bj][m][n], 0, 0, 0); __builtin_amdgcn_s_setprio(0); } while (0)
; #define PG8_WAIT_V(n) asm volatile("s_waitcnt vmcnt(" #n ")" ::: "memory")
; #define PG8_WAIT_L(n) asm volatile("s_waitcnt lgkmcnt(" #n ")" ::: "memory")
; #define PG8_BAR __builtin_amdgcn_s_barrier()
; #define PG8_SCHED __builtin_amdgcn_sched_barrier(0)
; template <int EK, int SK = -1>
; __device__ __forceinline__ void gemm_phase(LAS unsigned char* lds, const bf16_t* A, const bf16_t* Bt, int nM, int N, int K, const EpiArgs& E) {
;     ...
;             PG8_WAIT_V(8); PG8_WAIT_L(0); PG8_BAR; PG8_MMA(0, 0, At, B0); PG8_MMA(0, 1, At, B1); PG8_BAR; PG8_SCHED;
;             PG8_LDA(At, 0, 1); PG8_STAGEB(PG8_SB(0, 0), b2); PG8_STAGEB(PG8_SB(0, 1), b2 + hstep); PG8_STAGEA(PG8_SA(0, 0), a2);
;             PG8_WAIT_V(8); PG8_WAIT_L(0); PG8_BAR; PG8_MMA(1, 0, At, B0); PG8_MMA(1, 1, At, B1); PG8_BAR; PG8_SCHED;
	s_waitcnt lgkmcnt(0)
	v_mfma_f32_16x16x32_bf16 v[110:113], v[150:153], v[190:193], v[110:113]
	v_mfma_f32_16x16x32_bf16 v[102:105], v[150:153], v[198:201], v[102:105]
	v_mfma_f32_16x16x32_bf16 v[94:97], v[150:153], v[206:209], v[94:97]
	v_mfma_f32_16x16x32_bf16 v[86:89], v[150:153], v[214:217], v[86:89]
	v_mfma_f32_16x16x32_bf16 v[82:85], v[166:169], v[214:217], v[82:85]
	v_mfma_f32_16x16x32_bf16 v[90:93], v[166:169], v[206:209], v[90:93]
	v_mfma_f32_16x16x32_bf16 v[98:101], v[166:169], v[198:201], v[98:101]
	v_mfma_f32_16x16x32_bf16 v[106:109], v[166:169], v[190:193], v[106:109]
	v_mfma_f32_16x16x32_bf16 v[110:113], v[154:157], v[194:197], v[110:113]
	v_mfma_f32_16x16x32_bf16 v[102:105], v[154:157], v[202:205], v[102:105]
	v_mfma_f32_16x16x32_bf16 v[94:97], v[154:157], v[210:213], v[94:97]
	v_mfma_f32_16x16x32_bf16 v[86:89], v[154:157], v[218:221], v[86:89]
	v_mfma_f32_16x16x32_bf16 v[82:85], v[170:173], v[218:221], v[82:85]
	v_mfma_f32_16x16x32_bf16 v[90:93], v[170:173], v[210:213], v[90:93]
	v_mfma_f32_16x16x32_bf16 v[98:101], v[170:173], v[202:205], v[98:101]
	v_mfma_f32_16x16x32_bf16 v[106:109], v[170:173], v[194:197], v[106:109]
	v_mfma_f32_16x16x32_bf16 v[78:81], v[174:177], v[190:193], v[78:81]
	v_mfma_f32_16x16x32_bf16 v[70:73], v[174:177], v[198:201], v[70:73]
	v_mfma_f32_16x16x32_bf16 v[62:65], v[174:177], v[206:209], v[62:65]
	v_mfma_f32_16x16x32_bf16 v[54:57], v[174:177], v[214:217], v[54:57]
	v_mfma_f32_16x16x32_bf16 v[50:53], v[182:185], v[214:217], v[50:53]
	v_mfma_f32_16x16x32_bf16 v[58:61], v[182:185], v[206:209], v[58:61]
	v_mfma_f32_16x16x32_bf16 v[66:69], v[182:185], v[198:201], v[66:69]
	v_mfma_f32_16x16x32_bf16 v[74:77], v[182:185], v[190:193], v[74:77]
	v_mfma_f32_16x16x32_bf16 v[78:81], v[178:181], v[194:197], v[78:81]
	v_mfma_f32_16x16x32_bf16 v[70:73], v[178:181], v[202:205], v[70:73]
	v_mfma_f32_16x16x32_bf16 v[62:65], v[178:181], v[210:213], v[62:65]
	v_mfma_f32_16x16x32_bf16 v[54:57], v[178:181], v[218:221], v[54:57]
	v_mfma_f32_16x16x32_bf16 v[50:53], v[186:189], v[218:221], v[50:53]
	v_mfma_f32_16x16x32_bf16 v[58:61], v[186:189], v[210:213], v[58:61]
	v_mfma_f32_16x16x32_bf16 v[66:69], v[186:189], v[202:205], v[66:69]
	v_mfma_f32_16x16x32_bf16 v[74:77], v[186:189], v[194:197], v[74:77]
	s_barrier
	s_add_i32 s90, s82, s53
	v_lshl_add_u64 v[158:159], s[76:77], 0, v[132:133]
	s_mov_b32 m0, s90
	ds_read_b128 v[190:193], v163 offset:16384
	ds_read_b128 v[194:197], v163 offset:17408
	ds_read_b128 v[198:201], v163 offset:18432
	ds_read_b128 v[202:205], v163 offset:19456
	ds_read_b128 v[206:209], v163 offset:20480
	ds_read_b128 v[210:213], v163 offset:21504
	ds_read_b128 v[214:217], v163 offset:22528
	ds_read_b128 v[218:221], v163 offset:23552
	global_load_lds_dwordx4 v[158:159], off
	s_add_i32 m0, s90, 0x2000
	s_add_u32 s90, s76, 0x40000
	v_lshl_add_u64 v[222:223], s[76:77], 0, v[136:137]
	s_addc_u32 s91, s77, 0
	s_add_i32 s92, s83, s53
	global_load_lds_dwordx4 v[222:223], off
	v_lshl_add_u64 v[224:225], s[90:91], 0, v[132:133]
	s_mov_b32 m0, s92
	v_lshl_add_u64 v[226:227], s[78:79], 0, v[134:135]
	global_load_lds_dwordx4 v[224:225], off
	v_lshl_add_u64 v[224:225], s[90:91], 0, v[136:137]
	s_add_i32 m0, s92, 0x2000
	s_nop 0
	global_load_lds_dwordx4 v[224:225], off
	v_lshl_add_u64 v[224:225], s[78:79], 0, v[130:131]
	s_mov_b32 m0, s23
	s_nop 0
	global_load_lds_dwordx4 v[224:225], off
	s_mov_b32 m0, s27
	s_nop 0
	global_load_lds_dwordx4 v[226:227], off
	s_waitcnt vmcnt(8)
	s_waitcnt lgkmcnt(0)
	s_barrier
	s_waitcnt lgkmcnt(0)
	v_mfma_f32_16x16x32_bf16 v[46:49], v[150:153], v[190:193], v[46:49]
	v_mfma_f32_16x16x32_bf16 v[38:41], v[150:153], v[198:201], v[38:41]
	v_mfma_f32_16x16x32_bf16 v[30:33], v[150:153], v[206:209], v[30:33]
	v_mfma_f32_16x16x32_bf16 v[22:25], v[150:153], v[214:217], v[22:25]
	v_mfma_f32_16x16x32_bf16 v[18:21], v[166:169], v[214:217], v[18:21]
	v_mfma_f32_16x16x32_bf16 v[26:29], v[166:169], v[206:209], v[26:29]
	v_mfma_f32_16x16x32_bf16 v[34:37], v[166:169], v[198:201], v[34:37]
	v_mfma_f32_16x16x32_bf16 v[42:45], v[166:169], v[190:193], v[42:45]
	v_mfma_f32_16x16x32_bf16 v[46:49], v[154:157], v[194:197], v[46:49]
	v_mfma_f32_16x16x32_bf16 v[38:41], v[154:157], v[202:205], v[38:41]
	v_mfma_f32_16x16x32_bf16 v[30:33], v[154:157], v[210:213], v[30:33]
	v_mfma_f32_16x16x32_bf16 v[22:25], v[154:157], v[218:221], v[22:25]
	v_mfma_f32_16x16x32_bf16 v[18:21], v[170:173], v[218:221], v[18:21]
	v_mfma_f32_16x16x32_bf16 v[26:29], v[170:173], v[210:213], v[26:29]
	v_mfma_f32_16x16x32_bf16 v[34:37], v[170:173], v[202:205], v[34:37]
	v_mfma_f32_16x16x32_bf16 v[42:45], v[170:173], v[194:197], v[42:45]
	v_mfma_f32_16x16x32_bf16 v[14:17], v[174:177], v[190:193], v[14:17]
	v_mfma_f32_16x16x32_bf16 v[6:9], v[174:177], v[198:201], v[6:9]
	v_mfma_f32_16x16x32_bf16 v[114:117], v[174:177], v[206:209], v[114:117]
	v_mfma_f32_16x16x32_bf16 v[122:125], v[174:177], v[214:217], v[122:125]
	v_mfma_f32_16x16x32_bf16 v[126:129], v[182:185], v[214:217], v[126:129]
	v_mfma_f32_16x16x32_bf16 v[118:121], v[182:185], v[206:209], v[118:121]
	v_mfma_f32_16x16x32_bf16 v[2:5], v[182:185], v[198:201], v[2:5]
	v_mfma_f32_16x16x32_bf16 v[10:13], v[182:185], v[190:193], v[10:13]
	v_mfma_f32_16x16x32_bf16 v[14:17], v[178:181], v[194:197], v[14:17]
	v_mfma_f32_16x16x32_bf16 v[6:9], v[178:181], v[202:205], v[6:9]
	v_mfma_f32_16x16x32_bf16 v[114:117], v[178:181], v[210:213], v[114:117]
	v_mfma_f32_16x16x32_bf16 v[122:125], v[178:181], v[218:221], v[122:125]
	v_mfma_f32_16x16x32_bf16 v[126:129], v[186:189], v[218:221], v[126:129]
	v_mfma_f32_16x16x32_bf16 v[118:121], v[186:189], v[210:213], v[118:121]
	v_mfma_f32_16x16x32_bf16 v[2:5], v[186:189], v[202:205], v[2:5]
	v_mfma_f32_16x16x32_bf16 v[10:13], v[186:189], v[194:197], v[10:13]
	s_barrier
; #define PG8_STAGEA(bufoff, gbase) PG8_STAGE_(bufoff, gbase, voffA)
; #define PG8_STAGEB(bufoff, gbase) PG8_STAGE_(bufoff, gbase, voffB)
; #define PG8_LDA(dst, b, h) do { _Pragma("unroll") for (int m = 0; m < 4; ++m) _Pragma("unroll") for (int k = 0; k < 2; ++k) dst[m][k] = *(const LAS bf16x8*)(lds + PG8_SA(b, h) + aoff + m * 2048 + k * 1024); } while (0)
; #define PG8_LDB(dst, b, h) do { _Pragma("unroll") for (int n = 0; n < 2; ++n) _Pragma("unroll") for (int k = 0; k < 2; ++k) dst[n][k] = *(const LAS bf16x8*)(lds + PG8_SB(b, h) + boff + n * 2048 + k * 1024); } while (0)
; #define PG8_MMA(ai, bj, At, Bt_) do { __builtin_amdgcn_s_setprio(1); _Pragma("unroll") for (int m = 0; m < 4; ++m) _Pragma("unroll") for (int n = 0; n < 2; ++n) _Pragma("unroll") for (int k = 0; k < 2; ++k) \
;         acc[ai][bj][m][n] = __builtin_amdgcn_mfma_f32_16x16x32_bf16(Bt_[n][k], At[m][k], acc[ai][bj][m][n], 0, 0, 0); __builtin_amdgcn_s_setprio(0); } while (0)
; #define PG8_WAIT_V(n) asm volatile("s_waitcnt vmcnt(" #n ")" ::: "memory")
; #define PG8_WAIT_L(n) asm volatile("s_waitcnt lgkmcnt(" #n ")" ::: "memory")
; #define PG8_BAR __builtin_amdgcn_s_barrier()
; #define PG8_SCHED __builtin_amdgcn_sched_barrier(0)
; template <int EK, int SK = -1>
; __device__ __forceinline__ void gemm_phase(LAS unsigned char* lds, const bf16_t* A, const bf16_t* Bt, int nM, int N, int K, const EpiArgs& E) {
;     ...
;             PG8_LDB(B0, 1, 0); PG8_LDB(B1, 1, 1); PG8_SCHED; PG8_LDA(At, 1, 0); PG8_STAGEA(PG8_SA(0, 1), a2 + hstep);
;             PG8_WAIT_V(8); PG8_WAIT_L(0); PG8_BAR; PG8_MMA(0, 0, At, B0); PG8_MMA(0, 1, At, B1); PG8_BAR; PG8_SCHED;
;             PG8_LDA(At, 1, 1); PG8_STAGEB(PG8_SB(1, 0), b3); PG8_STAGEB(PG8_SB(1, 1), b3 + hstep); PG8_STAGEA(PG8_SA(1, 0), a3);
;             PG8_WAIT_V(8); PG8_WAIT_L(0); PG8_BAR; PG8_MMA(1, 0, At, B0); PG8_MMA(1, 1, At, B1); PG8_BAR; PG8_SCHED;
;         }
	s_add_i32 s90, 0, 0x18000
	v_add_u32_e32 v165, s90, v160
	s_add_i32 s91, 0, 0x1c000
	ds_read_b128 v[150:153], v165
	ds_read_b128 v[154:157], v165 offset:1024
	ds_read_b128 v[166:169], v165 offset:2048
	ds_read_b128 v[170:173], v165 offset:3072
	v_add_u32_e32 v165, s91, v160
	ds_read_b128 v[174:177], v165
	ds_read_b128 v[178:181], v165 offset:1024
	ds_read_b128 v[182:185], v165 offset:2048
	ds_read_b128 v[186:189], v165 offset:3072
	s_add_u32 s78, s78, 0x40000
	s_addc_u32 s79, s79, 0
	s_mov_b32 m0, s55
	v_lshl_add_u64 v[228:229], s[78:79], 0, v[130:131]
	ds_read_b128 v[190:193], v163 offset:32768
	ds_read_b128 v[194:197], v163 offset:33792
	ds_read_b128 v[198:201], v163 offset:34816
	ds_read_b128 v[202:205], v163 offset:35840
	ds_read_b128 v[206:209], v163 offset:36864
	ds_read_b128 v[210:213], v163 offset:37888
	ds_read_b128 v[214:217], v163 offset:38912
	ds_read_b128 v[218:221], v163 offset:39936
	global_load_lds_dwordx4 v[228:229], off
	v_lshl_add_u64 v[228:229], s[78:79], 0, v[134:135]
	s_mov_b32 m0, s57
	s_nop 0
	global_load_lds_dwordx4 v[228:229], off
	s_waitcnt vmcnt(8)
	s_waitcnt lgkmcnt(0)
	s_barrier
	s_waitcnt lgkmcnt(0)
	v_mfma_f32_16x16x32_bf16 v[110:113], v[150:153], v[190:193], v[110:113]
	v_mfma_f32_16x16x32_bf16 v[102:105], v[150:153], v[198:201], v[102:105]
	v_mfma_f32_16x16x32_bf16 v[94:97], v[150:153], v[206:209], v[94:97]
	v_mfma_f32_16x16x32_bf16 v[86:89], v[150:153], v[214:217], v[86:89]
	v_mfma_f32_16x16x32_bf16 v[82:85], v[166:169], v[214:217], v[82:85]
	v_mfma_f32_16x16x32_bf16 v[90:93], v[166:169], v[206:209], v[90:93]
	v_mfma_f32_16x16x32_bf16 v[98:101], v[166:169], v[198:201], v[98:101]
	v_mfma_f32_16x16x32_bf16 v[106:109], v[166:169], v[190:193], v[106:109]
	v_mfma_f32_16x16x32_bf16 v[110:113], v[154:157], v[194:197], v[110:113]
	v_mfma_f32_16x16x32_bf16 v[102:105], v[154:157], v[202:205], v[102:105]
	v_mfma_f32_16x16x32_bf16 v[94:97], v[154:157], v[210:213], v[94:97]
	v_mfma_f32_16x16x32_bf16 v[86:89], v[154:157], v[218:221], v[86:89]
	v_mfma_f32_16x16x32_bf16 v[82:85], v[170:173], v[218:221], v[82:85]
	v_mfma_f32_16x16x32_bf16 v[90:93], v[170:173], v[210:213], v[90:93]
	v_mfma_f32_16x16x32_bf16 v[98:101], v[170:173], v[202:205], v[98:101]
	v_mfma_f32_16x16x32_bf16 v[106:109], v[170:173], v[194:197], v[106:109]
	v_mfma_f32_16x16x32_bf16 v[78:81], v[174:177], v[190:193], v[78:81]
	v_mfma_f32_16x16x32_bf16 v[70:73], v[174:177], v[198:201], v[70:73]
	v_mfma_f32_16x16x32_bf16 v[62:65], v[174:177], v[206:209], v[62:65]
	v_mfma_f32_16x16x32_bf16 v[54:57], v[174:177], v[214:217], v[54:57]
	v_mfma_f32_16x16x32_bf16 v[50:53], v[182:185], v[214:217], v[50:53]
	v_mfma_f32_16x16x32_bf16 v[58:61], v[182:185], v[206:209], v[58:61]
	v_mfma_f32_16x16x32_bf16 v[66:69], v[182:185], v[198:201], v[66:69]
	v_mfma_f32_16x16x32_bf16 v[74:77], v[182:185], v[190:193], v[74:77]
	v_mfma_f32_16x16x32_bf16 v[78:81], v[178:181], v[194:197], v[78:81]
	v_mfma_f32_16x16x32_bf16 v[70:73], v[178:181], v[202:205], v[70:73]
	v_mfma_f32_16x16x32_bf16 v[62:65], v[178:181], v[210:213], v[62:65]
	v_mfma_f32_16x16x32_bf16 v[54:57], v[178:181], v[218:221], v[54:57]
	v_mfma_f32_16x16x32_bf16 v[50:53], v[186:189], v[218:221], v[50:53]
	v_mfma_f32_16x16x32_bf16 v[58:61], v[186:189], v[210:213], v[58:61]
	v_mfma_f32_16x16x32_bf16 v[66:69], v[186:189], v[202:205], v[66:69]
	v_mfma_f32_16x16x32_bf16 v[74:77], v[186:189], v[194:197], v[74:77]
	s_barrier
	s_add_i32 s78, s90, s53
	v_lshl_add_u64 v[158:159], v[158:159], 0, s[16:17]
	s_mov_b32 m0, s78
	ds_read_b128 v[190:193], v163 offset:49152
	ds_read_b128 v[194:197], v163 offset:50176
	ds_read_b128 v[198:201], v163 offset:51200
	ds_read_b128 v[202:205], v163 offset:52224
	ds_read_b128 v[206:209], v163 offset:53248
	ds_read_b128 v[210:213], v163 offset:54272
	ds_read_b128 v[214:217], v163 offset:55296
	ds_read_b128 v[218:221], v163 offset:56320
	global_load_lds_dwordx4 v[158:159], off
	s_add_i32 m0, s78, 0x2000
	s_add_u32 s76, s76, 0x40080
	v_lshl_add_u64 v[158:159], v[222:223], 0, s[16:17]
	s_addc_u32 s77, s77, 0
	s_add_i32 s78, s91, s53
	global_load_lds_dwordx4 v[158:159], off
	v_lshl_add_u64 v[158:159], s[76:77], 0, v[132:133]
	s_mov_b32 m0, s78
	s_nop 0
	global_load_lds_dwordx4 v[158:159], off
	v_lshl_add_u64 v[158:159], s[76:77], 0, v[136:137]
	s_add_i32 m0, s78, 0x2000
	s_nop 0
	global_load_lds_dwordx4 v[158:159], off
	v_lshl_add_u64 v[158:159], v[224:225], 0, s[16:17]
	s_mov_b32 m0, s80
	s_nop 0
	global_load_lds_dwordx4 v[158:159], off
	v_lshl_add_u64 v[158:159], v[226:227], 0, s[16:17]
	s_mov_b32 m0, s81
	s_nop 0
	global_load_lds_dwordx4 v[158:159], off
	s_waitcnt vmcnt(8)
	s_waitcnt lgkmcnt(0)
	s_barrier
	s_waitcnt lgkmcnt(0)
	v_mfma_f32_16x16x32_bf16 v[46:49], v[150:153], v[190:193], v[46:49]
	v_mfma_f32_16x16x32_bf16 v[38:41], v[150:153], v[198:201], v[38:41]
	v_mfma_f32_16x16x32_bf16 v[30:33], v[150:153], v[206:209], v[30:33]
	v_mfma_f32_16x16x32_bf16 v[22:25], v[150:153], v[214:217], v[22:25]
	v_mfma_f32_16x16x32_bf16 v[18:21], v[166:169], v[214:217], v[18:21]
	v_mfma_f32_16x16x32_bf16 v[26:29], v[166:169], v[206:209], v[26:29]
	v_mfma_f32_16x16x32_bf16 v[34:37], v[166:169], v[198:201], v[34:37]
	v_mfma_f32_16x16x32_bf16 v[42:45], v[166:169], v[190:193], v[42:45]
	v_mfma_f32_16x16x32_bf16 v[46:49], v[154:157], v[194:197], v[46:49]
	v_mfma_f32_16x16x32_bf16 v[38:41], v[154:157], v[202:205], v[38:41]
	v_mfma_f32_16x16x32_bf16 v[30:33], v[154:157], v[210:213], v[30:33]
	v_mfma_f32_16x16x32_bf16 v[22:25], v[154:157], v[218:221], v[22:25]
	v_mfma_f32_16x16x32_bf16 v[18:21], v[170:173], v[218:221], v[18:21]
	v_mfma_f32_16x16x32_bf16 v[26:29], v[170:173], v[210:213], v[26:29]
	v_mfma_f32_16x16x32_bf16 v[34:37], v[170:173], v[202:205], v[34:37]
	v_mfma_f32_16x16x32_bf16 v[42:45], v[170:173], v[194:197], v[42:45]
	v_mfma_f32_16x16x32_bf16 v[14:17], v[174:177], v[190:193], v[14:17]
	v_mfma_f32_16x16x32_bf16 v[6:9], v[174:177], v[198:201], v[6:9]
	v_mfma_f32_16x16x32_bf16 v[114:117], v[174:177], v[206:209], v[114:117]
	v_mfma_f32_16x16x32_bf16 v[122:125], v[174:177], v[214:217], v[122:125]
	v_mfma_f32_16x16x32_bf16 v[126:129], v[182:185], v[214:217], v[126:129]
	v_mfma_f32_16x16x32_bf16 v[118:121], v[182:185], v[206:209], v[118:121]
	v_mfma_f32_16x16x32_bf16 v[2:5], v[182:185], v[198:201], v[2:5]
	v_mfma_f32_16x16x32_bf16 v[10:13], v[182:185], v[190:193], v[10:13]
	v_mfma_f32_16x16x32_bf16 v[14:17], v[178:181], v[194:197], v[14:17]
	v_mfma_f32_16x16x32_bf16 v[6:9], v[178:181], v[202:205], v[6:9]
	v_mfma_f32_16x16x32_bf16 v[114:117], v[178:181], v[210:213], v[114:117]
	v_mfma_f32_16x16x32_bf16 v[122:125], v[178:181], v[218:221], v[122:125]
	v_mfma_f32_16x16x32_bf16 v[126:129], v[186:189], v[218:221], v[126:129]
	v_mfma_f32_16x16x32_bf16 v[118:121], v[186:189], v[210:213], v[118:121]
	v_mfma_f32_16x16x32_bf16 v[2:5], v[186:189], v[202:205], v[2:5]
	v_mfma_f32_16x16x32_bf16 v[10:13], v[186:189], v[194:197], v[10:13]
	s_barrier
	s_add_i32 s89, s89, 2
	s_add_u32 s10, s10, 0x100
	s_addc_u32 s11, s11, 0
	s_cmp_gt_u32 s89, 13
	s_cbranch_scc0 .LBB0_929

; #define PG8_STAGEA(bufoff, gbase) PG8_STAGE_(bufoff, gbase, voffA)
; #define PG8_STAGEB(bufoff, gbase) PG8_STAGE_(bufoff, gbase, voffB)
; #define PG8_LDA(dst, b, h) do { _Pragma("unroll") for (int m = 0; m < 4; ++m) _Pragma("unroll") for (int k = 0; k < 2; ++k) dst[m][k] = *(const LAS bf16x8*)(lds + PG8_SA(b, h) + aoff + m * 2048 + k * 1024); } while (0)
; #define PG8_LDB(dst, b, h) do { _Pragma("unroll") for (int n = 0; n < 2; ++n) _Pragma("unroll") for (int k = 0; k < 2; ++k) dst[n][k] = *(const LAS bf16x8*)(lds + PG8_SB(b, h) + boff + n * 2048 + k * 1024); } while (0)
; #define PG8_MMA(ai, bj, At, Bt_) do { __builtin_amdgcn_s_setprio(1); _Pragma("unroll") for (int m = 0; m < 4; ++m) _Pragma("unroll") for (int n = 0; n < 2; ++n) _Pragma("unroll") for (int k = 0; k < 2; ++k) \
;         acc[ai][bj][m][n] = __builtin_amdgcn_mfma_f32_16x16x32_bf16(Bt_[n][k], At[m][k], acc[ai][bj][m][n], 0, 0, 0); __builtin_amdgcn_s_setprio(0); } while (0)
; #define PG8_WAIT_V(n) asm volatile("s_waitcnt vmcnt(" #n ")" ::: "memory")
; #define PG8_WAIT_L(n) asm volatile("s_waitcnt lgkmcnt(" #n ")" ::: "memory")
; #define PG8_BAR __builtin_amdgcn_s_barrier()
; #define PG8_SCHED __builtin_amdgcn_sched_barrier(0)
; template <int EK, int SK = -1>
; __device__ __forceinline__ void gemm_phase(LAS unsigned char* lds, const bf16_t* A, const bf16_t* Bt, int nM, int N, int K, const EpiArgs& E) {
;     ...
;         const bool has_next = S.next(ui + 1, nxt);
;         const char* nA = has_next ? (const char*)A + (size_t)nxt.pm * tstep : cA; const char* nB = has_next ? (const char*)Bt + (size_t)nxt.pn * tstep : cB;
;         for (int t = 0; t < nt; t += 2) {
;             const bool last = (t == nt - 2);
;             const char* a1 = cA + (size_t)(t + 1) * kstep;
;             const char* a2 = last ? nA : cA + (size_t)(t + 2) * kstep; const char* b2 = last ? nB : cB + (size_t)(t + 2) * kstep;
;             const char* a3 = a2 + kstep; const char* b3 = b2 + kstep;
;             PG8_LDB(B0, 0, 0); PG8_LDB(B1, 0, 1); PG8_SCHED; PG8_LDA(At, 0, 0); PG8_STAGEA(PG8_SA(1, 1), a1 + hstep);
;             PG8_WAIT_V(8); PG8_WAIT_L(0); PG8_BAR; PG8_MMA(0, 0, At, B0); PG8_MMA(0, 1, At, B1); PG8_BAR; PG8_SCHED;
;             PG8_LDA(At, 0, 1); PG8_STAGEB(PG8_SB(0, 0), b2); PG8_STAGEB(PG8_SB(0, 1), b2 + hstep); PG8_STAGEA(PG8_SA(0, 0), a2);
.LBB0_1119:
	s_add_u32 s73, s46, 0x100
	s_addc_u32 s74, s47, 0
	s_ashr_i32 s41, s40, 31
	s_lshl_b64 s[42:43], s[40:41], 19
	s_add_u32 s44, s66, s42
	s_addc_u32 s45, s67, s43
	s_and_b64 s[42:43], s[8:9], exec
	s_cselect_b32 s22, s45, s19
	s_cselect_b32 s41, s44, s18
	s_ashr_i32 s39, s38, 31
	s_lshl_b64 s[42:43], s[38:39], 19
	s_add_u32 s42, s52, s42
	s_addc_u32 s43, s53, s43
	s_and_b64 s[48:49], s[8:9], exec
	s_cselect_b32 s39, s43, s47
	s_cselect_b32 s75, s42, s46
	v_lshl_add_u64 v[146:147], s[18:19], 0, v[138:139]
	v_lshl_add_u64 v[148:149], s[18:19], 0, v[140:141]
	s_mov_b32 s76, -2
	s_mov_b64 s[46:47], 0
	v_add_u32_e32 v150, s69, v152
	ds_read_b128 v[156:159], v150
	ds_read_b128 v[160:163], v150 offset:1024
	ds_read_b128 v[164:167], v150 offset:2048
	ds_read_b128 v[168:171], v150 offset:3072
	v_add_u32_e32 v150, s70, v152
	s_add_u32 s48, s18, s46
	ds_read_b128 v[172:175], v150
	ds_read_b128 v[176:179], v150 offset:1024
	ds_read_b128 v[180:183], v150 offset:2048
	ds_read_b128 v[184:187], v150 offset:3072
	s_addc_u32 s49, s19, s47
	s_add_u32 s48, s48, 0x100
	s_addc_u32 s49, s49, 0
	s_add_u32 s77, s73, s46
	s_addc_u32 s78, s74, s47
	s_cmpk_eq_i32 s46, 0x700
	s_cselect_b32 s51, s22, s49
	s_cselect_b32 s50, s41, s48
	s_cselect_b32 s49, s39, s78
	s_cselect_b32 s48, s75, s77
	v_lshl_add_u64 v[150:151], v[146:147], 0, s[46:47]
	s_add_i32 m0, s15, 0xc000
	ds_read_b128 v[188:191], v154
	ds_read_b128 v[192:195], v154 offset:1024
	ds_read_b128 v[196:199], v154 offset:2048
	ds_read_b128 v[200:203], v154 offset:3072
	ds_read_b128 v[204:207], v154 offset:4096
	ds_read_b128 v[208:211], v154 offset:5120
	ds_read_b128 v[212:215], v154 offset:6144
	ds_read_b128 v[216:219], v154 offset:7168
	global_load_lds_dwordx4 v[150:151], off
	v_lshl_add_u64 v[150:151], v[148:149], 0, s[46:47]
	s_add_i32 m0, s15, 0xe000
	s_nop 0
	global_load_lds_dwordx4 v[150:151], off
	s_waitcnt vmcnt(8)
	s_waitcnt lgkmcnt(0)
	s_barrier
	s_waitcnt lgkmcnt(0)
	v_mfma_f32_16x16x32_bf16 v[126:129], v[156:159], v[188:191], 0
	v_mfma_f32_16x16x32_bf16 v[118:121], v[156:159], v[196:199], 0
	v_mfma_f32_16x16x32_bf16 v[110:113], v[156:159], v[204:207], 0
	v_mfma_f32_16x16x32_bf16 v[102:105], v[156:159], v[212:215], 0
	v_mfma_f32_16x16x32_bf16 v[98:101], v[164:167], v[212:215], 0
	v_mfma_f32_16x16x32_bf16 v[106:109], v[164:167], v[204:207], 0
	v_mfma_f32_16x16x32_bf16 v[114:117], v[164:167], v[196:199], 0
	v_mfma_f32_16x16x32_bf16 v[122:125], v[164:167], v[188:191], 0
	v_mfma_f32_16x16x32_bf16 v[126:129], v[160:163], v[192:195], v[126:129]
	v_mfma_f32_16x16x32_bf16 v[118:121], v[160:163], v[200:203], v[118:121]
	v_mfma_f32_16x16x32_bf16 v[110:113], v[160:163], v[208:211], v[110:113]
	v_mfma_f32_16x16x32_bf16 v[102:105], v[160:163], v[216:219], v[102:105]
	v_mfma_f32_16x16x32_bf16 v[98:101], v[168:171], v[216:219], v[98:101]
	v_mfma_f32_16x16x32_bf16 v[106:109], v[168:171], v[208:211], v[106:109]
	v_mfma_f32_16x16x32_bf16 v[114:117], v[168:171], v[200:203], v[114:117]
	v_mfma_f32_16x16x32_bf16 v[122:125], v[168:171], v[192:195], v[122:125]
	v_mfma_f32_16x16x32_bf16 v[94:97], v[172:175], v[188:191], 0
	v_mfma_f32_16x16x32_bf16 v[86:89], v[172:175], v[196:199], 0
	v_mfma_f32_16x16x32_bf16 v[78:81], v[172:175], v[204:207], 0
	v_mfma_f32_16x16x32_bf16 v[70:73], v[172:175], v[212:215], 0
	v_mfma_f32_16x16x32_bf16 v[66:69], v[180:183], v[212:215], 0
	v_mfma_f32_16x16x32_bf16 v[74:77], v[180:183], v[204:207], 0
	v_mfma_f32_16x16x32_bf16 v[82:85], v[180:183], v[196:199], 0
	v_mfma_f32_16x16x32_bf16 v[90:93], v[180:183], v[188:191], 0
	v_mfma_f32_16x16x32_bf16 v[94:97], v[176:179], v[192:195], v[94:97]
	v_mfma_f32_16x16x32_bf16 v[86:89], v[176:179], v[200:203], v[86:89]
	v_mfma_f32_16x16x32_bf16 v[78:81], v[176:179], v[208:211], v[78:81]
	v_mfma_f32_16x16x32_bf16 v[70:73], v[176:179], v[216:219], v[70:73]
	v_mfma_f32_16x16x32_bf16 v[66:69], v[184:187], v[216:219], v[66:69]
	v_mfma_f32_16x16x32_bf16 v[74:77], v[184:187], v[208:211], v[74:77]
	v_mfma_f32_16x16x32_bf16 v[82:85], v[184:187], v[200:203], v[82:85]
	v_mfma_f32_16x16x32_bf16 v[90:93], v[184:187], v[192:195], v[90:93]
	s_barrier
	s_add_i32 s77, s69, s54
	v_lshl_add_u64 v[150:151], s[48:49], 0, v[132:133]
	s_mov_b32 m0, s77
	ds_read_b128 v[188:191], v154 offset:16384
	ds_read_b128 v[192:195], v154 offset:17408
	ds_read_b128 v[196:199], v154 offset:18432
	ds_read_b128 v[200:203], v154 offset:19456
	ds_read_b128 v[204:207], v154 offset:20480
	ds_read_b128 v[208:211], v154 offset:21504
	ds_read_b128 v[212:215], v154 offset:22528
	ds_read_b128 v[216:219], v154 offset:23552
	global_load_lds_dwordx4 v[150:151], off
	s_add_i32 m0, s77, 0x2000
	s_add_u32 s78, s48, 0x40000
	v_lshl_add_u64 v[220:221], s[48:49], 0, v[136:137]
	s_addc_u32 s79, s49, 0
	s_add_i32 s77, s70, s54
	global_load_lds_dwordx4 v[220:221], off
	v_lshl_add_u64 v[222:223], s[78:79], 0, v[132:133]
	s_mov_b32 m0, s77
	v_lshl_add_u64 v[224:225], s[50:51], 0, v[134:135]
	global_load_lds_dwordx4 v[222:223], off
	v_lshl_add_u64 v[222:223], s[78:79], 0, v[136:137]
	s_add_i32 m0, s77, 0x2000
	s_nop 0
	global_load_lds_dwordx4 v[222:223], off
	v_lshl_add_u64 v[222:223], s[50:51], 0, v[130:131]
	s_mov_b32 m0, s15
	s_nop 0
	global_load_lds_dwordx4 v[222:223], off
	s_mov_b32 m0, s17
	s_nop 0
	global_load_lds_dwordx4 v[224:225], off
	s_waitcnt vmcnt(8)
	s_waitcnt lgkmcnt(0)
	s_barrier
; #define PG8_STAGEA(bufoff, gbase) PG8_STAGE_(bufoff, gbase, voffA)
; #define PG8_LDA(dst, b, h) do { _Pragma("unroll") for (int m = 0; m < 4; ++m) _Pragma("unroll") for (int k = 0; k < 2; ++k) dst[m][k] = *(const LAS bf16x8*)(lds + PG8_SA(b, h) + aoff + m * 2048 + k * 1024); } while (0)
; #define PG8_LDB(dst, b, h) do { _Pragma("unroll") for (int n = 0; n < 2; ++n) _Pragma("unroll") for (int k = 0; k < 2; ++k) dst[n][k] = *(const LAS bf16x8*)(lds + PG8_SB(b, h) + boff + n * 2048 + k * 1024); } while (0)
; #define PG8_MMA(ai, bj, At, Bt_) do { __builtin_amdgcn_s_setprio(1); _Pragma("unroll") for (int m = 0; m < 4; ++m) _Pragma("unroll") for (int n = 0; n < 2; ++n) _Pragma("unroll") for (int k = 0; k < 2; ++k) \
;         acc[ai][bj][m][n] = __builtin_amdgcn_mfma_f32_16x16x32_bf16(Bt_[n][k], At[m][k], acc[ai][bj][m][n], 0, 0, 0); __builtin_amdgcn_s_setprio(0); } while (0)
; #define PG8_WAIT_V(n) asm volatile("s_waitcnt vmcnt(" #n ")" ::: "memory")
; #define PG8_WAIT_L(n) asm volatile("s_waitcnt lgkmcnt(" #n ")" ::: "memory")
; #define PG8_BAR __builtin_amdgcn_s_barrier()
; #define PG8_SCHED __builtin_amdgcn_sched_barrier(0)
; template <int EK, int SK = -1>
; __device__ __forceinline__ void gemm_phase(LAS unsigned char* lds, const bf16_t* A, const bf16_t* Bt, int nM, int N, int K, const EpiArgs& E) {
;     ...
;             PG8_WAIT_V(8); PG8_WAIT_L(0); PG8_BAR; PG8_MMA(1, 0, At, B0); PG8_MMA(1, 1, At, B1); PG8_BAR; PG8_SCHED;
;             PG8_LDB(B0, 1, 0); PG8_LDB(B1, 1, 1); PG8_SCHED; PG8_LDA(At, 1, 0); PG8_STAGEA(PG8_SA(0, 1), a2 + hstep);
;             PG8_WAIT_V(8); PG8_WAIT_L(0); PG8_BAR; PG8_MMA(0, 0, At, B0); PG8_MMA(0, 1, At, B1); PG8_BAR; PG8_SCHED;
	s_waitcnt lgkmcnt(0)
	v_mfma_f32_16x16x32_bf16 v[62:65], v[156:159], v[188:191], 0
	v_mfma_f32_16x16x32_bf16 v[54:57], v[156:159], v[196:199], 0
	v_mfma_f32_16x16x32_bf16 v[46:49], v[156:159], v[204:207], 0
	v_mfma_f32_16x16x32_bf16 v[38:41], v[156:159], v[212:215], 0
	v_mfma_f32_16x16x32_bf16 v[34:37], v[164:167], v[212:215], 0
	v_mfma_f32_16x16x32_bf16 v[42:45], v[164:167], v[204:207], 0
	v_mfma_f32_16x16x32_bf16 v[50:53], v[164:167], v[196:199], 0
	v_mfma_f32_16x16x32_bf16 v[58:61], v[164:167], v[188:191], 0
	v_mfma_f32_16x16x32_bf16 v[62:65], v[160:163], v[192:195], v[62:65]
	v_mfma_f32_16x16x32_bf16 v[54:57], v[160:163], v[200:203], v[54:57]
	v_mfma_f32_16x16x32_bf16 v[46:49], v[160:163], v[208:211], v[46:49]
	v_mfma_f32_16x16x32_bf16 v[38:41], v[160:163], v[216:219], v[38:41]
	v_mfma_f32_16x16x32_bf16 v[34:37], v[168:171], v[216:219], v[34:37]
	v_mfma_f32_16x16x32_bf16 v[42:45], v[168:171], v[208:211], v[42:45]
	v_mfma_f32_16x16x32_bf16 v[50:53], v[168:171], v[200:203], v[50:53]
	v_mfma_f32_16x16x32_bf16 v[58:61], v[168:171], v[192:195], v[58:61]
	v_mfma_f32_16x16x32_bf16 v[30:33], v[172:175], v[188:191], 0
	v_mfma_f32_16x16x32_bf16 v[22:25], v[172:175], v[196:199], 0
	v_mfma_f32_16x16x32_bf16 v[14:17], v[172:175], v[204:207], 0
	v_mfma_f32_16x16x32_bf16 v[6:9], v[172:175], v[212:215], 0
	v_mfma_f32_16x16x32_bf16 v[2:5], v[180:183], v[212:215], 0
	v_mfma_f32_16x16x32_bf16 v[10:13], v[180:183], v[204:207], 0
	v_mfma_f32_16x16x32_bf16 v[18:21], v[180:183], v[196:199], 0
	v_mfma_f32_16x16x32_bf16 v[26:29], v[180:183], v[188:191], 0
	v_mfma_f32_16x16x32_bf16 v[30:33], v[176:179], v[192:195], v[30:33]
	v_mfma_f32_16x16x32_bf16 v[22:25], v[176:179], v[200:203], v[22:25]
	v_mfma_f32_16x16x32_bf16 v[14:17], v[176:179], v[208:211], v[14:17]
	v_mfma_f32_16x16x32_bf16 v[6:9], v[176:179], v[216:219], v[6:9]
	v_mfma_f32_16x16x32_bf16 v[2:5], v[184:187], v[216:219], v[2:5]
	v_mfma_f32_16x16x32_bf16 v[10:13], v[184:187], v[208:211], v[10:13]
	v_mfma_f32_16x16x32_bf16 v[18:21], v[184:187], v[200:203], v[18:21]
	v_mfma_f32_16x16x32_bf16 v[26:29], v[184:187], v[192:195], v[26:29]
	s_barrier
	s_add_i32 s77, 0, 0x18000
	s_add_i32 s78, 0, 0x1c000
	v_add_u32_e32 v168, s77, v152
	v_add_u32_e32 v184, s78, v152
	ds_read_b128 v[156:159], v168
	ds_read_b128 v[160:163], v168 offset:1024
	ds_read_b128 v[164:167], v168 offset:2048
	ds_read_b128 v[168:171], v168 offset:3072
	ds_read_b128 v[172:175], v184
	ds_read_b128 v[176:179], v184 offset:1024
	ds_read_b128 v[180:183], v184 offset:2048
	ds_read_b128 v[184:187], v184 offset:3072
	s_add_u32 s50, s50, 0x40000
	s_addc_u32 s51, s51, 0
	s_mov_b32 m0, s55
	v_lshl_add_u64 v[226:227], s[50:51], 0, v[130:131]
	ds_read_b128 v[188:191], v154 offset:32768
	ds_read_b128 v[192:195], v154 offset:33792
	ds_read_b128 v[196:199], v154 offset:34816
	ds_read_b128 v[200:203], v154 offset:35840
	ds_read_b128 v[204:207], v154 offset:36864
	ds_read_b128 v[208:211], v154 offset:37888
	ds_read_b128 v[212:215], v154 offset:38912
	ds_read_b128 v[216:219], v154 offset:39936
	global_load_lds_dwordx4 v[226:227], off
	v_lshl_add_u64 v[226:227], s[50:51], 0, v[134:135]
	s_mov_b32 m0, s56
	s_nop 0
	global_load_lds_dwordx4 v[226:227], off
	s_waitcnt vmcnt(8)
	s_waitcnt lgkmcnt(0)
	s_barrier
	s_waitcnt lgkmcnt(0)
	v_mfma_f32_16x16x32_bf16 v[126:129], v[156:159], v[188:191], v[126:129]
	v_mfma_f32_16x16x32_bf16 v[118:121], v[156:159], v[196:199], v[118:121]
	v_mfma_f32_16x16x32_bf16 v[110:113], v[156:159], v[204:207], v[110:113]
	v_mfma_f32_16x16x32_bf16 v[102:105], v[156:159], v[212:215], v[102:105]
	v_mfma_f32_16x16x32_bf16 v[98:101], v[164:167], v[212:215], v[98:101]
	v_mfma_f32_16x16x32_bf16 v[106:109], v[164:167], v[204:207], v[106:109]
	v_mfma_f32_16x16x32_bf16 v[114:117], v[164:167], v[196:199], v[114:117]
	v_mfma_f32_16x16x32_bf16 v[122:125], v[164:167], v[188:191], v[122:125]
	v_mfma_f32_16x16x32_bf16 v[126:129], v[160:163], v[192:195], v[126:129]
	v_mfma_f32_16x16x32_bf16 v[118:121], v[160:163], v[200:203], v[118:121]
	v_mfma_f32_16x16x32_bf16 v[110:113], v[160:163], v[208:211], v[110:113]
	v_mfma_f32_16x16x32_bf16 v[102:105], v[160:163], v[216:219], v[102:105]
	v_mfma_f32_16x16x32_bf16 v[98:101], v[168:171], v[216:219], v[98:101]
	v_mfma_f32_16x16x32_bf16 v[106:109], v[168:171], v[208:211], v[106:109]
	v_mfma_f32_16x16x32_bf16 v[114:117], v[168:171], v[200:203], v[114:117]
	v_mfma_f32_16x16x32_bf16 v[122:125], v[168:171], v[192:195], v[122:125]
	v_mfma_f32_16x16x32_bf16 v[94:97], v[172:175], v[188:191], v[94:97]
	v_mfma_f32_16x16x32_bf16 v[86:89], v[172:175], v[196:199], v[86:89]
	v_mfma_f32_16x16x32_bf16 v[78:81], v[172:175], v[204:207], v[78:81]
	v_mfma_f32_16x16x32_bf16 v[70:73], v[172:175], v[212:215], v[70:73]
	v_mfma_f32_16x16x32_bf16 v[66:69], v[180:183], v[212:215], v[66:69]
	v_mfma_f32_16x16x32_bf16 v[74:77], v[180:183], v[204:207], v[74:77]
	v_mfma_f32_16x16x32_bf16 v[82:85], v[180:183], v[196:199], v[82:85]
	v_mfma_f32_16x16x32_bf16 v[90:93], v[180:183], v[188:191], v[90:93]
	v_mfma_f32_16x16x32_bf16 v[94:97], v[176:179], v[192:195], v[94:97]
	v_mfma_f32_16x16x32_bf16 v[86:89], v[176:179], v[200:203], v[86:89]
	v_mfma_f32_16x16x32_bf16 v[78:81], v[176:179], v[208:211], v[78:81]
	v_mfma_f32_16x16x32_bf16 v[70:73], v[176:179], v[216:219], v[70:73]
	v_mfma_f32_16x16x32_bf16 v[66:69], v[184:187], v[216:219], v[66:69]
	v_mfma_f32_16x16x32_bf16 v[74:77], v[184:187], v[208:211], v[74:77]
	v_mfma_f32_16x16x32_bf16 v[82:85], v[184:187], v[200:203], v[82:85]
	v_mfma_f32_16x16x32_bf16 v[90:93], v[184:187], v[192:195], v[90:93]
	s_barrier
; #define PG8_STAGEA(bufoff, gbase) PG8_STAGE_(bufoff, gbase, voffA)
; #define PG8_STAGEB(bufoff, gbase) PG8_STAGE_(bufoff, gbase, voffB)
; #define PG8_LDA(dst, b, h) do { _Pragma("unroll") for (int m = 0; m < 4; ++m) _Pragma("unroll") for (int k = 0; k < 2; ++k) dst[m][k] = *(const LAS bf16x8*)(lds + PG8_SA(b, h) + aoff + m * 2048 + k * 1024); } while (0)
; #define PG8_LDB(dst, b, h) do { _Pragma("unroll") for (int n = 0; n < 2; ++n) _Pragma("unroll") for (int k = 0; k < 2; ++k) dst[n][k] = *(const LAS bf16x8*)(lds + PG8_SB(b, h) + boff + n * 2048 + k * 1024); } while (0)
; #define PG8_MMA(ai, bj, At, Bt_) do { __builtin_amdgcn_s_setprio(1); _Pragma("unroll") for (int m = 0; m < 4; ++m) _Pragma("unroll") for (int n = 0; n < 2; ++n) _Pragma("unroll") for (int k = 0; k < 2; ++k) \
;         acc[ai][bj][m][n] = __builtin_amdgcn_mfma_f32_16x16x32_bf16(Bt_[n][k], At[m][k], acc[ai][bj][m][n], 0, 0, 0); __builtin_amdgcn_s_setprio(0); } while (0)
; #define PG8_WAIT_V(n) asm volatile("s_waitcnt vmcnt(" #n ")" ::: "memory")
; #define PG8_WAIT_L(n) asm volatile("s_waitcnt lgkmcnt(" #n ")" ::: "memory")
; #define PG8_BAR __builtin_amdgcn_s_barrier()
; #define PG8_SCHED __builtin_amdgcn_sched_barrier(0)
; template <int EK, int SK = -1>
; __device__ __forceinline__ void gemm_phase(LAS unsigned char* lds, const bf16_t* A, const bf16_t* Bt, int nM, int N, int K, const EpiArgs& E) {
;     ...
;             PG8_LDB(B0, 0, 0); PG8_LDB(B1, 0, 1); PG8_SCHED; PG8_LDA(At, 0, 0); PG8_STAGEA(PG8_SA(1, 1), a1 + hstep);
;             PG8_WAIT_V(8); PG8_WAIT_L(0); PG8_BAR; PG8_MMA(0, 0, At, B0); PG8_MMA(0, 1, At, B1); PG8_BAR; PG8_SCHED;
;             PG8_LDA(At, 0, 1); PG8_STAGEB(PG8_SB(0, 0), b2); PG8_STAGEB(PG8_SB(0, 1), b2 + hstep); PG8_STAGEA(PG8_SA(0, 0), a2);
;             PG8_WAIT_V(8); PG8_WAIT_L(0); PG8_BAR; PG8_MMA(1, 0, At, B0); PG8_MMA(1, 1, At, B1); PG8_BAR; PG8_SCHED;
;             PG8_LDB(B0, 1, 0); PG8_LDB(B1, 1, 1); PG8_SCHED; PG8_LDA(At, 1, 0); PG8_STAGEA(PG8_SA(0, 1), a2 + hstep);
;             PG8_WAIT_V(8); PG8_WAIT_L(0); PG8_BAR; PG8_MMA(0, 0, At, B0); PG8_MMA(0, 1, At, B1); PG8_BAR; PG8_SCHED;
;             PG8_LDA(At, 1, 1); PG8_STAGEB(PG8_SB(1, 0), b3); PG8_STAGEB(PG8_SB(1, 1), b3 + hstep); PG8_STAGEA(PG8_SA(1, 0), a3);
;             PG8_WAIT_V(8); PG8_WAIT_L(0); PG8_BAR; PG8_MMA(1, 0, At, B0); PG8_MMA(1, 1, At, B1); PG8_BAR; PG8_SCHED;
;         }
	s_add_i32 s50, s77, s54
	v_lshl_add_u64 v[150:151], v[150:151], 0, s[26:27]
	s_mov_b32 m0, s50
	ds_read_b128 v[188:191], v154 offset:49152
	ds_read_b128 v[192:195], v154 offset:50176
	ds_read_b128 v[196:199], v154 offset:51200
	ds_read_b128 v[200:203], v154 offset:52224
	ds_read_b128 v[204:207], v154 offset:53248
	ds_read_b128 v[208:211], v154 offset:54272
	ds_read_b128 v[212:215], v154 offset:55296
	ds_read_b128 v[216:219], v154 offset:56320
	global_load_lds_dwordx4 v[150:151], off
	s_add_i32 m0, s50, 0x2000
	s_add_u32 s48, s48, 0x40080
	v_lshl_add_u64 v[150:151], v[220:221], 0, s[26:27]
	s_addc_u32 s49, s49, 0
	s_add_i32 s50, s78, s54
	global_load_lds_dwordx4 v[150:151], off
	v_lshl_add_u64 v[150:151], s[48:49], 0, v[132:133]
	s_mov_b32 m0, s50
	s_nop 0
	global_load_lds_dwordx4 v[150:151], off
	v_lshl_add_u64 v[150:151], s[48:49], 0, v[136:137]
	s_add_i32 m0, s50, 0x2000
	s_nop 0
	global_load_lds_dwordx4 v[150:151], off
	v_lshl_add_u64 v[150:151], v[222:223], 0, s[26:27]
	s_mov_b32 m0, s59
	s_nop 0
	global_load_lds_dwordx4 v[150:151], off
	v_lshl_add_u64 v[150:151], v[224:225], 0, s[26:27]
	s_mov_b32 m0, s68
	s_nop 0
	global_load_lds_dwordx4 v[150:151], off
	s_waitcnt vmcnt(8)
	s_waitcnt lgkmcnt(0)
	s_barrier
	s_waitcnt lgkmcnt(0)
	v_mfma_f32_16x16x32_bf16 v[62:65], v[156:159], v[188:191], v[62:65]
	v_mfma_f32_16x16x32_bf16 v[54:57], v[156:159], v[196:199], v[54:57]
	v_mfma_f32_16x16x32_bf16 v[46:49], v[156:159], v[204:207], v[46:49]
	v_mfma_f32_16x16x32_bf16 v[38:41], v[156:159], v[212:215], v[38:41]
	v_mfma_f32_16x16x32_bf16 v[34:37], v[164:167], v[212:215], v[34:37]
	v_mfma_f32_16x16x32_bf16 v[42:45], v[164:167], v[204:207], v[42:45]
	v_mfma_f32_16x16x32_bf16 v[50:53], v[164:167], v[196:199], v[50:53]
	v_mfma_f32_16x16x32_bf16 v[58:61], v[164:167], v[188:191], v[58:61]
	v_mfma_f32_16x16x32_bf16 v[62:65], v[160:163], v[192:195], v[62:65]
	v_mfma_f32_16x16x32_bf16 v[54:57], v[160:163], v[200:203], v[54:57]
	v_mfma_f32_16x16x32_bf16 v[46:49], v[160:163], v[208:211], v[46:49]
	v_mfma_f32_16x16x32_bf16 v[38:41], v[160:163], v[216:219], v[38:41]
	v_mfma_f32_16x16x32_bf16 v[34:37], v[168:171], v[216:219], v[34:37]
	v_mfma_f32_16x16x32_bf16 v[42:45], v[168:171], v[208:211], v[42:45]
	v_mfma_f32_16x16x32_bf16 v[50:53], v[168:171], v[200:203], v[50:53]
	v_mfma_f32_16x16x32_bf16 v[58:61], v[168:171], v[192:195], v[58:61]
	v_mfma_f32_16x16x32_bf16 v[30:33], v[172:175], v[188:191], v[30:33]
	v_mfma_f32_16x16x32_bf16 v[22:25], v[172:175], v[196:199], v[22:25]
	v_mfma_f32_16x16x32_bf16 v[14:17], v[172:175], v[204:207], v[14:17]
	v_mfma_f32_16x16x32_bf16 v[6:9], v[172:175], v[212:215], v[6:9]
	v_mfma_f32_16x16x32_bf16 v[2:5], v[180:183], v[212:215], v[2:5]
	v_mfma_f32_16x16x32_bf16 v[10:13], v[180:183], v[204:207], v[10:13]
	v_mfma_f32_16x16x32_bf16 v[18:21], v[180:183], v[196:199], v[18:21]
	v_mfma_f32_16x16x32_bf16 v[26:29], v[180:183], v[188:191], v[26:29]
	v_mfma_f32_16x16x32_bf16 v[30:33], v[176:179], v[192:195], v[30:33]
	v_mfma_f32_16x16x32_bf16 v[22:25], v[176:179], v[200:203], v[22:25]
	v_mfma_f32_16x16x32_bf16 v[14:17], v[176:179], v[208:211], v[14:17]
	v_mfma_f32_16x16x32_bf16 v[6:9], v[176:179], v[216:219], v[6:9]
	v_mfma_f32_16x16x32_bf16 v[2:5], v[184:187], v[216:219], v[2:5]
	v_mfma_f32_16x16x32_bf16 v[10:13], v[184:187], v[208:211], v[10:13]
	v_mfma_f32_16x16x32_bf16 v[18:21], v[184:187], v[200:203], v[18:21]
	v_mfma_f32_16x16x32_bf16 v[26:29], v[184:187], v[192:195], v[26:29]
	s_barrier
	s_add_i32 s76, s76, 2
	s_add_u32 s46, s46, 0x100
	s_addc_u32 s47, s47, 0
	s_cmp_gt_u32 s76, 13
	s_cbranch_scc0 .LBB0_1120
	s_branch .Lmy_kexit_5
.LBB0_1120:
	v_add_u32_e32 v150, s69, v152
	ds_read_b128 v[156:159], v150
	ds_read_b128 v[160:163], v150 offset:1024
	ds_read_b128 v[164:167], v150 offset:2048
	ds_read_b128 v[168:171], v150 offset:3072
	v_add_u32_e32 v150, s70, v152
	s_add_u32 s48, s18, s46
	ds_read_b128 v[172:175], v150
	ds_read_b128 v[176:179], v150 offset:1024
	ds_read_b128 v[180:183], v150 offset:2048
	ds_read_b128 v[184:187], v150 offset:3072
	s_addc_u32 s49, s19, s47
	s_add_u32 s48, s48, 0x100
	s_addc_u32 s49, s49, 0
	s_add_u32 s77, s73, s46
	s_addc_u32 s78, s74, s47
	s_cmpk_eq_i32 s46, 0x700
	s_cselect_b32 s51, s22, s49
	s_cselect_b32 s50, s41, s48
	s_cselect_b32 s49, s39, s78
	s_cselect_b32 s48, s75, s77
	v_lshl_add_u64 v[150:151], v[146:147], 0, s[46:47]
	s_add_i32 m0, s15, 0xc000
	ds_read_b128 v[188:191], v154
	ds_read_b128 v[192:195], v154 offset:1024
	ds_read_b128 v[196:199], v154 offset:2048
	ds_read_b128 v[200:203], v154 offset:3072
	ds_read_b128 v[204:207], v154 offset:4096
	ds_read_b128 v[208:211], v154 offset:5120
	ds_read_b128 v[212:215], v154 offset:6144
	ds_read_b128 v[216:219], v154 offset:7168
	global_load_lds_dwordx4 v[150:151], off
	v_lshl_add_u64 v[150:151], v[148:149], 0, s[46:47]
	s_add_i32 m0, s15, 0xe000
	s_nop 0
	global_load_lds_dwordx4 v[150:151], off
	s_waitcnt vmcnt(8)
	s_waitcnt lgkmcnt(0)
	s_barrier
; #define PG8_STAGEA(bufoff, gbase) PG8_STAGE_(bufoff, gbase, voffA)
; #define PG8_STAGEB(bufoff, gbase) PG8_STAGE_(bufoff, gbase, voffB)
; #define PG8_LDA(dst, b, h) do { _Pragma("unroll") for (int m = 0; m < 4; ++m) _Pragma("unroll") for (int k = 0; k < 2; ++k) dst[m][k] = *(const LAS bf16x8*)(lds + PG8_SA(b, h) + aoff + m * 2048 + k * 1024); } while (0)
; #define PG8_MMA(ai, bj, At, Bt_) do { __builtin_amdgcn_s_setprio(1); _Pragma("unroll") for (int m = 0; m < 4; ++m) _Pragma("unroll") for (int n = 0; n < 2; ++n) _Pragma("unroll") for (int k = 0; k < 2; ++k) \
;         acc[ai][bj][m][n] = __builtin_amdgcn_mfma_f32_16x16x32_bf16(Bt_[n][k], At[m][k], acc[ai][bj][m][n], 0, 0, 0); __builtin_amdgcn_s_setprio(0); } while (0)
; #define PG8_WAIT_V(n) asm volatile("s_waitcnt vmcnt(" #n ")" ::: "memory")
; #define PG8_WAIT_L(n) asm volatile("s_waitcnt lgkmcnt(" #n ")" ::: "memory")
; #define PG8_BAR __builtin_amdgcn_s_barrier()
; #define PG8_SCHED __builtin_amdgcn_sched_barrier(0)
; template <int EK, int SK = -1>
; __device__ __forceinline__ void gemm_phase(LAS unsigned char* lds, const bf16_t* A, const bf16_t* Bt, int nM, int N, int K, const EpiArgs& E) {
;     ...
;             PG8_WAIT_V(8); PG8_WAIT_L(0); PG8_BAR; PG8_MMA(0, 0, At, B0); PG8_MMA(0, 1, At, B1); PG8_BAR; PG8_SCHED;
;             PG8_LDA(At, 0, 1); PG8_STAGEB(PG8_SB(0, 0), b2); PG8_STAGEB(PG8_SB(0, 1), b2 + hstep); PG8_STAGEA(PG8_SA(0, 0), a2);
;             PG8_WAIT_V(8); PG8_WAIT_L(0); PG8_BAR; PG8_MMA(1, 0, At, B0); PG8_MMA(1, 1, At, B1); PG8_BAR; PG8_SCHED;
	s_waitcnt lgkmcnt(0)
	v_mfma_f32_16x16x32_bf16 v[126:129], v[156:159], v[188:191], v[126:129]
	v_mfma_f32_16x16x32_bf16 v[118:121], v[156:159], v[196:199], v[118:121]
	v_mfma_f32_16x16x32_bf16 v[110:113], v[156:159], v[204:207], v[110:113]
	v_mfma_f32_16x16x32_bf16 v[102:105], v[156:159], v[212:215], v[102:105]
	v_mfma_f32_16x16x32_bf16 v[98:101], v[164:167], v[212:215], v[98:101]
	v_mfma_f32_16x16x32_bf16 v[106:109], v[164:167], v[204:207], v[106:109]
	v_mfma_f32_16x16x32_bf16 v[114:117], v[164:167], v[196:199], v[114:117]
	v_mfma_f32_16x16x32_bf16 v[122:125], v[164:167], v[188:191], v[122:125]
	v_mfma_f32_16x16x32_bf16 v[126:129], v[160:163], v[192:195], v[126:129]
	v_mfma_f32_16x16x32_bf16 v[118:121], v[160:163], v[200:203], v[118:121]
	v_mfma_f32_16x16x32_bf16 v[110:113], v[160:163], v[208:211], v[110:113]
	v_mfma_f32_16x16x32_bf16 v[102:105], v[160:163], v[216:219], v[102:105]
	v_mfma_f32_16x16x32_bf16 v[98:101], v[168:171], v[216:219], v[98:101]
	v_mfma_f32_16x16x32_bf16 v[106:109], v[168:171], v[208:211], v[106:109]
	v_mfma_f32_16x16x32_bf16 v[114:117], v[168:171], v[200:203], v[114:117]
	v_mfma_f32_16x16x32_bf16 v[122:125], v[168:171], v[192:195], v[122:125]
	v_mfma_f32_16x16x32_bf16 v[94:97], v[172:175], v[188:191], v[94:97]
	v_mfma_f32_16x16x32_bf16 v[86:89], v[172:175], v[196:199], v[86:89]
	v_mfma_f32_16x16x32_bf16 v[78:81], v[172:175], v[204:207], v[78:81]
	v_mfma_f32_16x16x32_bf16 v[70:73], v[172:175], v[212:215], v[70:73]
	v_mfma_f32_16x16x32_bf16 v[66:69], v[180:183], v[212:215], v[66:69]
	v_mfma_f32_16x16x32_bf16 v[74:77], v[180:183], v[204:207], v[74:77]
	v_mfma_f32_16x16x32_bf16 v[82:85], v[180:183], v[196:199], v[82:85]
	v_mfma_f32_16x16x32_bf16 v[90:93], v[180:183], v[188:191], v[90:93]
	v_mfma_f32_16x16x32_bf16 v[94:97], v[176:179], v[192:195], v[94:97]
	v_mfma_f32_16x16x32_bf16 v[86:89], v[176:179], v[200:203], v[86:89]
	v_mfma_f32_16x16x32_bf16 v[78:81], v[176:179], v[208:211], v[78:81]
	v_mfma_f32_16x16x32_bf16 v[70:73], v[176:179], v[216:219], v[70:73]
	v_mfma_f32_16x16x32_bf16 v[66:69], v[184:187], v[216:219], v[66:69]
	v_mfma_f32_16x16x32_bf16 v[74:77], v[184:187], v[208:211], v[74:77]
	v_mfma_f32_16x16x32_bf16 v[82:85], v[184:187], v[200:203], v[82:85]
	v_mfma_f32_16x16x32_bf16 v[90:93], v[184:187], v[192:195], v[90:93]
	s_barrier
	s_add_i32 s77, s69, s54
	v_lshl_add_u64 v[150:151], s[48:49], 0, v[132:133]
	s_mov_b32 m0, s77
	ds_read_b128 v[188:191], v154 offset:16384
	ds_read_b128 v[192:195], v154 offset:17408
	ds_read_b128 v[196:199], v154 offset:18432
	ds_read_b128 v[200:203], v154 offset:19456
	ds_read_b128 v[204:207], v154 offset:20480
	ds_read_b128 v[208:211], v154 offset:21504
	ds_read_b128 v[212:215], v154 offset:22528
	ds_read_b128 v[216:219], v154 offset:23552
	global_load_lds_dwordx4 v[150:151], off
	s_add_i32 m0, s77, 0x2000
	s_add_u32 s78, s48, 0x40000
	v_lshl_add_u64 v[220:221], s[48:49], 0, v[136:137]
	s_addc_u32 s79, s49, 0
	s_add_i32 s77, s70, s54
	global_load_lds_dwordx4 v[220:221], off
	v_lshl_add_u64 v[222:223], s[78:79], 0, v[132:133]
	s_mov_b32 m0, s77
	v_lshl_add_u64 v[224:225], s[50:51], 0, v[134:135]
	global_load_lds_dwordx4 v[222:223], off
	v_lshl_add_u64 v[222:223], s[78:79], 0, v[136:137]
	s_add_i32 m0, s77, 0x2000
	s_nop 0
	global_load_lds_dwordx4 v[222:223], off
	v_lshl_add_u64 v[222:223], s[50:51], 0, v[130:131]
	s_mov_b32 m0, s15
	s_nop 0
	global_load_lds_dwordx4 v[222:223], off
	s_mov_b32 m0, s17
	s_nop 0
	global_load_lds_dwordx4 v[224:225], off
	s_waitcnt vmcnt(8)
	s_waitcnt lgkmcnt(0)
	s_barrier
	s_waitcnt lgkmcnt(0)
	v_mfma_f32_16x16x32_bf16 v[62:65], v[156:159], v[188:191], v[62:65]
	v_mfma_f32_16x16x32_bf16 v[54:57], v[156:159], v[196:199], v[54:57]
	v_mfma_f32_16x16x32_bf16 v[46:49], v[156:159], v[204:207], v[46:49]
	v_mfma_f32_16x16x32_bf16 v[38:41], v[156:159], v[212:215], v[38:41]
	v_mfma_f32_16x16x32_bf16 v[34:37], v[164:167], v[212:215], v[34:37]
	v_mfma_f32_16x16x32_bf16 v[42:45], v[164:167], v[204:207], v[42:45]
	v_mfma_f32_16x16x32_bf16 v[50:53], v[164:167], v[196:199], v[50:53]
	v_mfma_f32_16x16x32_bf16 v[58:61], v[164:167], v[188:191], v[58:61]
	v_mfma_f32_16x16x32_bf16 v[62:65], v[160:163], v[192:195], v[62:65]
	v_mfma_f32_16x16x32_bf16 v[54:57], v[160:163], v[200:203], v[54:57]
	v_mfma_f32_16x16x32_bf16 v[46:49], v[160:163], v[208:211], v[46:49]
	v_mfma_f32_16x16x32_bf16 v[38:41], v[160:163], v[216:219], v[38:41]
	v_mfma_f32_16x16x32_bf16 v[34:37], v[168:171], v[216:219], v[34:37]
	v_mfma_f32_16x16x32_bf16 v[42:45], v[168:171], v[208:211], v[42:45]
	v_mfma_f32_16x16x32_bf16 v[50:53], v[168:171], v[200:203], v[50:53]
	v_mfma_f32_16x16x32_bf16 v[58:61], v[168:171], v[192:195], v[58:61]
	v_mfma_f32_16x16x32_bf16 v[30:33], v[172:175], v[188:191], v[30:33]
	v_mfma_f32_16x16x32_bf16 v[22:25], v[172:175], v[196:199], v[22:25]
	v_mfma_f32_16x16x32_bf16 v[14:17], v[172:175], v[204:207], v[14:17]
	v_mfma_f32_16x16x32_bf16 v[6:9], v[172:175], v[212:215], v[6:9]
	v_mfma_f32_16x16x32_bf16 v[2:5], v[180:183], v[212:215], v[2:5]
	v_mfma_f32_16x16x32_bf16 v[10:13], v[180:183], v[204:207], v[10:13]
	v_mfma_f32_16x16x32_bf16 v[18:21], v[180:183], v[196:199], v[18:21]
	v_mfma_f32_16x16x32_bf16 v[26:29], v[180:183], v[188:191], v[26:29]
	v_mfma_f32_16x16x32_bf16 v[30:33], v[176:179], v[192:195], v[30:33]
	v_mfma_f32_16x16x32_bf16 v[22:25], v[176:179], v[200:203], v[22:25]
	v_mfma_f32_16x16x32_bf16 v[14:17], v[176:179], v[208:211], v[14:17]
	v_mfma_f32_16x16x32_bf16 v[6:9], v[176:179], v[216:219], v[6:9]
	v_mfma_f32_16x16x32_bf16 v[2:5], v[184:187], v[216:219], v[2:5]
	v_mfma_f32_16x16x32_bf16 v[10:13], v[184:187], v[208:211], v[10:13]
	v_mfma_f32_16x16x32_bf16 v[18:21], v[184:187], v[200:203], v[18:21]
	v_mfma_f32_16x16x32_bf16 v[26:29], v[184:187], v[192:195], v[26:29]
	s_barrier
; #define PG8_STAGEA(bufoff, gbase) PG8_STAGE_(bufoff, gbase, voffA)
; #define PG8_STAGEB(bufoff, gbase) PG8_STAGE_(bufoff, gbase, voffB)
; #define PG8_LDA(dst, b, h) do { _Pragma("unroll") for (int m = 0; m < 4; ++m) _Pragma("unroll") for (int k = 0; k < 2; ++k) dst[m][k] = *(const LAS bf16x8*)(lds + PG8_SA(b, h) + aoff + m * 2048 + k * 1024); } while (0)
; #define PG8_LDB(dst, b, h) do { _Pragma("unroll") for (int n = 0; n < 2; ++n) _Pragma("unroll") for (int k = 0; k < 2; ++k) dst[n][k] = *(const LAS bf16x8*)(lds + PG8_SB(b, h) + boff + n * 2048 + k * 1024); } while (0)
; #define PG8_MMA(ai, bj, At, Bt_) do { __builtin_amdgcn_s_setprio(1); _Pragma("unroll") for (int m = 0; m < 4; ++m) _Pragma("unroll") for (int n = 0; n < 2; ++n) _Pragma("unroll") for (int k = 0; k < 2; ++k) \
;         acc[ai][bj][m][n] = __builtin_amdgcn_mfma_f32_16x16x32_bf16(Bt_[n][k], At[m][k], acc[ai][bj][m][n], 0, 0, 0); __builtin_amdgcn_s_setprio(0); } while (0)
; #define PG8_WAIT_V(n) asm volatile("s_waitcnt vmcnt(" #n ")" ::: "memory")
; #define PG8_WAIT_L(n) asm volatile("s_waitcnt lgkmcnt(" #n ")" ::: "memory")
; #define PG8_BAR __builtin_amdgcn_s_barrier()
; #define PG8_SCHED __builtin_amdgcn_sched_barrier(0)
; template <int EK, int SK = -1>
; __device__ __forceinline__ void gemm_phase(LAS unsigned char* lds, const bf16_t* A, const bf16_t* Bt, int nM, int N, int K, const EpiArgs& E) {
;     ...
;             PG8_LDB(B0, 1, 0); PG8_LDB(B1, 1, 1); PG8_SCHED; PG8_LDA(At, 1, 0); PG8_STAGEA(PG8_SA(0, 1), a2 + hstep);
;             PG8_WAIT_V(8); PG8_WAIT_L(0); PG8_BAR; PG8_MMA(0, 0, At, B0); PG8_MMA(0, 1, At, B1); PG8_BAR; PG8_SCHED;
;             PG8_LDA(At, 1, 1); PG8_STAGEB(PG8_SB(1, 0), b3); PG8_STAGEB(PG8_SB(1, 1), b3 + hstep); PG8_STAGEA(PG8_SA(1, 0), a3);
;             PG8_WAIT_V(8); PG8_WAIT_L(0); PG8_BAR; PG8_MMA(1, 0, At, B0); PG8_MMA(1, 1, At, B1); PG8_BAR; PG8_SCHED;
;         }
	s_add_i32 s77, 0, 0x18000
	s_add_i32 s78, 0, 0x1c000
	v_add_u32_e32 v168, s77, v152
	v_add_u32_e32 v184, s78, v152
	ds_read_b128 v[156:159], v168
	ds_read_b128 v[160:163], v168 offset:1024
	ds_read_b128 v[164:167], v168 offset:2048
	ds_read_b128 v[168:171], v168 offset:3072
	ds_read_b128 v[172:175], v184
	ds_read_b128 v[176:179], v184 offset:1024
	ds_read_b128 v[180:183], v184 offset:2048
	ds_read_b128 v[184:187], v184 offset:3072
	s_add_u32 s50, s50, 0x40000
	s_addc_u32 s51, s51, 0
	s_mov_b32 m0, s55
	v_lshl_add_u64 v[226:227], s[50:51], 0, v[130:131]
	ds_read_b128 v[188:191], v154 offset:32768
	ds_read_b128 v[192:195], v154 offset:33792
	ds_read_b128 v[196:199], v154 offset:34816
	ds_read_b128 v[200:203], v154 offset:35840
	ds_read_b128 v[204:207], v154 offset:36864
	ds_read_b128 v[208:211], v154 offset:37888
	ds_read_b128 v[212:215], v154 offset:38912
	ds_read_b128 v[216:219], v154 offset:39936
	global_load_lds_dwordx4 v[226:227], off
	v_lshl_add_u64 v[226:227], s[50:51], 0, v[134:135]
	s_mov_b32 m0, s56
	s_nop 0
	global_load_lds_dwordx4 v[226:227], off
	s_waitcnt vmcnt(8)
	s_waitcnt lgkmcnt(0)
	s_barrier
	s_waitcnt lgkmcnt(0)
	v_mfma_f32_16x16x32_bf16 v[126:129], v[156:159], v[188:191], v[126:129]
	v_mfma_f32_16x16x32_bf16 v[118:121], v[156:159], v[196:199], v[118:121]
	v_mfma_f32_16x16x32_bf16 v[110:113], v[156:159], v[204:207], v[110:113]
	v_mfma_f32_16x16x32_bf16 v[102:105], v[156:159], v[212:215], v[102:105]
	v_mfma_f32_16x16x32_bf16 v[98:101], v[164:167], v[212:215], v[98:101]
	v_mfma_f32_16x16x32_bf16 v[106:109], v[164:167], v[204:207], v[106:109]
	v_mfma_f32_16x16x32_bf16 v[114:117], v[164:167], v[196:199], v[114:117]
	v_mfma_f32_16x16x32_bf16 v[122:125], v[164:167], v[188:191], v[122:125]
	v_mfma_f32_16x16x32_bf16 v[126:129], v[160:163], v[192:195], v[126:129]
	v_mfma_f32_16x16x32_bf16 v[118:121], v[160:163], v[200:203], v[118:121]
	v_mfma_f32_16x16x32_bf16 v[110:113], v[160:163], v[208:211], v[110:113]
	v_mfma_f32_16x16x32_bf16 v[102:105], v[160:163], v[216:219], v[102:105]
	v_mfma_f32_16x16x32_bf16 v[98:101], v[168:171], v[216:219], v[98:101]
	v_mfma_f32_16x16x32_bf16 v[106:109], v[168:171], v[208:211], v[106:109]
	v_mfma_f32_16x16x32_bf16 v[114:117], v[168:171], v[200:203], v[114:117]
	v_mfma_f32_16x16x32_bf16 v[122:125], v[168:171], v[192:195], v[122:125]
	v_mfma_f32_16x16x32_bf16 v[94:97], v[172:175], v[188:191], v[94:97]
	v_mfma_f32_16x16x32_bf16 v[86:89], v[172:175], v[196:199], v[86:89]
	v_mfma_f32_16x16x32_bf16 v[78:81], v[172:175], v[204:207], v[78:81]
	v_mfma_f32_16x16x32_bf16 v[70:73], v[172:175], v[212:215], v[70:73]
	v_mfma_f32_16x16x32_bf16 v[66:69], v[180:183], v[212:215], v[66:69]
	v_mfma_f32_16x16x32_bf16 v[74:77], v[180:183], v[204:207], v[74:77]
	v_mfma_f32_16x16x32_bf16 v[82:85], v[180:183], v[196:199], v[82:85]
	v_mfma_f32_16x16x32_bf16 v[90:93], v[180:183], v[188:191], v[90:93]
	v_mfma_f32_16x16x32_bf16 v[94:97], v[176:179], v[192:195], v[94:97]
	v_mfma_f32_16x16x32_bf16 v[86:89], v[176:179], v[200:203], v[86:89]
	v_mfma_f32_16x16x32_bf16 v[78:81], v[176:179], v[208:211], v[78:81]
	v_mfma_f32_16x16x32_bf16 v[70:73], v[176:179], v[216:219], v[70:73]
	v_mfma_f32_16x16x32_bf16 v[66:69], v[184:187], v[216:219], v[66:69]
	v_mfma_f32_16x16x32_bf16 v[74:77], v[184:187], v[208:211], v[74:77]
	v_mfma_f32_16x16x32_bf16 v[82:85], v[184:187], v[200:203], v[82:85]
	v_mfma_f32_16x16x32_bf16 v[90:93], v[184:187], v[192:195], v[90:93]
	s_barrier
	s_add_i32 s50, s77, s54
	v_lshl_add_u64 v[150:151], v[150:151], 0, s[26:27]
	s_mov_b32 m0, s50
	ds_read_b128 v[188:191], v154 offset:49152
	ds_read_b128 v[192:195], v154 offset:50176
	ds_read_b128 v[196:199], v154 offset:51200
	ds_read_b128 v[200:203], v154 offset:52224
	ds_read_b128 v[204:207], v154 offset:53248
	ds_read_b128 v[208:211], v154 offset:54272
	ds_read_b128 v[212:215], v154 offset:55296
	ds_read_b128 v[216:219], v154 offset:56320
	global_load_lds_dwordx4 v[150:151], off
	s_add_i32 m0, s50, 0x2000
	s_add_u32 s48, s48, 0x40080
	v_lshl_add_u64 v[150:151], v[220:221], 0, s[26:27]
	s_addc_u32 s49, s49, 0
	s_add_i32 s50, s78, s54
	global_load_lds_dwordx4 v[150:151], off
	v_lshl_add_u64 v[150:151], s[48:49], 0, v[132:133]
	s_mov_b32 m0, s50
	s_nop 0
	global_load_lds_dwordx4 v[150:151], off
	v_lshl_add_u64 v[150:151], s[48:49], 0, v[136:137]
	s_add_i32 m0, s50, 0x2000
	s_nop 0
	global_load_lds_dwordx4 v[150:151], off
	v_lshl_add_u64 v[150:151], v[222:223], 0, s[26:27]
	s_mov_b32 m0, s59
	s_nop 0
	global_load_lds_dwordx4 v[150:151], off
	v_lshl_add_u64 v[150:151], v[224:225], 0, s[26:27]
	s_mov_b32 m0, s68
	s_nop 0
	global_load_lds_dwordx4 v[150:151], off
	s_waitcnt vmcnt(8)
	s_waitcnt lgkmcnt(0)
	s_barrier
	s_waitcnt lgkmcnt(0)
	v_mfma_f32_16x16x32_bf16 v[62:65], v[156:159], v[188:191], v[62:65]
	v_mfma_f32_16x16x32_bf16 v[54:57], v[156:159], v[196:199], v[54:57]
	v_mfma_f32_16x16x32_bf16 v[46:49], v[156:159], v[204:207], v[46:49]
	v_mfma_f32_16x16x32_bf16 v[38:41], v[156:159], v[212:215], v[38:41]
	v_mfma_f32_16x16x32_bf16 v[34:37], v[164:167], v[212:215], v[34:37]
	v_mfma_f32_16x16x32_bf16 v[42:45], v[164:167], v[204:207], v[42:45]
	v_mfma_f32_16x16x32_bf16 v[50:53], v[164:167], v[196:199], v[50:53]
	v_mfma_f32_16x16x32_bf16 v[58:61], v[164:167], v[188:191], v[58:61]
	v_mfma_f32_16x16x32_bf16 v[62:65], v[160:163], v[192:195], v[62:65]
	v_mfma_f32_16x16x32_bf16 v[54:57], v[160:163], v[200:203], v[54:57]
	v_mfma_f32_16x16x32_bf16 v[46:49], v[160:163], v[208:211], v[46:49]
	v_mfma_f32_16x16x32_bf16 v[38:41], v[160:163], v[216:219], v[38:41]
	v_mfma_f32_16x16x32_bf16 v[34:37], v[168:171], v[216:219], v[34:37]
	v_mfma_f32_16x16x32_bf16 v[42:45], v[168:171], v[208:211], v[42:45]
	v_mfma_f32_16x16x32_bf16 v[50:53], v[168:171], v[200:203], v[50:53]
	v_mfma_f32_16x16x32_bf16 v[58:61], v[168:171], v[192:195], v[58:61]
	v_mfma_f32_16x16x32_bf16 v[30:33], v[172:175], v[188:191], v[30:33]
	v_mfma_f32_16x16x32_bf16 v[22:25], v[172:175], v[196:199], v[22:25]
	v_mfma_f32_16x16x32_bf16 v[14:17], v[172:175], v[204:207], v[14:17]
	v_mfma_f32_16x16x32_bf16 v[6:9], v[172:175], v[212:215], v[6:9]
	v_mfma_f32_16x16x32_bf16 v[2:5], v[180:183], v[212:215], v[2:5]
	v_mfma_f32_16x16x32_bf16 v[10:13], v[180:183], v[204:207], v[10:13]
	v_mfma_f32_16x16x32_bf16 v[18:21], v[180:183], v[196:199], v[18:21]
	v_mfma_f32_16x16x32_bf16 v[26:29], v[180:183], v[188:191], v[26:29]
	v_mfma_f32_16x16x32_bf16 v[30:33], v[176:179], v[192:195], v[30:33]
	v_mfma_f32_16x16x32_bf16 v[22:25], v[176:179], v[200:203], v[22:25]
	v_mfma_f32_16x16x32_bf16 v[14:17], v[176:179], v[208:211], v[14:17]
	v_mfma_f32_16x16x32_bf16 v[6:9], v[176:179], v[216:219], v[6:9]
	v_mfma_f32_16x16x32_bf16 v[2:5], v[184:187], v[216:219], v[2:5]
	v_mfma_f32_16x16x32_bf16 v[10:13], v[184:187], v[208:211], v[10:13]
	v_mfma_f32_16x16x32_bf16 v[18:21], v[184:187], v[200:203], v[18:21]
	v_mfma_f32_16x16x32_bf16 v[26:29], v[184:187], v[192:195], v[26:29]
	s_barrier
	s_add_i32 s76, s76, 2
	s_add_u32 s46, s46, 0x100
	s_addc_u32 s47, s47, 0
	s_cmp_gt_u32 s76, 13
	s_cbranch_scc0 .LBB0_1120

; #define PG8_STAGEA(bufoff, gbase) PG8_STAGE_(bufoff, gbase, voffA)
; #define PG8_STAGEB(bufoff, gbase) PG8_STAGE_(bufoff, gbase, voffB)
; #define PG8_LDA(dst, b, h) do { _Pragma("unroll") for (int m = 0; m < 4; ++m) _Pragma("unroll") for (int k = 0; k < 2; ++k) dst[m][k] = *(const LAS bf16x8*)(lds + PG8_SA(b, h) + aoff + m * 2048 + k * 1024); } while (0)
; #define PG8_LDB(dst, b, h) do { _Pragma("unroll") for (int n = 0; n < 2; ++n) _Pragma("unroll") for (int k = 0; k < 2; ++k) dst[n][k] = *(const LAS bf16x8*)(lds + PG8_SB(b, h) + boff + n * 2048 + k * 1024); } while (0)
; #define PG8_MMA(ai, bj, At, Bt_) do { __builtin_amdgcn_s_setprio(1); _Pragma("unroll") for (int m = 0; m < 4; ++m) _Pragma("unroll") for (int n = 0; n < 2; ++n) _Pragma("unroll") for (int k = 0; k < 2; ++k) \
;         acc[ai][bj][m][n] = __builtin_amdgcn_mfma_f32_16x16x32_bf16(Bt_[n][k], At[m][k], acc[ai][bj][m][n], 0, 0, 0); __builtin_amdgcn_s_setprio(0); } while (0)
; #define PG8_WAIT_V(n) asm volatile("s_waitcnt vmcnt(" #n ")" ::: "memory")
; #define PG8_WAIT_L(n) asm volatile("s_waitcnt lgkmcnt(" #n ")" ::: "memory")
; #define PG8_BAR __builtin_amdgcn_s_barrier()
; #define PG8_SCHED __builtin_amdgcn_sched_barrier(0)
; template <int EK, int SK = -1>
; __device__ __forceinline__ void gemm_phase(LAS unsigned char* lds, const bf16_t* A, const bf16_t* Bt, int nM, int N, int K, const EpiArgs& E) {
;     ...
;         const bool has_next = S.next(ui + 1, nxt);
;         const char* nA = has_next ? (const char*)A + (size_t)nxt.pm * tstep : cA; const char* nB = has_next ? (const char*)Bt + (size_t)nxt.pn * tstep : cB;
;         for (int t = 0; t < nt; t += 2) {
;             const bool last = (t == nt - 2);
;             const char* a1 = cA + (size_t)(t + 1) * kstep;
;             const char* a2 = last ? nA : cA + (size_t)(t + 2) * kstep; const char* b2 = last ? nB : cB + (size_t)(t + 2) * kstep;
;             const char* a3 = a2 + kstep; const char* b3 = b2 + kstep;
;             PG8_LDB(B0, 0, 0); PG8_LDB(B1, 0, 1); PG8_SCHED; PG8_LDA(At, 0, 0); PG8_STAGEA(PG8_SA(1, 1), a1 + hstep);
;             PG8_WAIT_V(8); PG8_WAIT_L(0); PG8_BAR; PG8_MMA(0, 0, At, B0); PG8_MMA(0, 1, At, B1); PG8_BAR; PG8_SCHED;
;             PG8_LDA(At, 0, 1); PG8_STAGEB(PG8_SB(0, 0), b2); PG8_STAGEB(PG8_SB(0, 1), b2 + hstep); PG8_STAGEA(PG8_SA(0, 0), a2);
.LBB0_1244:
	s_add_u32 s59, s40, 0x100
	s_addc_u32 s66, s41, 0
	s_ashr_i32 s27, s26, 31
	s_lshl_b64 s[36:37], s[26:27], 19
	s_add_u32 s38, s62, s36
	s_addc_u32 s39, s63, s37
	s_and_b64 s[36:37], s[6:7], exec
	s_cselect_b32 s27, s39, s21
	s_cselect_b32 s67, s38, s20
	s_ashr_i32 s23, s22, 31
	s_lshl_b64 s[36:37], s[22:23], 19
	s_add_u32 s36, s47, s36
	s_addc_u32 s37, s48, s37
	s_and_b64 s[42:43], s[6:7], exec
	s_cselect_b32 s23, s37, s41
	s_cselect_b32 s68, s36, s40
	v_lshl_add_u64 v[146:147], s[20:21], 0, v[138:139]
	v_lshl_add_u64 v[148:149], s[20:21], 0, v[140:141]
	s_mov_b32 s69, -2
	s_mov_b64 s[40:41], 0
	v_add_u32_e32 v154, s54, v156
	ds_read_b128 v[150:153], v154
	ds_read_b128 v[160:163], v154 offset:1024
	ds_read_b128 v[164:167], v154 offset:2048
	ds_read_b128 v[168:171], v154 offset:3072
	v_add_u32_e32 v154, s55, v156
	s_add_u32 s42, s20, s40
	ds_read_b128 v[172:175], v154
	ds_read_b128 v[176:179], v154 offset:1024
	ds_read_b128 v[180:183], v154 offset:2048
	ds_read_b128 v[184:187], v154 offset:3072
	s_addc_u32 s43, s21, s41
	s_add_u32 s42, s42, 0x100
	s_addc_u32 s43, s43, 0
	s_add_u32 s70, s59, s40
	s_addc_u32 s71, s66, s41
	s_cmpk_eq_i32 s40, 0x700
	s_cselect_b32 s45, s27, s43
	s_cselect_b32 s44, s67, s42
	s_cselect_b32 s43, s23, s71
	s_cselect_b32 s42, s68, s70
	v_lshl_add_u64 v[154:155], v[146:147], 0, s[40:41]
	s_add_i32 m0, s17, 0xc000
	ds_read_b128 v[188:191], v159
	ds_read_b128 v[192:195], v159 offset:1024
	ds_read_b128 v[196:199], v159 offset:2048
	ds_read_b128 v[200:203], v159 offset:3072
	ds_read_b128 v[204:207], v159 offset:4096
	ds_read_b128 v[208:211], v159 offset:5120
	ds_read_b128 v[212:215], v159 offset:6144
	ds_read_b128 v[216:219], v159 offset:7168
	global_load_lds_dwordx4 v[154:155], off
	v_lshl_add_u64 v[154:155], v[148:149], 0, s[40:41]
	s_add_i32 m0, s17, 0xe000
	s_nop 0
	global_load_lds_dwordx4 v[154:155], off
	s_waitcnt vmcnt(8)
	s_waitcnt lgkmcnt(0)
	s_barrier
	s_waitcnt lgkmcnt(0)
	v_mfma_f32_16x16x32_bf16 v[110:113], v[150:153], v[188:191], 0
	v_mfma_f32_16x16x32_bf16 v[102:105], v[150:153], v[196:199], 0
	v_mfma_f32_16x16x32_bf16 v[94:97], v[150:153], v[204:207], 0
	v_mfma_f32_16x16x32_bf16 v[86:89], v[150:153], v[212:215], 0
	v_mfma_f32_16x16x32_bf16 v[82:85], v[164:167], v[212:215], 0
	v_mfma_f32_16x16x32_bf16 v[90:93], v[164:167], v[204:207], 0
	v_mfma_f32_16x16x32_bf16 v[98:101], v[164:167], v[196:199], 0
	v_mfma_f32_16x16x32_bf16 v[106:109], v[164:167], v[188:191], 0
	v_mfma_f32_16x16x32_bf16 v[110:113], v[160:163], v[192:195], v[110:113]
	v_mfma_f32_16x16x32_bf16 v[102:105], v[160:163], v[200:203], v[102:105]
	v_mfma_f32_16x16x32_bf16 v[94:97], v[160:163], v[208:211], v[94:97]
	v_mfma_f32_16x16x32_bf16 v[86:89], v[160:163], v[216:219], v[86:89]
	v_mfma_f32_16x16x32_bf16 v[82:85], v[168:171], v[216:219], v[82:85]
	v_mfma_f32_16x16x32_bf16 v[90:93], v[168:171], v[208:211], v[90:93]
	v_mfma_f32_16x16x32_bf16 v[98:101], v[168:171], v[200:203], v[98:101]
	v_mfma_f32_16x16x32_bf16 v[106:109], v[168:171], v[192:195], v[106:109]
	v_mfma_f32_16x16x32_bf16 v[78:81], v[172:175], v[188:191], 0
	v_mfma_f32_16x16x32_bf16 v[70:73], v[172:175], v[196:199], 0
	v_mfma_f32_16x16x32_bf16 v[62:65], v[172:175], v[204:207], 0
	v_mfma_f32_16x16x32_bf16 v[54:57], v[172:175], v[212:215], 0
	v_mfma_f32_16x16x32_bf16 v[50:53], v[180:183], v[212:215], 0
	v_mfma_f32_16x16x32_bf16 v[58:61], v[180:183], v[204:207], 0
	v_mfma_f32_16x16x32_bf16 v[66:69], v[180:183], v[196:199], 0
	v_mfma_f32_16x16x32_bf16 v[74:77], v[180:183], v[188:191], 0
	v_mfma_f32_16x16x32_bf16 v[78:81], v[176:179], v[192:195], v[78:81]
	v_mfma_f32_16x16x32_bf16 v[70:73], v[176:179], v[200:203], v[70:73]
	v_mfma_f32_16x16x32_bf16 v[62:65], v[176:179], v[208:211], v[62:65]
	v_mfma_f32_16x16x32_bf16 v[54:57], v[176:179], v[216:219], v[54:57]
	v_mfma_f32_16x16x32_bf16 v[50:53], v[184:187], v[216:219], v[50:53]
	v_mfma_f32_16x16x32_bf16 v[58:61], v[184:187], v[208:211], v[58:61]
	v_mfma_f32_16x16x32_bf16 v[66:69], v[184:187], v[200:203], v[66:69]
	v_mfma_f32_16x16x32_bf16 v[74:77], v[184:187], v[192:195], v[74:77]
	s_barrier
	s_add_i32 s70, s54, s49
	v_lshl_add_u64 v[154:155], s[42:43], 0, v[132:133]
	s_mov_b32 m0, s70
	ds_read_b128 v[188:191], v159 offset:16384
	ds_read_b128 v[192:195], v159 offset:17408
	ds_read_b128 v[196:199], v159 offset:18432
	ds_read_b128 v[200:203], v159 offset:19456
	ds_read_b128 v[204:207], v159 offset:20480
	ds_read_b128 v[208:211], v159 offset:21504
	ds_read_b128 v[212:215], v159 offset:22528
	ds_read_b128 v[216:219], v159 offset:23552
	global_load_lds_dwordx4 v[154:155], off
	s_add_i32 m0, s70, 0x2000
	s_add_u32 s70, s42, 0x40000
	v_lshl_add_u64 v[220:221], s[42:43], 0, v[136:137]
	s_addc_u32 s71, s43, 0
	s_add_i32 s72, s55, s49
	global_load_lds_dwordx4 v[220:221], off
	v_lshl_add_u64 v[222:223], s[70:71], 0, v[132:133]
	s_mov_b32 m0, s72
	v_lshl_add_u64 v[224:225], s[44:45], 0, v[134:135]
	global_load_lds_dwordx4 v[222:223], off
	v_lshl_add_u64 v[222:223], s[70:71], 0, v[136:137]
	s_add_i32 m0, s72, 0x2000
	s_nop 0
	global_load_lds_dwordx4 v[222:223], off
	v_lshl_add_u64 v[222:223], s[44:45], 0, v[130:131]
	s_mov_b32 m0, s17
	s_nop 0
	global_load_lds_dwordx4 v[222:223], off
	s_mov_b32 m0, s19
	s_nop 0
	global_load_lds_dwordx4 v[224:225], off
	s_waitcnt vmcnt(8)
	s_waitcnt lgkmcnt(0)
	s_barrier
; #define PG8_STAGEA(bufoff, gbase) PG8_STAGE_(bufoff, gbase, voffA)
; #define PG8_LDA(dst, b, h) do { _Pragma("unroll") for (int m = 0; m < 4; ++m) _Pragma("unroll") for (int k = 0; k < 2; ++k) dst[m][k] = *(const LAS bf16x8*)(lds + PG8_SA(b, h) + aoff + m * 2048 + k * 1024); } while (0)
; #define PG8_LDB(dst, b, h) do { _Pragma("unroll") for (int n = 0; n < 2; ++n) _Pragma("unroll") for (int k = 0; k < 2; ++k) dst[n][k] = *(const LAS bf16x8*)(lds + PG8_SB(b, h) + boff + n * 2048 + k * 1024); } while (0)
; #define PG8_MMA(ai, bj, At, Bt_) do { __builtin_amdgcn_s_setprio(1); _Pragma("unroll") for (int m = 0; m < 4; ++m) _Pragma("unroll") for (int n = 0; n < 2; ++n) _Pragma("unroll") for (int k = 0; k < 2; ++k) \
;         acc[ai][bj][m][n] = __builtin_amdgcn_mfma_f32_16x16x32_bf16(Bt_[n][k], At[m][k], acc[ai][bj][m][n], 0, 0, 0); __builtin_amdgcn_s_setprio(0); } while (0)
; #define PG8_WAIT_V(n) asm volatile("s_waitcnt vmcnt(" #n ")" ::: "memory")
; #define PG8_WAIT_L(n) asm volatile("s_waitcnt lgkmcnt(" #n ")" ::: "memory")
; #define PG8_BAR __builtin_amdgcn_s_barrier()
; #define PG8_SCHED __builtin_amdgcn_sched_barrier(0)
; template <int EK, int SK = -1>
; __device__ __forceinline__ void gemm_phase(LAS unsigned char* lds, const bf16_t* A, const bf16_t* Bt, int nM, int N, int K, const EpiArgs& E) {
;     ...
;             PG8_WAIT_V(8); PG8_WAIT_L(0); PG8_BAR; PG8_MMA(1, 0, At, B0); PG8_MMA(1, 1, At, B1); PG8_BAR; PG8_SCHED;
;             PG8_LDB(B0, 1, 0); PG8_LDB(B1, 1, 1); PG8_SCHED; PG8_LDA(At, 1, 0); PG8_STAGEA(PG8_SA(0, 1), a2 + hstep);
;             PG8_WAIT_V(8); PG8_WAIT_L(0); PG8_BAR; PG8_MMA(0, 0, At, B0); PG8_MMA(0, 1, At, B1); PG8_BAR; PG8_SCHED;
	s_waitcnt lgkmcnt(0)
	v_mfma_f32_16x16x32_bf16 v[46:49], v[150:153], v[188:191], 0
	v_mfma_f32_16x16x32_bf16 v[38:41], v[150:153], v[196:199], 0
	v_mfma_f32_16x16x32_bf16 v[30:33], v[150:153], v[204:207], 0
	v_mfma_f32_16x16x32_bf16 v[22:25], v[150:153], v[212:215], 0
	v_mfma_f32_16x16x32_bf16 v[18:21], v[164:167], v[212:215], 0
	v_mfma_f32_16x16x32_bf16 v[26:29], v[164:167], v[204:207], 0
	v_mfma_f32_16x16x32_bf16 v[34:37], v[164:167], v[196:199], 0
	v_mfma_f32_16x16x32_bf16 v[42:45], v[164:167], v[188:191], 0
	v_mfma_f32_16x16x32_bf16 v[46:49], v[160:163], v[192:195], v[46:49]
	v_mfma_f32_16x16x32_bf16 v[38:41], v[160:163], v[200:203], v[38:41]
	v_mfma_f32_16x16x32_bf16 v[30:33], v[160:163], v[208:211], v[30:33]
	v_mfma_f32_16x16x32_bf16 v[22:25], v[160:163], v[216:219], v[22:25]
	v_mfma_f32_16x16x32_bf16 v[18:21], v[168:171], v[216:219], v[18:21]
	v_mfma_f32_16x16x32_bf16 v[26:29], v[168:171], v[208:211], v[26:29]
	v_mfma_f32_16x16x32_bf16 v[34:37], v[168:171], v[200:203], v[34:37]
	v_mfma_f32_16x16x32_bf16 v[42:45], v[168:171], v[192:195], v[42:45]
	v_mfma_f32_16x16x32_bf16 v[14:17], v[172:175], v[188:191], 0
	v_mfma_f32_16x16x32_bf16 v[6:9], v[172:175], v[196:199], 0
	v_mfma_f32_16x16x32_bf16 v[114:117], v[172:175], v[204:207], 0
	v_mfma_f32_16x16x32_bf16 v[122:125], v[172:175], v[212:215], 0
	v_mfma_f32_16x16x32_bf16 v[126:129], v[180:183], v[212:215], 0
	v_mfma_f32_16x16x32_bf16 v[118:121], v[180:183], v[204:207], 0
	v_mfma_f32_16x16x32_bf16 v[2:5], v[180:183], v[196:199], 0
	v_mfma_f32_16x16x32_bf16 v[10:13], v[180:183], v[188:191], 0
	v_mfma_f32_16x16x32_bf16 v[14:17], v[176:179], v[192:195], v[14:17]
	v_mfma_f32_16x16x32_bf16 v[6:9], v[176:179], v[200:203], v[6:9]
	v_mfma_f32_16x16x32_bf16 v[114:117], v[176:179], v[208:211], v[114:117]
	v_mfma_f32_16x16x32_bf16 v[122:125], v[176:179], v[216:219], v[122:125]
	v_mfma_f32_16x16x32_bf16 v[126:129], v[184:187], v[216:219], v[126:129]
	v_mfma_f32_16x16x32_bf16 v[118:121], v[184:187], v[208:211], v[118:121]
	v_mfma_f32_16x16x32_bf16 v[2:5], v[184:187], v[200:203], v[2:5]
	v_mfma_f32_16x16x32_bf16 v[10:13], v[184:187], v[192:195], v[10:13]
	s_barrier
	s_add_i32 s70, 0, 0x18000
	s_add_i32 s71, 0, 0x1c000
	v_add_u32_e32 v168, s70, v156
	v_add_u32_e32 v184, s71, v156
	ds_read_b128 v[150:153], v168
	ds_read_b128 v[160:163], v168 offset:1024
	ds_read_b128 v[164:167], v168 offset:2048
	ds_read_b128 v[168:171], v168 offset:3072
	ds_read_b128 v[172:175], v184
	ds_read_b128 v[176:179], v184 offset:1024
	ds_read_b128 v[180:183], v184 offset:2048
	ds_read_b128 v[184:187], v184 offset:3072
	s_add_u32 s44, s44, 0x40000
	s_addc_u32 s45, s45, 0
	s_mov_b32 m0, s50
	v_lshl_add_u64 v[226:227], s[44:45], 0, v[130:131]
	ds_read_b128 v[188:191], v159 offset:32768
	ds_read_b128 v[192:195], v159 offset:33792
	ds_read_b128 v[196:199], v159 offset:34816
	ds_read_b128 v[200:203], v159 offset:35840
	ds_read_b128 v[204:207], v159 offset:36864
	ds_read_b128 v[208:211], v159 offset:37888
	ds_read_b128 v[212:215], v159 offset:38912
	ds_read_b128 v[216:219], v159 offset:39936
	global_load_lds_dwordx4 v[226:227], off
	v_lshl_add_u64 v[226:227], s[44:45], 0, v[134:135]
	s_mov_b32 m0, s51
	s_nop 0
	global_load_lds_dwordx4 v[226:227], off
	s_waitcnt vmcnt(8)
	s_waitcnt lgkmcnt(0)
	s_barrier
	s_waitcnt lgkmcnt(0)
	v_mfma_f32_16x16x32_bf16 v[110:113], v[150:153], v[188:191], v[110:113]
	v_mfma_f32_16x16x32_bf16 v[102:105], v[150:153], v[196:199], v[102:105]
	v_mfma_f32_16x16x32_bf16 v[94:97], v[150:153], v[204:207], v[94:97]
	v_mfma_f32_16x16x32_bf16 v[86:89], v[150:153], v[212:215], v[86:89]
	v_mfma_f32_16x16x32_bf16 v[82:85], v[164:167], v[212:215], v[82:85]
	v_mfma_f32_16x16x32_bf16 v[90:93], v[164:167], v[204:207], v[90:93]
	v_mfma_f32_16x16x32_bf16 v[98:101], v[164:167], v[196:199], v[98:101]
	v_mfma_f32_16x16x32_bf16 v[106:109], v[164:167], v[188:191], v[106:109]
	v_mfma_f32_16x16x32_bf16 v[110:113], v[160:163], v[192:195], v[110:113]
	v_mfma_f32_16x16x32_bf16 v[102:105], v[160:163], v[200:203], v[102:105]
	v_mfma_f32_16x16x32_bf16 v[94:97], v[160:163], v[208:211], v[94:97]
	v_mfma_f32_16x16x32_bf16 v[86:89], v[160:163], v[216:219], v[86:89]
	v_mfma_f32_16x16x32_bf16 v[82:85], v[168:171], v[216:219], v[82:85]
	v_mfma_f32_16x16x32_bf16 v[90:93], v[168:171], v[208:211], v[90:93]
	v_mfma_f32_16x16x32_bf16 v[98:101], v[168:171], v[200:203], v[98:101]
	v_mfma_f32_16x16x32_bf16 v[106:109], v[168:171], v[192:195], v[106:109]
	v_mfma_f32_16x16x32_bf16 v[78:81], v[172:175], v[188:191], v[78:81]
	v_mfma_f32_16x16x32_bf16 v[70:73], v[172:175], v[196:199], v[70:73]
	v_mfma_f32_16x16x32_bf16 v[62:65], v[172:175], v[204:207], v[62:65]
	v_mfma_f32_16x16x32_bf16 v[54:57], v[172:175], v[212:215], v[54:57]
	v_mfma_f32_16x16x32_bf16 v[50:53], v[180:183], v[212:215], v[50:53]
	v_mfma_f32_16x16x32_bf16 v[58:61], v[180:183], v[204:207], v[58:61]
	v_mfma_f32_16x16x32_bf16 v[66:69], v[180:183], v[196:199], v[66:69]
	v_mfma_f32_16x16x32_bf16 v[74:77], v[180:183], v[188:191], v[74:77]
	v_mfma_f32_16x16x32_bf16 v[78:81], v[176:179], v[192:195], v[78:81]
	v_mfma_f32_16x16x32_bf16 v[70:73], v[176:179], v[200:203], v[70:73]
	v_mfma_f32_16x16x32_bf16 v[62:65], v[176:179], v[208:211], v[62:65]
	v_mfma_f32_16x16x32_bf16 v[54:57], v[176:179], v[216:219], v[54:57]
	v_mfma_f32_16x16x32_bf16 v[50:53], v[184:187], v[216:219], v[50:53]
	v_mfma_f32_16x16x32_bf16 v[58:61], v[184:187], v[208:211], v[58:61]
	v_mfma_f32_16x16x32_bf16 v[66:69], v[184:187], v[200:203], v[66:69]
	v_mfma_f32_16x16x32_bf16 v[74:77], v[184:187], v[192:195], v[74:77]
	s_barrier
; #define PG8_STAGEA(bufoff, gbase) PG8_STAGE_(bufoff, gbase, voffA)
; #define PG8_STAGEB(bufoff, gbase) PG8_STAGE_(bufoff, gbase, voffB)
; #define PG8_LDA(dst, b, h) do { _Pragma("unroll") for (int m = 0; m < 4; ++m) _Pragma("unroll") for (int k = 0; k < 2; ++k) dst[m][k] = *(const LAS bf16x8*)(lds + PG8_SA(b, h) + aoff + m * 2048 + k * 1024); } while (0)
; #define PG8_LDB(dst, b, h) do { _Pragma("unroll") for (int n = 0; n < 2; ++n) _Pragma("unroll") for (int k = 0; k < 2; ++k) dst[n][k] = *(const LAS bf16x8*)(lds + PG8_SB(b, h) + boff + n * 2048 + k * 1024); } while (0)
; #define PG8_MMA(ai, bj, At, Bt_) do { __builtin_amdgcn_s_setprio(1); _Pragma("unroll") for (int m = 0; m < 4; ++m) _Pragma("unroll") for (int n = 0; n < 2; ++n) _Pragma("unroll") for (int k = 0; k < 2; ++k) \
;         acc[ai][bj][m][n] = __builtin_amdgcn_mfma_f32_16x16x32_bf16(Bt_[n][k], At[m][k], acc[ai][bj][m][n], 0, 0, 0); __builtin_amdgcn_s_setprio(0); } while (0)
; #define PG8_WAIT_V(n) asm volatile("s_waitcnt vmcnt(" #n ")" ::: "memory")
; #define PG8_WAIT_L(n) asm volatile("s_waitcnt lgkmcnt(" #n ")" ::: "memory")
; #define PG8_BAR __builtin_amdgcn_s_barrier()
; #define PG8_SCHED __builtin_amdgcn_sched_barrier(0)
; template <int EK, int SK = -1>
; __device__ __forceinline__ void gemm_phase(LAS unsigned char* lds, const bf16_t* A, const bf16_t* Bt, int nM, int N, int K, const EpiArgs& E) {
;     ...
;             PG8_LDB(B0, 0, 0); PG8_LDB(B1, 0, 1); PG8_SCHED; PG8_LDA(At, 0, 0); PG8_STAGEA(PG8_SA(1, 1), a1 + hstep);
;             PG8_WAIT_V(8); PG8_WAIT_L(0); PG8_BAR; PG8_MMA(0, 0, At, B0); PG8_MMA(0, 1, At, B1); PG8_BAR; PG8_SCHED;
;             PG8_LDA(At, 0, 1); PG8_STAGEB(PG8_SB(0, 0), b2); PG8_STAGEB(PG8_SB(0, 1), b2 + hstep); PG8_STAGEA(PG8_SA(0, 0), a2);
;             PG8_WAIT_V(8); PG8_WAIT_L(0); PG8_BAR; PG8_MMA(1, 0, At, B0); PG8_MMA(1, 1, At, B1); PG8_BAR; PG8_SCHED;
;             PG8_LDB(B0, 1, 0); PG8_LDB(B1, 1, 1); PG8_SCHED; PG8_LDA(At, 1, 0); PG8_STAGEA(PG8_SA(0, 1), a2 + hstep);
;             PG8_WAIT_V(8); PG8_WAIT_L(0); PG8_BAR; PG8_MMA(0, 0, At, B0); PG8_MMA(0, 1, At, B1); PG8_BAR; PG8_SCHED;
;             PG8_LDA(At, 1, 1); PG8_STAGEB(PG8_SB(1, 0), b3); PG8_STAGEB(PG8_SB(1, 1), b3 + hstep); PG8_STAGEA(PG8_SA(1, 0), a3);
;             PG8_WAIT_V(8); PG8_WAIT_L(0); PG8_BAR; PG8_MMA(1, 0, At, B0); PG8_MMA(1, 1, At, B1); PG8_BAR; PG8_SCHED;
;         }
	s_add_i32 s44, s70, s49
	v_lshl_add_u64 v[154:155], v[154:155], 0, s[10:11]
	s_mov_b32 m0, s44
	ds_read_b128 v[188:191], v159 offset:49152
	ds_read_b128 v[192:195], v159 offset:50176
	ds_read_b128 v[196:199], v159 offset:51200
	ds_read_b128 v[200:203], v159 offset:52224
	ds_read_b128 v[204:207], v159 offset:53248
	ds_read_b128 v[208:211], v159 offset:54272
	ds_read_b128 v[212:215], v159 offset:55296
	ds_read_b128 v[216:219], v159 offset:56320
	global_load_lds_dwordx4 v[154:155], off
	s_add_i32 m0, s44, 0x2000
	s_add_u32 s42, s42, 0x40080
	v_lshl_add_u64 v[154:155], v[220:221], 0, s[10:11]
	s_addc_u32 s43, s43, 0
	s_add_i32 s44, s71, s49
	global_load_lds_dwordx4 v[154:155], off
	v_lshl_add_u64 v[154:155], s[42:43], 0, v[132:133]
	s_mov_b32 m0, s44
	s_nop 0
	global_load_lds_dwordx4 v[154:155], off
	v_lshl_add_u64 v[154:155], s[42:43], 0, v[136:137]
	s_add_i32 m0, s44, 0x2000
	s_nop 0
	global_load_lds_dwordx4 v[154:155], off
	v_lshl_add_u64 v[154:155], v[222:223], 0, s[10:11]
	s_mov_b32 m0, s52
	s_nop 0
	global_load_lds_dwordx4 v[154:155], off
	v_lshl_add_u64 v[154:155], v[224:225], 0, s[10:11]
	s_mov_b32 m0, s53
	s_nop 0
	global_load_lds_dwordx4 v[154:155], off
	s_waitcnt vmcnt(8)
	s_waitcnt lgkmcnt(0)
	s_barrier
	s_waitcnt lgkmcnt(0)
	v_mfma_f32_16x16x32_bf16 v[46:49], v[150:153], v[188:191], v[46:49]
	v_mfma_f32_16x16x32_bf16 v[38:41], v[150:153], v[196:199], v[38:41]
	v_mfma_f32_16x16x32_bf16 v[30:33], v[150:153], v[204:207], v[30:33]
	v_mfma_f32_16x16x32_bf16 v[22:25], v[150:153], v[212:215], v[22:25]
	v_mfma_f32_16x16x32_bf16 v[18:21], v[164:167], v[212:215], v[18:21]
	v_mfma_f32_16x16x32_bf16 v[26:29], v[164:167], v[204:207], v[26:29]
	v_mfma_f32_16x16x32_bf16 v[34:37], v[164:167], v[196:199], v[34:37]
	v_mfma_f32_16x16x32_bf16 v[42:45], v[164:167], v[188:191], v[42:45]
	v_mfma_f32_16x16x32_bf16 v[46:49], v[160:163], v[192:195], v[46:49]
	v_mfma_f32_16x16x32_bf16 v[38:41], v[160:163], v[200:203], v[38:41]
	v_mfma_f32_16x16x32_bf16 v[30:33], v[160:163], v[208:211], v[30:33]
	v_mfma_f32_16x16x32_bf16 v[22:25], v[160:163], v[216:219], v[22:25]
	v_mfma_f32_16x16x32_bf16 v[18:21], v[168:171], v[216:219], v[18:21]
	v_mfma_f32_16x16x32_bf16 v[26:29], v[168:171], v[208:211], v[26:29]
	v_mfma_f32_16x16x32_bf16 v[34:37], v[168:171], v[200:203], v[34:37]
	v_mfma_f32_16x16x32_bf16 v[42:45], v[168:171], v[192:195], v[42:45]
	v_mfma_f32_16x16x32_bf16 v[14:17], v[172:175], v[188:191], v[14:17]
	v_mfma_f32_16x16x32_bf16 v[6:9], v[172:175], v[196:199], v[6:9]
	v_mfma_f32_16x16x32_bf16 v[114:117], v[172:175], v[204:207], v[114:117]
	v_mfma_f32_16x16x32_bf16 v[122:125], v[172:175], v[212:215], v[122:125]
	v_mfma_f32_16x16x32_bf16 v[126:129], v[180:183], v[212:215], v[126:129]
	v_mfma_f32_16x16x32_bf16 v[118:121], v[180:183], v[204:207], v[118:121]
	v_mfma_f32_16x16x32_bf16 v[2:5], v[180:183], v[196:199], v[2:5]
	v_mfma_f32_16x16x32_bf16 v[10:13], v[180:183], v[188:191], v[10:13]
	v_mfma_f32_16x16x32_bf16 v[14:17], v[176:179], v[192:195], v[14:17]
	v_mfma_f32_16x16x32_bf16 v[6:9], v[176:179], v[200:203], v[6:9]
	v_mfma_f32_16x16x32_bf16 v[114:117], v[176:179], v[208:211], v[114:117]
	v_mfma_f32_16x16x32_bf16 v[122:125], v[176:179], v[216:219], v[122:125]
	v_mfma_f32_16x16x32_bf16 v[126:129], v[184:187], v[216:219], v[126:129]
	v_mfma_f32_16x16x32_bf16 v[118:121], v[184:187], v[208:211], v[118:121]
	v_mfma_f32_16x16x32_bf16 v[2:5], v[184:187], v[200:203], v[2:5]
	v_mfma_f32_16x16x32_bf16 v[10:13], v[184:187], v[192:195], v[10:13]
	s_barrier
	s_add_i32 s69, s69, 2
	s_add_u32 s40, s40, 0x100
	s_addc_u32 s41, s41, 0
	s_cmp_gt_u32 s69, 13
	s_cbranch_scc0 .LBB0_1245
	s_branch .Lmy_kexit_6
.LBB0_1245:
	v_add_u32_e32 v154, s54, v156
	ds_read_b128 v[150:153], v154
	ds_read_b128 v[160:163], v154 offset:1024
	ds_read_b128 v[164:167], v154 offset:2048
	ds_read_b128 v[168:171], v154 offset:3072
	v_add_u32_e32 v154, s55, v156
	s_add_u32 s42, s20, s40
	ds_read_b128 v[172:175], v154
	ds_read_b128 v[176:179], v154 offset:1024
	ds_read_b128 v[180:183], v154 offset:2048
	ds_read_b128 v[184:187], v154 offset:3072
	s_addc_u32 s43, s21, s41
	s_add_u32 s42, s42, 0x100
	s_addc_u32 s43, s43, 0
	s_add_u32 s70, s59, s40
	s_addc_u32 s71, s66, s41
	s_cmpk_eq_i32 s40, 0x700
	s_cselect_b32 s45, s27, s43
	s_cselect_b32 s44, s67, s42
	s_cselect_b32 s43, s23, s71
	s_cselect_b32 s42, s68, s70
	v_lshl_add_u64 v[154:155], v[146:147], 0, s[40:41]
	s_add_i32 m0, s17, 0xc000
	ds_read_b128 v[188:191], v159
	ds_read_b128 v[192:195], v159 offset:1024
	ds_read_b128 v[196:199], v159 offset:2048
	ds_read_b128 v[200:203], v159 offset:3072
	ds_read_b128 v[204:207], v159 offset:4096
	ds_read_b128 v[208:211], v159 offset:5120
	ds_read_b128 v[212:215], v159 offset:6144
	ds_read_b128 v[216:219], v159 offset:7168
	global_load_lds_dwordx4 v[154:155], off
	v_lshl_add_u64 v[154:155], v[148:149], 0, s[40:41]
	s_add_i32 m0, s17, 0xe000
	s_nop 0
	global_load_lds_dwordx4 v[154:155], off
	s_waitcnt vmcnt(8)
	s_waitcnt lgkmcnt(0)
	s_barrier
; #define PG8_STAGEA(bufoff, gbase) PG8_STAGE_(bufoff, gbase, voffA)
; #define PG8_STAGEB(bufoff, gbase) PG8_STAGE_(bufoff, gbase, voffB)
; #define PG8_LDA(dst, b, h) do { _Pragma("unroll") for (int m = 0; m < 4; ++m) _Pragma("unroll") for (int k = 0; k < 2; ++k) dst[m][k] = *(const LAS bf16x8*)(lds + PG8_SA(b, h) + aoff + m * 2048 + k * 1024); } while (0)
; #define PG8_MMA(ai, bj, At, Bt_) do { __builtin_amdgcn_s_setprio(1); _Pragma("unroll") for (int m = 0; m < 4; ++m) _Pragma("unroll") for (int n = 0; n < 2; ++n) _Pragma("unroll") for (int k = 0; k < 2; ++k) \
;         acc[ai][bj][m][n] = __builtin_amdgcn_mfma_f32_16x16x32_bf16(Bt_[n][k], At[m][k], acc[ai][bj][m][n], 0, 0, 0); __builtin_amdgcn_s_setprio(0); } while (0)
; #define PG8_WAIT_V(n) asm volatile("s_waitcnt vmcnt(" #n ")" ::: "memory")
; #define PG8_WAIT_L(n) asm volatile("s_waitcnt lgkmcnt(" #n ")" ::: "memory")
; #define PG8_BAR __builtin_amdgcn_s_barrier()
; #define PG8_SCHED __builtin_amdgcn_sched_barrier(0)
; template <int EK, int SK = -1>
; __device__ __forceinline__ void gemm_phase(LAS unsigned char* lds, const bf16_t* A, const bf16_t* Bt, int nM, int N, int K, const EpiArgs& E) {
;     ...
;             PG8_WAIT_V(8); PG8_WAIT_L(0); PG8_BAR; PG8_MMA(0, 0, At, B0); PG8_MMA(0, 1, At, B1); PG8_BAR; PG8_SCHED;
;             PG8_LDA(At, 0, 1); PG8_STAGEB(PG8_SB(0, 0), b2); PG8_STAGEB(PG8_SB(0, 1), b2 + hstep); PG8_STAGEA(PG8_SA(0, 0), a2);
;             PG8_WAIT_V(8); PG8_WAIT_L(0); PG8_BAR; PG8_MMA(1, 0, At, B0); PG8_MMA(1, 1, At, B1); PG8_BAR; PG8_SCHED;
	s_waitcnt lgkmcnt(0)
	v_mfma_f32_16x16x32_bf16 v[110:113], v[150:153], v[188:191], v[110:113]
	v_mfma_f32_16x16x32_bf16 v[102:105], v[150:153], v[196:199], v[102:105]
	v_mfma_f32_16x16x32_bf16 v[94:97], v[150:153], v[204:207], v[94:97]
	v_mfma_f32_16x16x32_bf16 v[86:89], v[150:153], v[212:215], v[86:89]
	v_mfma_f32_16x16x32_bf16 v[82:85], v[164:167], v[212:215], v[82:85]
	v_mfma_f32_16x16x32_bf16 v[90:93], v[164:167], v[204:207], v[90:93]
	v_mfma_f32_16x16x32_bf16 v[98:101], v[164:167], v[196:199], v[98:101]
	v_mfma_f32_16x16x32_bf16 v[106:109], v[164:167], v[188:191], v[106:109]
	v_mfma_f32_16x16x32_bf16 v[110:113], v[160:163], v[192:195], v[110:113]
	v_mfma_f32_16x16x32_bf16 v[102:105], v[160:163], v[200:203], v[102:105]
	v_mfma_f32_16x16x32_bf16 v[94:97], v[160:163], v[208:211], v[94:97]
	v_mfma_f32_16x16x32_bf16 v[86:89], v[160:163], v[216:219], v[86:89]
	v_mfma_f32_16x16x32_bf16 v[82:85], v[168:171], v[216:219], v[82:85]
	v_mfma_f32_16x16x32_bf16 v[90:93], v[168:171], v[208:211], v[90:93]
	v_mfma_f32_16x16x32_bf16 v[98:101], v[168:171], v[200:203], v[98:101]
	v_mfma_f32_16x16x32_bf16 v[106:109], v[168:171], v[192:195], v[106:109]
	v_mfma_f32_16x16x32_bf16 v[78:81], v[172:175], v[188:191], v[78:81]
	v_mfma_f32_16x16x32_bf16 v[70:73], v[172:175], v[196:199], v[70:73]
	v_mfma_f32_16x16x32_bf16 v[62:65], v[172:175], v[204:207], v[62:65]
	v_mfma_f32_16x16x32_bf16 v[54:57], v[172:175], v[212:215], v[54:57]
	v_mfma_f32_16x16x32_bf16 v[50:53], v[180:183], v[212:215], v[50:53]
	v_mfma_f32_16x16x32_bf16 v[58:61], v[180:183], v[204:207], v[58:61]
	v_mfma_f32_16x16x32_bf16 v[66:69], v[180:183], v[196:199], v[66:69]
	v_mfma_f32_16x16x32_bf16 v[74:77], v[180:183], v[188:191], v[74:77]
	v_mfma_f32_16x16x32_bf16 v[78:81], v[176:179], v[192:195], v[78:81]
	v_mfma_f32_16x16x32_bf16 v[70:73], v[176:179], v[200:203], v[70:73]
	v_mfma_f32_16x16x32_bf16 v[62:65], v[176:179], v[208:211], v[62:65]
	v_mfma_f32_16x16x32_bf16 v[54:57], v[176:179], v[216:219], v[54:57]
	v_mfma_f32_16x16x32_bf16 v[50:53], v[184:187], v[216:219], v[50:53]
	v_mfma_f32_16x16x32_bf16 v[58:61], v[184:187], v[208:211], v[58:61]
	v_mfma_f32_16x16x32_bf16 v[66:69], v[184:187], v[200:203], v[66:69]
	v_mfma_f32_16x16x32_bf16 v[74:77], v[184:187], v[192:195], v[74:77]
	s_barrier
	s_add_i32 s70, s54, s49
	v_lshl_add_u64 v[154:155], s[42:43], 0, v[132:133]
	s_mov_b32 m0, s70
	ds_read_b128 v[188:191], v159 offset:16384
	ds_read_b128 v[192:195], v159 offset:17408
	ds_read_b128 v[196:199], v159 offset:18432
	ds_read_b128 v[200:203], v159 offset:19456
	ds_read_b128 v[204:207], v159 offset:20480
	ds_read_b128 v[208:211], v159 offset:21504
	ds_read_b128 v[212:215], v159 offset:22528
	ds_read_b128 v[216:219], v159 offset:23552
	global_load_lds_dwordx4 v[154:155], off
	s_add_i32 m0, s70, 0x2000
	s_add_u32 s70, s42, 0x40000
	v_lshl_add_u64 v[220:221], s[42:43], 0, v[136:137]
	s_addc_u32 s71, s43, 0
	s_add_i32 s72, s55, s49
	global_load_lds_dwordx4 v[220:221], off
	v_lshl_add_u64 v[222:223], s[70:71], 0, v[132:133]
	s_mov_b32 m0, s72
	v_lshl_add_u64 v[224:225], s[44:45], 0, v[134:135]
	global_load_lds_dwordx4 v[222:223], off
	v_lshl_add_u64 v[222:223], s[70:71], 0, v[136:137]
	s_add_i32 m0, s72, 0x2000
	s_nop 0
	global_load_lds_dwordx4 v[222:223], off
	v_lshl_add_u64 v[222:223], s[44:45], 0, v[130:131]
	s_mov_b32 m0, s17
	s_nop 0
	global_load_lds_dwordx4 v[222:223], off
	s_mov_b32 m0, s19
	s_nop 0
	global_load_lds_dwordx4 v[224:225], off
	s_waitcnt vmcnt(8)
	s_waitcnt lgkmcnt(0)
	s_barrier
	s_waitcnt lgkmcnt(0)
	v_mfma_f32_16x16x32_bf16 v[46:49], v[150:153], v[188:191], v[46:49]
	v_mfma_f32_16x16x32_bf16 v[38:41], v[150:153], v[196:199], v[38:41]
	v_mfma_f32_16x16x32_bf16 v[30:33], v[150:153], v[204:207], v[30:33]
	v_mfma_f32_16x16x32_bf16 v[22:25], v[150:153], v[212:215], v[22:25]
	v_mfma_f32_16x16x32_bf16 v[18:21], v[164:167], v[212:215], v[18:21]
	v_mfma_f32_16x16x32_bf16 v[26:29], v[164:167], v[204:207], v[26:29]
	v_mfma_f32_16x16x32_bf16 v[34:37], v[164:167], v[196:199], v[34:37]
	v_mfma_f32_16x16x32_bf16 v[42:45], v[164:167], v[188:191], v[42:45]
	v_mfma_f32_16x16x32_bf16 v[46:49], v[160:163], v[192:195], v[46:49]
	v_mfma_f32_16x16x32_bf16 v[38:41], v[160:163], v[200:203], v[38:41]
	v_mfma_f32_16x16x32_bf16 v[30:33], v[160:163], v[208:211], v[30:33]
	v_mfma_f32_16x16x32_bf16 v[22:25], v[160:163], v[216:219], v[22:25]
	v_mfma_f32_16x16x32_bf16 v[18:21], v[168:171], v[216:219], v[18:21]
	v_mfma_f32_16x16x32_bf16 v[26:29], v[168:171], v[208:211], v[26:29]
	v_mfma_f32_16x16x32_bf16 v[34:37], v[168:171], v[200:203], v[34:37]
	v_mfma_f32_16x16x32_bf16 v[42:45], v[168:171], v[192:195], v[42:45]
	v_mfma_f32_16x16x32_bf16 v[14:17], v[172:175], v[188:191], v[14:17]
	v_mfma_f32_16x16x32_bf16 v[6:9], v[172:175], v[196:199], v[6:9]
	v_mfma_f32_16x16x32_bf16 v[114:117], v[172:175], v[204:207], v[114:117]
	v_mfma_f32_16x16x32_bf16 v[122:125], v[172:175], v[212:215], v[122:125]
	v_mfma_f32_16x16x32_bf16 v[126:129], v[180:183], v[212:215], v[126:129]
	v_mfma_f32_16x16x32_bf16 v[118:121], v[180:183], v[204:207], v[118:121]
	v_mfma_f32_16x16x32_bf16 v[2:5], v[180:183], v[196:199], v[2:5]
	v_mfma_f32_16x16x32_bf16 v[10:13], v[180:183], v[188:191], v[10:13]
	v_mfma_f32_16x16x32_bf16 v[14:17], v[176:179], v[192:195], v[14:17]
	v_mfma_f32_16x16x32_bf16 v[6:9], v[176:179], v[200:203], v[6:9]
	v_mfma_f32_16x16x32_bf16 v[114:117], v[176:179], v[208:211], v[114:117]
	v_mfma_f32_16x16x32_bf16 v[122:125], v[176:179], v[216:219], v[122:125]
	v_mfma_f32_16x16x32_bf16 v[126:129], v[184:187], v[216:219], v[126:129]
	v_mfma_f32_16x16x32_bf16 v[118:121], v[184:187], v[208:211], v[118:121]
	v_mfma_f32_16x16x32_bf16 v[2:5], v[184:187], v[200:203], v[2:5]
	v_mfma_f32_16x16x32_bf16 v[10:13], v[184:187], v[192:195], v[10:13]
	s_barrier
; #define PG8_STAGEA(bufoff, gbase) PG8_STAGE_(bufoff, gbase, voffA)
; #define PG8_STAGEB(bufoff, gbase) PG8_STAGE_(bufoff, gbase, voffB)
; #define PG8_LDA(dst, b, h) do { _Pragma("unroll") for (int m = 0; m < 4; ++m) _Pragma("unroll") for (int k = 0; k < 2; ++k) dst[m][k] = *(const LAS bf16x8*)(lds + PG8_SA(b, h) + aoff + m * 2048 + k * 1024); } while (0)
; #define PG8_LDB(dst, b, h) do { _Pragma("unroll") for (int n = 0; n < 2; ++n) _Pragma("unroll") for (int k = 0; k < 2; ++k) dst[n][k] = *(const LAS bf16x8*)(lds + PG8_SB(b, h) + boff + n * 2048 + k * 1024); } while (0)
; #define PG8_MMA(ai, bj, At, Bt_) do { __builtin_amdgcn_s_setprio(1); _Pragma("unroll") for (int m = 0; m < 4; ++m) _Pragma("unroll") for (int n = 0; n < 2; ++n) _Pragma("unroll") for (int k = 0; k < 2; ++k) \
;         acc[ai][bj][m][n] = __builtin_amdgcn_mfma_f32_16x16x32_bf16(Bt_[n][k], At[m][k], acc[ai][bj][m][n], 0, 0, 0); __builtin_amdgcn_s_setprio(0); } while (0)
; #define PG8_WAIT_V(n) asm volatile("s_waitcnt vmcnt(" #n ")" ::: "memory")
; #define PG8_WAIT_L(n) asm volatile("s_waitcnt lgkmcnt(" #n ")" ::: "memory")
; #define PG8_BAR __builtin_amdgcn_s_barrier()
; #define PG8_SCHED __builtin_amdgcn_sched_barrier(0)
; template <int EK, int SK = -1>
; __device__ __forceinline__ void gemm_phase(LAS unsigned char* lds, const bf16_t* A, const bf16_t* Bt, int nM, int N, int K, const EpiArgs& E) {
;     ...
;             PG8_LDB(B0, 1, 0); PG8_LDB(B1, 1, 1); PG8_SCHED; PG8_LDA(At, 1, 0); PG8_STAGEA(PG8_SA(0, 1), a2 + hstep);
;             PG8_WAIT_V(8); PG8_WAIT_L(0); PG8_BAR; PG8_MMA(0, 0, At, B0); PG8_MMA(0, 1, At, B1); PG8_BAR; PG8_SCHED;
;             PG8_LDA(At, 1, 1); PG8_STAGEB(PG8_SB(1, 0), b3); PG8_STAGEB(PG8_SB(1, 1), b3 + hstep); PG8_STAGEA(PG8_SA(1, 0), a3);
;             PG8_WAIT_V(8); PG8_WAIT_L(0); PG8_BAR; PG8_MMA(1, 0, At, B0); PG8_MMA(1, 1, At, B1); PG8_BAR; PG8_SCHED;
;         }
	s_add_i32 s70, 0, 0x18000
	s_add_i32 s71, 0, 0x1c000
	v_add_u32_e32 v168, s70, v156
	v_add_u32_e32 v184, s71, v156
	ds_read_b128 v[150:153], v168
	ds_read_b128 v[160:163], v168 offset:1024
	ds_read_b128 v[164:167], v168 offset:2048
	ds_read_b128 v[168:171], v168 offset:3072
	ds_read_b128 v[172:175], v184
	ds_read_b128 v[176:179], v184 offset:1024
	ds_read_b128 v[180:183], v184 offset:2048
	ds_read_b128 v[184:187], v184 offset:3072
	s_add_u32 s44, s44, 0x40000
	s_addc_u32 s45, s45, 0
	s_mov_b32 m0, s50
	v_lshl_add_u64 v[226:227], s[44:45], 0, v[130:131]
	ds_read_b128 v[188:191], v159 offset:32768
	ds_read_b128 v[192:195], v159 offset:33792
	ds_read_b128 v[196:199], v159 offset:34816
	ds_read_b128 v[200:203], v159 offset:35840
	ds_read_b128 v[204:207], v159 offset:36864
	ds_read_b128 v[208:211], v159 offset:37888
	ds_read_b128 v[212:215], v159 offset:38912
	ds_read_b128 v[216:219], v159 offset:39936
	global_load_lds_dwordx4 v[226:227], off
	v_lshl_add_u64 v[226:227], s[44:45], 0, v[134:135]
	s_mov_b32 m0, s51
	s_nop 0
	global_load_lds_dwordx4 v[226:227], off
	s_waitcnt vmcnt(8)
	s_waitcnt lgkmcnt(0)
	s_barrier
	s_waitcnt lgkmcnt(0)
	v_mfma_f32_16x16x32_bf16 v[110:113], v[150:153], v[188:191], v[110:113]
	v_mfma_f32_16x16x32_bf16 v[102:105], v[150:153], v[196:199], v[102:105]
	v_mfma_f32_16x16x32_bf16 v[94:97], v[150:153], v[204:207], v[94:97]
	v_mfma_f32_16x16x32_bf16 v[86:89], v[150:153], v[212:215], v[86:89]
	v_mfma_f32_16x16x32_bf16 v[82:85], v[164:167], v[212:215], v[82:85]
	v_mfma_f32_16x16x32_bf16 v[90:93], v[164:167], v[204:207], v[90:93]
	v_mfma_f32_16x16x32_bf16 v[98:101], v[164:167], v[196:199], v[98:101]
	v_mfma_f32_16x16x32_bf16 v[106:109], v[164:167], v[188:191], v[106:109]
	v_mfma_f32_16x16x32_bf16 v[110:113], v[160:163], v[192:195], v[110:113]
	v_mfma_f32_16x16x32_bf16 v[102:105], v[160:163], v[200:203], v[102:105]
	v_mfma_f32_16x16x32_bf16 v[94:97], v[160:163], v[208:211], v[94:97]
	v_mfma_f32_16x16x32_bf16 v[86:89], v[160:163], v[216:219], v[86:89]
	v_mfma_f32_16x16x32_bf16 v[82:85], v[168:171], v[216:219], v[82:85]
	v_mfma_f32_16x16x32_bf16 v[90:93], v[168:171], v[208:211], v[90:93]
	v_mfma_f32_16x16x32_bf16 v[98:101], v[168:171], v[200:203], v[98:101]
	v_mfma_f32_16x16x32_bf16 v[106:109], v[168:171], v[192:195], v[106:109]
	v_mfma_f32_16x16x32_bf16 v[78:81], v[172:175], v[188:191], v[78:81]
	v_mfma_f32_16x16x32_bf16 v[70:73], v[172:175], v[196:199], v[70:73]
	v_mfma_f32_16x16x32_bf16 v[62:65], v[172:175], v[204:207], v[62:65]
	v_mfma_f32_16x16x32_bf16 v[54:57], v[172:175], v[212:215], v[54:57]
	v_mfma_f32_16x16x32_bf16 v[50:53], v[180:183], v[212:215], v[50:53]
	v_mfma_f32_16x16x32_bf16 v[58:61], v[180:183], v[204:207], v[58:61]
	v_mfma_f32_16x16x32_bf16 v[66:69], v[180:183], v[196:199], v[66:69]
	v_mfma_f32_16x16x32_bf16 v[74:77], v[180:183], v[188:191], v[74:77]
	v_mfma_f32_16x16x32_bf16 v[78:81], v[176:179], v[192:195], v[78:81]
	v_mfma_f32_16x16x32_bf16 v[70:73], v[176:179], v[200:203], v[70:73]
	v_mfma_f32_16x16x32_bf16 v[62:65], v[176:179], v[208:211], v[62:65]
	v_mfma_f32_16x16x32_bf16 v[54:57], v[176:179], v[216:219], v[54:57]
	v_mfma_f32_16x16x32_bf16 v[50:53], v[184:187], v[216:219], v[50:53]
	v_mfma_f32_16x16x32_bf16 v[58:61], v[184:187], v[208:211], v[58:61]
	v_mfma_f32_16x16x32_bf16 v[66:69], v[184:187], v[200:203], v[66:69]
	v_mfma_f32_16x16x32_bf16 v[74:77], v[184:187], v[192:195], v[74:77]
	s_barrier
	s_add_i32 s44, s70, s49
	v_lshl_add_u64 v[154:155], v[154:155], 0, s[10:11]
	s_mov_b32 m0, s44
	ds_read_b128 v[188:191], v159 offset:49152
	ds_read_b128 v[192:195], v159 offset:50176
	ds_read_b128 v[196:199], v159 offset:51200
	ds_read_b128 v[200:203], v159 offset:52224
	ds_read_b128 v[204:207], v159 offset:53248
	ds_read_b128 v[208:211], v159 offset:54272
	ds_read_b128 v[212:215], v159 offset:55296
	ds_read_b128 v[216:219], v159 offset:56320
	global_load_lds_dwordx4 v[154:155], off
	s_add_i32 m0, s44, 0x2000
	s_add_u32 s42, s42, 0x40080
	v_lshl_add_u64 v[154:155], v[220:221], 0, s[10:11]
	s_addc_u32 s43, s43, 0
	s_add_i32 s44, s71, s49
	global_load_lds_dwordx4 v[154:155], off
	v_lshl_add_u64 v[154:155], s[42:43], 0, v[132:133]
	s_mov_b32 m0, s44
	s_nop 0
	global_load_lds_dwordx4 v[154:155], off
	v_lshl_add_u64 v[154:155], s[42:43], 0, v[136:137]
	s_add_i32 m0, s44, 0x2000
	s_nop 0
	global_load_lds_dwordx4 v[154:155], off
	v_lshl_add_u64 v[154:155], v[222:223], 0, s[10:11]
	s_mov_b32 m0, s52
	s_nop 0
	global_load_lds_dwordx4 v[154:155], off
	v_lshl_add_u64 v[154:155], v[224:225], 0, s[10:11]
	s_mov_b32 m0, s53
	s_nop 0
	global_load_lds_dwordx4 v[154:155], off
	s_waitcnt vmcnt(8)
	s_waitcnt lgkmcnt(0)
	s_barrier
	s_waitcnt lgkmcnt(0)
	v_mfma_f32_16x16x32_bf16 v[46:49], v[150:153], v[188:191], v[46:49]
	v_mfma_f32_16x16x32_bf16 v[38:41], v[150:153], v[196:199], v[38:41]
	v_mfma_f32_16x16x32_bf16 v[30:33], v[150:153], v[204:207], v[30:33]
	v_mfma_f32_16x16x32_bf16 v[22:25], v[150:153], v[212:215], v[22:25]
	v_mfma_f32_16x16x32_bf16 v[18:21], v[164:167], v[212:215], v[18:21]
	v_mfma_f32_16x16x32_bf16 v[26:29], v[164:167], v[204:207], v[26:29]
	v_mfma_f32_16x16x32_bf16 v[34:37], v[164:167], v[196:199], v[34:37]
	v_mfma_f32_16x16x32_bf16 v[42:45], v[164:167], v[188:191], v[42:45]
	v_mfma_f32_16x16x32_bf16 v[46:49], v[160:163], v[192:195], v[46:49]
	v_mfma_f32_16x16x32_bf16 v[38:41], v[160:163], v[200:203], v[38:41]
	v_mfma_f32_16x16x32_bf16 v[30:33], v[160:163], v[208:211], v[30:33]
	v_mfma_f32_16x16x32_bf16 v[22:25], v[160:163], v[216:219], v[22:25]
	v_mfma_f32_16x16x32_bf16 v[18:21], v[168:171], v[216:219], v[18:21]
	v_mfma_f32_16x16x32_bf16 v[26:29], v[168:171], v[208:211], v[26:29]
	v_mfma_f32_16x16x32_bf16 v[34:37], v[168:171], v[200:203], v[34:37]
	v_mfma_f32_16x16x32_bf16 v[42:45], v[168:171], v[192:195], v[42:45]
	v_mfma_f32_16x16x32_bf16 v[14:17], v[172:175], v[188:191], v[14:17]
	v_mfma_f32_16x16x32_bf16 v[6:9], v[172:175], v[196:199], v[6:9]
	v_mfma_f32_16x16x32_bf16 v[114:117], v[172:175], v[204:207], v[114:117]
	v_mfma_f32_16x16x32_bf16 v[122:125], v[172:175], v[212:215], v[122:125]
	v_mfma_f32_16x16x32_bf16 v[126:129], v[180:183], v[212:215], v[126:129]
	v_mfma_f32_16x16x32_bf16 v[118:121], v[180:183], v[204:207], v[118:121]
	v_mfma_f32_16x16x32_bf16 v[2:5], v[180:183], v[196:199], v[2:5]
	v_mfma_f32_16x16x32_bf16 v[10:13], v[180:183], v[188:191], v[10:13]
	v_mfma_f32_16x16x32_bf16 v[14:17], v[176:179], v[192:195], v[14:17]
	v_mfma_f32_16x16x32_bf16 v[6:9], v[176:179], v[200:203], v[6:9]
	v_mfma_f32_16x16x32_bf16 v[114:117], v[176:179], v[208:211], v[114:117]
	v_mfma_f32_16x16x32_bf16 v[122:125], v[176:179], v[216:219], v[122:125]
	v_mfma_f32_16x16x32_bf16 v[126:129], v[184:187], v[216:219], v[126:129]
	v_mfma_f32_16x16x32_bf16 v[118:121], v[184:187], v[208:211], v[118:121]
	v_mfma_f32_16x16x32_bf16 v[2:5], v[184:187], v[200:203], v[2:5]
	v_mfma_f32_16x16x32_bf16 v[10:13], v[184:187], v[192:195], v[10:13]
	s_barrier
	s_add_i32 s69, s69, 2
	s_add_u32 s40, s40, 0x100
	s_addc_u32 s41, s41, 0
	s_cmp_gt_u32 s69, 13
	s_cbranch_scc0 .LBB0_1245

; #define PG8_STAGEA(bufoff, gbase) PG8_STAGE_(bufoff, gbase, voffA)
; #define PG8_STAGEB(bufoff, gbase) PG8_STAGE_(bufoff, gbase, voffB)
; #define PG8_LDA(dst, b, h) do { _Pragma("unroll") for (int m = 0; m < 4; ++m) _Pragma("unroll") for (int k = 0; k < 2; ++k) dst[m][k] = *(const LAS bf16x8*)(lds + PG8_SA(b, h) + aoff + m * 2048 + k * 1024); } while (0)
; #define PG8_LDB(dst, b, h) do { _Pragma("unroll") for (int n = 0; n < 2; ++n) _Pragma("unroll") for (int k = 0; k < 2; ++k) dst[n][k] = *(const LAS bf16x8*)(lds + PG8_SB(b, h) + boff + n * 2048 + k * 1024); } while (0)
; #define PG8_MMA(ai, bj, At, Bt_) do { __builtin_amdgcn_s_setprio(1); _Pragma("unroll") for (int m = 0; m < 4; ++m) _Pragma("unroll") for (int n = 0; n < 2; ++n) _Pragma("unroll") for (int k = 0; k < 2; ++k) \
;         acc[ai][bj][m][n] = __builtin_amdgcn_mfma_f32_16x16x32_bf16(Bt_[n][k], At[m][k], acc[ai][bj][m][n], 0, 0, 0); __builtin_amdgcn_s_setprio(0); } while (0)
; #define PG8_WAIT_V(n) asm volatile("s_waitcnt vmcnt(" #n ")" ::: "memory")
; #define PG8_WAIT_L(n) asm volatile("s_waitcnt lgkmcnt(" #n ")" ::: "memory")
; #define PG8_BAR __builtin_amdgcn_s_barrier()
; #define PG8_SCHED __builtin_amdgcn_sched_barrier(0)
; template <int EK, int SK = -1>
; __device__ __forceinline__ void gemm_phase(LAS unsigned char* lds, const bf16_t* A, const bf16_t* Bt, int nM, int N, int K, const EpiArgs& E) {
;     ...
;         const bool has_next = S.next(ui + 1, nxt);
;         const char* nA = has_next ? (const char*)A + (size_t)nxt.pm * tstep : cA; const char* nB = has_next ? (const char*)Bt + (size_t)nxt.pn * tstep : cB;
;         for (int t = 0; t < nt; t += 2) {
;             const bool last = (t == nt - 2);
;             const char* a1 = cA + (size_t)(t + 1) * kstep;
;             const char* a2 = last ? nA : cA + (size_t)(t + 2) * kstep; const char* b2 = last ? nB : cB + (size_t)(t + 2) * kstep;
;             const char* a3 = a2 + kstep; const char* b3 = b2 + kstep;
;             PG8_LDB(B0, 0, 0); PG8_LDB(B1, 0, 1); PG8_SCHED; PG8_LDA(At, 0, 0); PG8_STAGEA(PG8_SA(1, 1), a1 + hstep);
;             PG8_WAIT_V(8); PG8_WAIT_L(0); PG8_BAR; PG8_MMA(0, 0, At, B0); PG8_MMA(0, 1, At, B1); PG8_BAR; PG8_SCHED;
;             PG8_LDA(At, 0, 1); PG8_STAGEB(PG8_SB(0, 0), b2); PG8_STAGEB(PG8_SB(0, 1), b2 + hstep); PG8_STAGEA(PG8_SA(0, 0), a2);
.LBB0_1337:
	s_add_u32 s73, s42, 0x100
	s_addc_u32 s74, s43, 0
	s_waitcnt lgkmcnt(0)
	v_lshl_add_u64 v[146:147], s[20:21], 0, v[138:139]
	v_lshl_add_u64 v[148:149], s[20:21], 0, v[140:141]
	s_mov_b32 s26, -2
	s_mov_b64 s[42:43], 0
	v_add_u32_e32 v150, s67, v152
	ds_read_b128 v[156:159], v150
	ds_read_b128 v[160:163], v150 offset:1024
	ds_read_b128 v[164:167], v150 offset:2048
	ds_read_b128 v[168:171], v150 offset:3072
	v_add_u32_e32 v150, s68, v152
	s_add_u32 s44, s20, s42
	ds_read_b128 v[172:175], v150
	ds_read_b128 v[176:179], v150 offset:1024
	ds_read_b128 v[180:183], v150 offset:2048
	ds_read_b128 v[184:187], v150 offset:3072
	s_addc_u32 s45, s21, s43
	s_add_u32 s44, s44, 0x100
	s_addc_u32 s45, s45, 0
	s_add_u32 s75, s73, s42
	s_addc_u32 s76, s74, s43
	s_cmpk_eq_i32 s42, 0x1500
	s_cselect_b32 s47, s41, s45
	s_cselect_b32 s46, s40, s44
	s_cselect_b32 s45, s9, s76
	s_cselect_b32 s44, s8, s75
	v_lshl_add_u64 v[150:151], v[146:147], 0, s[42:43]
	s_add_i32 m0, s53, 0xc000
	ds_read_b128 v[188:191], v154
	ds_read_b128 v[192:195], v154 offset:1024
	ds_read_b128 v[196:199], v154 offset:2048
	ds_read_b128 v[200:203], v154 offset:3072
	ds_read_b128 v[204:207], v154 offset:4096
	ds_read_b128 v[208:211], v154 offset:5120
	ds_read_b128 v[212:215], v154 offset:6144
	ds_read_b128 v[216:219], v154 offset:7168
	global_load_lds_dwordx4 v[150:151], off
	v_lshl_add_u64 v[150:151], v[148:149], 0, s[42:43]
	s_add_i32 m0, s53, 0xe000
	s_nop 0
	global_load_lds_dwordx4 v[150:151], off
	s_waitcnt vmcnt(8)
	s_waitcnt lgkmcnt(0)
	s_barrier
	s_waitcnt lgkmcnt(0)
	v_mfma_f32_16x16x32_bf16 v[126:129], v[156:159], v[188:191], 0
	v_mfma_f32_16x16x32_bf16 v[118:121], v[156:159], v[196:199], 0
	v_mfma_f32_16x16x32_bf16 v[110:113], v[156:159], v[204:207], 0
	v_mfma_f32_16x16x32_bf16 v[102:105], v[156:159], v[212:215], 0
	v_mfma_f32_16x16x32_bf16 v[98:101], v[164:167], v[212:215], 0
	v_mfma_f32_16x16x32_bf16 v[106:109], v[164:167], v[204:207], 0
	v_mfma_f32_16x16x32_bf16 v[114:117], v[164:167], v[196:199], 0
	v_mfma_f32_16x16x32_bf16 v[122:125], v[164:167], v[188:191], 0
	v_mfma_f32_16x16x32_bf16 v[126:129], v[160:163], v[192:195], v[126:129]
	v_mfma_f32_16x16x32_bf16 v[118:121], v[160:163], v[200:203], v[118:121]
	v_mfma_f32_16x16x32_bf16 v[110:113], v[160:163], v[208:211], v[110:113]
	v_mfma_f32_16x16x32_bf16 v[102:105], v[160:163], v[216:219], v[102:105]
	v_mfma_f32_16x16x32_bf16 v[98:101], v[168:171], v[216:219], v[98:101]
	v_mfma_f32_16x16x32_bf16 v[106:109], v[168:171], v[208:211], v[106:109]
	v_mfma_f32_16x16x32_bf16 v[114:117], v[168:171], v[200:203], v[114:117]
	v_mfma_f32_16x16x32_bf16 v[122:125], v[168:171], v[192:195], v[122:125]
	v_mfma_f32_16x16x32_bf16 v[94:97], v[172:175], v[188:191], 0
	v_mfma_f32_16x16x32_bf16 v[86:89], v[172:175], v[196:199], 0
	v_mfma_f32_16x16x32_bf16 v[78:81], v[172:175], v[204:207], 0
	v_mfma_f32_16x16x32_bf16 v[70:73], v[172:175], v[212:215], 0
	v_mfma_f32_16x16x32_bf16 v[66:69], v[180:183], v[212:215], 0
	v_mfma_f32_16x16x32_bf16 v[74:77], v[180:183], v[204:207], 0
	v_mfma_f32_16x16x32_bf16 v[82:85], v[180:183], v[196:199], 0
	v_mfma_f32_16x16x32_bf16 v[90:93], v[180:183], v[188:191], 0
	v_mfma_f32_16x16x32_bf16 v[94:97], v[176:179], v[192:195], v[94:97]
	v_mfma_f32_16x16x32_bf16 v[86:89], v[176:179], v[200:203], v[86:89]
	v_mfma_f32_16x16x32_bf16 v[78:81], v[176:179], v[208:211], v[78:81]
	v_mfma_f32_16x16x32_bf16 v[70:73], v[176:179], v[216:219], v[70:73]
	v_mfma_f32_16x16x32_bf16 v[66:69], v[184:187], v[216:219], v[66:69]
	v_mfma_f32_16x16x32_bf16 v[74:77], v[184:187], v[208:211], v[74:77]
	v_mfma_f32_16x16x32_bf16 v[82:85], v[184:187], v[200:203], v[82:85]
	v_mfma_f32_16x16x32_bf16 v[90:93], v[184:187], v[192:195], v[90:93]
	s_barrier
	s_add_i32 s75, s67, s52
	v_lshl_add_u64 v[150:151], s[44:45], 0, v[132:133]
	s_mov_b32 m0, s75
	ds_read_b128 v[188:191], v154 offset:16384
	ds_read_b128 v[192:195], v154 offset:17408
	ds_read_b128 v[196:199], v154 offset:18432
	ds_read_b128 v[200:203], v154 offset:19456
	ds_read_b128 v[204:207], v154 offset:20480
	ds_read_b128 v[208:211], v154 offset:21504
	ds_read_b128 v[212:215], v154 offset:22528
	ds_read_b128 v[216:219], v154 offset:23552
	global_load_lds_dwordx4 v[150:151], off
	s_add_i32 m0, s75, 0x2000
	s_add_u32 s76, s44, 0xb0000
	v_lshl_add_u64 v[220:221], s[44:45], 0, v[136:137]
	s_addc_u32 s77, s45, 0
	s_add_i32 s75, s68, s52
	global_load_lds_dwordx4 v[220:221], off
	v_lshl_add_u64 v[222:223], s[76:77], 0, v[132:133]
	s_mov_b32 m0, s75
	v_lshl_add_u64 v[224:225], s[46:47], 0, v[134:135]
	global_load_lds_dwordx4 v[222:223], off
	v_lshl_add_u64 v[222:223], s[76:77], 0, v[136:137]
	s_add_i32 m0, s75, 0x2000
	s_nop 0
	global_load_lds_dwordx4 v[222:223], off
	v_lshl_add_u64 v[222:223], s[46:47], 0, v[130:131]
	s_mov_b32 m0, s53
	s_nop 0
	global_load_lds_dwordx4 v[222:223], off
	s_mov_b32 m0, s54
	s_nop 0
	global_load_lds_dwordx4 v[224:225], off
	s_waitcnt vmcnt(8)
	s_waitcnt lgkmcnt(0)
	s_barrier
; #define PG8_STAGEA(bufoff, gbase) PG8_STAGE_(bufoff, gbase, voffA)
; #define PG8_LDA(dst, b, h) do { _Pragma("unroll") for (int m = 0; m < 4; ++m) _Pragma("unroll") for (int k = 0; k < 2; ++k) dst[m][k] = *(const LAS bf16x8*)(lds + PG8_SA(b, h) + aoff + m * 2048 + k * 1024); } while (0)
; #define PG8_LDB(dst, b, h) do { _Pragma("unroll") for (int n = 0; n < 2; ++n) _Pragma("unroll") for (int k = 0; k < 2; ++k) dst[n][k] = *(const LAS bf16x8*)(lds + PG8_SB(b, h) + boff + n * 2048 + k * 1024); } while (0)
; #define PG8_MMA(ai, bj, At, Bt_) do { __builtin_amdgcn_s_setprio(1); _Pragma("unroll") for (int m = 0; m < 4; ++m) _Pragma("unroll") for (int n = 0; n < 2; ++n) _Pragma("unroll") for (int k = 0; k < 2; ++k) \
;         acc[ai][bj][m][n] = __builtin_amdgcn_mfma_f32_16x16x32_bf16(Bt_[n][k], At[m][k], acc[ai][bj][m][n], 0, 0, 0); __builtin_amdgcn_s_setprio(0); } while (0)
; #define PG8_WAIT_V(n) asm volatile("s_waitcnt vmcnt(" #n ")" ::: "memory")
; #define PG8_WAIT_L(n) asm volatile("s_waitcnt lgkmcnt(" #n ")" ::: "memory")
; #define PG8_BAR __builtin_amdgcn_s_barrier()
; #define PG8_SCHED __builtin_amdgcn_sched_barrier(0)
; template <int EK, int SK = -1>
; __device__ __forceinline__ void gemm_phase(LAS unsigned char* lds, const bf16_t* A, const bf16_t* Bt, int nM, int N, int K, const EpiArgs& E) {
;     ...
;             PG8_WAIT_V(8); PG8_WAIT_L(0); PG8_BAR; PG8_MMA(1, 0, At, B0); PG8_MMA(1, 1, At, B1); PG8_BAR; PG8_SCHED;
;             PG8_LDB(B0, 1, 0); PG8_LDB(B1, 1, 1); PG8_SCHED; PG8_LDA(At, 1, 0); PG8_STAGEA(PG8_SA(0, 1), a2 + hstep);
;             PG8_WAIT_V(8); PG8_WAIT_L(0); PG8_BAR; PG8_MMA(0, 0, At, B0); PG8_MMA(0, 1, At, B1); PG8_BAR; PG8_SCHED;
	s_waitcnt lgkmcnt(0)
	v_mfma_f32_16x16x32_bf16 v[62:65], v[156:159], v[188:191], 0
	v_mfma_f32_16x16x32_bf16 v[54:57], v[156:159], v[196:199], 0
	v_mfma_f32_16x16x32_bf16 v[46:49], v[156:159], v[204:207], 0
	v_mfma_f32_16x16x32_bf16 v[38:41], v[156:159], v[212:215], 0
	v_mfma_f32_16x16x32_bf16 v[34:37], v[164:167], v[212:215], 0
	v_mfma_f32_16x16x32_bf16 v[42:45], v[164:167], v[204:207], 0
	v_mfma_f32_16x16x32_bf16 v[50:53], v[164:167], v[196:199], 0
	v_mfma_f32_16x16x32_bf16 v[58:61], v[164:167], v[188:191], 0
	v_mfma_f32_16x16x32_bf16 v[62:65], v[160:163], v[192:195], v[62:65]
	v_mfma_f32_16x16x32_bf16 v[54:57], v[160:163], v[200:203], v[54:57]
	v_mfma_f32_16x16x32_bf16 v[46:49], v[160:163], v[208:211], v[46:49]
	v_mfma_f32_16x16x32_bf16 v[38:41], v[160:163], v[216:219], v[38:41]
	v_mfma_f32_16x16x32_bf16 v[34:37], v[168:171], v[216:219], v[34:37]
	v_mfma_f32_16x16x32_bf16 v[42:45], v[168:171], v[208:211], v[42:45]
	v_mfma_f32_16x16x32_bf16 v[50:53], v[168:171], v[200:203], v[50:53]
	v_mfma_f32_16x16x32_bf16 v[58:61], v[168:171], v[192:195], v[58:61]
	v_mfma_f32_16x16x32_bf16 v[30:33], v[172:175], v[188:191], 0
	v_mfma_f32_16x16x32_bf16 v[22:25], v[172:175], v[196:199], 0
	v_mfma_f32_16x16x32_bf16 v[14:17], v[172:175], v[204:207], 0
	v_mfma_f32_16x16x32_bf16 v[6:9], v[172:175], v[212:215], 0
	v_mfma_f32_16x16x32_bf16 v[2:5], v[180:183], v[212:215], 0
	v_mfma_f32_16x16x32_bf16 v[10:13], v[180:183], v[204:207], 0
	v_mfma_f32_16x16x32_bf16 v[18:21], v[180:183], v[196:199], 0
	v_mfma_f32_16x16x32_bf16 v[26:29], v[180:183], v[188:191], 0
	v_mfma_f32_16x16x32_bf16 v[30:33], v[176:179], v[192:195], v[30:33]
	v_mfma_f32_16x16x32_bf16 v[22:25], v[176:179], v[200:203], v[22:25]
	v_mfma_f32_16x16x32_bf16 v[14:17], v[176:179], v[208:211], v[14:17]
	v_mfma_f32_16x16x32_bf16 v[6:9], v[176:179], v[216:219], v[6:9]
	v_mfma_f32_16x16x32_bf16 v[2:5], v[184:187], v[216:219], v[2:5]
	v_mfma_f32_16x16x32_bf16 v[10:13], v[184:187], v[208:211], v[10:13]
	v_mfma_f32_16x16x32_bf16 v[18:21], v[184:187], v[200:203], v[18:21]
	v_mfma_f32_16x16x32_bf16 v[26:29], v[184:187], v[192:195], v[26:29]
	s_barrier
	s_add_i32 s75, 0, 0x18000
	s_add_i32 s76, 0, 0x1c000
	v_add_u32_e32 v168, s75, v152
	v_add_u32_e32 v184, s76, v152
	ds_read_b128 v[156:159], v168
	ds_read_b128 v[160:163], v168 offset:1024
	ds_read_b128 v[164:167], v168 offset:2048
	ds_read_b128 v[168:171], v168 offset:3072
	ds_read_b128 v[172:175], v184
	ds_read_b128 v[176:179], v184 offset:1024
	ds_read_b128 v[180:183], v184 offset:2048
	ds_read_b128 v[184:187], v184 offset:3072
	s_add_u32 s46, s46, 0xb0000
	s_addc_u32 s47, s47, 0
	s_mov_b32 m0, s55
	v_lshl_add_u64 v[226:227], s[46:47], 0, v[130:131]
	ds_read_b128 v[188:191], v154 offset:32768
	ds_read_b128 v[192:195], v154 offset:33792
	ds_read_b128 v[196:199], v154 offset:34816
	ds_read_b128 v[200:203], v154 offset:35840
	ds_read_b128 v[204:207], v154 offset:36864
	ds_read_b128 v[208:211], v154 offset:37888
	ds_read_b128 v[212:215], v154 offset:38912
	ds_read_b128 v[216:219], v154 offset:39936
	global_load_lds_dwordx4 v[226:227], off
	v_lshl_add_u64 v[226:227], s[46:47], 0, v[134:135]
	s_mov_b32 m0, s56
	s_nop 0
	global_load_lds_dwordx4 v[226:227], off
	s_waitcnt vmcnt(8)
	s_waitcnt lgkmcnt(0)
	s_barrier
	s_waitcnt lgkmcnt(0)
	v_mfma_f32_16x16x32_bf16 v[126:129], v[156:159], v[188:191], v[126:129]
	v_mfma_f32_16x16x32_bf16 v[118:121], v[156:159], v[196:199], v[118:121]
	v_mfma_f32_16x16x32_bf16 v[110:113], v[156:159], v[204:207], v[110:113]
	v_mfma_f32_16x16x32_bf16 v[102:105], v[156:159], v[212:215], v[102:105]
	v_mfma_f32_16x16x32_bf16 v[98:101], v[164:167], v[212:215], v[98:101]
	v_mfma_f32_16x16x32_bf16 v[106:109], v[164:167], v[204:207], v[106:109]
	v_mfma_f32_16x16x32_bf16 v[114:117], v[164:167], v[196:199], v[114:117]
	v_mfma_f32_16x16x32_bf16 v[122:125], v[164:167], v[188:191], v[122:125]
	v_mfma_f32_16x16x32_bf16 v[126:129], v[160:163], v[192:195], v[126:129]
	v_mfma_f32_16x16x32_bf16 v[118:121], v[160:163], v[200:203], v[118:121]
	v_mfma_f32_16x16x32_bf16 v[110:113], v[160:163], v[208:211], v[110:113]
	v_mfma_f32_16x16x32_bf16 v[102:105], v[160:163], v[216:219], v[102:105]
	v_mfma_f32_16x16x32_bf16 v[98:101], v[168:171], v[216:219], v[98:101]
	v_mfma_f32_16x16x32_bf16 v[106:109], v[168:171], v[208:211], v[106:109]
	v_mfma_f32_16x16x32_bf16 v[114:117], v[168:171], v[200:203], v[114:117]
	v_mfma_f32_16x16x32_bf16 v[122:125], v[168:171], v[192:195], v[122:125]
	v_mfma_f32_16x16x32_bf16 v[94:97], v[172:175], v[188:191], v[94:97]
	v_mfma_f32_16x16x32_bf16 v[86:89], v[172:175], v[196:199], v[86:89]
	v_mfma_f32_16x16x32_bf16 v[78:81], v[172:175], v[204:207], v[78:81]
	v_mfma_f32_16x16x32_bf16 v[70:73], v[172:175], v[212:215], v[70:73]
	v_mfma_f32_16x16x32_bf16 v[66:69], v[180:183], v[212:215], v[66:69]
	v_mfma_f32_16x16x32_bf16 v[74:77], v[180:183], v[204:207], v[74:77]
	v_mfma_f32_16x16x32_bf16 v[82:85], v[180:183], v[196:199], v[82:85]
	v_mfma_f32_16x16x32_bf16 v[90:93], v[180:183], v[188:191], v[90:93]
	v_mfma_f32_16x16x32_bf16 v[94:97], v[176:179], v[192:195], v[94:97]
	v_mfma_f32_16x16x32_bf16 v[86:89], v[176:179], v[200:203], v[86:89]
	v_mfma_f32_16x16x32_bf16 v[78:81], v[176:179], v[208:211], v[78:81]
	v_mfma_f32_16x16x32_bf16 v[70:73], v[176:179], v[216:219], v[70:73]
	v_mfma_f32_16x16x32_bf16 v[66:69], v[184:187], v[216:219], v[66:69]
	v_mfma_f32_16x16x32_bf16 v[74:77], v[184:187], v[208:211], v[74:77]
	v_mfma_f32_16x16x32_bf16 v[82:85], v[184:187], v[200:203], v[82:85]
	v_mfma_f32_16x16x32_bf16 v[90:93], v[184:187], v[192:195], v[90:93]
	s_barrier
; #define PG8_STAGEA(bufoff, gbase) PG8_STAGE_(bufoff, gbase, voffA)
; #define PG8_STAGEB(bufoff, gbase) PG8_STAGE_(bufoff, gbase, voffB)
; #define PG8_LDA(dst, b, h) do { _Pragma("unroll") for (int m = 0; m < 4; ++m) _Pragma("unroll") for (int k = 0; k < 2; ++k) dst[m][k] = *(const LAS bf16x8*)(lds + PG8_SA(b, h) + aoff + m * 2048 + k * 1024); } while (0)
; #define PG8_LDB(dst, b, h) do { _Pragma("unroll") for (int n = 0; n < 2; ++n) _Pragma("unroll") for (int k = 0; k < 2; ++k) dst[n][k] = *(const LAS bf16x8*)(lds + PG8_SB(b, h) + boff + n * 2048 + k * 1024); } while (0)
; #define PG8_MMA(ai, bj, At, Bt_) do { __builtin_amdgcn_s_setprio(1); _Pragma("unroll") for (int m = 0; m < 4; ++m) _Pragma("unroll") for (int n = 0; n < 2; ++n) _Pragma("unroll") for (int k = 0; k < 2; ++k) \
;         acc[ai][bj][m][n] = __builtin_amdgcn_mfma_f32_16x16x32_bf16(Bt_[n][k], At[m][k], acc[ai][bj][m][n], 0, 0, 0); __builtin_amdgcn_s_setprio(0); } while (0)
; #define PG8_WAIT_V(n) asm volatile("s_waitcnt vmcnt(" #n ")" ::: "memory")
; #define PG8_WAIT_L(n) asm volatile("s_waitcnt lgkmcnt(" #n ")" ::: "memory")
; #define PG8_BAR __builtin_amdgcn_s_barrier()
; #define PG8_SCHED __builtin_amdgcn_sched_barrier(0)
; template <int EK, int SK = -1>
; __device__ __forceinline__ void gemm_phase(LAS unsigned char* lds, const bf16_t* A, const bf16_t* Bt, int nM, int N, int K, const EpiArgs& E) {
;     ...
;             PG8_LDB(B0, 0, 0); PG8_LDB(B1, 0, 1); PG8_SCHED; PG8_LDA(At, 0, 0); PG8_STAGEA(PG8_SA(1, 1), a1 + hstep);
;             PG8_WAIT_V(8); PG8_WAIT_L(0); PG8_BAR; PG8_MMA(0, 0, At, B0); PG8_MMA(0, 1, At, B1); PG8_BAR; PG8_SCHED;
;             PG8_LDA(At, 0, 1); PG8_STAGEB(PG8_SB(0, 0), b2); PG8_STAGEB(PG8_SB(0, 1), b2 + hstep); PG8_STAGEA(PG8_SA(0, 0), a2);
;             PG8_WAIT_V(8); PG8_WAIT_L(0); PG8_BAR; PG8_MMA(1, 0, At, B0); PG8_MMA(1, 1, At, B1); PG8_BAR; PG8_SCHED;
;             PG8_LDB(B0, 1, 0); PG8_LDB(B1, 1, 1); PG8_SCHED; PG8_LDA(At, 1, 0); PG8_STAGEA(PG8_SA(0, 1), a2 + hstep);
;             PG8_WAIT_V(8); PG8_WAIT_L(0); PG8_BAR; PG8_MMA(0, 0, At, B0); PG8_MMA(0, 1, At, B1); PG8_BAR; PG8_SCHED;
;             PG8_LDA(At, 1, 1); PG8_STAGEB(PG8_SB(1, 0), b3); PG8_STAGEB(PG8_SB(1, 1), b3 + hstep); PG8_STAGEA(PG8_SA(1, 0), a3);
;             PG8_WAIT_V(8); PG8_WAIT_L(0); PG8_BAR; PG8_MMA(1, 0, At, B0); PG8_MMA(1, 1, At, B1); PG8_BAR; PG8_SCHED;
;         }
	s_add_i32 s46, s75, s52
	v_lshl_add_u64 v[150:151], v[150:151], 0, s[36:37]
	s_mov_b32 m0, s46
	ds_read_b128 v[188:191], v154 offset:49152
	ds_read_b128 v[192:195], v154 offset:50176
	ds_read_b128 v[196:199], v154 offset:51200
	ds_read_b128 v[200:203], v154 offset:52224
	ds_read_b128 v[204:207], v154 offset:53248
	ds_read_b128 v[208:211], v154 offset:54272
	ds_read_b128 v[212:215], v154 offset:55296
	ds_read_b128 v[216:219], v154 offset:56320
	global_load_lds_dwordx4 v[150:151], off
	s_add_i32 m0, s46, 0x2000
	s_add_u32 s44, s44, 0xb0080
	v_lshl_add_u64 v[150:151], v[220:221], 0, s[36:37]
	s_addc_u32 s45, s45, 0
	s_add_i32 s46, s76, s52
	global_load_lds_dwordx4 v[150:151], off
	v_lshl_add_u64 v[150:151], s[44:45], 0, v[132:133]
	s_mov_b32 m0, s46
	s_nop 0
	global_load_lds_dwordx4 v[150:151], off
	v_lshl_add_u64 v[150:151], s[44:45], 0, v[136:137]
	s_add_i32 m0, s46, 0x2000
	s_nop 0
	global_load_lds_dwordx4 v[150:151], off
	v_lshl_add_u64 v[150:151], v[222:223], 0, s[36:37]
	s_mov_b32 m0, s59
	s_nop 0
	global_load_lds_dwordx4 v[150:151], off
	v_lshl_add_u64 v[150:151], v[224:225], 0, s[36:37]
	s_mov_b32 m0, s66
	s_nop 0
	global_load_lds_dwordx4 v[150:151], off
	s_waitcnt vmcnt(8)
	s_waitcnt lgkmcnt(0)
	s_barrier
	s_waitcnt lgkmcnt(0)
	v_mfma_f32_16x16x32_bf16 v[62:65], v[156:159], v[188:191], v[62:65]
	v_mfma_f32_16x16x32_bf16 v[54:57], v[156:159], v[196:199], v[54:57]
	v_mfma_f32_16x16x32_bf16 v[46:49], v[156:159], v[204:207], v[46:49]
	v_mfma_f32_16x16x32_bf16 v[38:41], v[156:159], v[212:215], v[38:41]
	v_mfma_f32_16x16x32_bf16 v[34:37], v[164:167], v[212:215], v[34:37]
	v_mfma_f32_16x16x32_bf16 v[42:45], v[164:167], v[204:207], v[42:45]
	v_mfma_f32_16x16x32_bf16 v[50:53], v[164:167], v[196:199], v[50:53]
	v_mfma_f32_16x16x32_bf16 v[58:61], v[164:167], v[188:191], v[58:61]
	v_mfma_f32_16x16x32_bf16 v[62:65], v[160:163], v[192:195], v[62:65]
	v_mfma_f32_16x16x32_bf16 v[54:57], v[160:163], v[200:203], v[54:57]
	v_mfma_f32_16x16x32_bf16 v[46:49], v[160:163], v[208:211], v[46:49]
	v_mfma_f32_16x16x32_bf16 v[38:41], v[160:163], v[216:219], v[38:41]
	v_mfma_f32_16x16x32_bf16 v[34:37], v[168:171], v[216:219], v[34:37]
	v_mfma_f32_16x16x32_bf16 v[42:45], v[168:171], v[208:211], v[42:45]
	v_mfma_f32_16x16x32_bf16 v[50:53], v[168:171], v[200:203], v[50:53]
	v_mfma_f32_16x16x32_bf16 v[58:61], v[168:171], v[192:195], v[58:61]
	v_mfma_f32_16x16x32_bf16 v[30:33], v[172:175], v[188:191], v[30:33]
	v_mfma_f32_16x16x32_bf16 v[22:25], v[172:175], v[196:199], v[22:25]
	v_mfma_f32_16x16x32_bf16 v[14:17], v[172:175], v[204:207], v[14:17]
	v_mfma_f32_16x16x32_bf16 v[6:9], v[172:175], v[212:215], v[6:9]
	v_mfma_f32_16x16x32_bf16 v[2:5], v[180:183], v[212:215], v[2:5]
	v_mfma_f32_16x16x32_bf16 v[10:13], v[180:183], v[204:207], v[10:13]
	v_mfma_f32_16x16x32_bf16 v[18:21], v[180:183], v[196:199], v[18:21]
	v_mfma_f32_16x16x32_bf16 v[26:29], v[180:183], v[188:191], v[26:29]
	v_mfma_f32_16x16x32_bf16 v[30:33], v[176:179], v[192:195], v[30:33]
	v_mfma_f32_16x16x32_bf16 v[22:25], v[176:179], v[200:203], v[22:25]
	v_mfma_f32_16x16x32_bf16 v[14:17], v[176:179], v[208:211], v[14:17]
	v_mfma_f32_16x16x32_bf16 v[6:9], v[176:179], v[216:219], v[6:9]
	v_mfma_f32_16x16x32_bf16 v[2:5], v[184:187], v[216:219], v[2:5]
	v_mfma_f32_16x16x32_bf16 v[10:13], v[184:187], v[208:211], v[10:13]
	v_mfma_f32_16x16x32_bf16 v[18:21], v[184:187], v[200:203], v[18:21]
	v_mfma_f32_16x16x32_bf16 v[26:29], v[184:187], v[192:195], v[26:29]
	s_barrier
	s_add_i32 s26, s26, 2
	s_add_u32 s42, s42, 0x100
	s_addc_u32 s43, s43, 0
	s_cmp_gt_u32 s26, 41
	s_cbranch_scc0 .LBB0_1338
	s_branch .Lmy_kexit_7
.LBB0_1338:
	v_add_u32_e32 v150, s67, v152
	ds_read_b128 v[156:159], v150
	ds_read_b128 v[160:163], v150 offset:1024
	ds_read_b128 v[164:167], v150 offset:2048
	ds_read_b128 v[168:171], v150 offset:3072
	v_add_u32_e32 v150, s68, v152
	s_add_u32 s44, s20, s42
	ds_read_b128 v[172:175], v150
	ds_read_b128 v[176:179], v150 offset:1024
	ds_read_b128 v[180:183], v150 offset:2048
	ds_read_b128 v[184:187], v150 offset:3072
	s_addc_u32 s45, s21, s43
	s_add_u32 s44, s44, 0x100
	s_addc_u32 s45, s45, 0
	s_add_u32 s75, s73, s42
	s_addc_u32 s76, s74, s43
	s_cmpk_eq_i32 s42, 0x1500
	s_cselect_b32 s47, s41, s45
	s_cselect_b32 s46, s40, s44
	s_cselect_b32 s45, s9, s76
	s_cselect_b32 s44, s8, s75
	v_lshl_add_u64 v[150:151], v[146:147], 0, s[42:43]
	s_add_i32 m0, s53, 0xc000
	ds_read_b128 v[188:191], v154
	ds_read_b128 v[192:195], v154 offset:1024
	ds_read_b128 v[196:199], v154 offset:2048
	ds_read_b128 v[200:203], v154 offset:3072
	ds_read_b128 v[204:207], v154 offset:4096
	ds_read_b128 v[208:211], v154 offset:5120
	ds_read_b128 v[212:215], v154 offset:6144
	ds_read_b128 v[216:219], v154 offset:7168
	global_load_lds_dwordx4 v[150:151], off
	v_lshl_add_u64 v[150:151], v[148:149], 0, s[42:43]
	s_add_i32 m0, s53, 0xe000
	s_nop 0
	global_load_lds_dwordx4 v[150:151], off
	s_waitcnt vmcnt(8)
	s_waitcnt lgkmcnt(0)
	s_barrier
; #define PG8_STAGEA(bufoff, gbase) PG8_STAGE_(bufoff, gbase, voffA)
; #define PG8_STAGEB(bufoff, gbase) PG8_STAGE_(bufoff, gbase, voffB)
; #define PG8_LDA(dst, b, h) do { _Pragma("unroll") for (int m = 0; m < 4; ++m) _Pragma("unroll") for (int k = 0; k < 2; ++k) dst[m][k] = *(const LAS bf16x8*)(lds + PG8_SA(b, h) + aoff + m * 2048 + k * 1024); } while (0)
; #define PG8_MMA(ai, bj, At, Bt_) do { __builtin_amdgcn_s_setprio(1); _Pragma("unroll") for (int m = 0; m < 4; ++m) _Pragma("unroll") for (int n = 0; n < 2; ++n) _Pragma("unroll") for (int k = 0; k < 2; ++k) \
;         acc[ai][bj][m][n] = __builtin_amdgcn_mfma_f32_16x16x32_bf16(Bt_[n][k], At[m][k], acc[ai][bj][m][n], 0, 0, 0); __builtin_amdgcn_s_setprio(0); } while (0)
; #define PG8_WAIT_V(n) asm volatile("s_waitcnt vmcnt(" #n ")" ::: "memory")
; #define PG8_WAIT_L(n) asm volatile("s_waitcnt lgkmcnt(" #n ")" ::: "memory")
; #define PG8_BAR __builtin_amdgcn_s_barrier()
; #define PG8_SCHED __builtin_amdgcn_sched_barrier(0)
; template <int EK, int SK = -1>
; __device__ __forceinline__ void gemm_phase(LAS unsigned char* lds, const bf16_t* A, const bf16_t* Bt, int nM, int N, int K, const EpiArgs& E) {
;     ...
;             PG8_WAIT_V(8); PG8_WAIT_L(0); PG8_BAR; PG8_MMA(0, 0, At, B0); PG8_MMA(0, 1, At, B1); PG8_BAR; PG8_SCHED;
;             PG8_LDA(At, 0, 1); PG8_STAGEB(PG8_SB(0, 0), b2); PG8_STAGEB(PG8_SB(0, 1), b2 + hstep); PG8_STAGEA(PG8_SA(0, 0), a2);
;             PG8_WAIT_V(8); PG8_WAIT_L(0); PG8_BAR; PG8_MMA(1, 0, At, B0); PG8_MMA(1, 1, At, B1); PG8_BAR; PG8_SCHED;
	s_waitcnt lgkmcnt(0)
	v_mfma_f32_16x16x32_bf16 v[126:129], v[156:159], v[188:191], v[126:129]
	v_mfma_f32_16x16x32_bf16 v[118:121], v[156:159], v[196:199], v[118:121]
	v_mfma_f32_16x16x32_bf16 v[110:113], v[156:159], v[204:207], v[110:113]
	v_mfma_f32_16x16x32_bf16 v[102:105], v[156:159], v[212:215], v[102:105]
	v_mfma_f32_16x16x32_bf16 v[98:101], v[164:167], v[212:215], v[98:101]
	v_mfma_f32_16x16x32_bf16 v[106:109], v[164:167], v[204:207], v[106:109]
	v_mfma_f32_16x16x32_bf16 v[114:117], v[164:167], v[196:199], v[114:117]
	v_mfma_f32_16x16x32_bf16 v[122:125], v[164:167], v[188:191], v[122:125]
	v_mfma_f32_16x16x32_bf16 v[126:129], v[160:163], v[192:195], v[126:129]
	v_mfma_f32_16x16x32_bf16 v[118:121], v[160:163], v[200:203], v[118:121]
	v_mfma_f32_16x16x32_bf16 v[110:113], v[160:163], v[208:211], v[110:113]
	v_mfma_f32_16x16x32_bf16 v[102:105], v[160:163], v[216:219], v[102:105]
	v_mfma_f32_16x16x32_bf16 v[98:101], v[168:171], v[216:219], v[98:101]
	v_mfma_f32_16x16x32_bf16 v[106:109], v[168:171], v[208:211], v[106:109]
	v_mfma_f32_16x16x32_bf16 v[114:117], v[168:171], v[200:203], v[114:117]
	v_mfma_f32_16x16x32_bf16 v[122:125], v[168:171], v[192:195], v[122:125]
	v_mfma_f32_16x16x32_bf16 v[94:97], v[172:175], v[188:191], v[94:97]
	v_mfma_f32_16x16x32_bf16 v[86:89], v[172:175], v[196:199], v[86:89]
	v_mfma_f32_16x16x32_bf16 v[78:81], v[172:175], v[204:207], v[78:81]
	v_mfma_f32_16x16x32_bf16 v[70:73], v[172:175], v[212:215], v[70:73]
	v_mfma_f32_16x16x32_bf16 v[66:69], v[180:183], v[212:215], v[66:69]
	v_mfma_f32_16x16x32_bf16 v[74:77], v[180:183], v[204:207], v[74:77]
	v_mfma_f32_16x16x32_bf16 v[82:85], v[180:183], v[196:199], v[82:85]
	v_mfma_f32_16x16x32_bf16 v[90:93], v[180:183], v[188:191], v[90:93]
	v_mfma_f32_16x16x32_bf16 v[94:97], v[176:179], v[192:195], v[94:97]
	v_mfma_f32_16x16x32_bf16 v[86:89], v[176:179], v[200:203], v[86:89]
	v_mfma_f32_16x16x32_bf16 v[78:81], v[176:179], v[208:211], v[78:81]
	v_mfma_f32_16x16x32_bf16 v[70:73], v[176:179], v[216:219], v[70:73]
	v_mfma_f32_16x16x32_bf16 v[66:69], v[184:187], v[216:219], v[66:69]
	v_mfma_f32_16x16x32_bf16 v[74:77], v[184:187], v[208:211], v[74:77]
	v_mfma_f32_16x16x32_bf16 v[82:85], v[184:187], v[200:203], v[82:85]
	v_mfma_f32_16x16x32_bf16 v[90:93], v[184:187], v[192:195], v[90:93]
	s_barrier
	s_add_i32 s75, s67, s52
	v_lshl_add_u64 v[150:151], s[44:45], 0, v[132:133]
	s_mov_b32 m0, s75
	ds_read_b128 v[188:191], v154 offset:16384
	ds_read_b128 v[192:195], v154 offset:17408
	ds_read_b128 v[196:199], v154 offset:18432
	ds_read_b128 v[200:203], v154 offset:19456
	ds_read_b128 v[204:207], v154 offset:20480
	ds_read_b128 v[208:211], v154 offset:21504
	ds_read_b128 v[212:215], v154 offset:22528
	ds_read_b128 v[216:219], v154 offset:23552
	global_load_lds_dwordx4 v[150:151], off
	s_add_i32 m0, s75, 0x2000
	s_add_u32 s76, s44, 0xb0000
	v_lshl_add_u64 v[220:221], s[44:45], 0, v[136:137]
	s_addc_u32 s77, s45, 0
	s_add_i32 s75, s68, s52
	global_load_lds_dwordx4 v[220:221], off
	v_lshl_add_u64 v[222:223], s[76:77], 0, v[132:133]
	s_mov_b32 m0, s75
	v_lshl_add_u64 v[224:225], s[46:47], 0, v[134:135]
	global_load_lds_dwordx4 v[222:223], off
	v_lshl_add_u64 v[222:223], s[76:77], 0, v[136:137]
	s_add_i32 m0, s75, 0x2000
	s_nop 0
	global_load_lds_dwordx4 v[222:223], off
	v_lshl_add_u64 v[222:223], s[46:47], 0, v[130:131]
	s_mov_b32 m0, s53
	s_nop 0
	global_load_lds_dwordx4 v[222:223], off
	s_mov_b32 m0, s54
	s_nop 0
	global_load_lds_dwordx4 v[224:225], off
	s_waitcnt vmcnt(8)
	s_waitcnt lgkmcnt(0)
	s_barrier
	s_waitcnt lgkmcnt(0)
	v_mfma_f32_16x16x32_bf16 v[62:65], v[156:159], v[188:191], v[62:65]
	v_mfma_f32_16x16x32_bf16 v[54:57], v[156:159], v[196:199], v[54:57]
	v_mfma_f32_16x16x32_bf16 v[46:49], v[156:159], v[204:207], v[46:49]
	v_mfma_f32_16x16x32_bf16 v[38:41], v[156:159], v[212:215], v[38:41]
	v_mfma_f32_16x16x32_bf16 v[34:37], v[164:167], v[212:215], v[34:37]
	v_mfma_f32_16x16x32_bf16 v[42:45], v[164:167], v[204:207], v[42:45]
	v_mfma_f32_16x16x32_bf16 v[50:53], v[164:167], v[196:199], v[50:53]
	v_mfma_f32_16x16x32_bf16 v[58:61], v[164:167], v[188:191], v[58:61]
	v_mfma_f32_16x16x32_bf16 v[62:65], v[160:163], v[192:195], v[62:65]
	v_mfma_f32_16x16x32_bf16 v[54:57], v[160:163], v[200:203], v[54:57]
	v_mfma_f32_16x16x32_bf16 v[46:49], v[160:163], v[208:211], v[46:49]
	v_mfma_f32_16x16x32_bf16 v[38:41], v[160:163], v[216:219], v[38:41]
	v_mfma_f32_16x16x32_bf16 v[34:37], v[168:171], v[216:219], v[34:37]
	v_mfma_f32_16x16x32_bf16 v[42:45], v[168:171], v[208:211], v[42:45]
	v_mfma_f32_16x16x32_bf16 v[50:53], v[168:171], v[200:203], v[50:53]
	v_mfma_f32_16x16x32_bf16 v[58:61], v[168:171], v[192:195], v[58:61]
	v_mfma_f32_16x16x32_bf16 v[30:33], v[172:175], v[188:191], v[30:33]
	v_mfma_f32_16x16x32_bf16 v[22:25], v[172:175], v[196:199], v[22:25]
	v_mfma_f32_16x16x32_bf16 v[14:17], v[172:175], v[204:207], v[14:17]
	v_mfma_f32_16x16x32_bf16 v[6:9], v[172:175], v[212:215], v[6:9]
	v_mfma_f32_16x16x32_bf16 v[2:5], v[180:183], v[212:215], v[2:5]
	v_mfma_f32_16x16x32_bf16 v[10:13], v[180:183], v[204:207], v[10:13]
	v_mfma_f32_16x16x32_bf16 v[18:21], v[180:183], v[196:199], v[18:21]
	v_mfma_f32_16x16x32_bf16 v[26:29], v[180:183], v[188:191], v[26:29]
	v_mfma_f32_16x16x32_bf16 v[30:33], v[176:179], v[192:195], v[30:33]
	v_mfma_f32_16x16x32_bf16 v[22:25], v[176:179], v[200:203], v[22:25]
	v_mfma_f32_16x16x32_bf16 v[14:17], v[176:179], v[208:211], v[14:17]
	v_mfma_f32_16x16x32_bf16 v[6:9], v[176:179], v[216:219], v[6:9]
	v_mfma_f32_16x16x32_bf16 v[2:5], v[184:187], v[216:219], v[2:5]
	v_mfma_f32_16x16x32_bf16 v[10:13], v[184:187], v[208:211], v[10:13]
	v_mfma_f32_16x16x32_bf16 v[18:21], v[184:187], v[200:203], v[18:21]
	v_mfma_f32_16x16x32_bf16 v[26:29], v[184:187], v[192:195], v[26:29]
	s_barrier
; #define PG8_STAGEA(bufoff, gbase) PG8_STAGE_(bufoff, gbase, voffA)
; #define PG8_STAGEB(bufoff, gbase) PG8_STAGE_(bufoff, gbase, voffB)
; #define PG8_LDA(dst, b, h) do { _Pragma("unroll") for (int m = 0; m < 4; ++m) _Pragma("unroll") for (int k = 0; k < 2; ++k) dst[m][k] = *(const LAS bf16x8*)(lds + PG8_SA(b, h) + aoff + m * 2048 + k * 1024); } while (0)
; #define PG8_LDB(dst, b, h) do { _Pragma("unroll") for (int n = 0; n < 2; ++n) _Pragma("unroll") for (int k = 0; k < 2; ++k) dst[n][k] = *(const LAS bf16x8*)(lds + PG8_SB(b, h) + boff + n * 2048 + k * 1024); } while (0)
; #define PG8_MMA(ai, bj, At, Bt_) do { __builtin_amdgcn_s_setprio(1); _Pragma("unroll") for (int m = 0; m < 4; ++m) _Pragma("unroll") for (int n = 0; n < 2; ++n) _Pragma("unroll") for (int k = 0; k < 2; ++k) \
;         acc[ai][bj][m][n] = __builtin_amdgcn_mfma_f32_16x16x32_bf16(Bt_[n][k], At[m][k], acc[ai][bj][m][n], 0, 0, 0); __builtin_amdgcn_s_setprio(0); } while (0)
; #define PG8_WAIT_V(n) asm volatile("s_waitcnt vmcnt(" #n ")" ::: "memory")
; #define PG8_WAIT_L(n) asm volatile("s_waitcnt lgkmcnt(" #n ")" ::: "memory")
; #define PG8_BAR __builtin_amdgcn_s_barrier()
; #define PG8_SCHED __builtin_amdgcn_sched_barrier(0)
; template <int EK, int SK = -1>
; __device__ __forceinline__ void gemm_phase(LAS unsigned char* lds, const bf16_t* A, const bf16_t* Bt, int nM, int N, int K, const EpiArgs& E) {
;     ...
;             PG8_LDB(B0, 1, 0); PG8_LDB(B1, 1, 1); PG8_SCHED; PG8_LDA(At, 1, 0); PG8_STAGEA(PG8_SA(0, 1), a2 + hstep);
;             PG8_WAIT_V(8); PG8_WAIT_L(0); PG8_BAR; PG8_MMA(0, 0, At, B0); PG8_MMA(0, 1, At, B1); PG8_BAR; PG8_SCHED;
;             PG8_LDA(At, 1, 1); PG8_STAGEB(PG8_SB(1, 0), b3); PG8_STAGEB(PG8_SB(1, 1), b3 + hstep); PG8_STAGEA(PG8_SA(1, 0), a3);
;             PG8_WAIT_V(8); PG8_WAIT_L(0); PG8_BAR; PG8_MMA(1, 0, At, B0); PG8_MMA(1, 1, At, B1); PG8_BAR; PG8_SCHED;
;         }
	s_add_i32 s75, 0, 0x18000
	s_add_i32 s76, 0, 0x1c000
	v_add_u32_e32 v168, s75, v152
	v_add_u32_e32 v184, s76, v152
	ds_read_b128 v[156:159], v168
	ds_read_b128 v[160:163], v168 offset:1024
	ds_read_b128 v[164:167], v168 offset:2048
	ds_read_b128 v[168:171], v168 offset:3072
	ds_read_b128 v[172:175], v184
	ds_read_b128 v[176:179], v184 offset:1024
	ds_read_b128 v[180:183], v184 offset:2048
	ds_read_b128 v[184:187], v184 offset:3072
	s_add_u32 s46, s46, 0xb0000
	s_addc_u32 s47, s47, 0
	s_mov_b32 m0, s55
	v_lshl_add_u64 v[226:227], s[46:47], 0, v[130:131]
	ds_read_b128 v[188:191], v154 offset:32768
	ds_read_b128 v[192:195], v154 offset:33792
	ds_read_b128 v[196:199], v154 offset:34816
	ds_read_b128 v[200:203], v154 offset:35840
	ds_read_b128 v[204:207], v154 offset:36864
	ds_read_b128 v[208:211], v154 offset:37888
	ds_read_b128 v[212:215], v154 offset:38912
	ds_read_b128 v[216:219], v154 offset:39936
	global_load_lds_dwordx4 v[226:227], off
	v_lshl_add_u64 v[226:227], s[46:47], 0, v[134:135]
	s_mov_b32 m0, s56
	s_nop 0
	global_load_lds_dwordx4 v[226:227], off
	s_waitcnt vmcnt(8)
	s_waitcnt lgkmcnt(0)
	s_barrier
	s_waitcnt lgkmcnt(0)
	v_mfma_f32_16x16x32_bf16 v[126:129], v[156:159], v[188:191], v[126:129]
	v_mfma_f32_16x16x32_bf16 v[118:121], v[156:159], v[196:199], v[118:121]
	v_mfma_f32_16x16x32_bf16 v[110:113], v[156:159], v[204:207], v[110:113]
	v_mfma_f32_16x16x32_bf16 v[102:105], v[156:159], v[212:215], v[102:105]
	v_mfma_f32_16x16x32_bf16 v[98:101], v[164:167], v[212:215], v[98:101]
	v_mfma_f32_16x16x32_bf16 v[106:109], v[164:167], v[204:207], v[106:109]
	v_mfma_f32_16x16x32_bf16 v[114:117], v[164:167], v[196:199], v[114:117]
	v_mfma_f32_16x16x32_bf16 v[122:125], v[164:167], v[188:191], v[122:125]
	v_mfma_f32_16x16x32_bf16 v[126:129], v[160:163], v[192:195], v[126:129]
	v_mfma_f32_16x16x32_bf16 v[118:121], v[160:163], v[200:203], v[118:121]
	v_mfma_f32_16x16x32_bf16 v[110:113], v[160:163], v[208:211], v[110:113]
	v_mfma_f32_16x16x32_bf16 v[102:105], v[160:163], v[216:219], v[102:105]
	v_mfma_f32_16x16x32_bf16 v[98:101], v[168:171], v[216:219], v[98:101]
	v_mfma_f32_16x16x32_bf16 v[106:109], v[168:171], v[208:211], v[106:109]
	v_mfma_f32_16x16x32_bf16 v[114:117], v[168:171], v[200:203], v[114:117]
	v_mfma_f32_16x16x32_bf16 v[122:125], v[168:171], v[192:195], v[122:125]
	v_mfma_f32_16x16x32_bf16 v[94:97], v[172:175], v[188:191], v[94:97]
	v_mfma_f32_16x16x32_bf16 v[86:89], v[172:175], v[196:199], v[86:89]
	v_mfma_f32_16x16x32_bf16 v[78:81], v[172:175], v[204:207], v[78:81]
	v_mfma_f32_16x16x32_bf16 v[70:73], v[172:175], v[212:215], v[70:73]
	v_mfma_f32_16x16x32_bf16 v[66:69], v[180:183], v[212:215], v[66:69]
	v_mfma_f32_16x16x32_bf16 v[74:77], v[180:183], v[204:207], v[74:77]
	v_mfma_f32_16x16x32_bf16 v[82:85], v[180:183], v[196:199], v[82:85]
	v_mfma_f32_16x16x32_bf16 v[90:93], v[180:183], v[188:191], v[90:93]
	v_mfma_f32_16x16x32_bf16 v[94:97], v[176:179], v[192:195], v[94:97]
	v_mfma_f32_16x16x32_bf16 v[86:89], v[176:179], v[200:203], v[86:89]
	v_mfma_f32_16x16x32_bf16 v[78:81], v[176:179], v[208:211], v[78:81]
	v_mfma_f32_16x16x32_bf16 v[70:73], v[176:179], v[216:219], v[70:73]
	v_mfma_f32_16x16x32_bf16 v[66:69], v[184:187], v[216:219], v[66:69]
	v_mfma_f32_16x16x32_bf16 v[74:77], v[184:187], v[208:211], v[74:77]
	v_mfma_f32_16x16x32_bf16 v[82:85], v[184:187], v[200:203], v[82:85]
	v_mfma_f32_16x16x32_bf16 v[90:93], v[184:187], v[192:195], v[90:93]
	s_barrier
	s_add_i32 s46, s75, s52
	v_lshl_add_u64 v[150:151], v[150:151], 0, s[36:37]
	s_mov_b32 m0, s46
	ds_read_b128 v[188:191], v154 offset:49152
	ds_read_b128 v[192:195], v154 offset:50176
	ds_read_b128 v[196:199], v154 offset:51200
	ds_read_b128 v[200:203], v154 offset:52224
	ds_read_b128 v[204:207], v154 offset:53248
	ds_read_b128 v[208:211], v154 offset:54272
	ds_read_b128 v[212:215], v154 offset:55296
	ds_read_b128 v[216:219], v154 offset:56320
	global_load_lds_dwordx4 v[150:151], off
	s_add_i32 m0, s46, 0x2000
	s_add_u32 s44, s44, 0xb0080
	v_lshl_add_u64 v[150:151], v[220:221], 0, s[36:37]
	s_addc_u32 s45, s45, 0
	s_add_i32 s46, s76, s52
	global_load_lds_dwordx4 v[150:151], off
	v_lshl_add_u64 v[150:151], s[44:45], 0, v[132:133]
	s_mov_b32 m0, s46
	s_nop 0
	global_load_lds_dwordx4 v[150:151], off
	v_lshl_add_u64 v[150:151], s[44:45], 0, v[136:137]
	s_add_i32 m0, s46, 0x2000
	s_nop 0
	global_load_lds_dwordx4 v[150:151], off
	v_lshl_add_u64 v[150:151], v[222:223], 0, s[36:37]
	s_mov_b32 m0, s59
	s_nop 0
	global_load_lds_dwordx4 v[150:151], off
	v_lshl_add_u64 v[150:151], v[224:225], 0, s[36:37]
	s_mov_b32 m0, s66
	s_nop 0
	global_load_lds_dwordx4 v[150:151], off
	s_waitcnt vmcnt(8)
	s_waitcnt lgkmcnt(0)
	s_barrier
	s_waitcnt lgkmcnt(0)
	v_mfma_f32_16x16x32_bf16 v[62:65], v[156:159], v[188:191], v[62:65]
	v_mfma_f32_16x16x32_bf16 v[54:57], v[156:159], v[196:199], v[54:57]
	v_mfma_f32_16x16x32_bf16 v[46:49], v[156:159], v[204:207], v[46:49]
	v_mfma_f32_16x16x32_bf16 v[38:41], v[156:159], v[212:215], v[38:41]
	v_mfma_f32_16x16x32_bf16 v[34:37], v[164:167], v[212:215], v[34:37]
	v_mfma_f32_16x16x32_bf16 v[42:45], v[164:167], v[204:207], v[42:45]
	v_mfma_f32_16x16x32_bf16 v[50:53], v[164:167], v[196:199], v[50:53]
	v_mfma_f32_16x16x32_bf16 v[58:61], v[164:167], v[188:191], v[58:61]
	v_mfma_f32_16x16x32_bf16 v[62:65], v[160:163], v[192:195], v[62:65]
	v_mfma_f32_16x16x32_bf16 v[54:57], v[160:163], v[200:203], v[54:57]
	v_mfma_f32_16x16x32_bf16 v[46:49], v[160:163], v[208:211], v[46:49]
	v_mfma_f32_16x16x32_bf16 v[38:41], v[160:163], v[216:219], v[38:41]
	v_mfma_f32_16x16x32_bf16 v[34:37], v[168:171], v[216:219], v[34:37]
	v_mfma_f32_16x16x32_bf16 v[42:45], v[168:171], v[208:211], v[42:45]
	v_mfma_f32_16x16x32_bf16 v[50:53], v[168:171], v[200:203], v[50:53]
	v_mfma_f32_16x16x32_bf16 v[58:61], v[168:171], v[192:195], v[58:61]
	v_mfma_f32_16x16x32_bf16 v[30:33], v[172:175], v[188:191], v[30:33]
	v_mfma_f32_16x16x32_bf16 v[22:25], v[172:175], v[196:199], v[22:25]
	v_mfma_f32_16x16x32_bf16 v[14:17], v[172:175], v[204:207], v[14:17]
	v_mfma_f32_16x16x32_bf16 v[6:9], v[172:175], v[212:215], v[6:9]
	v_mfma_f32_16x16x32_bf16 v[2:5], v[180:183], v[212:215], v[2:5]
	v_mfma_f32_16x16x32_bf16 v[10:13], v[180:183], v[204:207], v[10:13]
	v_mfma_f32_16x16x32_bf16 v[18:21], v[180:183], v[196:199], v[18:21]
	v_mfma_f32_16x16x32_bf16 v[26:29], v[180:183], v[188:191], v[26:29]
	v_mfma_f32_16x16x32_bf16 v[30:33], v[176:179], v[192:195], v[30:33]
	v_mfma_f32_16x16x32_bf16 v[22:25], v[176:179], v[200:203], v[22:25]
	v_mfma_f32_16x16x32_bf16 v[14:17], v[176:179], v[208:211], v[14:17]
	v_mfma_f32_16x16x32_bf16 v[6:9], v[176:179], v[216:219], v[6:9]
	v_mfma_f32_16x16x32_bf16 v[2:5], v[184:187], v[216:219], v[2:5]
	v_mfma_f32_16x16x32_bf16 v[10:13], v[184:187], v[208:211], v[10:13]
	v_mfma_f32_16x16x32_bf16 v[18:21], v[184:187], v[200:203], v[18:21]
	v_mfma_f32_16x16x32_bf16 v[26:29], v[184:187], v[192:195], v[26:29]
	s_barrier
	s_add_i32 s26, s26, 2
	s_add_u32 s42, s42, 0x100
	s_addc_u32 s43, s43, 0
	s_cmp_gt_u32 s26, 41
	s_cbranch_scc0 .LBB0_1338

; #define PG8_STAGEA(bufoff, gbase) PG8_STAGE_(bufoff, gbase, voffA)
; #define PG8_STAGEB(bufoff, gbase) PG8_STAGE_(bufoff, gbase, voffB)
; #define PG8_LDA(dst, b, h) do { _Pragma("unroll") for (int m = 0; m < 4; ++m) _Pragma("unroll") for (int k = 0; k < 2; ++k) dst[m][k] = *(const LAS bf16x8*)(lds + PG8_SA(b, h) + aoff + m * 2048 + k * 1024); } while (0)
; #define PG8_LDB(dst, b, h) do { _Pragma("unroll") for (int n = 0; n < 2; ++n) _Pragma("unroll") for (int k = 0; k < 2; ++k) dst[n][k] = *(const LAS bf16x8*)(lds + PG8_SB(b, h) + boff + n * 2048 + k * 1024); } while (0)
; #define PG8_MMA(ai, bj, At, Bt_) do { __builtin_amdgcn_s_setprio(1); _Pragma("unroll") for (int m = 0; m < 4; ++m) _Pragma("unroll") for (int n = 0; n < 2; ++n) _Pragma("unroll") for (int k = 0; k < 2; ++k) \
;         acc[ai][bj][m][n] = __builtin_amdgcn_mfma_f32_16x16x32_bf16(Bt_[n][k], At[m][k], acc[ai][bj][m][n], 0, 0, 0); __builtin_amdgcn_s_setprio(0); } while (0)
; #define PG8_WAIT_V(n) asm volatile("s_waitcnt vmcnt(" #n ")" ::: "memory")
; #define PG8_WAIT_L(n) asm volatile("s_waitcnt lgkmcnt(" #n ")" ::: "memory")
; #define PG8_BAR __builtin_amdgcn_s_barrier()
; #define PG8_SCHED __builtin_amdgcn_sched_barrier(0)
; template <int EK, int SK = -1>
; __device__ __forceinline__ void gemm_phase(LAS unsigned char* lds, const bf16_t* A, const bf16_t* Bt, int nM, int N, int K, const EpiArgs& E) {
;     ...
;             PG8_LDB(B0, 0, 0); PG8_LDB(B1, 0, 1); PG8_SCHED; PG8_LDA(At, 0, 0); PG8_STAGEA(PG8_SA(1, 1), a1 + hstep);
;             PG8_WAIT_V(8); PG8_WAIT_L(0); PG8_BAR; PG8_MMA(0, 0, At, B0); PG8_MMA(0, 1, At, B1); PG8_BAR; PG8_SCHED;
;             PG8_LDA(At, 0, 1); PG8_STAGEB(PG8_SB(0, 0), b2); PG8_STAGEB(PG8_SB(0, 1), b2 + hstep); PG8_STAGEA(PG8_SA(0, 0), a2);
;             PG8_WAIT_V(8); PG8_WAIT_L(0); PG8_BAR; PG8_MMA(1, 0, At, B0); PG8_MMA(1, 1, At, B1); PG8_BAR; PG8_SCHED;
.LBB0_1401:
	v_add_u32_e32 v168, s66, v154
	v_add_u32_e32 v184, s67, v154
	s_add_u32 s42, s20, s40
	ds_read_b128 v[156:159], v168
	ds_read_b128 v[160:163], v168 offset:1024
	ds_read_b128 v[164:167], v168 offset:2048
	ds_read_b128 v[168:171], v168 offset:3072
	ds_read_b128 v[172:175], v184
	ds_read_b128 v[176:179], v184 offset:1024
	ds_read_b128 v[180:183], v184 offset:2048
	ds_read_b128 v[184:187], v184 offset:3072
	s_addc_u32 s43, s21, s41
	s_add_u32 s42, s42, 0x100
	s_addc_u32 s43, s43, 0
	s_add_u32 s73, s37, s40
	s_addc_u32 s74, s71, s41
	s_cmpk_eq_i32 s40, 0x1500
	s_cselect_b32 s45, s7, s43
	s_cselect_b32 s44, s6, s42
	s_cselect_b32 s43, s39, s74
	s_cselect_b32 s42, s38, s73
	v_lshl_add_u64 v[220:221], v[146:147], 0, s[40:41]
	s_add_i32 m0, s53, 0xc000
	ds_read_b128 v[188:191], v155
	ds_read_b128 v[192:195], v155 offset:1024
	ds_read_b128 v[196:199], v155 offset:2048
	ds_read_b128 v[200:203], v155 offset:3072
	ds_read_b128 v[204:207], v155 offset:4096
	ds_read_b128 v[208:211], v155 offset:5120
	ds_read_b128 v[212:215], v155 offset:6144
	ds_read_b128 v[216:219], v155 offset:7168
	global_load_lds_dwordx4 v[220:221], off
	v_lshl_add_u64 v[220:221], v[148:149], 0, s[40:41]
	s_add_i32 m0, s53, 0xe000
	s_nop 0
	global_load_lds_dwordx4 v[220:221], off
	s_waitcnt vmcnt(8)
	s_waitcnt lgkmcnt(0)
	s_barrier
	s_waitcnt lgkmcnt(0)
	v_mfma_f32_16x16x32_bf16 v[126:129], v[156:159], v[188:191], v[126:129]
	v_mfma_f32_16x16x32_bf16 v[110:113], v[156:159], v[196:199], v[110:113]
	v_mfma_f32_16x16x32_bf16 v[94:97], v[156:159], v[204:207], v[94:97]
	v_mfma_f32_16x16x32_bf16 v[78:81], v[156:159], v[212:215], v[78:81]
	v_mfma_f32_16x16x32_bf16 v[74:77], v[164:167], v[212:215], v[74:77]
	v_mfma_f32_16x16x32_bf16 v[90:93], v[164:167], v[204:207], v[90:93]
	v_mfma_f32_16x16x32_bf16 v[106:109], v[164:167], v[196:199], v[106:109]
	v_mfma_f32_16x16x32_bf16 v[122:125], v[164:167], v[188:191], v[122:125]
	v_mfma_f32_16x16x32_bf16 v[126:129], v[160:163], v[192:195], v[126:129]
	v_mfma_f32_16x16x32_bf16 v[110:113], v[160:163], v[200:203], v[110:113]
	v_mfma_f32_16x16x32_bf16 v[94:97], v[160:163], v[208:211], v[94:97]
	v_mfma_f32_16x16x32_bf16 v[78:81], v[160:163], v[216:219], v[78:81]
	v_mfma_f32_16x16x32_bf16 v[74:77], v[168:171], v[216:219], v[74:77]
	v_mfma_f32_16x16x32_bf16 v[90:93], v[168:171], v[208:211], v[90:93]
	v_mfma_f32_16x16x32_bf16 v[106:109], v[168:171], v[200:203], v[106:109]
	v_mfma_f32_16x16x32_bf16 v[122:125], v[168:171], v[192:195], v[122:125]
	v_mfma_f32_16x16x32_bf16 v[118:121], v[172:175], v[188:191], v[118:121]
	v_mfma_f32_16x16x32_bf16 v[102:105], v[172:175], v[196:199], v[102:105]
	v_mfma_f32_16x16x32_bf16 v[86:89], v[172:175], v[204:207], v[86:89]
	v_mfma_f32_16x16x32_bf16 v[70:73], v[172:175], v[212:215], v[70:73]
	v_mfma_f32_16x16x32_bf16 v[66:69], v[180:183], v[212:215], v[66:69]
	v_mfma_f32_16x16x32_bf16 v[82:85], v[180:183], v[204:207], v[82:85]
	v_mfma_f32_16x16x32_bf16 v[98:101], v[180:183], v[196:199], v[98:101]
	v_mfma_f32_16x16x32_bf16 v[114:117], v[180:183], v[188:191], v[114:117]
	v_mfma_f32_16x16x32_bf16 v[118:121], v[176:179], v[192:195], v[118:121]
	v_mfma_f32_16x16x32_bf16 v[102:105], v[176:179], v[200:203], v[102:105]
	v_mfma_f32_16x16x32_bf16 v[86:89], v[176:179], v[208:211], v[86:89]
	v_mfma_f32_16x16x32_bf16 v[70:73], v[176:179], v[216:219], v[70:73]
	v_mfma_f32_16x16x32_bf16 v[66:69], v[184:187], v[216:219], v[66:69]
	v_mfma_f32_16x16x32_bf16 v[82:85], v[184:187], v[208:211], v[82:85]
	v_mfma_f32_16x16x32_bf16 v[98:101], v[184:187], v[200:203], v[98:101]
	v_mfma_f32_16x16x32_bf16 v[114:117], v[184:187], v[192:195], v[114:117]
	s_barrier
	s_add_i32 s73, s66, s52
	v_lshl_add_u64 v[220:221], s[42:43], 0, v[132:133]
	s_mov_b32 m0, s73
	ds_read_b128 v[188:191], v155 offset:16384
	ds_read_b128 v[192:195], v155 offset:17408
	ds_read_b128 v[196:199], v155 offset:18432
	ds_read_b128 v[200:203], v155 offset:19456
	ds_read_b128 v[204:207], v155 offset:20480
	ds_read_b128 v[208:211], v155 offset:21504
	ds_read_b128 v[212:215], v155 offset:22528
	ds_read_b128 v[216:219], v155 offset:23552
	global_load_lds_dwordx4 v[220:221], off
	s_add_i32 m0, s73, 0x2000
	s_add_u32 s74, s42, 0xb0000
	v_lshl_add_u64 v[222:223], s[42:43], 0, v[136:137]
	s_addc_u32 s75, s43, 0
	s_add_i32 s73, s67, s52
	global_load_lds_dwordx4 v[222:223], off
	v_lshl_add_u64 v[224:225], s[74:75], 0, v[132:133]
	s_mov_b32 m0, s73
	v_lshl_add_u64 v[226:227], s[44:45], 0, v[134:135]
	global_load_lds_dwordx4 v[224:225], off
	v_lshl_add_u64 v[224:225], s[74:75], 0, v[136:137]
	s_add_i32 m0, s73, 0x2000
	s_nop 0
	global_load_lds_dwordx4 v[224:225], off
	v_lshl_add_u64 v[224:225], s[44:45], 0, v[130:131]
	s_mov_b32 m0, s53
	s_nop 0
	global_load_lds_dwordx4 v[224:225], off
	s_mov_b32 m0, s54
	s_nop 0
	global_load_lds_dwordx4 v[226:227], off
	s_waitcnt vmcnt(8)
	s_waitcnt lgkmcnt(0)
	s_barrier
; #define PG8_STAGEA(bufoff, gbase) PG8_STAGE_(bufoff, gbase, voffA)
; #define PG8_LDA(dst, b, h) do { _Pragma("unroll") for (int m = 0; m < 4; ++m) _Pragma("unroll") for (int k = 0; k < 2; ++k) dst[m][k] = *(const LAS bf16x8*)(lds + PG8_SA(b, h) + aoff + m * 2048 + k * 1024); } while (0)
; #define PG8_LDB(dst, b, h) do { _Pragma("unroll") for (int n = 0; n < 2; ++n) _Pragma("unroll") for (int k = 0; k < 2; ++k) dst[n][k] = *(const LAS bf16x8*)(lds + PG8_SB(b, h) + boff + n * 2048 + k * 1024); } while (0)
; #define PG8_MMA(ai, bj, At, Bt_) do { __builtin_amdgcn_s_setprio(1); _Pragma("unroll") for (int m = 0; m < 4; ++m) _Pragma("unroll") for (int n = 0; n < 2; ++n) _Pragma("unroll") for (int k = 0; k < 2; ++k) \
;         acc[ai][bj][m][n] = __builtin_amdgcn_mfma_f32_16x16x32_bf16(Bt_[n][k], At[m][k], acc[ai][bj][m][n], 0, 0, 0); __builtin_amdgcn_s_setprio(0); } while (0)
; #define PG8_WAIT_V(n) asm volatile("s_waitcnt vmcnt(" #n ")" ::: "memory")
; #define PG8_WAIT_L(n) asm volatile("s_waitcnt lgkmcnt(" #n ")" ::: "memory")
; #define PG8_BAR __builtin_amdgcn_s_barrier()
; #define PG8_SCHED __builtin_amdgcn_sched_barrier(0)
; template <int EK, int SK = -1>
; __device__ __forceinline__ void gemm_phase(LAS unsigned char* lds, const bf16_t* A, const bf16_t* Bt, int nM, int N, int K, const EpiArgs& E) {
;     ...
;             PG8_WAIT_V(8); PG8_WAIT_L(0); PG8_BAR; PG8_MMA(1, 0, At, B0); PG8_MMA(1, 1, At, B1); PG8_BAR; PG8_SCHED;
;             PG8_LDB(B0, 1, 0); PG8_LDB(B1, 1, 1); PG8_SCHED; PG8_LDA(At, 1, 0); PG8_STAGEA(PG8_SA(0, 1), a2 + hstep);
;             PG8_WAIT_V(8); PG8_WAIT_L(0); PG8_BAR; PG8_MMA(0, 0, At, B0); PG8_MMA(0, 1, At, B1); PG8_BAR; PG8_SCHED;
	s_waitcnt lgkmcnt(0)
	v_mfma_f32_16x16x32_bf16 v[62:65], v[156:159], v[188:191], v[62:65]
	v_mfma_f32_16x16x32_bf16 v[46:49], v[156:159], v[196:199], v[46:49]
	v_mfma_f32_16x16x32_bf16 v[30:33], v[156:159], v[204:207], v[30:33]
	v_mfma_f32_16x16x32_bf16 v[14:17], v[156:159], v[212:215], v[14:17]
	v_mfma_f32_16x16x32_bf16 v[10:13], v[164:167], v[212:215], v[10:13]
	v_mfma_f32_16x16x32_bf16 v[26:29], v[164:167], v[204:207], v[26:29]
	v_mfma_f32_16x16x32_bf16 v[42:45], v[164:167], v[196:199], v[42:45]
	v_mfma_f32_16x16x32_bf16 v[58:61], v[164:167], v[188:191], v[58:61]
	v_mfma_f32_16x16x32_bf16 v[62:65], v[160:163], v[192:195], v[62:65]
	v_mfma_f32_16x16x32_bf16 v[46:49], v[160:163], v[200:203], v[46:49]
	v_mfma_f32_16x16x32_bf16 v[30:33], v[160:163], v[208:211], v[30:33]
	v_mfma_f32_16x16x32_bf16 v[14:17], v[160:163], v[216:219], v[14:17]
	v_mfma_f32_16x16x32_bf16 v[10:13], v[168:171], v[216:219], v[10:13]
	v_mfma_f32_16x16x32_bf16 v[26:29], v[168:171], v[208:211], v[26:29]
	v_mfma_f32_16x16x32_bf16 v[42:45], v[168:171], v[200:203], v[42:45]
	v_mfma_f32_16x16x32_bf16 v[58:61], v[168:171], v[192:195], v[58:61]
	v_mfma_f32_16x16x32_bf16 v[54:57], v[172:175], v[188:191], v[54:57]
	v_mfma_f32_16x16x32_bf16 v[38:41], v[172:175], v[196:199], v[38:41]
	v_mfma_f32_16x16x32_bf16 v[22:25], v[172:175], v[204:207], v[22:25]
	v_mfma_f32_16x16x32_bf16 v[6:9], v[172:175], v[212:215], v[6:9]
	v_mfma_f32_16x16x32_bf16 v[2:5], v[180:183], v[212:215], v[2:5]
	v_mfma_f32_16x16x32_bf16 v[18:21], v[180:183], v[204:207], v[18:21]
	v_mfma_f32_16x16x32_bf16 v[34:37], v[180:183], v[196:199], v[34:37]
	v_mfma_f32_16x16x32_bf16 v[50:53], v[180:183], v[188:191], v[50:53]
	v_mfma_f32_16x16x32_bf16 v[54:57], v[176:179], v[192:195], v[54:57]
	v_mfma_f32_16x16x32_bf16 v[38:41], v[176:179], v[200:203], v[38:41]
	v_mfma_f32_16x16x32_bf16 v[22:25], v[176:179], v[208:211], v[22:25]
	v_mfma_f32_16x16x32_bf16 v[6:9], v[176:179], v[216:219], v[6:9]
	v_mfma_f32_16x16x32_bf16 v[2:5], v[184:187], v[216:219], v[2:5]
	v_mfma_f32_16x16x32_bf16 v[18:21], v[184:187], v[208:211], v[18:21]
	v_mfma_f32_16x16x32_bf16 v[34:37], v[184:187], v[200:203], v[34:37]
	v_mfma_f32_16x16x32_bf16 v[50:53], v[184:187], v[192:195], v[50:53]
	s_barrier
	s_add_i32 s73, 0, 0x18000
	s_add_i32 s74, 0, 0x1c000
	v_add_u32_e32 v168, s73, v154
	v_add_u32_e32 v184, s74, v154
	ds_read_b128 v[156:159], v168
	ds_read_b128 v[160:163], v168 offset:1024
	ds_read_b128 v[164:167], v168 offset:2048
	ds_read_b128 v[168:171], v168 offset:3072
	ds_read_b128 v[172:175], v184
	ds_read_b128 v[176:179], v184 offset:1024
	ds_read_b128 v[180:183], v184 offset:2048
	ds_read_b128 v[184:187], v184 offset:3072
	s_add_u32 s44, s44, 0xb0000
	s_addc_u32 s45, s45, 0
	s_mov_b32 m0, s55
	v_lshl_add_u64 v[228:229], s[44:45], 0, v[130:131]
	ds_read_b128 v[188:191], v155 offset:32768
	ds_read_b128 v[192:195], v155 offset:33792
	ds_read_b128 v[196:199], v155 offset:34816
	ds_read_b128 v[200:203], v155 offset:35840
	ds_read_b128 v[204:207], v155 offset:36864
	ds_read_b128 v[208:211], v155 offset:37888
	ds_read_b128 v[212:215], v155 offset:38912
	ds_read_b128 v[216:219], v155 offset:39936
	global_load_lds_dwordx4 v[228:229], off
	v_lshl_add_u64 v[228:229], s[44:45], 0, v[134:135]
	s_mov_b32 m0, s56
	s_nop 0
	global_load_lds_dwordx4 v[228:229], off
	s_waitcnt vmcnt(8)
	s_waitcnt lgkmcnt(0)
	s_barrier
	s_waitcnt lgkmcnt(0)
	v_mfma_f32_16x16x32_bf16 v[126:129], v[156:159], v[188:191], v[126:129]
	v_mfma_f32_16x16x32_bf16 v[110:113], v[156:159], v[196:199], v[110:113]
	v_mfma_f32_16x16x32_bf16 v[94:97], v[156:159], v[204:207], v[94:97]
	v_mfma_f32_16x16x32_bf16 v[78:81], v[156:159], v[212:215], v[78:81]
	v_mfma_f32_16x16x32_bf16 v[74:77], v[164:167], v[212:215], v[74:77]
	v_mfma_f32_16x16x32_bf16 v[90:93], v[164:167], v[204:207], v[90:93]
	v_mfma_f32_16x16x32_bf16 v[106:109], v[164:167], v[196:199], v[106:109]
	v_mfma_f32_16x16x32_bf16 v[122:125], v[164:167], v[188:191], v[122:125]
	v_mfma_f32_16x16x32_bf16 v[126:129], v[160:163], v[192:195], v[126:129]
	v_mfma_f32_16x16x32_bf16 v[110:113], v[160:163], v[200:203], v[110:113]
	v_mfma_f32_16x16x32_bf16 v[94:97], v[160:163], v[208:211], v[94:97]
	v_mfma_f32_16x16x32_bf16 v[78:81], v[160:163], v[216:219], v[78:81]
	v_mfma_f32_16x16x32_bf16 v[74:77], v[168:171], v[216:219], v[74:77]
	v_mfma_f32_16x16x32_bf16 v[90:93], v[168:171], v[208:211], v[90:93]
	v_mfma_f32_16x16x32_bf16 v[106:109], v[168:171], v[200:203], v[106:109]
	v_mfma_f32_16x16x32_bf16 v[122:125], v[168:171], v[192:195], v[122:125]
	v_mfma_f32_16x16x32_bf16 v[118:121], v[172:175], v[188:191], v[118:121]
	v_mfma_f32_16x16x32_bf16 v[102:105], v[172:175], v[196:199], v[102:105]
	v_mfma_f32_16x16x32_bf16 v[86:89], v[172:175], v[204:207], v[86:89]
	v_mfma_f32_16x16x32_bf16 v[70:73], v[172:175], v[212:215], v[70:73]
	v_mfma_f32_16x16x32_bf16 v[66:69], v[180:183], v[212:215], v[66:69]
	v_mfma_f32_16x16x32_bf16 v[82:85], v[180:183], v[204:207], v[82:85]
	v_mfma_f32_16x16x32_bf16 v[98:101], v[180:183], v[196:199], v[98:101]
	v_mfma_f32_16x16x32_bf16 v[114:117], v[180:183], v[188:191], v[114:117]
	v_mfma_f32_16x16x32_bf16 v[118:121], v[176:179], v[192:195], v[118:121]
	v_mfma_f32_16x16x32_bf16 v[102:105], v[176:179], v[200:203], v[102:105]
	v_mfma_f32_16x16x32_bf16 v[86:89], v[176:179], v[208:211], v[86:89]
	v_mfma_f32_16x16x32_bf16 v[70:73], v[176:179], v[216:219], v[70:73]
	v_mfma_f32_16x16x32_bf16 v[66:69], v[184:187], v[216:219], v[66:69]
	v_mfma_f32_16x16x32_bf16 v[82:85], v[184:187], v[208:211], v[82:85]
	v_mfma_f32_16x16x32_bf16 v[98:101], v[184:187], v[200:203], v[98:101]
	v_mfma_f32_16x16x32_bf16 v[114:117], v[184:187], v[192:195], v[114:117]
	s_barrier
; #define PG8_STAGEA(bufoff, gbase) PG8_STAGE_(bufoff, gbase, voffA)
; #define PG8_STAGEB(bufoff, gbase) PG8_STAGE_(bufoff, gbase, voffB)
; #define PG8_LDA(dst, b, h) do { _Pragma("unroll") for (int m = 0; m < 4; ++m) _Pragma("unroll") for (int k = 0; k < 2; ++k) dst[m][k] = *(const LAS bf16x8*)(lds + PG8_SA(b, h) + aoff + m * 2048 + k * 1024); } while (0)
; #define PG8_MMA(ai, bj, At, Bt_) do { __builtin_amdgcn_s_setprio(1); _Pragma("unroll") for (int m = 0; m < 4; ++m) _Pragma("unroll") for (int n = 0; n < 2; ++n) _Pragma("unroll") for (int k = 0; k < 2; ++k) \
;         acc[ai][bj][m][n] = __builtin_amdgcn_mfma_f32_16x16x32_bf16(Bt_[n][k], At[m][k], acc[ai][bj][m][n], 0, 0, 0); __builtin_amdgcn_s_setprio(0); } while (0)
; #define PG8_WAIT_V(n) asm volatile("s_waitcnt vmcnt(" #n ")" ::: "memory")
; #define PG8_WAIT_L(n) asm volatile("s_waitcnt lgkmcnt(" #n ")" ::: "memory")
; #define PG8_BAR __builtin_amdgcn_s_barrier()
; #define PG8_SCHED __builtin_amdgcn_sched_barrier(0)
; template <int EK, int SK = -1>
; __device__ __forceinline__ void gemm_phase(LAS unsigned char* lds, const bf16_t* A, const bf16_t* Bt, int nM, int N, int K, const EpiArgs& E) {
;     ...
;             PG8_LDA(At, 1, 1); PG8_STAGEB(PG8_SB(1, 0), b3); PG8_STAGEB(PG8_SB(1, 1), b3 + hstep); PG8_STAGEA(PG8_SA(1, 0), a3);
;             PG8_WAIT_V(8); PG8_WAIT_L(0); PG8_BAR; PG8_MMA(1, 0, At, B0); PG8_MMA(1, 1, At, B1); PG8_BAR; PG8_SCHED;
;         }
;         if (wr == 0) PG8_BAR;
	s_add_i32 s44, s73, s52
	v_lshl_add_u64 v[220:221], v[220:221], 0, s[22:23]
	s_mov_b32 m0, s44
	ds_read_b128 v[188:191], v155 offset:49152
	ds_read_b128 v[192:195], v155 offset:50176
	ds_read_b128 v[196:199], v155 offset:51200
	ds_read_b128 v[200:203], v155 offset:52224
	ds_read_b128 v[204:207], v155 offset:53248
	ds_read_b128 v[208:211], v155 offset:54272
	ds_read_b128 v[212:215], v155 offset:55296
	ds_read_b128 v[216:219], v155 offset:56320
	global_load_lds_dwordx4 v[220:221], off
	s_add_i32 m0, s44, 0x2000
	s_add_u32 s42, s42, 0xb0080
	v_lshl_add_u64 v[220:221], v[222:223], 0, s[22:23]
	s_addc_u32 s43, s43, 0
	s_add_i32 s44, s74, s52
	global_load_lds_dwordx4 v[220:221], off
	v_lshl_add_u64 v[220:221], s[42:43], 0, v[132:133]
	s_mov_b32 m0, s44
	s_nop 0
	global_load_lds_dwordx4 v[220:221], off
	v_lshl_add_u64 v[220:221], s[42:43], 0, v[136:137]
	s_add_i32 m0, s44, 0x2000
	s_nop 0
	global_load_lds_dwordx4 v[220:221], off
	v_lshl_add_u64 v[220:221], v[224:225], 0, s[22:23]
	s_mov_b32 m0, s58
	s_nop 0
	global_load_lds_dwordx4 v[220:221], off
	v_lshl_add_u64 v[220:221], v[226:227], 0, s[22:23]
	s_mov_b32 m0, s59
	s_nop 0
	global_load_lds_dwordx4 v[220:221], off
	s_waitcnt vmcnt(8)
	s_waitcnt lgkmcnt(0)
	s_barrier
	s_waitcnt lgkmcnt(0)
	v_mfma_f32_16x16x32_bf16 v[62:65], v[156:159], v[188:191], v[62:65]
	v_mfma_f32_16x16x32_bf16 v[46:49], v[156:159], v[196:199], v[46:49]
	v_mfma_f32_16x16x32_bf16 v[30:33], v[156:159], v[204:207], v[30:33]
	v_mfma_f32_16x16x32_bf16 v[14:17], v[156:159], v[212:215], v[14:17]
	v_mfma_f32_16x16x32_bf16 v[10:13], v[164:167], v[212:215], v[10:13]
	v_mfma_f32_16x16x32_bf16 v[26:29], v[164:167], v[204:207], v[26:29]
	v_mfma_f32_16x16x32_bf16 v[42:45], v[164:167], v[196:199], v[42:45]
	v_mfma_f32_16x16x32_bf16 v[58:61], v[164:167], v[188:191], v[58:61]
	v_mfma_f32_16x16x32_bf16 v[62:65], v[160:163], v[192:195], v[62:65]
	v_mfma_f32_16x16x32_bf16 v[46:49], v[160:163], v[200:203], v[46:49]
	v_mfma_f32_16x16x32_bf16 v[30:33], v[160:163], v[208:211], v[30:33]
	v_mfma_f32_16x16x32_bf16 v[14:17], v[160:163], v[216:219], v[14:17]
	v_mfma_f32_16x16x32_bf16 v[10:13], v[168:171], v[216:219], v[10:13]
	v_mfma_f32_16x16x32_bf16 v[26:29], v[168:171], v[208:211], v[26:29]
	v_mfma_f32_16x16x32_bf16 v[42:45], v[168:171], v[200:203], v[42:45]
	v_mfma_f32_16x16x32_bf16 v[58:61], v[168:171], v[192:195], v[58:61]
	v_mfma_f32_16x16x32_bf16 v[54:57], v[172:175], v[188:191], v[54:57]
	v_mfma_f32_16x16x32_bf16 v[38:41], v[172:175], v[196:199], v[38:41]
	v_mfma_f32_16x16x32_bf16 v[22:25], v[172:175], v[204:207], v[22:25]
	v_mfma_f32_16x16x32_bf16 v[6:9], v[172:175], v[212:215], v[6:9]
	v_mfma_f32_16x16x32_bf16 v[2:5], v[180:183], v[212:215], v[2:5]
	v_mfma_f32_16x16x32_bf16 v[18:21], v[180:183], v[204:207], v[18:21]
	v_mfma_f32_16x16x32_bf16 v[34:37], v[180:183], v[196:199], v[34:37]
	v_mfma_f32_16x16x32_bf16 v[50:53], v[180:183], v[188:191], v[50:53]
	v_mfma_f32_16x16x32_bf16 v[54:57], v[176:179], v[192:195], v[54:57]
	v_mfma_f32_16x16x32_bf16 v[38:41], v[176:179], v[200:203], v[38:41]
	v_mfma_f32_16x16x32_bf16 v[22:25], v[176:179], v[208:211], v[22:25]
	v_mfma_f32_16x16x32_bf16 v[6:9], v[176:179], v[216:219], v[6:9]
	v_mfma_f32_16x16x32_bf16 v[2:5], v[184:187], v[216:219], v[2:5]
	v_mfma_f32_16x16x32_bf16 v[18:21], v[184:187], v[208:211], v[18:21]
	v_mfma_f32_16x16x32_bf16 v[34:37], v[184:187], v[200:203], v[34:37]
	v_mfma_f32_16x16x32_bf16 v[50:53], v[184:187], v[192:195], v[50:53]
	s_barrier
	s_add_i32 s72, s72, 2
	s_add_u32 s40, s40, 0x100
	s_addc_u32 s41, s41, 0
	s_cmp_gt_u32 s72, 41
	s_cbranch_scc0 .LBB0_1401
	s_and_b64 vcc, exec, s[26:27]
	s_cbranch_vccz .LBB0_1404
	s_barrier
